# K-loop rebalance part 2: 4th load segment's last 2 LDS-DMA pieces deferred to next iteration's 1st segment (all segments 4 pieces), waits recounted
# baseline (speedup 1.0000x reference)
.LBB0_409:
	s_ashr_i32 s21, s20, 31
	s_lshl_b64 s[22:23], s[20:21], 19
	s_add_u32 s22, s37, s22
	s_addc_u32 s23, s38, s23
	s_and_b64 s[24:25], s[4:5], exec
	s_cselect_b32 s21, s23, s29
	s_cselect_b32 s61, s22, s28
	s_ashr_i32 s19, s18, 31
	s_lshl_b64 s[24:25], s[18:19], 19
	s_add_u32 s24, s39, s24
	s_addc_u32 s25, s40, s25
	s_and_b64 s[34:35], s[4:5], exec
	s_cselect_b32 s19, s25, s31
	s_cselect_b32 s62, s24, s30
	s_add_u32 s28, s28, 0x40080
	s_addc_u32 s29, s29, 0
	s_add_u32 s63, s30, 0x100
	v_mov_b32_e32 v8, 0
	s_addc_u32 s70, s31, 0
	s_mov_b32 s71, -2
	v_mov_b32_e32 v9, v8
	v_mov_b32_e32 v10, v8
	v_mov_b32_e32 v11, v8
	v_mov_b32_e32 v12, v8
	v_mov_b32_e32 v13, v8
	v_mov_b32_e32 v14, v8
	v_mov_b32_e32 v15, v8
	v_mov_b32_e32 v24, v8
	v_mov_b32_e32 v25, v8
	v_mov_b32_e32 v26, v8
	v_mov_b32_e32 v27, v8
	v_mov_b32_e32 v28, v8
	v_mov_b32_e32 v29, v8
	v_mov_b32_e32 v30, v8
	v_mov_b32_e32 v31, v8
	s_waitcnt vmcnt(0)
	v_mov_b32_e32 v40, v8
	v_mov_b32_e32 v41, v8
	v_mov_b32_e32 v42, v8
	v_mov_b32_e32 v43, v8
	v_mov_b32_e32 v44, v8
	v_mov_b32_e32 v45, v8
	v_mov_b32_e32 v46, v8
	v_mov_b32_e32 v47, v8
	v_mov_b32_e32 v56, v8
	v_mov_b32_e32 v57, v8
	v_mov_b32_e32 v58, v8
	v_mov_b32_e32 v59, v8
	v_mov_b32_e32 v60, v8
	v_mov_b32_e32 v61, v8
	v_mov_b32_e32 v62, v8
	v_mov_b32_e32 v63, v8
	v_mov_b32_e32 v0, v8
	v_mov_b32_e32 v1, v8
	v_mov_b32_e32 v2, v8
	v_mov_b32_e32 v3, v8
	v_mov_b32_e32 v4, v8
	v_mov_b32_e32 v5, v8
	v_mov_b32_e32 v6, v8
	v_mov_b32_e32 v7, v8
	v_mov_b32_e32 v16, v8
	v_mov_b32_e32 v17, v8
	v_mov_b32_e32 v18, v8
	v_mov_b32_e32 v19, v8
	v_mov_b32_e32 v20, v8
	v_mov_b32_e32 v21, v8
	v_mov_b32_e32 v22, v8
	v_mov_b32_e32 v23, v8
	v_mov_b32_e32 v32, v8
	v_mov_b32_e32 v33, v8
	v_mov_b32_e32 v34, v8
	v_mov_b32_e32 v35, v8
	v_mov_b32_e32 v36, v8
	v_mov_b32_e32 v37, v8
	v_mov_b32_e32 v38, v8
	v_mov_b32_e32 v39, v8
	v_mov_b32_e32 v48, v8
	v_mov_b32_e32 v49, v8
	v_mov_b32_e32 v50, v8
	v_mov_b32_e32 v51, v8
	v_mov_b32_e32 v52, v8
	v_mov_b32_e32 v53, v8
	v_mov_b32_e32 v54, v8
	v_mov_b32_e32 v55, v8
	v_mov_b32_e32 v72, v8
	v_mov_b32_e32 v73, v8
	v_mov_b32_e32 v74, v8
	v_mov_b32_e32 v75, v8
	v_mov_b32_e32 v76, v8
	v_mov_b32_e32 v77, v8
	v_mov_b32_e32 v78, v8
	v_mov_b32_e32 v79, v8
	v_mov_b32_e32 v88, v8
	v_mov_b32_e32 v89, v8
	v_mov_b32_e32 v90, v8
	v_mov_b32_e32 v91, v8
	v_mov_b32_e32 v92, v8
	v_mov_b32_e32 v93, v8
	v_mov_b32_e32 v94, v8
	v_mov_b32_e32 v95, v8
	v_mov_b32_e32 v104, v8
	v_mov_b32_e32 v105, v8
	v_mov_b32_e32 v106, v8
	v_mov_b32_e32 v107, v8
	v_mov_b32_e32 v108, v8
	v_mov_b32_e32 v109, v8
	v_mov_b32_e32 v110, v8
	v_mov_b32_e32 v111, v8
	v_mov_b32_e32 v120, v8
	v_mov_b32_e32 v121, v8
	v_mov_b32_e32 v122, v8
	v_mov_b32_e32 v123, v8
	v_mov_b32_e32 v124, v8
	v_mov_b32_e32 v125, v8
	v_mov_b32_e32 v126, v8
	v_mov_b32_e32 v127, v8
	v_mov_b32_e32 v64, v8
	v_mov_b32_e32 v65, v8
	v_mov_b32_e32 v66, v8
	v_mov_b32_e32 v67, v8
	v_mov_b32_e32 v68, v8
	v_mov_b32_e32 v69, v8
	v_mov_b32_e32 v70, v8
	v_mov_b32_e32 v71, v8
	v_mov_b32_e32 v80, v8
	v_mov_b32_e32 v81, v8
	v_mov_b32_e32 v82, v8
	v_mov_b32_e32 v83, v8
	v_mov_b32_e32 v84, v8
	v_mov_b32_e32 v85, v8
	v_mov_b32_e32 v86, v8
	v_mov_b32_e32 v87, v8
	v_mov_b32_e32 v96, v8
	v_mov_b32_e32 v97, v8
	v_mov_b32_e32 v98, v8
	v_mov_b32_e32 v99, v8
	v_mov_b32_e32 v100, v8
	v_mov_b32_e32 v101, v8
	v_mov_b32_e32 v102, v8
	v_mov_b32_e32 v103, v8
	v_mov_b32_e32 v112, v8
	v_mov_b32_e32 v113, v8
	v_mov_b32_e32 v114, v8
	v_mov_b32_e32 v115, v8
	v_mov_b32_e32 v116, v8
	v_mov_b32_e32 v117, v8
	v_mov_b32_e32 v118, v8
	v_mov_b32_e32 v119, v8
	s_mov_b32 s99, 0
.LBB0_410:
	ds_read_b128 v[154:157], v149
	ds_read_b128 v[158:161], v149 offset:1024
	ds_read_b128 v[162:165], v149 offset:2048
	ds_read_b128 v[166:169], v149 offset:3072
	ds_read_b128 v[170:173], v150
	ds_read_b128 v[174:177], v150 offset:1024
	ds_read_b128 v[178:181], v150 offset:2048
	ds_read_b128 v[182:185], v150 offset:3072
	s_add_u32 s30, s28, 0xfffc0080
	s_addc_u32 s31, s29, -1
	s_cmp_eq_u32 s71, 12
	s_cselect_b32 s35, s21, s31
	s_cselect_b32 s34, s61, s30
	s_cselect_b32 s31, s19, s70
	s_cselect_b32 s30, s62, s63
	v_lshl_add_u64 v[144:145], s[28:29], 0, v[136:137]
	ds_read_b128 v[186:189], v151
	ds_read_b128 v[190:193], v151 offset:1024
	ds_read_b128 v[196:199], v151 offset:2048
	ds_read_b128 v[200:203], v151 offset:3072
	ds_read_b128 v[204:207], v151 offset:4096
	ds_read_b128 v[208:211], v151 offset:5120
	ds_read_b128 v[212:215], v151 offset:6144
	ds_read_b128 v[216:219], v151 offset:7168
	s_cmp_eq_u32 s99, 0
	s_cbranch_scc1 .Lkb_first_0
	v_lshl_add_u64 v[222:223], v[222:223], 0, s[12:13]
	s_mov_b32 m0, s51
	s_nop 0
	global_load_lds_dwordx4 v[222:223], off
	v_lshl_add_u64 v[224:225], v[224:225], 0, s[12:13]
	s_mov_b32 m0, s52
	s_nop 0
	global_load_lds_dwordx4 v[224:225], off
	s_branch .Lkb_join_0
.Lkb_first_0:
	s_add_i32 m0, s27, 0xc000
	s_nop 0
	global_load_lds_dwordx4 v[144:145], off
	global_load_lds_dwordx4 v[144:145], off
.Lkb_join_0:
	s_add_i32 m0, s27, 0xc000
	s_nop 0
	global_load_lds_dwordx4 v[144:145], off
	v_lshl_add_u64 v[144:145], s[28:29], 0, v[138:139]
	s_add_i32 m0, s27, 0xe000
	s_nop 0
	global_load_lds_dwordx4 v[144:145], off
	s_waitcnt vmcnt(8)
	s_waitcnt lgkmcnt(0)
	s_barrier
	s_setprio 1
	s_waitcnt lgkmcnt(0)
	v_mfma_f32_16x16x32_bf16 v[116:119], v[154:157], v[186:189], v[116:119]
	v_mfma_f32_16x16x32_bf16 v[112:115], v[162:165], v[186:189], v[112:115]
	v_mfma_f32_16x16x32_bf16 v[100:103], v[154:157], v[196:199], v[100:103]
	v_mfma_f32_16x16x32_bf16 v[96:99], v[162:165], v[196:199], v[96:99]
	v_mfma_f32_16x16x32_bf16 v[84:87], v[154:157], v[204:207], v[84:87]
	v_mfma_f32_16x16x32_bf16 v[80:83], v[162:165], v[204:207], v[80:83]
	v_mfma_f32_16x16x32_bf16 v[68:71], v[154:157], v[212:215], v[68:71]
	v_mfma_f32_16x16x32_bf16 v[64:67], v[162:165], v[212:215], v[64:67]
	v_mfma_f32_16x16x32_bf16 v[116:119], v[158:161], v[190:193], v[116:119]
	v_mfma_f32_16x16x32_bf16 v[112:115], v[166:169], v[190:193], v[112:115]
	v_mfma_f32_16x16x32_bf16 v[100:103], v[158:161], v[200:203], v[100:103]
	v_mfma_f32_16x16x32_bf16 v[96:99], v[166:169], v[200:203], v[96:99]
	v_mfma_f32_16x16x32_bf16 v[84:87], v[158:161], v[208:211], v[84:87]
	v_mfma_f32_16x16x32_bf16 v[80:83], v[166:169], v[208:211], v[80:83]
	v_mfma_f32_16x16x32_bf16 v[68:71], v[158:161], v[216:219], v[68:71]
	v_mfma_f32_16x16x32_bf16 v[64:67], v[166:169], v[216:219], v[64:67]
	s_setprio 0
	s_setprio 1
	v_mfma_f32_16x16x32_bf16 v[124:127], v[170:173], v[186:189], v[124:127]
	v_mfma_f32_16x16x32_bf16 v[120:123], v[178:181], v[186:189], v[120:123]
	v_mfma_f32_16x16x32_bf16 v[108:111], v[170:173], v[196:199], v[108:111]
	v_mfma_f32_16x16x32_bf16 v[104:107], v[178:181], v[196:199], v[104:107]
	v_mfma_f32_16x16x32_bf16 v[92:95], v[170:173], v[204:207], v[92:95]
	v_mfma_f32_16x16x32_bf16 v[88:91], v[178:181], v[204:207], v[88:91]
	v_mfma_f32_16x16x32_bf16 v[76:79], v[170:173], v[212:215], v[76:79]
	v_mfma_f32_16x16x32_bf16 v[72:75], v[178:181], v[212:215], v[72:75]
	v_mfma_f32_16x16x32_bf16 v[124:127], v[174:177], v[190:193], v[124:127]
	v_mfma_f32_16x16x32_bf16 v[120:123], v[182:185], v[190:193], v[120:123]
	v_mfma_f32_16x16x32_bf16 v[108:111], v[174:177], v[200:203], v[108:111]
	v_mfma_f32_16x16x32_bf16 v[104:107], v[182:185], v[200:203], v[104:107]
	v_mfma_f32_16x16x32_bf16 v[92:95], v[174:177], v[208:211], v[92:95]
	v_mfma_f32_16x16x32_bf16 v[88:91], v[182:185], v[208:211], v[88:91]
	v_mfma_f32_16x16x32_bf16 v[76:79], v[174:177], v[216:219], v[76:79]
	v_mfma_f32_16x16x32_bf16 v[72:75], v[182:185], v[216:219], v[72:75]
	s_setprio 0
	s_barrier
	s_add_i32 s72, s54, s41
	v_lshl_add_u64 v[144:145], s[30:31], 0, v[132:133]
	s_mov_b32 m0, s72
	ds_read_b128 v[186:189], v151 offset:16384
	ds_read_b128 v[190:193], v151 offset:17408
	ds_read_b128 v[196:199], v151 offset:18432
	ds_read_b128 v[200:203], v151 offset:19456
	ds_read_b128 v[204:207], v151 offset:20480
	ds_read_b128 v[208:211], v151 offset:21504
	ds_read_b128 v[212:215], v151 offset:22528
	ds_read_b128 v[216:219], v151 offset:23552
	global_load_lds_dwordx4 v[144:145], off
	s_add_i32 m0, s72, 0x2000
	s_add_u32 s72, s30, 0x40000
	v_lshl_add_u64 v[220:221], s[30:31], 0, v[128:129]
	s_addc_u32 s73, s31, 0
	s_add_i32 s77, s55, s41
	global_load_lds_dwordx4 v[220:221], off
	v_lshl_add_u64 v[222:223], s[72:73], 0, v[132:133]
	s_mov_b32 m0, s77
	v_lshl_add_u64 v[224:225], s[34:35], 0, v[130:131]
	global_load_lds_dwordx4 v[222:223], off
	v_lshl_add_u64 v[222:223], s[72:73], 0, v[128:129]
	s_add_i32 m0, s77, 0x2000
	s_nop 0
	global_load_lds_dwordx4 v[222:223], off
	v_lshl_add_u64 v[222:223], s[34:35], 0, v[134:135]
	s_waitcnt vmcnt(6)
	s_waitcnt lgkmcnt(0)
	s_barrier
	s_setprio 1
	s_waitcnt lgkmcnt(0)
	v_mfma_f32_16x16x32_bf16 v[52:55], v[154:157], v[186:189], v[52:55]
	v_mfma_f32_16x16x32_bf16 v[48:51], v[162:165], v[186:189], v[48:51]
	v_mfma_f32_16x16x32_bf16 v[36:39], v[154:157], v[196:199], v[36:39]
	v_mfma_f32_16x16x32_bf16 v[32:35], v[162:165], v[196:199], v[32:35]
	v_mfma_f32_16x16x32_bf16 v[20:23], v[154:157], v[204:207], v[20:23]
	v_mfma_f32_16x16x32_bf16 v[16:19], v[162:165], v[204:207], v[16:19]
	v_mfma_f32_16x16x32_bf16 v[4:7], v[154:157], v[212:215], v[4:7]
	v_mfma_f32_16x16x32_bf16 v[0:3], v[162:165], v[212:215], v[0:3]
	v_mfma_f32_16x16x32_bf16 v[52:55], v[158:161], v[190:193], v[52:55]
	v_mfma_f32_16x16x32_bf16 v[48:51], v[166:169], v[190:193], v[48:51]
	v_mfma_f32_16x16x32_bf16 v[36:39], v[158:161], v[200:203], v[36:39]
	v_mfma_f32_16x16x32_bf16 v[32:35], v[166:169], v[200:203], v[32:35]
	v_mfma_f32_16x16x32_bf16 v[20:23], v[158:161], v[208:211], v[20:23]
	v_mfma_f32_16x16x32_bf16 v[16:19], v[166:169], v[208:211], v[16:19]
	v_mfma_f32_16x16x32_bf16 v[4:7], v[158:161], v[216:219], v[4:7]
	v_mfma_f32_16x16x32_bf16 v[0:3], v[166:169], v[216:219], v[0:3]
	s_setprio 0
	s_setprio 1
	v_mfma_f32_16x16x32_bf16 v[60:63], v[170:173], v[186:189], v[60:63]
	v_mfma_f32_16x16x32_bf16 v[56:59], v[178:181], v[186:189], v[56:59]
	v_mfma_f32_16x16x32_bf16 v[44:47], v[170:173], v[196:199], v[44:47]
	v_mfma_f32_16x16x32_bf16 v[40:43], v[178:181], v[196:199], v[40:43]
	v_mfma_f32_16x16x32_bf16 v[28:31], v[170:173], v[204:207], v[28:31]
	v_mfma_f32_16x16x32_bf16 v[24:27], v[178:181], v[204:207], v[24:27]
	v_mfma_f32_16x16x32_bf16 v[12:15], v[170:173], v[212:215], v[12:15]
	v_mfma_f32_16x16x32_bf16 v[8:11], v[178:181], v[212:215], v[8:11]
	v_mfma_f32_16x16x32_bf16 v[60:63], v[174:177], v[190:193], v[60:63]
	v_mfma_f32_16x16x32_bf16 v[56:59], v[182:185], v[190:193], v[56:59]
	v_mfma_f32_16x16x32_bf16 v[44:47], v[174:177], v[200:203], v[44:47]
	v_mfma_f32_16x16x32_bf16 v[40:43], v[182:185], v[200:203], v[40:43]
	v_mfma_f32_16x16x32_bf16 v[28:31], v[174:177], v[208:211], v[28:31]
	v_mfma_f32_16x16x32_bf16 v[24:27], v[182:185], v[208:211], v[24:27]
	v_mfma_f32_16x16x32_bf16 v[12:15], v[174:177], v[216:219], v[12:15]
	v_mfma_f32_16x16x32_bf16 v[8:11], v[182:185], v[216:219], v[8:11]
	s_setprio 0
	s_barrier
	s_add_i32 s72, 0, 0x18000
	v_add_u32_e32 v153, s72, v147
	s_add_i32 s73, 0, 0x1c000
	ds_read_b128 v[154:157], v153
	ds_read_b128 v[158:161], v153 offset:1024
	ds_read_b128 v[162:165], v153 offset:2048
	ds_read_b128 v[166:169], v153 offset:3072
	v_add_u32_e32 v153, s73, v147
	ds_read_b128 v[170:173], v153
	ds_read_b128 v[174:177], v153 offset:1024
	ds_read_b128 v[178:181], v153 offset:2048
	ds_read_b128 v[182:185], v153 offset:3072
	s_add_u32 s34, s34, 0x40000
	s_addc_u32 s35, s35, 0
	v_lshl_add_u64 v[226:227], s[34:35], 0, v[134:135]
	ds_read_b128 v[186:189], v151 offset:32768
	ds_read_b128 v[190:193], v151 offset:33792
	ds_read_b128 v[196:199], v151 offset:34816
	ds_read_b128 v[200:203], v151 offset:35840
	ds_read_b128 v[204:207], v151 offset:36864
	ds_read_b128 v[208:211], v151 offset:37888
	ds_read_b128 v[212:215], v151 offset:38912
	ds_read_b128 v[216:219], v151 offset:39936
	s_mov_b32 m0, s27
	s_nop 0
	global_load_lds_dwordx4 v[222:223], off
	s_mov_b32 m0, s43
	s_nop 0
	global_load_lds_dwordx4 v[224:225], off
	s_mov_b32 m0, s44
	s_nop 0
	global_load_lds_dwordx4 v[226:227], off
	v_lshl_add_u64 v[226:227], s[34:35], 0, v[130:131]
	s_mov_b32 m0, s45
	s_nop 0
	global_load_lds_dwordx4 v[226:227], off
	s_waitcnt vmcnt(8)
	s_waitcnt lgkmcnt(0)
	s_barrier
	s_setprio 1
	s_waitcnt lgkmcnt(0)
	v_mfma_f32_16x16x32_bf16 v[116:119], v[154:157], v[186:189], v[116:119]
	v_mfma_f32_16x16x32_bf16 v[112:115], v[162:165], v[186:189], v[112:115]
	v_mfma_f32_16x16x32_bf16 v[100:103], v[154:157], v[196:199], v[100:103]
	v_mfma_f32_16x16x32_bf16 v[96:99], v[162:165], v[196:199], v[96:99]
	v_mfma_f32_16x16x32_bf16 v[84:87], v[154:157], v[204:207], v[84:87]
	v_mfma_f32_16x16x32_bf16 v[80:83], v[162:165], v[204:207], v[80:83]
	v_mfma_f32_16x16x32_bf16 v[68:71], v[154:157], v[212:215], v[68:71]
	v_mfma_f32_16x16x32_bf16 v[64:67], v[162:165], v[212:215], v[64:67]
	v_mfma_f32_16x16x32_bf16 v[116:119], v[158:161], v[190:193], v[116:119]
	v_mfma_f32_16x16x32_bf16 v[112:115], v[166:169], v[190:193], v[112:115]
	v_mfma_f32_16x16x32_bf16 v[100:103], v[158:161], v[200:203], v[100:103]
	v_mfma_f32_16x16x32_bf16 v[96:99], v[166:169], v[200:203], v[96:99]
	v_mfma_f32_16x16x32_bf16 v[84:87], v[158:161], v[208:211], v[84:87]
	v_mfma_f32_16x16x32_bf16 v[80:83], v[166:169], v[208:211], v[80:83]
	v_mfma_f32_16x16x32_bf16 v[68:71], v[158:161], v[216:219], v[68:71]
	v_mfma_f32_16x16x32_bf16 v[64:67], v[166:169], v[216:219], v[64:67]
	s_setprio 0
	s_setprio 1
	v_mfma_f32_16x16x32_bf16 v[124:127], v[170:173], v[186:189], v[124:127]
	v_mfma_f32_16x16x32_bf16 v[120:123], v[178:181], v[186:189], v[120:123]
	v_mfma_f32_16x16x32_bf16 v[108:111], v[170:173], v[196:199], v[108:111]
	v_mfma_f32_16x16x32_bf16 v[104:107], v[178:181], v[196:199], v[104:107]
	v_mfma_f32_16x16x32_bf16 v[92:95], v[170:173], v[204:207], v[92:95]
	v_mfma_f32_16x16x32_bf16 v[88:91], v[178:181], v[204:207], v[88:91]
	v_mfma_f32_16x16x32_bf16 v[76:79], v[170:173], v[212:215], v[76:79]
	v_mfma_f32_16x16x32_bf16 v[72:75], v[178:181], v[212:215], v[72:75]
	v_mfma_f32_16x16x32_bf16 v[124:127], v[174:177], v[190:193], v[124:127]
	v_mfma_f32_16x16x32_bf16 v[120:123], v[182:185], v[190:193], v[120:123]
	v_mfma_f32_16x16x32_bf16 v[108:111], v[174:177], v[200:203], v[108:111]
	v_mfma_f32_16x16x32_bf16 v[104:107], v[182:185], v[200:203], v[104:107]
	v_mfma_f32_16x16x32_bf16 v[92:95], v[174:177], v[208:211], v[92:95]
	v_mfma_f32_16x16x32_bf16 v[88:91], v[182:185], v[208:211], v[88:91]
	v_mfma_f32_16x16x32_bf16 v[76:79], v[174:177], v[216:219], v[76:79]
	v_mfma_f32_16x16x32_bf16 v[72:75], v[182:185], v[216:219], v[72:75]
	s_setprio 0
	s_barrier
	s_add_i32 s34, s72, s41
	v_lshl_add_u64 v[144:145], v[144:145], 0, s[12:13]
	s_mov_b32 m0, s34
	ds_read_b128 v[186:189], v151 offset:49152
	ds_read_b128 v[190:193], v151 offset:50176
	ds_read_b128 v[196:199], v151 offset:51200
	ds_read_b128 v[200:203], v151 offset:52224
	ds_read_b128 v[204:207], v151 offset:53248
	ds_read_b128 v[208:211], v151 offset:54272
	ds_read_b128 v[212:215], v151 offset:55296
	ds_read_b128 v[216:219], v151 offset:56320
	global_load_lds_dwordx4 v[144:145], off
	s_add_i32 m0, s34, 0x2000
	s_add_u32 s30, s30, 0x40080
	v_lshl_add_u64 v[144:145], v[220:221], 0, s[12:13]
	s_addc_u32 s31, s31, 0
	s_add_i32 s34, s73, s41
	global_load_lds_dwordx4 v[144:145], off
	v_lshl_add_u64 v[144:145], s[30:31], 0, v[132:133]
	s_mov_b32 m0, s34
	s_nop 0
	global_load_lds_dwordx4 v[144:145], off
	v_lshl_add_u64 v[144:145], s[30:31], 0, v[128:129]
	s_add_i32 m0, s34, 0x2000
	s_nop 0
	global_load_lds_dwordx4 v[144:145], off
	s_mov_b32 s99, 1
	s_waitcnt vmcnt(6)
	s_waitcnt lgkmcnt(0)
	s_barrier
	s_setprio 1
	s_waitcnt lgkmcnt(0)
	v_mfma_f32_16x16x32_bf16 v[52:55], v[154:157], v[186:189], v[52:55]
	v_mfma_f32_16x16x32_bf16 v[48:51], v[162:165], v[186:189], v[48:51]
	v_mfma_f32_16x16x32_bf16 v[36:39], v[154:157], v[196:199], v[36:39]
	v_mfma_f32_16x16x32_bf16 v[32:35], v[162:165], v[196:199], v[32:35]
	v_mfma_f32_16x16x32_bf16 v[20:23], v[154:157], v[204:207], v[20:23]
	v_mfma_f32_16x16x32_bf16 v[16:19], v[162:165], v[204:207], v[16:19]
	v_mfma_f32_16x16x32_bf16 v[4:7], v[154:157], v[212:215], v[4:7]
	v_mfma_f32_16x16x32_bf16 v[0:3], v[162:165], v[212:215], v[0:3]
	v_mfma_f32_16x16x32_bf16 v[52:55], v[158:161], v[190:193], v[52:55]
	v_mfma_f32_16x16x32_bf16 v[48:51], v[166:169], v[190:193], v[48:51]
	v_mfma_f32_16x16x32_bf16 v[36:39], v[158:161], v[200:203], v[36:39]
	v_mfma_f32_16x16x32_bf16 v[32:35], v[166:169], v[200:203], v[32:35]
	v_mfma_f32_16x16x32_bf16 v[20:23], v[158:161], v[208:211], v[20:23]
	v_mfma_f32_16x16x32_bf16 v[16:19], v[166:169], v[208:211], v[16:19]
	v_mfma_f32_16x16x32_bf16 v[4:7], v[158:161], v[216:219], v[4:7]
	v_mfma_f32_16x16x32_bf16 v[0:3], v[166:169], v[216:219], v[0:3]
	s_setprio 0
	s_setprio 1
	v_mfma_f32_16x16x32_bf16 v[60:63], v[170:173], v[186:189], v[60:63]
	v_mfma_f32_16x16x32_bf16 v[56:59], v[178:181], v[186:189], v[56:59]
	v_mfma_f32_16x16x32_bf16 v[44:47], v[170:173], v[196:199], v[44:47]
	v_mfma_f32_16x16x32_bf16 v[40:43], v[178:181], v[196:199], v[40:43]
	v_mfma_f32_16x16x32_bf16 v[28:31], v[170:173], v[204:207], v[28:31]
	v_mfma_f32_16x16x32_bf16 v[24:27], v[178:181], v[204:207], v[24:27]
	v_mfma_f32_16x16x32_bf16 v[12:15], v[170:173], v[212:215], v[12:15]
	v_mfma_f32_16x16x32_bf16 v[8:11], v[178:181], v[212:215], v[8:11]
	v_mfma_f32_16x16x32_bf16 v[60:63], v[174:177], v[190:193], v[60:63]
	v_mfma_f32_16x16x32_bf16 v[56:59], v[182:185], v[190:193], v[56:59]
	v_mfma_f32_16x16x32_bf16 v[44:47], v[174:177], v[200:203], v[44:47]
	v_mfma_f32_16x16x32_bf16 v[40:43], v[182:185], v[200:203], v[40:43]
	v_mfma_f32_16x16x32_bf16 v[28:31], v[174:177], v[208:211], v[28:31]
	v_mfma_f32_16x16x32_bf16 v[24:27], v[182:185], v[208:211], v[24:27]
	v_mfma_f32_16x16x32_bf16 v[12:15], v[174:177], v[216:219], v[12:15]
	v_mfma_f32_16x16x32_bf16 v[8:11], v[182:185], v[216:219], v[8:11]
	s_setprio 0
	s_barrier
	s_add_i32 s71, s71, 2
	s_add_u32 s28, s28, 0x100
	s_addc_u32 s29, s29, 0
	s_add_u32 s63, s63, 0x100
	s_addc_u32 s70, s70, 0
	s_cmp_gt_u32 s71, 13
	s_cbranch_scc0 .LBB0_410
	v_lshl_add_u64 v[222:223], v[222:223], 0, s[12:13]
	s_mov_b32 m0, s51
	s_nop 0
	global_load_lds_dwordx4 v[222:223], off
	v_lshl_add_u64 v[224:225], v[224:225], 0, s[12:13]
	s_mov_b32 m0, s52
	s_nop 0
	global_load_lds_dwordx4 v[224:225], off
	s_and_b64 vcc, exec, s[16:17]
	s_cbranch_vccz .LBB0_413
	s_barrier

.LBB0_531:
	s_add_u32 s72, s30, 0x100
	v_mov_b32_e32 v0, 0
	s_addc_u32 s73, s31, 0
	s_mov_b32 s77, -2
	s_waitcnt lgkmcnt(0)
	v_mov_b32_e32 v1, v0
	v_mov_b32_e32 v2, v0
	v_mov_b32_e32 v3, v0
	v_mov_b32_e32 v4, v0
	v_mov_b32_e32 v5, v0
	v_mov_b32_e32 v6, v0
	v_mov_b32_e32 v7, v0
	v_mov_b32_e32 v16, v0
	v_mov_b32_e32 v17, v0
	v_mov_b32_e32 v18, v0
	v_mov_b32_e32 v19, v0
	v_mov_b32_e32 v20, v0
	v_mov_b32_e32 v21, v0
	v_mov_b32_e32 v22, v0
	v_mov_b32_e32 v23, v0
	v_mov_b32_e32 v32, v0
	v_mov_b32_e32 v33, v0
	v_mov_b32_e32 v34, v0
	v_mov_b32_e32 v35, v0
	v_mov_b32_e32 v36, v0
	v_mov_b32_e32 v37, v0
	s_waitcnt vmcnt(0)
	v_mov_b32_e32 v38, v0
	v_mov_b32_e32 v39, v0
	v_mov_b32_e32 v48, v0
	v_mov_b32_e32 v49, v0
	v_mov_b32_e32 v50, v0
	v_mov_b32_e32 v51, v0
	v_mov_b32_e32 v52, v0
	v_mov_b32_e32 v53, v0
	v_mov_b32_e32 v54, v0
	v_mov_b32_e32 v55, v0
	v_mov_b32_e32 v8, v0
	v_mov_b32_e32 v9, v0
	v_mov_b32_e32 v10, v0
	v_mov_b32_e32 v11, v0
	v_mov_b32_e32 v12, v0
	v_mov_b32_e32 v13, v0
	v_mov_b32_e32 v14, v0
	v_mov_b32_e32 v15, v0
	v_mov_b32_e32 v24, v0
	v_mov_b32_e32 v25, v0
	v_mov_b32_e32 v26, v0
	v_mov_b32_e32 v27, v0
	v_mov_b32_e32 v28, v0
	v_mov_b32_e32 v29, v0
	v_mov_b32_e32 v30, v0
	v_mov_b32_e32 v31, v0
	v_mov_b32_e32 v40, v0
	v_mov_b32_e32 v41, v0
	v_mov_b32_e32 v42, v0
	v_mov_b32_e32 v43, v0
	v_mov_b32_e32 v44, v0
	v_mov_b32_e32 v45, v0
	v_mov_b32_e32 v46, v0
	v_mov_b32_e32 v47, v0
	v_mov_b32_e32 v56, v0
	v_mov_b32_e32 v57, v0
	v_mov_b32_e32 v58, v0
	v_mov_b32_e32 v59, v0
	v_mov_b32_e32 v60, v0
	v_mov_b32_e32 v61, v0
	v_mov_b32_e32 v62, v0
	v_mov_b32_e32 v63, v0
	v_mov_b32_e32 v64, v0
	v_mov_b32_e32 v65, v0
	v_mov_b32_e32 v66, v0
	v_mov_b32_e32 v67, v0
	v_mov_b32_e32 v68, v0
	v_mov_b32_e32 v69, v0
	v_mov_b32_e32 v70, v0
	v_mov_b32_e32 v71, v0
	v_mov_b32_e32 v80, v0
	v_mov_b32_e32 v81, v0
	v_mov_b32_e32 v82, v0
	v_mov_b32_e32 v83, v0
	v_mov_b32_e32 v84, v0
	v_mov_b32_e32 v85, v0
	v_mov_b32_e32 v86, v0
	v_mov_b32_e32 v87, v0
	v_mov_b32_e32 v96, v0
	v_mov_b32_e32 v97, v0
	v_mov_b32_e32 v98, v0
	v_mov_b32_e32 v99, v0
	v_mov_b32_e32 v100, v0
	v_mov_b32_e32 v101, v0
	v_mov_b32_e32 v102, v0
	v_mov_b32_e32 v103, v0
	v_mov_b32_e32 v112, v0
	v_mov_b32_e32 v113, v0
	v_mov_b32_e32 v114, v0
	v_mov_b32_e32 v115, v0
	v_mov_b32_e32 v116, v0
	v_mov_b32_e32 v117, v0
	v_mov_b32_e32 v118, v0
	v_mov_b32_e32 v119, v0
	v_mov_b32_e32 v72, v0
	v_mov_b32_e32 v73, v0
	v_mov_b32_e32 v74, v0
	v_mov_b32_e32 v75, v0
	v_mov_b32_e32 v76, v0
	v_mov_b32_e32 v77, v0
	v_mov_b32_e32 v78, v0
	v_mov_b32_e32 v79, v0
	v_mov_b32_e32 v88, v0
	v_mov_b32_e32 v89, v0
	v_mov_b32_e32 v90, v0
	v_mov_b32_e32 v91, v0
	v_mov_b32_e32 v92, v0
	v_mov_b32_e32 v93, v0
	v_mov_b32_e32 v94, v0
	v_mov_b32_e32 v95, v0
	v_mov_b32_e32 v104, v0
	v_mov_b32_e32 v105, v0
	v_mov_b32_e32 v106, v0
	v_mov_b32_e32 v107, v0
	v_mov_b32_e32 v108, v0
	v_mov_b32_e32 v109, v0
	v_mov_b32_e32 v110, v0
	v_mov_b32_e32 v111, v0
	v_mov_b32_e32 v120, v0
	v_mov_b32_e32 v121, v0
	v_mov_b32_e32 v122, v0
	v_mov_b32_e32 v123, v0
	v_mov_b32_e32 v124, v0
	v_mov_b32_e32 v125, v0
	v_mov_b32_e32 v126, v0
	v_mov_b32_e32 v127, v0
	s_mov_b32 s99, 0
.LBB0_532:
	ds_read_b128 v[146:149], v155
	ds_read_b128 v[160:163], v155 offset:1024
	ds_read_b128 v[164:167], v155 offset:2048
	ds_read_b128 v[168:171], v155 offset:3072
	ds_read_b128 v[172:175], v156
	ds_read_b128 v[176:179], v156 offset:1024
	ds_read_b128 v[180:183], v156 offset:2048
	ds_read_b128 v[184:187], v156 offset:3072
	s_add_u32 s30, s28, 0x100
	s_addc_u32 s31, s29, 0
	s_cmp_eq_u32 s77, 40
	s_cselect_b32 s37, s1, s31
	s_cselect_b32 s36, s0, s30
	s_cselect_b32 s35, s27, s73
	s_cselect_b32 s34, s26, s72
	v_lshl_add_u64 v[150:151], s[28:29], 0, v[138:139]
	ds_read_b128 v[188:191], v157
	ds_read_b128 v[196:199], v157 offset:1024
	ds_read_b128 v[200:203], v157 offset:2048
	ds_read_b128 v[204:207], v157 offset:3072
	ds_read_b128 v[208:211], v157 offset:4096
	ds_read_b128 v[212:215], v157 offset:5120
	ds_read_b128 v[216:219], v157 offset:6144
	ds_read_b128 v[220:223], v157 offset:7168
	s_cmp_eq_u32 s99, 0
	s_cbranch_scc1 .Lkb_first_1
	v_lshl_add_u64 v[224:225], v[224:225], 0, s[22:23]
	s_mov_b32 m0, s55
	s_nop 0
	global_load_lds_dwordx4 v[224:225], off
	v_lshl_add_u64 v[226:227], v[226:227], 0, s[22:23]
	s_mov_b32 m0, s58
	s_nop 0
	global_load_lds_dwordx4 v[226:227], off
	s_branch .Lkb_join_1
.Lkb_first_1:
	s_add_i32 m0, s44, 0xc000
	s_nop 0
	global_load_lds_dwordx4 v[150:151], off
	global_load_lds_dwordx4 v[150:151], off
.Lkb_join_1:
	s_add_i32 m0, s44, 0xc000
	s_nop 0
	global_load_lds_dwordx4 v[150:151], off
	v_lshl_add_u64 v[150:151], s[28:29], 0, v[140:141]
	s_add_i32 m0, s44, 0xe000
	s_nop 0
	global_load_lds_dwordx4 v[150:151], off
	s_waitcnt vmcnt(8)
	s_waitcnt lgkmcnt(0)
	s_barrier
	s_setprio 1
	s_waitcnt lgkmcnt(0)
	v_mfma_f32_16x16x32_bf16 v[124:127], v[146:149], v[188:191], v[124:127]
	v_mfma_f32_16x16x32_bf16 v[120:123], v[164:167], v[188:191], v[120:123]
	v_mfma_f32_16x16x32_bf16 v[108:111], v[146:149], v[200:203], v[108:111]
	v_mfma_f32_16x16x32_bf16 v[104:107], v[164:167], v[200:203], v[104:107]
	v_mfma_f32_16x16x32_bf16 v[92:95], v[146:149], v[208:211], v[92:95]
	v_mfma_f32_16x16x32_bf16 v[88:91], v[164:167], v[208:211], v[88:91]
	v_mfma_f32_16x16x32_bf16 v[76:79], v[146:149], v[216:219], v[76:79]
	v_mfma_f32_16x16x32_bf16 v[72:75], v[164:167], v[216:219], v[72:75]
	v_mfma_f32_16x16x32_bf16 v[124:127], v[160:163], v[196:199], v[124:127]
	v_mfma_f32_16x16x32_bf16 v[120:123], v[168:171], v[196:199], v[120:123]
	v_mfma_f32_16x16x32_bf16 v[108:111], v[160:163], v[204:207], v[108:111]
	v_mfma_f32_16x16x32_bf16 v[104:107], v[168:171], v[204:207], v[104:107]
	v_mfma_f32_16x16x32_bf16 v[92:95], v[160:163], v[212:215], v[92:95]
	v_mfma_f32_16x16x32_bf16 v[88:91], v[168:171], v[212:215], v[88:91]
	v_mfma_f32_16x16x32_bf16 v[76:79], v[160:163], v[220:223], v[76:79]
	v_mfma_f32_16x16x32_bf16 v[72:75], v[168:171], v[220:223], v[72:75]
	s_setprio 0
	s_setprio 1
	v_mfma_f32_16x16x32_bf16 v[116:119], v[172:175], v[188:191], v[116:119]
	v_mfma_f32_16x16x32_bf16 v[112:115], v[180:183], v[188:191], v[112:115]
	v_mfma_f32_16x16x32_bf16 v[100:103], v[172:175], v[200:203], v[100:103]
	v_mfma_f32_16x16x32_bf16 v[96:99], v[180:183], v[200:203], v[96:99]
	v_mfma_f32_16x16x32_bf16 v[84:87], v[172:175], v[208:211], v[84:87]
	v_mfma_f32_16x16x32_bf16 v[80:83], v[180:183], v[208:211], v[80:83]
	v_mfma_f32_16x16x32_bf16 v[68:71], v[172:175], v[216:219], v[68:71]
	v_mfma_f32_16x16x32_bf16 v[64:67], v[180:183], v[216:219], v[64:67]
	v_mfma_f32_16x16x32_bf16 v[116:119], v[176:179], v[196:199], v[116:119]
	v_mfma_f32_16x16x32_bf16 v[112:115], v[184:187], v[196:199], v[112:115]
	v_mfma_f32_16x16x32_bf16 v[100:103], v[176:179], v[204:207], v[100:103]
	v_mfma_f32_16x16x32_bf16 v[96:99], v[184:187], v[204:207], v[96:99]
	v_mfma_f32_16x16x32_bf16 v[84:87], v[176:179], v[212:215], v[84:87]
	v_mfma_f32_16x16x32_bf16 v[80:83], v[184:187], v[212:215], v[80:83]
	v_mfma_f32_16x16x32_bf16 v[68:71], v[176:179], v[220:223], v[68:71]
	v_mfma_f32_16x16x32_bf16 v[64:67], v[184:187], v[220:223], v[64:67]
	s_setprio 0
	s_barrier
	s_add_i32 s28, s60, s43
	v_lshl_add_u64 v[150:151], s[34:35], 0, v[132:133]
	s_mov_b32 m0, s28
	ds_read_b128 v[188:191], v157 offset:16384
	ds_read_b128 v[196:199], v157 offset:17408
	ds_read_b128 v[200:203], v157 offset:18432
	ds_read_b128 v[204:207], v157 offset:19456
	ds_read_b128 v[208:211], v157 offset:20480
	ds_read_b128 v[212:215], v157 offset:21504
	ds_read_b128 v[216:219], v157 offset:22528
	ds_read_b128 v[220:223], v157 offset:23552
	global_load_lds_dwordx4 v[150:151], off
	s_add_i32 m0, s28, 0x2000
	s_add_u32 s28, s34, 0xb0000
	v_lshl_add_u64 v[192:193], s[34:35], 0, v[136:137]
	s_addc_u32 s29, s35, 0
	s_add_i32 s78, s61, s43
	global_load_lds_dwordx4 v[192:193], off
	v_lshl_add_u64 v[224:225], s[28:29], 0, v[132:133]
	s_mov_b32 m0, s78
	v_lshl_add_u64 v[226:227], s[36:37], 0, v[134:135]
	global_load_lds_dwordx4 v[224:225], off
	v_lshl_add_u64 v[224:225], s[28:29], 0, v[136:137]
	s_add_i32 m0, s78, 0x2000
	s_nop 0
	global_load_lds_dwordx4 v[224:225], off
	v_lshl_add_u64 v[224:225], s[36:37], 0, v[130:131]
	s_waitcnt vmcnt(6)
	s_waitcnt lgkmcnt(0)
	s_barrier
	s_setprio 1
	s_waitcnt lgkmcnt(0)
	v_mfma_f32_16x16x32_bf16 v[60:63], v[146:149], v[188:191], v[60:63]
	v_mfma_f32_16x16x32_bf16 v[56:59], v[164:167], v[188:191], v[56:59]
	v_mfma_f32_16x16x32_bf16 v[44:47], v[146:149], v[200:203], v[44:47]
	v_mfma_f32_16x16x32_bf16 v[40:43], v[164:167], v[200:203], v[40:43]
	v_mfma_f32_16x16x32_bf16 v[28:31], v[146:149], v[208:211], v[28:31]
	v_mfma_f32_16x16x32_bf16 v[24:27], v[164:167], v[208:211], v[24:27]
	v_mfma_f32_16x16x32_bf16 v[12:15], v[146:149], v[216:219], v[12:15]
	v_mfma_f32_16x16x32_bf16 v[8:11], v[164:167], v[216:219], v[8:11]
	v_mfma_f32_16x16x32_bf16 v[60:63], v[160:163], v[196:199], v[60:63]
	v_mfma_f32_16x16x32_bf16 v[56:59], v[168:171], v[196:199], v[56:59]
	v_mfma_f32_16x16x32_bf16 v[44:47], v[160:163], v[204:207], v[44:47]
	v_mfma_f32_16x16x32_bf16 v[40:43], v[168:171], v[204:207], v[40:43]
	v_mfma_f32_16x16x32_bf16 v[28:31], v[160:163], v[212:215], v[28:31]
	v_mfma_f32_16x16x32_bf16 v[24:27], v[168:171], v[212:215], v[24:27]
	v_mfma_f32_16x16x32_bf16 v[12:15], v[160:163], v[220:223], v[12:15]
	v_mfma_f32_16x16x32_bf16 v[8:11], v[168:171], v[220:223], v[8:11]
	s_setprio 0
	s_setprio 1
	v_mfma_f32_16x16x32_bf16 v[52:55], v[172:175], v[188:191], v[52:55]
	v_mfma_f32_16x16x32_bf16 v[48:51], v[180:183], v[188:191], v[48:51]
	v_mfma_f32_16x16x32_bf16 v[36:39], v[172:175], v[200:203], v[36:39]
	v_mfma_f32_16x16x32_bf16 v[32:35], v[180:183], v[200:203], v[32:35]
	v_mfma_f32_16x16x32_bf16 v[20:23], v[172:175], v[208:211], v[20:23]
	v_mfma_f32_16x16x32_bf16 v[16:19], v[180:183], v[208:211], v[16:19]
	v_mfma_f32_16x16x32_bf16 v[4:7], v[172:175], v[216:219], v[4:7]
	v_mfma_f32_16x16x32_bf16 v[0:3], v[180:183], v[216:219], v[0:3]
	v_mfma_f32_16x16x32_bf16 v[52:55], v[176:179], v[196:199], v[52:55]
	v_mfma_f32_16x16x32_bf16 v[48:51], v[184:187], v[196:199], v[48:51]
	v_mfma_f32_16x16x32_bf16 v[36:39], v[176:179], v[204:207], v[36:39]
	v_mfma_f32_16x16x32_bf16 v[32:35], v[184:187], v[204:207], v[32:35]
	v_mfma_f32_16x16x32_bf16 v[20:23], v[176:179], v[212:215], v[20:23]
	v_mfma_f32_16x16x32_bf16 v[16:19], v[184:187], v[212:215], v[16:19]
	v_mfma_f32_16x16x32_bf16 v[4:7], v[176:179], v[220:223], v[4:7]
	v_mfma_f32_16x16x32_bf16 v[0:3], v[184:187], v[220:223], v[0:3]
	s_setprio 0
	s_barrier
	s_add_i32 s78, 0, 0x18000
	v_add_u32_e32 v159, s78, v153
	s_add_i32 s79, 0, 0x1c000
	ds_read_b128 v[146:149], v159
	ds_read_b128 v[160:163], v159 offset:1024
	ds_read_b128 v[164:167], v159 offset:2048
	ds_read_b128 v[168:171], v159 offset:3072
	v_add_u32_e32 v159, s79, v153
	ds_read_b128 v[172:175], v159
	ds_read_b128 v[176:179], v159 offset:1024
	ds_read_b128 v[180:183], v159 offset:2048
	ds_read_b128 v[184:187], v159 offset:3072
	s_add_u32 s28, s36, 0xb0000
	s_addc_u32 s29, s37, 0
	v_lshl_add_u64 v[228:229], s[28:29], 0, v[130:131]
	ds_read_b128 v[188:191], v157 offset:32768
	ds_read_b128 v[196:199], v157 offset:33792
	ds_read_b128 v[200:203], v157 offset:34816
	ds_read_b128 v[204:207], v157 offset:35840
	ds_read_b128 v[208:211], v157 offset:36864
	ds_read_b128 v[212:215], v157 offset:37888
	ds_read_b128 v[216:219], v157 offset:38912
	ds_read_b128 v[220:223], v157 offset:39936
	s_mov_b32 m0, s44
	s_nop 0
	global_load_lds_dwordx4 v[224:225], off
	s_mov_b32 m0, s45
	s_nop 0
	global_load_lds_dwordx4 v[226:227], off
	s_mov_b32 m0, s50
	s_nop 0
	global_load_lds_dwordx4 v[228:229], off
	v_lshl_add_u64 v[228:229], s[28:29], 0, v[134:135]
	s_mov_b32 m0, s51
	s_nop 0
	global_load_lds_dwordx4 v[228:229], off
	s_waitcnt vmcnt(8)
	s_waitcnt lgkmcnt(0)
	s_barrier
	s_setprio 1
	s_waitcnt lgkmcnt(0)
	v_mfma_f32_16x16x32_bf16 v[124:127], v[146:149], v[188:191], v[124:127]
	v_mfma_f32_16x16x32_bf16 v[120:123], v[164:167], v[188:191], v[120:123]
	v_mfma_f32_16x16x32_bf16 v[108:111], v[146:149], v[200:203], v[108:111]
	v_mfma_f32_16x16x32_bf16 v[104:107], v[164:167], v[200:203], v[104:107]
	v_mfma_f32_16x16x32_bf16 v[92:95], v[146:149], v[208:211], v[92:95]
	v_mfma_f32_16x16x32_bf16 v[88:91], v[164:167], v[208:211], v[88:91]
	v_mfma_f32_16x16x32_bf16 v[76:79], v[146:149], v[216:219], v[76:79]
	v_mfma_f32_16x16x32_bf16 v[72:75], v[164:167], v[216:219], v[72:75]
	v_mfma_f32_16x16x32_bf16 v[124:127], v[160:163], v[196:199], v[124:127]
	v_mfma_f32_16x16x32_bf16 v[120:123], v[168:171], v[196:199], v[120:123]
	v_mfma_f32_16x16x32_bf16 v[108:111], v[160:163], v[204:207], v[108:111]
	v_mfma_f32_16x16x32_bf16 v[104:107], v[168:171], v[204:207], v[104:107]
	v_mfma_f32_16x16x32_bf16 v[92:95], v[160:163], v[212:215], v[92:95]
	v_mfma_f32_16x16x32_bf16 v[88:91], v[168:171], v[212:215], v[88:91]
	v_mfma_f32_16x16x32_bf16 v[76:79], v[160:163], v[220:223], v[76:79]
	v_mfma_f32_16x16x32_bf16 v[72:75], v[168:171], v[220:223], v[72:75]
	s_setprio 0
	s_setprio 1
	v_mfma_f32_16x16x32_bf16 v[116:119], v[172:175], v[188:191], v[116:119]
	v_mfma_f32_16x16x32_bf16 v[112:115], v[180:183], v[188:191], v[112:115]
	v_mfma_f32_16x16x32_bf16 v[100:103], v[172:175], v[200:203], v[100:103]
	v_mfma_f32_16x16x32_bf16 v[96:99], v[180:183], v[200:203], v[96:99]
	v_mfma_f32_16x16x32_bf16 v[84:87], v[172:175], v[208:211], v[84:87]
	v_mfma_f32_16x16x32_bf16 v[80:83], v[180:183], v[208:211], v[80:83]
	v_mfma_f32_16x16x32_bf16 v[68:71], v[172:175], v[216:219], v[68:71]
	v_mfma_f32_16x16x32_bf16 v[64:67], v[180:183], v[216:219], v[64:67]
	v_mfma_f32_16x16x32_bf16 v[116:119], v[176:179], v[196:199], v[116:119]
	v_mfma_f32_16x16x32_bf16 v[112:115], v[184:187], v[196:199], v[112:115]
	v_mfma_f32_16x16x32_bf16 v[100:103], v[176:179], v[204:207], v[100:103]
	v_mfma_f32_16x16x32_bf16 v[96:99], v[184:187], v[204:207], v[96:99]
	v_mfma_f32_16x16x32_bf16 v[84:87], v[176:179], v[212:215], v[84:87]
	v_mfma_f32_16x16x32_bf16 v[80:83], v[184:187], v[212:215], v[80:83]
	v_mfma_f32_16x16x32_bf16 v[68:71], v[176:179], v[220:223], v[68:71]
	v_mfma_f32_16x16x32_bf16 v[64:67], v[184:187], v[220:223], v[64:67]
	s_setprio 0
	s_barrier
	s_add_i32 s28, s78, s43
	v_lshl_add_u64 v[150:151], v[150:151], 0, s[22:23]
	s_mov_b32 m0, s28
	ds_read_b128 v[188:191], v157 offset:49152
	ds_read_b128 v[196:199], v157 offset:50176
	ds_read_b128 v[200:203], v157 offset:51200
	ds_read_b128 v[204:207], v157 offset:52224
	ds_read_b128 v[208:211], v157 offset:53248
	ds_read_b128 v[212:215], v157 offset:54272
	ds_read_b128 v[216:219], v157 offset:55296
	ds_read_b128 v[220:223], v157 offset:56320
	global_load_lds_dwordx4 v[150:151], off
	s_add_i32 m0, s28, 0x2000
	s_add_u32 s28, s34, 0xb0080
	v_lshl_add_u64 v[150:151], v[192:193], 0, s[22:23]
	s_addc_u32 s29, s35, 0
	s_add_i32 s34, s79, s43
	global_load_lds_dwordx4 v[150:151], off
	v_lshl_add_u64 v[150:151], s[28:29], 0, v[132:133]
	s_mov_b32 m0, s34
	s_nop 0
	global_load_lds_dwordx4 v[150:151], off
	v_lshl_add_u64 v[150:151], s[28:29], 0, v[136:137]
	s_add_i32 m0, s34, 0x2000
	s_nop 0
	global_load_lds_dwordx4 v[150:151], off
	s_mov_b32 s99, 1
	s_waitcnt vmcnt(6)
	s_waitcnt lgkmcnt(0)
	s_barrier
	s_setprio 1
	s_waitcnt lgkmcnt(0)
	v_mfma_f32_16x16x32_bf16 v[60:63], v[146:149], v[188:191], v[60:63]
	v_mfma_f32_16x16x32_bf16 v[56:59], v[164:167], v[188:191], v[56:59]
	v_mfma_f32_16x16x32_bf16 v[44:47], v[146:149], v[200:203], v[44:47]
	v_mfma_f32_16x16x32_bf16 v[40:43], v[164:167], v[200:203], v[40:43]
	v_mfma_f32_16x16x32_bf16 v[28:31], v[146:149], v[208:211], v[28:31]
	v_mfma_f32_16x16x32_bf16 v[24:27], v[164:167], v[208:211], v[24:27]
	v_mfma_f32_16x16x32_bf16 v[12:15], v[146:149], v[216:219], v[12:15]
	v_mfma_f32_16x16x32_bf16 v[8:11], v[164:167], v[216:219], v[8:11]
	v_mfma_f32_16x16x32_bf16 v[60:63], v[160:163], v[196:199], v[60:63]
	v_mfma_f32_16x16x32_bf16 v[56:59], v[168:171], v[196:199], v[56:59]
	v_mfma_f32_16x16x32_bf16 v[44:47], v[160:163], v[204:207], v[44:47]
	v_mfma_f32_16x16x32_bf16 v[40:43], v[168:171], v[204:207], v[40:43]
	v_mfma_f32_16x16x32_bf16 v[28:31], v[160:163], v[212:215], v[28:31]
	v_mfma_f32_16x16x32_bf16 v[24:27], v[168:171], v[212:215], v[24:27]
	v_mfma_f32_16x16x32_bf16 v[12:15], v[160:163], v[220:223], v[12:15]
	v_mfma_f32_16x16x32_bf16 v[8:11], v[168:171], v[220:223], v[8:11]
	s_setprio 0
	s_setprio 1
	v_mfma_f32_16x16x32_bf16 v[52:55], v[172:175], v[188:191], v[52:55]
	v_mfma_f32_16x16x32_bf16 v[48:51], v[180:183], v[188:191], v[48:51]
	v_mfma_f32_16x16x32_bf16 v[36:39], v[172:175], v[200:203], v[36:39]
	v_mfma_f32_16x16x32_bf16 v[32:35], v[180:183], v[200:203], v[32:35]
	v_mfma_f32_16x16x32_bf16 v[20:23], v[172:175], v[208:211], v[20:23]
	v_mfma_f32_16x16x32_bf16 v[16:19], v[180:183], v[208:211], v[16:19]
	v_mfma_f32_16x16x32_bf16 v[4:7], v[172:175], v[216:219], v[4:7]
	v_mfma_f32_16x16x32_bf16 v[0:3], v[180:183], v[216:219], v[0:3]
	v_mfma_f32_16x16x32_bf16 v[52:55], v[176:179], v[196:199], v[52:55]
	v_mfma_f32_16x16x32_bf16 v[48:51], v[184:187], v[196:199], v[48:51]
	v_mfma_f32_16x16x32_bf16 v[36:39], v[176:179], v[204:207], v[36:39]
	v_mfma_f32_16x16x32_bf16 v[32:35], v[184:187], v[204:207], v[32:35]
	v_mfma_f32_16x16x32_bf16 v[20:23], v[176:179], v[212:215], v[20:23]
	v_mfma_f32_16x16x32_bf16 v[16:19], v[184:187], v[212:215], v[16:19]
	v_mfma_f32_16x16x32_bf16 v[4:7], v[176:179], v[220:223], v[4:7]
	v_mfma_f32_16x16x32_bf16 v[0:3], v[184:187], v[220:223], v[0:3]
	s_setprio 0
	s_barrier
	s_add_i32 s77, s77, 2
	s_add_u32 s72, s72, 0x100
	s_addc_u32 s73, s73, 0
	s_cmp_gt_u32 s77, 41
	s_mov_b64 s[28:29], s[30:31]
	s_cbranch_scc0 .LBB0_532
	v_lshl_add_u64 v[224:225], v[224:225], 0, s[22:23]
	s_mov_b32 m0, s55
	s_nop 0
	global_load_lds_dwordx4 v[224:225], off
	v_lshl_add_u64 v[226:227], v[226:227], 0, s[22:23]
	s_mov_b32 m0, s58
	s_nop 0
	global_load_lds_dwordx4 v[226:227], off
	s_and_b64 vcc, exec, s[24:25]
	s_cbranch_vccz .LBB0_535
	s_barrier

.LBB0_625:
	s_ashr_i32 s31, s30, 31
	s_lshl_b64 s[34:35], s[30:31], 19
	s_add_u32 s34, s45, s34
	s_addc_u32 s35, s50, s35
	s_and_b64 s[36:37], s[6:7], exec
	s_cselect_b32 s1, s35, s39
	s_cselect_b32 s11, s34, s38
	s_ashr_i32 s29, s28, 31
	s_lshl_b64 s[36:37], s[28:29], 19
	s_add_u32 s36, s51, s36
	s_addc_u32 s37, s54, s37
	s_and_b64 s[42:43], s[6:7], exec
	s_cselect_b32 s12, s37, s41
	s_cselect_b32 s29, s36, s40
	s_add_u32 s38, s38, 0x40080
	s_addc_u32 s39, s39, 0
	s_add_u32 s31, s40, 0x100
	v_mov_b32_e32 v0, 0
	s_addc_u32 s85, s41, 0
	s_mov_b32 s86, -2
	v_mov_b32_e32 v1, v0
	v_mov_b32_e32 v2, v0
	v_mov_b32_e32 v3, v0
	v_mov_b32_e32 v4, v0
	v_mov_b32_e32 v5, v0
	v_mov_b32_e32 v6, v0
	v_mov_b32_e32 v7, v0
	v_mov_b32_e32 v16, v0
	v_mov_b32_e32 v17, v0
	v_mov_b32_e32 v18, v0
	v_mov_b32_e32 v19, v0
	v_mov_b32_e32 v20, v0
	v_mov_b32_e32 v21, v0
	v_mov_b32_e32 v22, v0
	v_mov_b32_e32 v23, v0
	v_mov_b32_e32 v32, v0
	v_mov_b32_e32 v33, v0
	v_mov_b32_e32 v34, v0
	v_mov_b32_e32 v35, v0
	v_mov_b32_e32 v36, v0
	v_mov_b32_e32 v37, v0
	v_mov_b32_e32 v38, v0
	v_mov_b32_e32 v39, v0
	v_mov_b32_e32 v48, v0
	v_mov_b32_e32 v49, v0
	v_mov_b32_e32 v50, v0
	v_mov_b32_e32 v51, v0
	v_mov_b32_e32 v52, v0
	v_mov_b32_e32 v53, v0
	v_mov_b32_e32 v54, v0
	v_mov_b32_e32 v55, v0
	v_mov_b32_e32 v8, v0
	v_mov_b32_e32 v9, v0
	v_mov_b32_e32 v10, v0
	v_mov_b32_e32 v11, v0
	v_mov_b32_e32 v12, v0
	v_mov_b32_e32 v13, v0
	v_mov_b32_e32 v14, v0
	v_mov_b32_e32 v15, v0
	v_mov_b32_e32 v24, v0
	v_mov_b32_e32 v25, v0
	v_mov_b32_e32 v26, v0
	v_mov_b32_e32 v27, v0
	v_mov_b32_e32 v28, v0
	v_mov_b32_e32 v29, v0
	v_mov_b32_e32 v30, v0
	v_mov_b32_e32 v31, v0
	v_mov_b32_e32 v40, v0
	v_mov_b32_e32 v41, v0
	v_mov_b32_e32 v42, v0
	v_mov_b32_e32 v43, v0
	v_mov_b32_e32 v44, v0
	v_mov_b32_e32 v45, v0
	v_mov_b32_e32 v46, v0
	v_mov_b32_e32 v47, v0
	v_mov_b32_e32 v56, v0
	v_mov_b32_e32 v57, v0
	v_mov_b32_e32 v58, v0
	v_mov_b32_e32 v59, v0
	v_mov_b32_e32 v60, v0
	v_mov_b32_e32 v61, v0
	v_mov_b32_e32 v62, v0
	v_mov_b32_e32 v63, v0
	v_mov_b32_e32 v64, v0
	v_mov_b32_e32 v65, v0
	v_mov_b32_e32 v66, v0
	v_mov_b32_e32 v67, v0
	v_mov_b32_e32 v68, v0
	v_mov_b32_e32 v69, v0
	v_mov_b32_e32 v70, v0
	v_mov_b32_e32 v71, v0
	v_mov_b32_e32 v80, v0
	v_mov_b32_e32 v81, v0
	v_mov_b32_e32 v82, v0
	v_mov_b32_e32 v83, v0
	v_mov_b32_e32 v84, v0
	v_mov_b32_e32 v85, v0
	v_mov_b32_e32 v86, v0
	v_mov_b32_e32 v87, v0
	v_mov_b32_e32 v96, v0
	v_mov_b32_e32 v97, v0
	v_mov_b32_e32 v98, v0
	v_mov_b32_e32 v99, v0
	v_mov_b32_e32 v100, v0
	v_mov_b32_e32 v101, v0
	v_mov_b32_e32 v102, v0
	v_mov_b32_e32 v103, v0
	v_mov_b32_e32 v112, v0
	v_mov_b32_e32 v113, v0
	v_mov_b32_e32 v114, v0
	v_mov_b32_e32 v115, v0
	v_mov_b32_e32 v116, v0
	v_mov_b32_e32 v117, v0
	v_mov_b32_e32 v118, v0
	v_mov_b32_e32 v119, v0
	v_mov_b32_e32 v72, v0
	v_mov_b32_e32 v73, v0
	v_mov_b32_e32 v74, v0
	v_mov_b32_e32 v75, v0
	v_mov_b32_e32 v76, v0
	v_mov_b32_e32 v77, v0
	v_mov_b32_e32 v78, v0
	v_mov_b32_e32 v79, v0
	v_mov_b32_e32 v88, v0
	v_mov_b32_e32 v89, v0
	v_mov_b32_e32 v90, v0
	v_mov_b32_e32 v91, v0
	v_mov_b32_e32 v92, v0
	v_mov_b32_e32 v93, v0
	v_mov_b32_e32 v94, v0
	v_mov_b32_e32 v95, v0
	v_mov_b32_e32 v104, v0
	v_mov_b32_e32 v105, v0
	v_mov_b32_e32 v106, v0
	v_mov_b32_e32 v107, v0
	v_mov_b32_e32 v108, v0
	v_mov_b32_e32 v109, v0
	v_mov_b32_e32 v110, v0
	v_mov_b32_e32 v111, v0
	v_mov_b32_e32 v120, v0
	v_mov_b32_e32 v121, v0
	v_mov_b32_e32 v122, v0
	v_mov_b32_e32 v123, v0
	v_mov_b32_e32 v124, v0
	v_mov_b32_e32 v125, v0
	v_mov_b32_e32 v126, v0
	v_mov_b32_e32 v127, v0
	s_mov_b32 s99, 0
.LBB0_626:
	ds_read_b128 v[152:155], v157
	ds_read_b128 v[162:165], v157 offset:1024
	ds_read_b128 v[166:169], v157 offset:2048
	ds_read_b128 v[170:173], v157 offset:3072
	ds_read_b128 v[174:177], v158
	ds_read_b128 v[178:181], v158 offset:1024
	ds_read_b128 v[182:185], v158 offset:2048
	ds_read_b128 v[186:189], v158 offset:3072
	s_add_u32 s40, s38, 0xfffc0080
	s_addc_u32 s41, s39, -1
	s_cmp_eq_u32 s86, 12
	s_cselect_b32 s43, s1, s41
	s_cselect_b32 s42, s11, s40
	s_cselect_b32 s41, s12, s85
	s_cselect_b32 s40, s29, s31
	v_lshl_add_u64 v[224:225], s[38:39], 0, v[144:145]
	ds_read_b128 v[190:193], v159
	ds_read_b128 v[196:199], v159 offset:1024
	ds_read_b128 v[200:203], v159 offset:2048
	ds_read_b128 v[204:207], v159 offset:3072
	ds_read_b128 v[208:211], v159 offset:4096
	ds_read_b128 v[212:215], v159 offset:5120
	ds_read_b128 v[216:219], v159 offset:6144
	ds_read_b128 v[220:223], v159 offset:7168
	s_cmp_eq_u32 s99, 0
	s_cbranch_scc1 .Lkb_first_2
	v_lshl_add_u64 v[228:229], v[228:229], 0, s[24:25]
	s_mov_b32 m0, s70
	s_nop 0
	global_load_lds_dwordx4 v[228:229], off
	v_lshl_add_u64 v[230:231], v[230:231], 0, s[24:25]
	s_mov_b32 m0, s71
	s_nop 0
	global_load_lds_dwordx4 v[230:231], off
	s_branch .Lkb_join_2
.Lkb_first_2:
	s_add_i32 m0, s58, 0xc000
	s_nop 0
	global_load_lds_dwordx4 v[224:225], off
	global_load_lds_dwordx4 v[224:225], off
.Lkb_join_2:
	s_add_i32 m0, s58, 0xc000
	s_nop 0
	global_load_lds_dwordx4 v[224:225], off
	v_lshl_add_u64 v[224:225], s[38:39], 0, v[146:147]
	s_add_i32 m0, s58, 0xe000
	s_nop 0
	global_load_lds_dwordx4 v[224:225], off
	s_waitcnt vmcnt(8)
	s_waitcnt lgkmcnt(0)
	s_barrier
	s_setprio 1
	s_waitcnt lgkmcnt(0)
	v_mfma_f32_16x16x32_bf16 v[124:127], v[152:155], v[190:193], v[124:127]
	v_mfma_f32_16x16x32_bf16 v[120:123], v[166:169], v[190:193], v[120:123]
	v_mfma_f32_16x16x32_bf16 v[108:111], v[152:155], v[200:203], v[108:111]
	v_mfma_f32_16x16x32_bf16 v[104:107], v[166:169], v[200:203], v[104:107]
	v_mfma_f32_16x16x32_bf16 v[92:95], v[152:155], v[208:211], v[92:95]
	v_mfma_f32_16x16x32_bf16 v[88:91], v[166:169], v[208:211], v[88:91]
	v_mfma_f32_16x16x32_bf16 v[76:79], v[152:155], v[216:219], v[76:79]
	v_mfma_f32_16x16x32_bf16 v[72:75], v[166:169], v[216:219], v[72:75]
	v_mfma_f32_16x16x32_bf16 v[124:127], v[162:165], v[196:199], v[124:127]
	v_mfma_f32_16x16x32_bf16 v[120:123], v[170:173], v[196:199], v[120:123]
	v_mfma_f32_16x16x32_bf16 v[108:111], v[162:165], v[204:207], v[108:111]
	v_mfma_f32_16x16x32_bf16 v[104:107], v[170:173], v[204:207], v[104:107]
	v_mfma_f32_16x16x32_bf16 v[92:95], v[162:165], v[212:215], v[92:95]
	v_mfma_f32_16x16x32_bf16 v[88:91], v[170:173], v[212:215], v[88:91]
	v_mfma_f32_16x16x32_bf16 v[76:79], v[162:165], v[220:223], v[76:79]
	v_mfma_f32_16x16x32_bf16 v[72:75], v[170:173], v[220:223], v[72:75]
	s_setprio 0
	s_setprio 1
	v_mfma_f32_16x16x32_bf16 v[116:119], v[174:177], v[190:193], v[116:119]
	v_mfma_f32_16x16x32_bf16 v[112:115], v[182:185], v[190:193], v[112:115]
	v_mfma_f32_16x16x32_bf16 v[100:103], v[174:177], v[200:203], v[100:103]
	v_mfma_f32_16x16x32_bf16 v[96:99], v[182:185], v[200:203], v[96:99]
	v_mfma_f32_16x16x32_bf16 v[84:87], v[174:177], v[208:211], v[84:87]
	v_mfma_f32_16x16x32_bf16 v[80:83], v[182:185], v[208:211], v[80:83]
	v_mfma_f32_16x16x32_bf16 v[68:71], v[174:177], v[216:219], v[68:71]
	v_mfma_f32_16x16x32_bf16 v[64:67], v[182:185], v[216:219], v[64:67]
	v_mfma_f32_16x16x32_bf16 v[116:119], v[178:181], v[196:199], v[116:119]
	v_mfma_f32_16x16x32_bf16 v[112:115], v[186:189], v[196:199], v[112:115]
	v_mfma_f32_16x16x32_bf16 v[100:103], v[178:181], v[204:207], v[100:103]
	v_mfma_f32_16x16x32_bf16 v[96:99], v[186:189], v[204:207], v[96:99]
	v_mfma_f32_16x16x32_bf16 v[84:87], v[178:181], v[212:215], v[84:87]
	v_mfma_f32_16x16x32_bf16 v[80:83], v[186:189], v[212:215], v[80:83]
	v_mfma_f32_16x16x32_bf16 v[68:71], v[178:181], v[220:223], v[68:71]
	v_mfma_f32_16x16x32_bf16 v[64:67], v[186:189], v[220:223], v[64:67]
	s_setprio 0
	s_barrier
	s_add_i32 s87, s73, s55
	v_lshl_add_u64 v[224:225], s[40:41], 0, v[130:131]
	s_mov_b32 m0, s87
	ds_read_b128 v[190:193], v159 offset:16384
	ds_read_b128 v[196:199], v159 offset:17408
	ds_read_b128 v[200:203], v159 offset:18432
	ds_read_b128 v[204:207], v159 offset:19456
	ds_read_b128 v[208:211], v159 offset:20480
	ds_read_b128 v[212:215], v159 offset:21504
	ds_read_b128 v[216:219], v159 offset:22528
	ds_read_b128 v[220:223], v159 offset:23552
	global_load_lds_dwordx4 v[224:225], off
	s_add_i32 m0, s87, 0x2000
	s_add_u32 s88, s40, 0x40000
	v_lshl_add_u64 v[226:227], s[40:41], 0, v[134:135]
	s_addc_u32 s89, s41, 0
	s_add_i32 s87, s77, s55
	global_load_lds_dwordx4 v[226:227], off
	v_lshl_add_u64 v[228:229], s[88:89], 0, v[130:131]
	s_mov_b32 m0, s87
	v_lshl_add_u64 v[230:231], s[42:43], 0, v[132:133]
	global_load_lds_dwordx4 v[228:229], off
	v_lshl_add_u64 v[228:229], s[88:89], 0, v[134:135]
	s_add_i32 m0, s87, 0x2000
	s_nop 0
	global_load_lds_dwordx4 v[228:229], off
	v_lshl_add_u64 v[228:229], s[42:43], 0, v[128:129]
	s_waitcnt vmcnt(6)
	s_waitcnt lgkmcnt(0)
	s_barrier
	s_setprio 1
	s_waitcnt lgkmcnt(0)
	v_mfma_f32_16x16x32_bf16 v[60:63], v[152:155], v[190:193], v[60:63]
	v_mfma_f32_16x16x32_bf16 v[56:59], v[166:169], v[190:193], v[56:59]
	v_mfma_f32_16x16x32_bf16 v[44:47], v[152:155], v[200:203], v[44:47]
	v_mfma_f32_16x16x32_bf16 v[40:43], v[166:169], v[200:203], v[40:43]
	v_mfma_f32_16x16x32_bf16 v[28:31], v[152:155], v[208:211], v[28:31]
	v_mfma_f32_16x16x32_bf16 v[24:27], v[166:169], v[208:211], v[24:27]
	v_mfma_f32_16x16x32_bf16 v[12:15], v[152:155], v[216:219], v[12:15]
	v_mfma_f32_16x16x32_bf16 v[8:11], v[166:169], v[216:219], v[8:11]
	v_mfma_f32_16x16x32_bf16 v[60:63], v[162:165], v[196:199], v[60:63]
	v_mfma_f32_16x16x32_bf16 v[56:59], v[170:173], v[196:199], v[56:59]
	v_mfma_f32_16x16x32_bf16 v[44:47], v[162:165], v[204:207], v[44:47]
	v_mfma_f32_16x16x32_bf16 v[40:43], v[170:173], v[204:207], v[40:43]
	v_mfma_f32_16x16x32_bf16 v[28:31], v[162:165], v[212:215], v[28:31]
	v_mfma_f32_16x16x32_bf16 v[24:27], v[170:173], v[212:215], v[24:27]
	v_mfma_f32_16x16x32_bf16 v[12:15], v[162:165], v[220:223], v[12:15]
	v_mfma_f32_16x16x32_bf16 v[8:11], v[170:173], v[220:223], v[8:11]
	s_setprio 0
	s_setprio 1
	v_mfma_f32_16x16x32_bf16 v[52:55], v[174:177], v[190:193], v[52:55]
	v_mfma_f32_16x16x32_bf16 v[48:51], v[182:185], v[190:193], v[48:51]
	v_mfma_f32_16x16x32_bf16 v[36:39], v[174:177], v[200:203], v[36:39]
	v_mfma_f32_16x16x32_bf16 v[32:35], v[182:185], v[200:203], v[32:35]
	v_mfma_f32_16x16x32_bf16 v[20:23], v[174:177], v[208:211], v[20:23]
	v_mfma_f32_16x16x32_bf16 v[16:19], v[182:185], v[208:211], v[16:19]
	v_mfma_f32_16x16x32_bf16 v[4:7], v[174:177], v[216:219], v[4:7]
	v_mfma_f32_16x16x32_bf16 v[0:3], v[182:185], v[216:219], v[0:3]
	v_mfma_f32_16x16x32_bf16 v[52:55], v[178:181], v[196:199], v[52:55]
	v_mfma_f32_16x16x32_bf16 v[48:51], v[186:189], v[196:199], v[48:51]
	v_mfma_f32_16x16x32_bf16 v[36:39], v[178:181], v[204:207], v[36:39]
	v_mfma_f32_16x16x32_bf16 v[32:35], v[186:189], v[204:207], v[32:35]
	v_mfma_f32_16x16x32_bf16 v[20:23], v[178:181], v[212:215], v[20:23]
	v_mfma_f32_16x16x32_bf16 v[16:19], v[186:189], v[212:215], v[16:19]
	v_mfma_f32_16x16x32_bf16 v[4:7], v[178:181], v[220:223], v[4:7]
	v_mfma_f32_16x16x32_bf16 v[0:3], v[186:189], v[220:223], v[0:3]
	s_setprio 0
	s_barrier
	s_add_i32 s87, 0, 0x18000
	v_add_u32_e32 v136, s87, v141
	s_add_i32 s88, 0, 0x1c000
	ds_read_b128 v[152:155], v136
	ds_read_b128 v[162:165], v136 offset:1024
	ds_read_b128 v[166:169], v136 offset:2048
	ds_read_b128 v[170:173], v136 offset:3072
	v_add_u32_e32 v136, s88, v141
	ds_read_b128 v[174:177], v136
	ds_read_b128 v[178:181], v136 offset:1024
	ds_read_b128 v[182:185], v136 offset:2048
	ds_read_b128 v[186:189], v136 offset:3072
	s_add_u32 s42, s42, 0x40000
	s_addc_u32 s43, s43, 0
	v_lshl_add_u64 v[232:233], s[42:43], 0, v[128:129]
	ds_read_b128 v[190:193], v159 offset:32768
	ds_read_b128 v[196:199], v159 offset:33792
	ds_read_b128 v[200:203], v159 offset:34816
	ds_read_b128 v[204:207], v159 offset:35840
	ds_read_b128 v[208:211], v159 offset:36864
	ds_read_b128 v[212:215], v159 offset:37888
	ds_read_b128 v[216:219], v159 offset:38912
	ds_read_b128 v[220:223], v159 offset:39936
	s_mov_b32 m0, s58
	s_nop 0
	global_load_lds_dwordx4 v[228:229], off
	s_mov_b32 m0, s59
	s_nop 0
	global_load_lds_dwordx4 v[230:231], off
	s_mov_b32 m0, s60
	s_nop 0
	global_load_lds_dwordx4 v[232:233], off
	v_lshl_add_u64 v[232:233], s[42:43], 0, v[132:133]
	s_mov_b32 m0, s61
	s_nop 0
	global_load_lds_dwordx4 v[232:233], off
	s_waitcnt vmcnt(8)
	s_waitcnt lgkmcnt(0)
	s_barrier
	s_setprio 1
	s_waitcnt lgkmcnt(0)
	v_mfma_f32_16x16x32_bf16 v[124:127], v[152:155], v[190:193], v[124:127]
	v_mfma_f32_16x16x32_bf16 v[120:123], v[166:169], v[190:193], v[120:123]
	v_mfma_f32_16x16x32_bf16 v[108:111], v[152:155], v[200:203], v[108:111]
	v_mfma_f32_16x16x32_bf16 v[104:107], v[166:169], v[200:203], v[104:107]
	v_mfma_f32_16x16x32_bf16 v[92:95], v[152:155], v[208:211], v[92:95]
	v_mfma_f32_16x16x32_bf16 v[88:91], v[166:169], v[208:211], v[88:91]
	v_mfma_f32_16x16x32_bf16 v[76:79], v[152:155], v[216:219], v[76:79]
	v_mfma_f32_16x16x32_bf16 v[72:75], v[166:169], v[216:219], v[72:75]
	v_mfma_f32_16x16x32_bf16 v[124:127], v[162:165], v[196:199], v[124:127]
	v_mfma_f32_16x16x32_bf16 v[120:123], v[170:173], v[196:199], v[120:123]
	v_mfma_f32_16x16x32_bf16 v[108:111], v[162:165], v[204:207], v[108:111]
	v_mfma_f32_16x16x32_bf16 v[104:107], v[170:173], v[204:207], v[104:107]
	v_mfma_f32_16x16x32_bf16 v[92:95], v[162:165], v[212:215], v[92:95]
	v_mfma_f32_16x16x32_bf16 v[88:91], v[170:173], v[212:215], v[88:91]
	v_mfma_f32_16x16x32_bf16 v[76:79], v[162:165], v[220:223], v[76:79]
	v_mfma_f32_16x16x32_bf16 v[72:75], v[170:173], v[220:223], v[72:75]
	s_setprio 0
	s_setprio 1
	v_mfma_f32_16x16x32_bf16 v[116:119], v[174:177], v[190:193], v[116:119]
	v_mfma_f32_16x16x32_bf16 v[112:115], v[182:185], v[190:193], v[112:115]
	v_mfma_f32_16x16x32_bf16 v[100:103], v[174:177], v[200:203], v[100:103]
	v_mfma_f32_16x16x32_bf16 v[96:99], v[182:185], v[200:203], v[96:99]
	v_mfma_f32_16x16x32_bf16 v[84:87], v[174:177], v[208:211], v[84:87]
	v_mfma_f32_16x16x32_bf16 v[80:83], v[182:185], v[208:211], v[80:83]
	v_mfma_f32_16x16x32_bf16 v[68:71], v[174:177], v[216:219], v[68:71]
	v_mfma_f32_16x16x32_bf16 v[64:67], v[182:185], v[216:219], v[64:67]
	v_mfma_f32_16x16x32_bf16 v[116:119], v[178:181], v[196:199], v[116:119]
	v_mfma_f32_16x16x32_bf16 v[112:115], v[186:189], v[196:199], v[112:115]
	v_mfma_f32_16x16x32_bf16 v[100:103], v[178:181], v[204:207], v[100:103]
	v_mfma_f32_16x16x32_bf16 v[96:99], v[186:189], v[204:207], v[96:99]
	v_mfma_f32_16x16x32_bf16 v[84:87], v[178:181], v[212:215], v[84:87]
	v_mfma_f32_16x16x32_bf16 v[80:83], v[186:189], v[212:215], v[80:83]
	v_mfma_f32_16x16x32_bf16 v[68:71], v[178:181], v[220:223], v[68:71]
	v_mfma_f32_16x16x32_bf16 v[64:67], v[186:189], v[220:223], v[64:67]
	s_setprio 0
	s_barrier
	s_add_i32 s42, s87, s55
	v_lshl_add_u64 v[224:225], v[224:225], 0, s[24:25]
	s_mov_b32 m0, s42
	ds_read_b128 v[190:193], v159 offset:49152
	ds_read_b128 v[196:199], v159 offset:50176
	ds_read_b128 v[200:203], v159 offset:51200
	ds_read_b128 v[204:207], v159 offset:52224
	ds_read_b128 v[208:211], v159 offset:53248
	ds_read_b128 v[212:215], v159 offset:54272
	ds_read_b128 v[216:219], v159 offset:55296
	ds_read_b128 v[220:223], v159 offset:56320
	global_load_lds_dwordx4 v[224:225], off
	s_add_i32 m0, s42, 0x2000
	s_add_u32 s40, s40, 0x40080
	v_lshl_add_u64 v[224:225], v[226:227], 0, s[24:25]
	s_addc_u32 s41, s41, 0
	s_add_i32 s42, s88, s55
	global_load_lds_dwordx4 v[224:225], off
	v_lshl_add_u64 v[224:225], s[40:41], 0, v[130:131]
	s_mov_b32 m0, s42
	s_nop 0
	global_load_lds_dwordx4 v[224:225], off
	v_lshl_add_u64 v[224:225], s[40:41], 0, v[134:135]
	s_add_i32 m0, s42, 0x2000
	s_nop 0
	global_load_lds_dwordx4 v[224:225], off
	s_mov_b32 s99, 1
	s_waitcnt vmcnt(6)
	s_waitcnt lgkmcnt(0)
	s_barrier
	s_setprio 1
	s_waitcnt lgkmcnt(0)
	v_mfma_f32_16x16x32_bf16 v[60:63], v[152:155], v[190:193], v[60:63]
	v_mfma_f32_16x16x32_bf16 v[56:59], v[166:169], v[190:193], v[56:59]
	v_mfma_f32_16x16x32_bf16 v[44:47], v[152:155], v[200:203], v[44:47]
	v_mfma_f32_16x16x32_bf16 v[40:43], v[166:169], v[200:203], v[40:43]
	v_mfma_f32_16x16x32_bf16 v[28:31], v[152:155], v[208:211], v[28:31]
	v_mfma_f32_16x16x32_bf16 v[24:27], v[166:169], v[208:211], v[24:27]
	v_mfma_f32_16x16x32_bf16 v[12:15], v[152:155], v[216:219], v[12:15]
	v_mfma_f32_16x16x32_bf16 v[8:11], v[166:169], v[216:219], v[8:11]
	v_mfma_f32_16x16x32_bf16 v[60:63], v[162:165], v[196:199], v[60:63]
	v_mfma_f32_16x16x32_bf16 v[56:59], v[170:173], v[196:199], v[56:59]
	v_mfma_f32_16x16x32_bf16 v[44:47], v[162:165], v[204:207], v[44:47]
	v_mfma_f32_16x16x32_bf16 v[40:43], v[170:173], v[204:207], v[40:43]
	v_mfma_f32_16x16x32_bf16 v[28:31], v[162:165], v[212:215], v[28:31]
	v_mfma_f32_16x16x32_bf16 v[24:27], v[170:173], v[212:215], v[24:27]
	v_mfma_f32_16x16x32_bf16 v[12:15], v[162:165], v[220:223], v[12:15]
	v_mfma_f32_16x16x32_bf16 v[8:11], v[170:173], v[220:223], v[8:11]
	s_setprio 0
	s_setprio 1
	v_mfma_f32_16x16x32_bf16 v[52:55], v[174:177], v[190:193], v[52:55]
	v_mfma_f32_16x16x32_bf16 v[48:51], v[182:185], v[190:193], v[48:51]
	v_mfma_f32_16x16x32_bf16 v[36:39], v[174:177], v[200:203], v[36:39]
	v_mfma_f32_16x16x32_bf16 v[32:35], v[182:185], v[200:203], v[32:35]
	v_mfma_f32_16x16x32_bf16 v[20:23], v[174:177], v[208:211], v[20:23]
	v_mfma_f32_16x16x32_bf16 v[16:19], v[182:185], v[208:211], v[16:19]
	v_mfma_f32_16x16x32_bf16 v[4:7], v[174:177], v[216:219], v[4:7]
	v_mfma_f32_16x16x32_bf16 v[0:3], v[182:185], v[216:219], v[0:3]
	v_mfma_f32_16x16x32_bf16 v[52:55], v[178:181], v[196:199], v[52:55]
	v_mfma_f32_16x16x32_bf16 v[48:51], v[186:189], v[196:199], v[48:51]
	v_mfma_f32_16x16x32_bf16 v[36:39], v[178:181], v[204:207], v[36:39]
	v_mfma_f32_16x16x32_bf16 v[32:35], v[186:189], v[204:207], v[32:35]
	v_mfma_f32_16x16x32_bf16 v[20:23], v[178:181], v[212:215], v[20:23]
	v_mfma_f32_16x16x32_bf16 v[16:19], v[186:189], v[212:215], v[16:19]
	v_mfma_f32_16x16x32_bf16 v[4:7], v[178:181], v[220:223], v[4:7]
	v_mfma_f32_16x16x32_bf16 v[0:3], v[186:189], v[220:223], v[0:3]
	s_setprio 0
	s_barrier
	s_add_i32 s86, s86, 2
	s_add_u32 s38, s38, 0x100
	s_addc_u32 s39, s39, 0
	s_add_u32 s31, s31, 0x100
	s_addc_u32 s85, s85, 0
	s_cmp_gt_u32 s86, 13
	s_cbranch_scc0 .LBB0_626
	v_lshl_add_u64 v[228:229], v[228:229], 0, s[24:25]
	s_mov_b32 m0, s70
	s_nop 0
	global_load_lds_dwordx4 v[228:229], off
	v_lshl_add_u64 v[230:231], v[230:231], 0, s[24:25]
	s_mov_b32 m0, s71
	s_nop 0
	global_load_lds_dwordx4 v[230:231], off
	s_and_b64 vcc, exec, s[26:27]
	s_cbranch_vccz .LBB0_629
	s_barrier

.LBB0_759:
	s_lshl_b64 s[30:31], s[24:25], 18
	s_add_u32 s13, s45, s30
	s_addc_u32 s25, s50, s31
	s_and_b64 s[30:31], s[26:27], exec
	s_cselect_b32 s31, s25, s37
	s_cselect_b32 s30, s13, s36
	s_add_u32 s13, s36, 0x100
	v_mov_b32_e32 v0, 0
	s_addc_u32 s25, s37, 0
	s_mov_b32 s83, -2
	v_mov_b32_e32 v1, v0
	v_mov_b32_e32 v2, v0
	v_mov_b32_e32 v3, v0
	v_mov_b32_e32 v4, v0
	v_mov_b32_e32 v5, v0
	v_mov_b32_e32 v6, v0
	v_mov_b32_e32 v7, v0
	v_mov_b32_e32 v8, v0
	v_mov_b32_e32 v9, v0
	v_mov_b32_e32 v10, v0
	v_mov_b32_e32 v11, v0
	v_mov_b32_e32 v12, v0
	v_mov_b32_e32 v13, v0
	v_mov_b32_e32 v14, v0
	v_mov_b32_e32 v15, v0
	v_mov_b32_e32 v20, v0
	v_mov_b32_e32 v21, v0
	v_mov_b32_e32 v22, v0
	v_mov_b32_e32 v23, v0
	v_mov_b32_e32 v28, v0
	v_mov_b32_e32 v29, v0
	v_mov_b32_e32 v30, v0
	v_mov_b32_e32 v31, v0
	v_mov_b32_e32 v36, v0
	v_mov_b32_e32 v37, v0
	v_mov_b32_e32 v38, v0
	v_mov_b32_e32 v39, v0
	v_mov_b32_e32 v44, v0
	v_mov_b32_e32 v45, v0
	v_mov_b32_e32 v46, v0
	v_mov_b32_e32 v47, v0
	v_mov_b32_e32 v16, v0
	v_mov_b32_e32 v17, v0
	v_mov_b32_e32 v18, v0
	v_mov_b32_e32 v19, v0
	v_mov_b32_e32 v24, v0
	v_mov_b32_e32 v25, v0
	v_mov_b32_e32 v26, v0
	v_mov_b32_e32 v27, v0
	v_mov_b32_e32 v32, v0
	v_mov_b32_e32 v33, v0
	v_mov_b32_e32 v34, v0
	v_mov_b32_e32 v35, v0
	v_mov_b32_e32 v40, v0
	v_mov_b32_e32 v41, v0
	v_mov_b32_e32 v42, v0
	v_mov_b32_e32 v43, v0
	v_mov_b32_e32 v48, v0
	v_mov_b32_e32 v49, v0
	v_mov_b32_e32 v50, v0
	v_mov_b32_e32 v51, v0
	v_mov_b32_e32 v52, v0
	v_mov_b32_e32 v53, v0
	v_mov_b32_e32 v54, v0
	v_mov_b32_e32 v55, v0
	v_mov_b32_e32 v56, v0
	v_mov_b32_e32 v57, v0
	v_mov_b32_e32 v58, v0
	v_mov_b32_e32 v59, v0
	v_mov_b32_e32 v60, v0
	v_mov_b32_e32 v61, v0
	v_mov_b32_e32 v62, v0
	v_mov_b32_e32 v63, v0
	v_mov_b32_e32 v64, v0
	v_mov_b32_e32 v65, v0
	v_mov_b32_e32 v66, v0
	v_mov_b32_e32 v67, v0
	v_mov_b32_e32 v68, v0
	v_mov_b32_e32 v69, v0
	v_mov_b32_e32 v70, v0
	v_mov_b32_e32 v71, v0
	v_mov_b32_e32 v72, v0
	v_mov_b32_e32 v73, v0
	v_mov_b32_e32 v74, v0
	v_mov_b32_e32 v75, v0
	v_mov_b32_e32 v76, v0
	v_mov_b32_e32 v77, v0
	v_mov_b32_e32 v78, v0
	v_mov_b32_e32 v79, v0
	v_mov_b32_e32 v84, v0
	v_mov_b32_e32 v85, v0
	v_mov_b32_e32 v86, v0
	v_mov_b32_e32 v87, v0
	v_mov_b32_e32 v92, v0
	v_mov_b32_e32 v93, v0
	v_mov_b32_e32 v94, v0
	v_mov_b32_e32 v95, v0
	v_mov_b32_e32 v100, v0
	v_mov_b32_e32 v101, v0
	v_mov_b32_e32 v102, v0
	v_mov_b32_e32 v103, v0
	v_mov_b32_e32 v108, v0
	v_mov_b32_e32 v109, v0
	v_mov_b32_e32 v110, v0
	v_mov_b32_e32 v111, v0
	v_mov_b32_e32 v80, v0
	v_mov_b32_e32 v81, v0
	v_mov_b32_e32 v82, v0
	v_mov_b32_e32 v83, v0
	v_mov_b32_e32 v88, v0
	v_mov_b32_e32 v89, v0
	v_mov_b32_e32 v90, v0
	v_mov_b32_e32 v91, v0
	v_mov_b32_e32 v96, v0
	v_mov_b32_e32 v97, v0
	v_mov_b32_e32 v98, v0
	v_mov_b32_e32 v99, v0
	v_mov_b32_e32 v104, v0
	v_mov_b32_e32 v105, v0
	v_mov_b32_e32 v106, v0
	v_mov_b32_e32 v107, v0
	v_mov_b32_e32 v112, v0
	v_mov_b32_e32 v113, v0
	v_mov_b32_e32 v114, v0
	v_mov_b32_e32 v115, v0
	v_mov_b32_e32 v116, v0
	v_mov_b32_e32 v117, v0
	v_mov_b32_e32 v118, v0
	v_mov_b32_e32 v119, v0
	v_mov_b32_e32 v120, v0
	v_mov_b32_e32 v121, v0
	v_mov_b32_e32 v122, v0
	v_mov_b32_e32 v123, v0
	v_mov_b32_e32 v124, v0
	v_mov_b32_e32 v125, v0
	v_mov_b32_e32 v126, v0
	v_mov_b32_e32 v127, v0
	s_mov_b32 s99, 0
.LBB0_760:
	ds_read_b128 v[148:151], v144
	ds_read_b128 v[152:155], v144 offset:1024
	ds_read_b128 v[156:159], v144 offset:2048
	ds_read_b128 v[160:163], v144 offset:3072
	ds_read_b128 v[164:167], v145
	ds_read_b128 v[168:171], v145 offset:1024
	ds_read_b128 v[172:175], v145 offset:2048
	ds_read_b128 v[176:179], v145 offset:3072
	s_add_u32 s36, s34, 0x100
	s_addc_u32 s37, s35, 0
	s_cmp_eq_u32 s83, 4
	s_cselect_b32 s41, s29, s37
	s_cselect_b32 s40, s28, s36
	s_cselect_b32 s39, s31, s25
	s_cselect_b32 s38, s30, s13
	v_lshl_add_u64 v[192:193], s[34:35], 0, v[138:139]
	ds_read_b128 v[180:183], v146
	ds_read_b128 v[184:187], v146 offset:1024
	ds_read_b128 v[188:191], v146 offset:2048
	ds_read_b128 v[196:199], v146 offset:3072
	ds_read_b128 v[200:203], v146 offset:4096
	ds_read_b128 v[204:207], v146 offset:5120
	ds_read_b128 v[208:211], v146 offset:6144
	ds_read_b128 v[212:215], v146 offset:7168
	s_cmp_eq_u32 s99, 0
	s_cbranch_scc1 .Lkb_first_3
	v_lshl_add_u64 v[218:219], v[218:219], 0, s[10:11]
	s_mov_b32 m0, s71
	s_nop 0
	global_load_lds_dwordx4 v[218:219], off
	v_lshl_add_u64 v[220:221], v[220:221], 0, s[10:11]
	s_mov_b32 m0, s72
	s_nop 0
	global_load_lds_dwordx4 v[220:221], off
	s_branch .Lkb_join_3
.Lkb_first_3:
	s_add_i32 m0, s58, 0xc000
	s_nop 0
	global_load_lds_dwordx4 v[192:193], off
	global_load_lds_dwordx4 v[192:193], off
.Lkb_join_3:
	s_add_i32 m0, s58, 0xc000
	s_nop 0
	global_load_lds_dwordx4 v[192:193], off
	v_lshl_add_u64 v[192:193], s[34:35], 0, v[140:141]
	s_add_i32 m0, s58, 0xe000
	s_nop 0
	global_load_lds_dwordx4 v[192:193], off
	s_waitcnt vmcnt(8)
	s_waitcnt lgkmcnt(0)
	s_barrier
	s_setprio 1
	s_waitcnt lgkmcnt(0)
	v_mfma_f32_16x16x32_bf16 v[124:127], v[148:151], v[180:183], v[124:127]
	v_mfma_f32_16x16x32_bf16 v[120:123], v[156:159], v[180:183], v[120:123]
	v_mfma_f32_16x16x32_bf16 v[116:119], v[148:151], v[188:191], v[116:119]
	v_mfma_f32_16x16x32_bf16 v[112:115], v[156:159], v[188:191], v[112:115]
	v_mfma_f32_16x16x32_bf16 v[104:107], v[148:151], v[200:203], v[104:107]
	v_mfma_f32_16x16x32_bf16 v[96:99], v[156:159], v[200:203], v[96:99]
	v_mfma_f32_16x16x32_bf16 v[88:91], v[148:151], v[208:211], v[88:91]
	v_mfma_f32_16x16x32_bf16 v[80:83], v[156:159], v[208:211], v[80:83]
	v_mfma_f32_16x16x32_bf16 v[124:127], v[152:155], v[184:187], v[124:127]
	v_mfma_f32_16x16x32_bf16 v[120:123], v[160:163], v[184:187], v[120:123]
	v_mfma_f32_16x16x32_bf16 v[116:119], v[152:155], v[196:199], v[116:119]
	v_mfma_f32_16x16x32_bf16 v[112:115], v[160:163], v[196:199], v[112:115]
	v_mfma_f32_16x16x32_bf16 v[104:107], v[152:155], v[204:207], v[104:107]
	v_mfma_f32_16x16x32_bf16 v[96:99], v[160:163], v[204:207], v[96:99]
	v_mfma_f32_16x16x32_bf16 v[88:91], v[152:155], v[212:215], v[88:91]
	v_mfma_f32_16x16x32_bf16 v[80:83], v[160:163], v[212:215], v[80:83]
	s_setprio 0
	s_setprio 1
	v_mfma_f32_16x16x32_bf16 v[108:111], v[164:167], v[180:183], v[108:111]
	v_mfma_f32_16x16x32_bf16 v[100:103], v[172:175], v[180:183], v[100:103]
	v_mfma_f32_16x16x32_bf16 v[92:95], v[164:167], v[188:191], v[92:95]
	v_mfma_f32_16x16x32_bf16 v[84:87], v[172:175], v[188:191], v[84:87]
	v_mfma_f32_16x16x32_bf16 v[76:79], v[164:167], v[200:203], v[76:79]
	v_mfma_f32_16x16x32_bf16 v[72:75], v[172:175], v[200:203], v[72:75]
	v_mfma_f32_16x16x32_bf16 v[68:71], v[164:167], v[208:211], v[68:71]
	v_mfma_f32_16x16x32_bf16 v[64:67], v[172:175], v[208:211], v[64:67]
	v_mfma_f32_16x16x32_bf16 v[108:111], v[168:171], v[184:187], v[108:111]
	v_mfma_f32_16x16x32_bf16 v[100:103], v[176:179], v[184:187], v[100:103]
	v_mfma_f32_16x16x32_bf16 v[92:95], v[168:171], v[196:199], v[92:95]
	v_mfma_f32_16x16x32_bf16 v[84:87], v[176:179], v[196:199], v[84:87]
	v_mfma_f32_16x16x32_bf16 v[76:79], v[168:171], v[204:207], v[76:79]
	v_mfma_f32_16x16x32_bf16 v[72:75], v[176:179], v[204:207], v[72:75]
	v_mfma_f32_16x16x32_bf16 v[68:71], v[168:171], v[212:215], v[68:71]
	v_mfma_f32_16x16x32_bf16 v[64:67], v[176:179], v[212:215], v[64:67]
	s_setprio 0
	s_barrier
	s_add_i32 s34, s77, s51
	v_lshl_add_u64 v[192:193], s[38:39], 0, v[132:133]
	s_mov_b32 m0, s34
	ds_read_b128 v[180:183], v146 offset:16384
	ds_read_b128 v[184:187], v146 offset:17408
	ds_read_b128 v[188:191], v146 offset:18432
	ds_read_b128 v[196:199], v146 offset:19456
	ds_read_b128 v[200:203], v146 offset:20480
	ds_read_b128 v[204:207], v146 offset:21504
	ds_read_b128 v[208:211], v146 offset:22528
	ds_read_b128 v[212:215], v146 offset:23552
	global_load_lds_dwordx4 v[192:193], off
	s_add_i32 m0, s34, 0x2000
	s_add_u32 s34, s38, 0x20000
	v_lshl_add_u64 v[216:217], s[38:39], 0, v[128:129]
	s_addc_u32 s35, s39, 0
	s_add_i32 s84, s78, s51
	global_load_lds_dwordx4 v[216:217], off
	v_lshl_add_u64 v[218:219], s[34:35], 0, v[132:133]
	s_mov_b32 m0, s84
	v_lshl_add_u64 v[220:221], s[40:41], 0, v[130:131]
	global_load_lds_dwordx4 v[218:219], off
	v_lshl_add_u64 v[218:219], s[34:35], 0, v[128:129]
	s_add_i32 m0, s84, 0x2000
	s_nop 0
	global_load_lds_dwordx4 v[218:219], off
	v_lshl_add_u64 v[218:219], s[40:41], 0, v[134:135]
	s_waitcnt vmcnt(6)
	s_waitcnt lgkmcnt(0)
	s_barrier
	s_setprio 1
	s_waitcnt lgkmcnt(0)
	v_mfma_f32_16x16x32_bf16 v[60:63], v[148:151], v[180:183], v[60:63]
	v_mfma_f32_16x16x32_bf16 v[56:59], v[156:159], v[180:183], v[56:59]
	v_mfma_f32_16x16x32_bf16 v[52:55], v[148:151], v[188:191], v[52:55]
	v_mfma_f32_16x16x32_bf16 v[48:51], v[156:159], v[188:191], v[48:51]
	v_mfma_f32_16x16x32_bf16 v[40:43], v[148:151], v[200:203], v[40:43]
	v_mfma_f32_16x16x32_bf16 v[32:35], v[156:159], v[200:203], v[32:35]
	v_mfma_f32_16x16x32_bf16 v[24:27], v[148:151], v[208:211], v[24:27]
	v_mfma_f32_16x16x32_bf16 v[16:19], v[156:159], v[208:211], v[16:19]
	v_mfma_f32_16x16x32_bf16 v[60:63], v[152:155], v[184:187], v[60:63]
	v_mfma_f32_16x16x32_bf16 v[56:59], v[160:163], v[184:187], v[56:59]
	v_mfma_f32_16x16x32_bf16 v[52:55], v[152:155], v[196:199], v[52:55]
	v_mfma_f32_16x16x32_bf16 v[48:51], v[160:163], v[196:199], v[48:51]
	v_mfma_f32_16x16x32_bf16 v[40:43], v[152:155], v[204:207], v[40:43]
	v_mfma_f32_16x16x32_bf16 v[32:35], v[160:163], v[204:207], v[32:35]
	v_mfma_f32_16x16x32_bf16 v[24:27], v[152:155], v[212:215], v[24:27]
	v_mfma_f32_16x16x32_bf16 v[16:19], v[160:163], v[212:215], v[16:19]
	s_setprio 0
	s_setprio 1
	v_mfma_f32_16x16x32_bf16 v[44:47], v[164:167], v[180:183], v[44:47]
	v_mfma_f32_16x16x32_bf16 v[36:39], v[172:175], v[180:183], v[36:39]
	v_mfma_f32_16x16x32_bf16 v[28:31], v[164:167], v[188:191], v[28:31]
	v_mfma_f32_16x16x32_bf16 v[20:23], v[172:175], v[188:191], v[20:23]
	v_mfma_f32_16x16x32_bf16 v[12:15], v[164:167], v[200:203], v[12:15]
	v_mfma_f32_16x16x32_bf16 v[8:11], v[172:175], v[200:203], v[8:11]
	v_mfma_f32_16x16x32_bf16 v[4:7], v[164:167], v[208:211], v[4:7]
	v_mfma_f32_16x16x32_bf16 v[0:3], v[172:175], v[208:211], v[0:3]
	v_mfma_f32_16x16x32_bf16 v[44:47], v[168:171], v[184:187], v[44:47]
	v_mfma_f32_16x16x32_bf16 v[36:39], v[176:179], v[184:187], v[36:39]
	v_mfma_f32_16x16x32_bf16 v[28:31], v[168:171], v[196:199], v[28:31]
	v_mfma_f32_16x16x32_bf16 v[20:23], v[176:179], v[196:199], v[20:23]
	v_mfma_f32_16x16x32_bf16 v[12:15], v[168:171], v[204:207], v[12:15]
	v_mfma_f32_16x16x32_bf16 v[8:11], v[176:179], v[204:207], v[8:11]
	v_mfma_f32_16x16x32_bf16 v[4:7], v[168:171], v[212:215], v[4:7]
	v_mfma_f32_16x16x32_bf16 v[0:3], v[176:179], v[212:215], v[0:3]
	s_setprio 0
	s_barrier
	s_add_i32 s84, 0, 0x18000
	v_add_u32_e32 v147, s84, v143
	s_add_i32 s85, 0, 0x1c000
	ds_read_b128 v[148:151], v147
	ds_read_b128 v[152:155], v147 offset:1024
	ds_read_b128 v[156:159], v147 offset:2048
	ds_read_b128 v[160:163], v147 offset:3072
	v_add_u32_e32 v147, s85, v143
	ds_read_b128 v[164:167], v147
	ds_read_b128 v[168:171], v147 offset:1024
	ds_read_b128 v[172:175], v147 offset:2048
	ds_read_b128 v[176:179], v147 offset:3072
	s_add_u32 s34, s40, 0x30000
	s_addc_u32 s35, s41, 0
	v_lshl_add_u64 v[222:223], s[34:35], 0, v[134:135]
	ds_read_b128 v[180:183], v146 offset:32768
	ds_read_b128 v[184:187], v146 offset:33792
	ds_read_b128 v[188:191], v146 offset:34816
	ds_read_b128 v[196:199], v146 offset:35840
	ds_read_b128 v[200:203], v146 offset:36864
	ds_read_b128 v[204:207], v146 offset:37888
	ds_read_b128 v[208:211], v146 offset:38912
	ds_read_b128 v[212:215], v146 offset:39936
	s_mov_b32 m0, s58
	s_nop 0
	global_load_lds_dwordx4 v[218:219], off
	s_mov_b32 m0, s59
	s_nop 0
	global_load_lds_dwordx4 v[220:221], off
	s_mov_b32 m0, s60
	s_nop 0
	global_load_lds_dwordx4 v[222:223], off
	v_lshl_add_u64 v[222:223], s[34:35], 0, v[130:131]
	s_mov_b32 m0, s61
	s_nop 0
	global_load_lds_dwordx4 v[222:223], off
	s_waitcnt vmcnt(8)
	s_waitcnt lgkmcnt(0)
	s_barrier
	s_setprio 1
	s_waitcnt lgkmcnt(0)
	v_mfma_f32_16x16x32_bf16 v[124:127], v[148:151], v[180:183], v[124:127]
	v_mfma_f32_16x16x32_bf16 v[120:123], v[156:159], v[180:183], v[120:123]
	v_mfma_f32_16x16x32_bf16 v[116:119], v[148:151], v[188:191], v[116:119]
	v_mfma_f32_16x16x32_bf16 v[112:115], v[156:159], v[188:191], v[112:115]
	v_mfma_f32_16x16x32_bf16 v[104:107], v[148:151], v[200:203], v[104:107]
	v_mfma_f32_16x16x32_bf16 v[96:99], v[156:159], v[200:203], v[96:99]
	v_mfma_f32_16x16x32_bf16 v[88:91], v[148:151], v[208:211], v[88:91]
	v_mfma_f32_16x16x32_bf16 v[80:83], v[156:159], v[208:211], v[80:83]
	v_mfma_f32_16x16x32_bf16 v[124:127], v[152:155], v[184:187], v[124:127]
	v_mfma_f32_16x16x32_bf16 v[120:123], v[160:163], v[184:187], v[120:123]
	v_mfma_f32_16x16x32_bf16 v[116:119], v[152:155], v[196:199], v[116:119]
	v_mfma_f32_16x16x32_bf16 v[112:115], v[160:163], v[196:199], v[112:115]
	v_mfma_f32_16x16x32_bf16 v[104:107], v[152:155], v[204:207], v[104:107]
	v_mfma_f32_16x16x32_bf16 v[96:99], v[160:163], v[204:207], v[96:99]
	v_mfma_f32_16x16x32_bf16 v[88:91], v[152:155], v[212:215], v[88:91]
	v_mfma_f32_16x16x32_bf16 v[80:83], v[160:163], v[212:215], v[80:83]
	s_setprio 0
	s_setprio 1
	v_mfma_f32_16x16x32_bf16 v[108:111], v[164:167], v[180:183], v[108:111]
	v_mfma_f32_16x16x32_bf16 v[100:103], v[172:175], v[180:183], v[100:103]
	v_mfma_f32_16x16x32_bf16 v[92:95], v[164:167], v[188:191], v[92:95]
	v_mfma_f32_16x16x32_bf16 v[84:87], v[172:175], v[188:191], v[84:87]
	v_mfma_f32_16x16x32_bf16 v[76:79], v[164:167], v[200:203], v[76:79]
	v_mfma_f32_16x16x32_bf16 v[72:75], v[172:175], v[200:203], v[72:75]
	v_mfma_f32_16x16x32_bf16 v[68:71], v[164:167], v[208:211], v[68:71]
	v_mfma_f32_16x16x32_bf16 v[64:67], v[172:175], v[208:211], v[64:67]
	v_mfma_f32_16x16x32_bf16 v[108:111], v[168:171], v[184:187], v[108:111]
	v_mfma_f32_16x16x32_bf16 v[100:103], v[176:179], v[184:187], v[100:103]
	v_mfma_f32_16x16x32_bf16 v[92:95], v[168:171], v[196:199], v[92:95]
	v_mfma_f32_16x16x32_bf16 v[84:87], v[176:179], v[196:199], v[84:87]
	v_mfma_f32_16x16x32_bf16 v[76:79], v[168:171], v[204:207], v[76:79]
	v_mfma_f32_16x16x32_bf16 v[72:75], v[176:179], v[204:207], v[72:75]
	v_mfma_f32_16x16x32_bf16 v[68:71], v[168:171], v[212:215], v[68:71]
	v_mfma_f32_16x16x32_bf16 v[64:67], v[176:179], v[212:215], v[64:67]
	s_setprio 0
	s_barrier
	s_add_i32 s34, s84, s51
	v_lshl_add_u64 v[192:193], v[192:193], 0, s[10:11]
	s_mov_b32 m0, s34
	ds_read_b128 v[180:183], v146 offset:49152
	ds_read_b128 v[184:187], v146 offset:50176
	ds_read_b128 v[188:191], v146 offset:51200
	ds_read_b128 v[196:199], v146 offset:52224
	ds_read_b128 v[200:203], v146 offset:53248
	ds_read_b128 v[204:207], v146 offset:54272
	ds_read_b128 v[208:211], v146 offset:55296
	ds_read_b128 v[212:215], v146 offset:56320
	global_load_lds_dwordx4 v[192:193], off
	s_add_i32 m0, s34, 0x2000
	s_add_u32 s34, s38, 0x20080
	v_lshl_add_u64 v[192:193], v[216:217], 0, s[10:11]
	s_addc_u32 s35, s39, 0
	s_add_i32 s38, s85, s51
	global_load_lds_dwordx4 v[192:193], off
	v_lshl_add_u64 v[192:193], s[34:35], 0, v[132:133]
	s_mov_b32 m0, s38
	s_nop 0
	global_load_lds_dwordx4 v[192:193], off
	v_lshl_add_u64 v[192:193], s[34:35], 0, v[128:129]
	s_add_i32 m0, s38, 0x2000
	s_nop 0
	global_load_lds_dwordx4 v[192:193], off
	s_mov_b32 s99, 1
	s_waitcnt vmcnt(6)
	s_waitcnt lgkmcnt(0)
	s_barrier
	s_setprio 1
	s_waitcnt lgkmcnt(0)
	v_mfma_f32_16x16x32_bf16 v[60:63], v[148:151], v[180:183], v[60:63]
	v_mfma_f32_16x16x32_bf16 v[56:59], v[156:159], v[180:183], v[56:59]
	v_mfma_f32_16x16x32_bf16 v[52:55], v[148:151], v[188:191], v[52:55]
	v_mfma_f32_16x16x32_bf16 v[48:51], v[156:159], v[188:191], v[48:51]
	v_mfma_f32_16x16x32_bf16 v[40:43], v[148:151], v[200:203], v[40:43]
	v_mfma_f32_16x16x32_bf16 v[32:35], v[156:159], v[200:203], v[32:35]
	v_mfma_f32_16x16x32_bf16 v[24:27], v[148:151], v[208:211], v[24:27]
	v_mfma_f32_16x16x32_bf16 v[16:19], v[156:159], v[208:211], v[16:19]
	v_mfma_f32_16x16x32_bf16 v[60:63], v[152:155], v[184:187], v[60:63]
	v_mfma_f32_16x16x32_bf16 v[56:59], v[160:163], v[184:187], v[56:59]
	v_mfma_f32_16x16x32_bf16 v[52:55], v[152:155], v[196:199], v[52:55]
	v_mfma_f32_16x16x32_bf16 v[48:51], v[160:163], v[196:199], v[48:51]
	v_mfma_f32_16x16x32_bf16 v[40:43], v[152:155], v[204:207], v[40:43]
	v_mfma_f32_16x16x32_bf16 v[32:35], v[160:163], v[204:207], v[32:35]
	v_mfma_f32_16x16x32_bf16 v[24:27], v[152:155], v[212:215], v[24:27]
	v_mfma_f32_16x16x32_bf16 v[16:19], v[160:163], v[212:215], v[16:19]
	s_setprio 0
	s_setprio 1
	v_mfma_f32_16x16x32_bf16 v[44:47], v[164:167], v[180:183], v[44:47]
	v_mfma_f32_16x16x32_bf16 v[36:39], v[172:175], v[180:183], v[36:39]
	v_mfma_f32_16x16x32_bf16 v[28:31], v[164:167], v[188:191], v[28:31]
	v_mfma_f32_16x16x32_bf16 v[20:23], v[172:175], v[188:191], v[20:23]
	v_mfma_f32_16x16x32_bf16 v[12:15], v[164:167], v[200:203], v[12:15]
	v_mfma_f32_16x16x32_bf16 v[8:11], v[172:175], v[200:203], v[8:11]
	v_mfma_f32_16x16x32_bf16 v[4:7], v[164:167], v[208:211], v[4:7]
	v_mfma_f32_16x16x32_bf16 v[0:3], v[172:175], v[208:211], v[0:3]
	v_mfma_f32_16x16x32_bf16 v[44:47], v[168:171], v[184:187], v[44:47]
	v_mfma_f32_16x16x32_bf16 v[36:39], v[176:179], v[184:187], v[36:39]
	v_mfma_f32_16x16x32_bf16 v[28:31], v[168:171], v[196:199], v[28:31]
	v_mfma_f32_16x16x32_bf16 v[20:23], v[176:179], v[196:199], v[20:23]
	v_mfma_f32_16x16x32_bf16 v[12:15], v[168:171], v[204:207], v[12:15]
	v_mfma_f32_16x16x32_bf16 v[8:11], v[176:179], v[204:207], v[8:11]
	v_mfma_f32_16x16x32_bf16 v[4:7], v[168:171], v[212:215], v[4:7]
	v_mfma_f32_16x16x32_bf16 v[0:3], v[176:179], v[212:215], v[0:3]
	s_setprio 0
	s_barrier
	s_add_i32 s83, s83, 2
	s_add_u32 s13, s13, 0x100
	s_addc_u32 s25, s25, 0
	s_cmp_gt_u32 s83, 5
	s_mov_b64 s[34:35], s[36:37]
	s_cbranch_scc0 .LBB0_760
	v_lshl_add_u64 v[218:219], v[218:219], 0, s[10:11]
	s_mov_b32 m0, s71
	s_nop 0
	global_load_lds_dwordx4 v[218:219], off
	v_lshl_add_u64 v[220:221], v[220:221], 0, s[10:11]
	s_mov_b32 m0, s72
	s_nop 0
	global_load_lds_dwordx4 v[220:221], off
	s_and_b64 vcc, exec, s[16:17]
	s_cbranch_vccz .LBB0_763
	s_barrier

.LBB0_785:
	s_ashr_i32 s25, s24, 31
	s_lshl_b64 s[26:27], s[24:25], 19
	s_add_u32 s26, s41, s26
	s_addc_u32 s27, s42, s27
	s_and_b64 s[28:29], s[6:7], exec
	s_cselect_b32 s25, s27, s31
	s_cselect_b32 s78, s26, s30
	s_ashr_i32 s23, s22, 31
	s_lshl_b64 s[28:29], s[22:23], 19
	s_add_u32 s28, s43, s28
	s_addc_u32 s29, s44, s29
	s_and_b64 s[36:37], s[6:7], exec
	s_cselect_b32 s23, s29, s35
	s_cselect_b32 s79, s28, s34
	s_add_u32 s30, s30, 0x40080
	s_addc_u32 s31, s31, 0
	s_add_u32 s80, s34, 0x100
	v_mov_b32_e32 v0, 0
	s_addc_u32 s81, s35, 0
	s_mov_b32 s82, -2
	v_mov_b32_e32 v1, v0
	v_mov_b32_e32 v2, v0
	v_mov_b32_e32 v3, v0
	v_mov_b32_e32 v4, v0
	v_mov_b32_e32 v5, v0
	v_mov_b32_e32 v6, v0
	v_mov_b32_e32 v7, v0
	v_mov_b32_e32 v16, v0
	v_mov_b32_e32 v17, v0
	v_mov_b32_e32 v18, v0
	v_mov_b32_e32 v19, v0
	v_mov_b32_e32 v20, v0
	v_mov_b32_e32 v21, v0
	v_mov_b32_e32 v22, v0
	v_mov_b32_e32 v23, v0
	v_mov_b32_e32 v32, v0
	v_mov_b32_e32 v33, v0
	v_mov_b32_e32 v34, v0
	v_mov_b32_e32 v35, v0
	v_mov_b32_e32 v36, v0
	v_mov_b32_e32 v37, v0
	v_mov_b32_e32 v38, v0
	v_mov_b32_e32 v39, v0
	v_mov_b32_e32 v48, v0
	v_mov_b32_e32 v49, v0
	v_mov_b32_e32 v50, v0
	v_mov_b32_e32 v51, v0
	v_mov_b32_e32 v52, v0
	v_mov_b32_e32 v53, v0
	v_mov_b32_e32 v54, v0
	v_mov_b32_e32 v55, v0
	v_mov_b32_e32 v8, v0
	v_mov_b32_e32 v9, v0
	v_mov_b32_e32 v10, v0
	v_mov_b32_e32 v11, v0
	v_mov_b32_e32 v12, v0
	v_mov_b32_e32 v13, v0
	v_mov_b32_e32 v14, v0
	v_mov_b32_e32 v15, v0
	v_mov_b32_e32 v24, v0
	v_mov_b32_e32 v25, v0
	v_mov_b32_e32 v26, v0
	v_mov_b32_e32 v27, v0
	v_mov_b32_e32 v28, v0
	v_mov_b32_e32 v29, v0
	v_mov_b32_e32 v30, v0
	v_mov_b32_e32 v31, v0
	v_mov_b32_e32 v40, v0
	v_mov_b32_e32 v41, v0
	v_mov_b32_e32 v42, v0
	v_mov_b32_e32 v43, v0
	v_mov_b32_e32 v44, v0
	v_mov_b32_e32 v45, v0
	v_mov_b32_e32 v46, v0
	v_mov_b32_e32 v47, v0
	v_mov_b32_e32 v56, v0
	v_mov_b32_e32 v57, v0
	v_mov_b32_e32 v58, v0
	v_mov_b32_e32 v59, v0
	v_mov_b32_e32 v60, v0
	v_mov_b32_e32 v61, v0
	v_mov_b32_e32 v62, v0
	v_mov_b32_e32 v63, v0
	v_mov_b32_e32 v64, v0
	v_mov_b32_e32 v65, v0
	v_mov_b32_e32 v66, v0
	v_mov_b32_e32 v67, v0
	v_mov_b32_e32 v68, v0
	v_mov_b32_e32 v69, v0
	v_mov_b32_e32 v70, v0
	v_mov_b32_e32 v71, v0
	v_mov_b32_e32 v80, v0
	v_mov_b32_e32 v81, v0
	v_mov_b32_e32 v82, v0
	v_mov_b32_e32 v83, v0
	v_mov_b32_e32 v84, v0
	v_mov_b32_e32 v85, v0
	v_mov_b32_e32 v86, v0
	v_mov_b32_e32 v87, v0
	v_mov_b32_e32 v96, v0
	v_mov_b32_e32 v97, v0
	v_mov_b32_e32 v98, v0
	v_mov_b32_e32 v99, v0
	v_mov_b32_e32 v100, v0
	v_mov_b32_e32 v101, v0
	v_mov_b32_e32 v102, v0
	v_mov_b32_e32 v103, v0
	v_mov_b32_e32 v112, v0
	v_mov_b32_e32 v113, v0
	v_mov_b32_e32 v114, v0
	v_mov_b32_e32 v115, v0
	v_mov_b32_e32 v116, v0
	v_mov_b32_e32 v117, v0
	v_mov_b32_e32 v118, v0
	v_mov_b32_e32 v119, v0
	v_mov_b32_e32 v72, v0
	v_mov_b32_e32 v73, v0
	v_mov_b32_e32 v74, v0
	v_mov_b32_e32 v75, v0
	v_mov_b32_e32 v76, v0
	v_mov_b32_e32 v77, v0
	v_mov_b32_e32 v78, v0
	v_mov_b32_e32 v79, v0
	v_mov_b32_e32 v88, v0
	v_mov_b32_e32 v89, v0
	v_mov_b32_e32 v90, v0
	v_mov_b32_e32 v91, v0
	v_mov_b32_e32 v92, v0
	v_mov_b32_e32 v93, v0
	v_mov_b32_e32 v94, v0
	v_mov_b32_e32 v95, v0
	v_mov_b32_e32 v104, v0
	v_mov_b32_e32 v105, v0
	v_mov_b32_e32 v106, v0
	v_mov_b32_e32 v107, v0
	v_mov_b32_e32 v108, v0
	v_mov_b32_e32 v109, v0
	v_mov_b32_e32 v110, v0
	v_mov_b32_e32 v111, v0
	v_mov_b32_e32 v120, v0
	v_mov_b32_e32 v121, v0
	v_mov_b32_e32 v122, v0
	v_mov_b32_e32 v123, v0
	v_mov_b32_e32 v124, v0
	v_mov_b32_e32 v125, v0
	v_mov_b32_e32 v126, v0
	v_mov_b32_e32 v127, v0
	s_mov_b32 s99, 0
.LBB0_786:
	ds_read_b128 v[144:147], v153
	ds_read_b128 v[158:161], v153 offset:1024
	ds_read_b128 v[162:165], v153 offset:2048
	ds_read_b128 v[166:169], v153 offset:3072
	ds_read_b128 v[170:173], v154
	ds_read_b128 v[174:177], v154 offset:1024
	ds_read_b128 v[178:181], v154 offset:2048
	ds_read_b128 v[182:185], v154 offset:3072
	s_add_u32 s34, s30, 0xfffc0080
	s_addc_u32 s35, s31, -1
	s_cmp_eq_u32 s82, 12
	s_cselect_b32 s37, s25, s35
	s_cselect_b32 s36, s78, s34
	s_cselect_b32 s35, s23, s81
	s_cselect_b32 s34, s79, s80
	v_lshl_add_u64 v[148:149], s[30:31], 0, v[136:137]
	ds_read_b128 v[186:189], v155
	ds_read_b128 v[190:193], v155 offset:1024
	ds_read_b128 v[196:199], v155 offset:2048
	ds_read_b128 v[200:203], v155 offset:3072
	ds_read_b128 v[204:207], v155 offset:4096
	ds_read_b128 v[208:211], v155 offset:5120
	ds_read_b128 v[212:215], v155 offset:6144
	ds_read_b128 v[216:219], v155 offset:7168
	s_cmp_eq_u32 s99, 0
	s_cbranch_scc1 .Lkb_first_4
	v_lshl_add_u64 v[222:223], v[222:223], 0, s[18:19]
	s_mov_b32 m0, s61
	s_nop 0
	global_load_lds_dwordx4 v[222:223], off
	v_lshl_add_u64 v[224:225], v[224:225], 0, s[18:19]
	s_mov_b32 m0, s62
	s_nop 0
	global_load_lds_dwordx4 v[224:225], off
	s_branch .Lkb_join_4
.Lkb_first_4:
	s_add_i32 m0, s50, 0xc000
	s_nop 0
	global_load_lds_dwordx4 v[148:149], off
	global_load_lds_dwordx4 v[148:149], off
.Lkb_join_4:
	s_add_i32 m0, s50, 0xc000
	s_nop 0
	global_load_lds_dwordx4 v[148:149], off
	v_lshl_add_u64 v[148:149], s[30:31], 0, v[138:139]
	s_add_i32 m0, s50, 0xe000
	s_nop 0
	global_load_lds_dwordx4 v[148:149], off
	s_waitcnt vmcnt(8)
	s_waitcnt lgkmcnt(0)
	s_barrier
	s_setprio 1
	s_waitcnt lgkmcnt(0)
	v_mfma_f32_16x16x32_bf16 v[124:127], v[144:147], v[186:189], v[124:127]
	v_mfma_f32_16x16x32_bf16 v[120:123], v[162:165], v[186:189], v[120:123]
	v_mfma_f32_16x16x32_bf16 v[108:111], v[144:147], v[196:199], v[108:111]
	v_mfma_f32_16x16x32_bf16 v[104:107], v[162:165], v[196:199], v[104:107]
	v_mfma_f32_16x16x32_bf16 v[92:95], v[144:147], v[204:207], v[92:95]
	v_mfma_f32_16x16x32_bf16 v[88:91], v[162:165], v[204:207], v[88:91]
	v_mfma_f32_16x16x32_bf16 v[76:79], v[144:147], v[212:215], v[76:79]
	v_mfma_f32_16x16x32_bf16 v[72:75], v[162:165], v[212:215], v[72:75]
	v_mfma_f32_16x16x32_bf16 v[124:127], v[158:161], v[190:193], v[124:127]
	v_mfma_f32_16x16x32_bf16 v[120:123], v[166:169], v[190:193], v[120:123]
	v_mfma_f32_16x16x32_bf16 v[108:111], v[158:161], v[200:203], v[108:111]
	v_mfma_f32_16x16x32_bf16 v[104:107], v[166:169], v[200:203], v[104:107]
	v_mfma_f32_16x16x32_bf16 v[92:95], v[158:161], v[208:211], v[92:95]
	v_mfma_f32_16x16x32_bf16 v[88:91], v[166:169], v[208:211], v[88:91]
	v_mfma_f32_16x16x32_bf16 v[76:79], v[158:161], v[216:219], v[76:79]
	v_mfma_f32_16x16x32_bf16 v[72:75], v[166:169], v[216:219], v[72:75]
	s_setprio 0
	s_setprio 1
	v_mfma_f32_16x16x32_bf16 v[116:119], v[170:173], v[186:189], v[116:119]
	v_mfma_f32_16x16x32_bf16 v[112:115], v[178:181], v[186:189], v[112:115]
	v_mfma_f32_16x16x32_bf16 v[100:103], v[170:173], v[196:199], v[100:103]
	v_mfma_f32_16x16x32_bf16 v[96:99], v[178:181], v[196:199], v[96:99]
	v_mfma_f32_16x16x32_bf16 v[84:87], v[170:173], v[204:207], v[84:87]
	v_mfma_f32_16x16x32_bf16 v[80:83], v[178:181], v[204:207], v[80:83]
	v_mfma_f32_16x16x32_bf16 v[68:71], v[170:173], v[212:215], v[68:71]
	v_mfma_f32_16x16x32_bf16 v[64:67], v[178:181], v[212:215], v[64:67]
	v_mfma_f32_16x16x32_bf16 v[116:119], v[174:177], v[190:193], v[116:119]
	v_mfma_f32_16x16x32_bf16 v[112:115], v[182:185], v[190:193], v[112:115]
	v_mfma_f32_16x16x32_bf16 v[100:103], v[174:177], v[200:203], v[100:103]
	v_mfma_f32_16x16x32_bf16 v[96:99], v[182:185], v[200:203], v[96:99]
	v_mfma_f32_16x16x32_bf16 v[84:87], v[174:177], v[208:211], v[84:87]
	v_mfma_f32_16x16x32_bf16 v[80:83], v[182:185], v[208:211], v[80:83]
	v_mfma_f32_16x16x32_bf16 v[68:71], v[174:177], v[216:219], v[68:71]
	v_mfma_f32_16x16x32_bf16 v[64:67], v[182:185], v[216:219], v[64:67]
	s_setprio 0
	s_barrier
	s_add_i32 s83, s70, s45
	v_lshl_add_u64 v[148:149], s[34:35], 0, v[130:131]
	s_mov_b32 m0, s83
	ds_read_b128 v[186:189], v155 offset:16384
	ds_read_b128 v[190:193], v155 offset:17408
	ds_read_b128 v[196:199], v155 offset:18432
	ds_read_b128 v[200:203], v155 offset:19456
	ds_read_b128 v[204:207], v155 offset:20480
	ds_read_b128 v[208:211], v155 offset:21504
	ds_read_b128 v[212:215], v155 offset:22528
	ds_read_b128 v[216:219], v155 offset:23552
	global_load_lds_dwordx4 v[148:149], off
	s_add_i32 m0, s83, 0x2000
	s_add_u32 s84, s34, 0x40000
	v_lshl_add_u64 v[220:221], s[34:35], 0, v[134:135]
	s_addc_u32 s85, s35, 0
	s_add_i32 s83, s71, s45
	global_load_lds_dwordx4 v[220:221], off
	v_lshl_add_u64 v[222:223], s[84:85], 0, v[130:131]
	s_mov_b32 m0, s83
	v_lshl_add_u64 v[224:225], s[36:37], 0, v[132:133]
	global_load_lds_dwordx4 v[222:223], off
	v_lshl_add_u64 v[222:223], s[84:85], 0, v[134:135]
	s_add_i32 m0, s83, 0x2000
	s_nop 0
	global_load_lds_dwordx4 v[222:223], off
	v_lshl_add_u64 v[222:223], s[36:37], 0, v[128:129]
	s_waitcnt vmcnt(6)
	s_waitcnt lgkmcnt(0)
	s_barrier
	s_setprio 1
	s_waitcnt lgkmcnt(0)
	v_mfma_f32_16x16x32_bf16 v[60:63], v[144:147], v[186:189], v[60:63]
	v_mfma_f32_16x16x32_bf16 v[56:59], v[162:165], v[186:189], v[56:59]
	v_mfma_f32_16x16x32_bf16 v[44:47], v[144:147], v[196:199], v[44:47]
	v_mfma_f32_16x16x32_bf16 v[40:43], v[162:165], v[196:199], v[40:43]
	v_mfma_f32_16x16x32_bf16 v[28:31], v[144:147], v[204:207], v[28:31]
	v_mfma_f32_16x16x32_bf16 v[24:27], v[162:165], v[204:207], v[24:27]
	v_mfma_f32_16x16x32_bf16 v[12:15], v[144:147], v[212:215], v[12:15]
	v_mfma_f32_16x16x32_bf16 v[8:11], v[162:165], v[212:215], v[8:11]
	v_mfma_f32_16x16x32_bf16 v[60:63], v[158:161], v[190:193], v[60:63]
	v_mfma_f32_16x16x32_bf16 v[56:59], v[166:169], v[190:193], v[56:59]
	v_mfma_f32_16x16x32_bf16 v[44:47], v[158:161], v[200:203], v[44:47]
	v_mfma_f32_16x16x32_bf16 v[40:43], v[166:169], v[200:203], v[40:43]
	v_mfma_f32_16x16x32_bf16 v[28:31], v[158:161], v[208:211], v[28:31]
	v_mfma_f32_16x16x32_bf16 v[24:27], v[166:169], v[208:211], v[24:27]
	v_mfma_f32_16x16x32_bf16 v[12:15], v[158:161], v[216:219], v[12:15]
	v_mfma_f32_16x16x32_bf16 v[8:11], v[166:169], v[216:219], v[8:11]
	s_setprio 0
	s_setprio 1
	v_mfma_f32_16x16x32_bf16 v[52:55], v[170:173], v[186:189], v[52:55]
	v_mfma_f32_16x16x32_bf16 v[48:51], v[178:181], v[186:189], v[48:51]
	v_mfma_f32_16x16x32_bf16 v[36:39], v[170:173], v[196:199], v[36:39]
	v_mfma_f32_16x16x32_bf16 v[32:35], v[178:181], v[196:199], v[32:35]
	v_mfma_f32_16x16x32_bf16 v[20:23], v[170:173], v[204:207], v[20:23]
	v_mfma_f32_16x16x32_bf16 v[16:19], v[178:181], v[204:207], v[16:19]
	v_mfma_f32_16x16x32_bf16 v[4:7], v[170:173], v[212:215], v[4:7]
	v_mfma_f32_16x16x32_bf16 v[0:3], v[178:181], v[212:215], v[0:3]
	v_mfma_f32_16x16x32_bf16 v[52:55], v[174:177], v[190:193], v[52:55]
	v_mfma_f32_16x16x32_bf16 v[48:51], v[182:185], v[190:193], v[48:51]
	v_mfma_f32_16x16x32_bf16 v[36:39], v[174:177], v[200:203], v[36:39]
	v_mfma_f32_16x16x32_bf16 v[32:35], v[182:185], v[200:203], v[32:35]
	v_mfma_f32_16x16x32_bf16 v[20:23], v[174:177], v[208:211], v[20:23]
	v_mfma_f32_16x16x32_bf16 v[16:19], v[182:185], v[208:211], v[16:19]
	v_mfma_f32_16x16x32_bf16 v[4:7], v[174:177], v[216:219], v[4:7]
	v_mfma_f32_16x16x32_bf16 v[0:3], v[182:185], v[216:219], v[0:3]
	s_setprio 0
	s_barrier
	s_add_i32 s83, 0, 0x18000
	v_add_u32_e32 v157, s83, v151
	s_add_i32 s84, 0, 0x1c000
	ds_read_b128 v[144:147], v157
	ds_read_b128 v[158:161], v157 offset:1024
	ds_read_b128 v[162:165], v157 offset:2048
	ds_read_b128 v[166:169], v157 offset:3072
	v_add_u32_e32 v157, s84, v151
	ds_read_b128 v[170:173], v157
	ds_read_b128 v[174:177], v157 offset:1024
	ds_read_b128 v[178:181], v157 offset:2048
	ds_read_b128 v[182:185], v157 offset:3072
	s_add_u32 s36, s36, 0x40000
	s_addc_u32 s37, s37, 0
	v_lshl_add_u64 v[226:227], s[36:37], 0, v[128:129]
	ds_read_b128 v[186:189], v155 offset:32768
	ds_read_b128 v[190:193], v155 offset:33792
	ds_read_b128 v[196:199], v155 offset:34816
	ds_read_b128 v[200:203], v155 offset:35840
	ds_read_b128 v[204:207], v155 offset:36864
	ds_read_b128 v[208:211], v155 offset:37888
	ds_read_b128 v[212:215], v155 offset:38912
	ds_read_b128 v[216:219], v155 offset:39936
	s_mov_b32 m0, s50
	s_nop 0
	global_load_lds_dwordx4 v[222:223], off
	s_mov_b32 m0, s51
	s_nop 0
	global_load_lds_dwordx4 v[224:225], off
	s_mov_b32 m0, s58
	s_nop 0
	global_load_lds_dwordx4 v[226:227], off
	v_lshl_add_u64 v[226:227], s[36:37], 0, v[132:133]
	s_mov_b32 m0, s59
	s_nop 0
	global_load_lds_dwordx4 v[226:227], off
	s_waitcnt vmcnt(8)
	s_waitcnt lgkmcnt(0)
	s_barrier
	s_setprio 1
	s_waitcnt lgkmcnt(0)
	v_mfma_f32_16x16x32_bf16 v[124:127], v[144:147], v[186:189], v[124:127]
	v_mfma_f32_16x16x32_bf16 v[120:123], v[162:165], v[186:189], v[120:123]
	v_mfma_f32_16x16x32_bf16 v[108:111], v[144:147], v[196:199], v[108:111]
	v_mfma_f32_16x16x32_bf16 v[104:107], v[162:165], v[196:199], v[104:107]
	v_mfma_f32_16x16x32_bf16 v[92:95], v[144:147], v[204:207], v[92:95]
	v_mfma_f32_16x16x32_bf16 v[88:91], v[162:165], v[204:207], v[88:91]
	v_mfma_f32_16x16x32_bf16 v[76:79], v[144:147], v[212:215], v[76:79]
	v_mfma_f32_16x16x32_bf16 v[72:75], v[162:165], v[212:215], v[72:75]
	v_mfma_f32_16x16x32_bf16 v[124:127], v[158:161], v[190:193], v[124:127]
	v_mfma_f32_16x16x32_bf16 v[120:123], v[166:169], v[190:193], v[120:123]
	v_mfma_f32_16x16x32_bf16 v[108:111], v[158:161], v[200:203], v[108:111]
	v_mfma_f32_16x16x32_bf16 v[104:107], v[166:169], v[200:203], v[104:107]
	v_mfma_f32_16x16x32_bf16 v[92:95], v[158:161], v[208:211], v[92:95]
	v_mfma_f32_16x16x32_bf16 v[88:91], v[166:169], v[208:211], v[88:91]
	v_mfma_f32_16x16x32_bf16 v[76:79], v[158:161], v[216:219], v[76:79]
	v_mfma_f32_16x16x32_bf16 v[72:75], v[166:169], v[216:219], v[72:75]
	s_setprio 0
	s_setprio 1
	v_mfma_f32_16x16x32_bf16 v[116:119], v[170:173], v[186:189], v[116:119]
	v_mfma_f32_16x16x32_bf16 v[112:115], v[178:181], v[186:189], v[112:115]
	v_mfma_f32_16x16x32_bf16 v[100:103], v[170:173], v[196:199], v[100:103]
	v_mfma_f32_16x16x32_bf16 v[96:99], v[178:181], v[196:199], v[96:99]
	v_mfma_f32_16x16x32_bf16 v[84:87], v[170:173], v[204:207], v[84:87]
	v_mfma_f32_16x16x32_bf16 v[80:83], v[178:181], v[204:207], v[80:83]
	v_mfma_f32_16x16x32_bf16 v[68:71], v[170:173], v[212:215], v[68:71]
	v_mfma_f32_16x16x32_bf16 v[64:67], v[178:181], v[212:215], v[64:67]
	v_mfma_f32_16x16x32_bf16 v[116:119], v[174:177], v[190:193], v[116:119]
	v_mfma_f32_16x16x32_bf16 v[112:115], v[182:185], v[190:193], v[112:115]
	v_mfma_f32_16x16x32_bf16 v[100:103], v[174:177], v[200:203], v[100:103]
	v_mfma_f32_16x16x32_bf16 v[96:99], v[182:185], v[200:203], v[96:99]
	v_mfma_f32_16x16x32_bf16 v[84:87], v[174:177], v[208:211], v[84:87]
	v_mfma_f32_16x16x32_bf16 v[80:83], v[182:185], v[208:211], v[80:83]
	v_mfma_f32_16x16x32_bf16 v[68:71], v[174:177], v[216:219], v[68:71]
	v_mfma_f32_16x16x32_bf16 v[64:67], v[182:185], v[216:219], v[64:67]
	s_setprio 0
	s_barrier
	s_add_i32 s36, s83, s45
	v_lshl_add_u64 v[148:149], v[148:149], 0, s[18:19]
	s_mov_b32 m0, s36
	ds_read_b128 v[186:189], v155 offset:49152
	ds_read_b128 v[190:193], v155 offset:50176
	ds_read_b128 v[196:199], v155 offset:51200
	ds_read_b128 v[200:203], v155 offset:52224
	ds_read_b128 v[204:207], v155 offset:53248
	ds_read_b128 v[208:211], v155 offset:54272
	ds_read_b128 v[212:215], v155 offset:55296
	ds_read_b128 v[216:219], v155 offset:56320
	global_load_lds_dwordx4 v[148:149], off
	s_add_i32 m0, s36, 0x2000
	s_add_u32 s34, s34, 0x40080
	v_lshl_add_u64 v[148:149], v[220:221], 0, s[18:19]
	s_addc_u32 s35, s35, 0
	s_add_i32 s36, s84, s45
	global_load_lds_dwordx4 v[148:149], off
	v_lshl_add_u64 v[148:149], s[34:35], 0, v[130:131]
	s_mov_b32 m0, s36
	s_nop 0
	global_load_lds_dwordx4 v[148:149], off
	v_lshl_add_u64 v[148:149], s[34:35], 0, v[134:135]
	s_add_i32 m0, s36, 0x2000
	s_nop 0
	global_load_lds_dwordx4 v[148:149], off
	s_mov_b32 s99, 1
	s_waitcnt vmcnt(6)
	s_waitcnt lgkmcnt(0)
	s_barrier
	s_setprio 1
	s_waitcnt lgkmcnt(0)
	v_mfma_f32_16x16x32_bf16 v[60:63], v[144:147], v[186:189], v[60:63]
	v_mfma_f32_16x16x32_bf16 v[56:59], v[162:165], v[186:189], v[56:59]
	v_mfma_f32_16x16x32_bf16 v[44:47], v[144:147], v[196:199], v[44:47]
	v_mfma_f32_16x16x32_bf16 v[40:43], v[162:165], v[196:199], v[40:43]
	v_mfma_f32_16x16x32_bf16 v[28:31], v[144:147], v[204:207], v[28:31]
	v_mfma_f32_16x16x32_bf16 v[24:27], v[162:165], v[204:207], v[24:27]
	v_mfma_f32_16x16x32_bf16 v[12:15], v[144:147], v[212:215], v[12:15]
	v_mfma_f32_16x16x32_bf16 v[8:11], v[162:165], v[212:215], v[8:11]
	v_mfma_f32_16x16x32_bf16 v[60:63], v[158:161], v[190:193], v[60:63]
	v_mfma_f32_16x16x32_bf16 v[56:59], v[166:169], v[190:193], v[56:59]
	v_mfma_f32_16x16x32_bf16 v[44:47], v[158:161], v[200:203], v[44:47]
	v_mfma_f32_16x16x32_bf16 v[40:43], v[166:169], v[200:203], v[40:43]
	v_mfma_f32_16x16x32_bf16 v[28:31], v[158:161], v[208:211], v[28:31]
	v_mfma_f32_16x16x32_bf16 v[24:27], v[166:169], v[208:211], v[24:27]
	v_mfma_f32_16x16x32_bf16 v[12:15], v[158:161], v[216:219], v[12:15]
	v_mfma_f32_16x16x32_bf16 v[8:11], v[166:169], v[216:219], v[8:11]
	s_setprio 0
	s_setprio 1
	v_mfma_f32_16x16x32_bf16 v[52:55], v[170:173], v[186:189], v[52:55]
	v_mfma_f32_16x16x32_bf16 v[48:51], v[178:181], v[186:189], v[48:51]
	v_mfma_f32_16x16x32_bf16 v[36:39], v[170:173], v[196:199], v[36:39]
	v_mfma_f32_16x16x32_bf16 v[32:35], v[178:181], v[196:199], v[32:35]
	v_mfma_f32_16x16x32_bf16 v[20:23], v[170:173], v[204:207], v[20:23]
	v_mfma_f32_16x16x32_bf16 v[16:19], v[178:181], v[204:207], v[16:19]
	v_mfma_f32_16x16x32_bf16 v[4:7], v[170:173], v[212:215], v[4:7]
	v_mfma_f32_16x16x32_bf16 v[0:3], v[178:181], v[212:215], v[0:3]
	v_mfma_f32_16x16x32_bf16 v[52:55], v[174:177], v[190:193], v[52:55]
	v_mfma_f32_16x16x32_bf16 v[48:51], v[182:185], v[190:193], v[48:51]
	v_mfma_f32_16x16x32_bf16 v[36:39], v[174:177], v[200:203], v[36:39]
	v_mfma_f32_16x16x32_bf16 v[32:35], v[182:185], v[200:203], v[32:35]
	v_mfma_f32_16x16x32_bf16 v[20:23], v[174:177], v[208:211], v[20:23]
	v_mfma_f32_16x16x32_bf16 v[16:19], v[182:185], v[208:211], v[16:19]
	v_mfma_f32_16x16x32_bf16 v[4:7], v[174:177], v[216:219], v[4:7]
	v_mfma_f32_16x16x32_bf16 v[0:3], v[182:185], v[216:219], v[0:3]
	s_setprio 0
	s_barrier
	s_add_i32 s82, s82, 2
	s_add_u32 s30, s30, 0x100
	s_addc_u32 s31, s31, 0
	s_add_u32 s80, s80, 0x100
	s_addc_u32 s81, s81, 0
	s_cmp_gt_u32 s82, 13
	s_cbranch_scc0 .LBB0_786
	v_lshl_add_u64 v[222:223], v[222:223], 0, s[18:19]
	s_mov_b32 m0, s61
	s_nop 0
	global_load_lds_dwordx4 v[222:223], off
	v_lshl_add_u64 v[224:225], v[224:225], 0, s[18:19]
	s_mov_b32 m0, s62
	s_nop 0
	global_load_lds_dwordx4 v[224:225], off
	s_and_b64 vcc, exec, s[20:21]
	s_cbranch_vccz .LBB0_789
	s_barrier

.LBB0_922:
	s_add_u32 s73, s26, 0x100
	v_mov_b32_e32 v0, 0
	s_addc_u32 s78, s27, 0
	s_mov_b32 s79, -2
	v_mov_b32_e32 v1, v0
	v_mov_b32_e32 v2, v0
	v_mov_b32_e32 v3, v0
	v_mov_b32_e32 v4, v0
	v_mov_b32_e32 v5, v0
	v_mov_b32_e32 v6, v0
	v_mov_b32_e32 v7, v0
	v_mov_b32_e32 v16, v0
	v_mov_b32_e32 v17, v0
	v_mov_b32_e32 v18, v0
	v_mov_b32_e32 v19, v0
	v_mov_b32_e32 v20, v0
	v_mov_b32_e32 v21, v0
	v_mov_b32_e32 v22, v0
	v_mov_b32_e32 v23, v0
	v_mov_b32_e32 v32, v0
	v_mov_b32_e32 v33, v0
	v_mov_b32_e32 v34, v0
	v_mov_b32_e32 v35, v0
	v_mov_b32_e32 v36, v0
	v_mov_b32_e32 v37, v0
	v_mov_b32_e32 v38, v0
	v_mov_b32_e32 v39, v0
	v_mov_b32_e32 v48, v0
	v_mov_b32_e32 v49, v0
	v_mov_b32_e32 v50, v0
	v_mov_b32_e32 v51, v0
	v_mov_b32_e32 v52, v0
	v_mov_b32_e32 v53, v0
	v_mov_b32_e32 v54, v0
	v_mov_b32_e32 v55, v0
	v_mov_b32_e32 v8, v0
	v_mov_b32_e32 v9, v0
	v_mov_b32_e32 v10, v0
	v_mov_b32_e32 v11, v0
	v_mov_b32_e32 v12, v0
	v_mov_b32_e32 v13, v0
	v_mov_b32_e32 v14, v0
	v_mov_b32_e32 v15, v0
	v_mov_b32_e32 v24, v0
	v_mov_b32_e32 v25, v0
	v_mov_b32_e32 v26, v0
	v_mov_b32_e32 v27, v0
	v_mov_b32_e32 v28, v0
	v_mov_b32_e32 v29, v0
	v_mov_b32_e32 v30, v0
	v_mov_b32_e32 v31, v0
	v_mov_b32_e32 v40, v0
	v_mov_b32_e32 v41, v0
	v_mov_b32_e32 v42, v0
	v_mov_b32_e32 v43, v0
	v_mov_b32_e32 v44, v0
	v_mov_b32_e32 v45, v0
	v_mov_b32_e32 v46, v0
	v_mov_b32_e32 v47, v0
	v_mov_b32_e32 v56, v0
	v_mov_b32_e32 v57, v0
	v_mov_b32_e32 v58, v0
	v_mov_b32_e32 v59, v0
	v_mov_b32_e32 v60, v0
	v_mov_b32_e32 v61, v0
	v_mov_b32_e32 v62, v0
	v_mov_b32_e32 v63, v0
	v_mov_b32_e32 v64, v0
	v_mov_b32_e32 v65, v0
	v_mov_b32_e32 v66, v0
	v_mov_b32_e32 v67, v0
	v_mov_b32_e32 v68, v0
	v_mov_b32_e32 v69, v0
	v_mov_b32_e32 v70, v0
	v_mov_b32_e32 v71, v0
	v_mov_b32_e32 v80, v0
	v_mov_b32_e32 v81, v0
	v_mov_b32_e32 v82, v0
	v_mov_b32_e32 v83, v0
	v_mov_b32_e32 v84, v0
	v_mov_b32_e32 v85, v0
	v_mov_b32_e32 v86, v0
	v_mov_b32_e32 v87, v0
	v_mov_b32_e32 v96, v0
	v_mov_b32_e32 v97, v0
	v_mov_b32_e32 v98, v0
	v_mov_b32_e32 v99, v0
	v_mov_b32_e32 v100, v0
	v_mov_b32_e32 v101, v0
	v_mov_b32_e32 v102, v0
	v_mov_b32_e32 v103, v0
	v_mov_b32_e32 v112, v0
	v_mov_b32_e32 v113, v0
	v_mov_b32_e32 v114, v0
	v_mov_b32_e32 v115, v0
	v_mov_b32_e32 v116, v0
	v_mov_b32_e32 v117, v0
	v_mov_b32_e32 v118, v0
	v_mov_b32_e32 v119, v0
	v_mov_b32_e32 v72, v0
	v_mov_b32_e32 v73, v0
	v_mov_b32_e32 v74, v0
	v_mov_b32_e32 v75, v0
	v_mov_b32_e32 v76, v0
	v_mov_b32_e32 v77, v0
	v_mov_b32_e32 v78, v0
	v_mov_b32_e32 v79, v0
	v_mov_b32_e32 v88, v0
	v_mov_b32_e32 v89, v0
	v_mov_b32_e32 v90, v0
	v_mov_b32_e32 v91, v0
	v_mov_b32_e32 v92, v0
	v_mov_b32_e32 v93, v0
	v_mov_b32_e32 v94, v0
	v_mov_b32_e32 v95, v0
	v_mov_b32_e32 v104, v0
	v_mov_b32_e32 v105, v0
	v_mov_b32_e32 v106, v0
	v_mov_b32_e32 v107, v0
	v_mov_b32_e32 v108, v0
	v_mov_b32_e32 v109, v0
	v_mov_b32_e32 v110, v0
	v_mov_b32_e32 v111, v0
	v_mov_b32_e32 v120, v0
	v_mov_b32_e32 v121, v0
	v_mov_b32_e32 v122, v0
	v_mov_b32_e32 v123, v0
	v_mov_b32_e32 v124, v0
	v_mov_b32_e32 v125, v0
	v_mov_b32_e32 v126, v0
	v_mov_b32_e32 v127, v0
	s_mov_b32 s99, 0
.LBB0_923:
	ds_read_b128 v[152:155], v148
	ds_read_b128 v[156:159], v148 offset:1024
	ds_read_b128 v[160:163], v148 offset:2048
	ds_read_b128 v[164:167], v148 offset:3072
	ds_read_b128 v[168:171], v149
	ds_read_b128 v[172:175], v149 offset:1024
	ds_read_b128 v[176:179], v149 offset:2048
	ds_read_b128 v[180:183], v149 offset:3072
	s_add_u32 s26, s24, 0x100
	s_addc_u32 s27, s25, 0
	s_cmp_eq_u32 s79, 8
	s_cselect_b32 s31, s21, s27
	s_cselect_b32 s30, s20, s26
	s_cselect_b32 s29, s23, s78
	s_cselect_b32 s28, s22, s73
	v_lshl_add_u64 v[192:193], s[24:25], 0, v[138:139]
	ds_read_b128 v[184:187], v150
	ds_read_b128 v[188:191], v150 offset:1024
	ds_read_b128 v[196:199], v150 offset:2048
	ds_read_b128 v[200:203], v150 offset:3072
	ds_read_b128 v[204:207], v150 offset:4096
	ds_read_b128 v[208:211], v150 offset:5120
	ds_read_b128 v[212:215], v150 offset:6144
	ds_read_b128 v[216:219], v150 offset:7168
	s_cmp_eq_u32 s99, 0
	s_cbranch_scc1 .Lkb_first_5
	v_lshl_add_u64 v[222:223], v[222:223], 0, s[16:17]
	s_mov_b32 m0, s45
	s_nop 0
	global_load_lds_dwordx4 v[222:223], off
	v_lshl_add_u64 v[224:225], v[224:225], 0, s[16:17]
	s_mov_b32 m0, s50
	s_nop 0
	global_load_lds_dwordx4 v[224:225], off
	s_branch .Lkb_join_5
.Lkb_first_5:
	s_mov_b32 m0, s60
	s_nop 0
	global_load_lds_dwordx4 v[192:193], off
	global_load_lds_dwordx4 v[192:193], off
.Lkb_join_5:
	s_mov_b32 m0, s60
	s_nop 0
	global_load_lds_dwordx4 v[192:193], off
	v_lshl_add_u64 v[192:193], s[24:25], 0, v[140:141]
	s_add_i32 m0, s40, 0xe000
	s_nop 0
	global_load_lds_dwordx4 v[192:193], off
	s_waitcnt vmcnt(8)
	s_waitcnt lgkmcnt(0)
	s_barrier
	s_setprio 1
	s_waitcnt lgkmcnt(0)
	v_mfma_f32_16x16x32_bf16 v[124:127], v[152:155], v[184:187], v[124:127]
	v_mfma_f32_16x16x32_bf16 v[120:123], v[160:163], v[184:187], v[120:123]
	v_mfma_f32_16x16x32_bf16 v[108:111], v[152:155], v[196:199], v[108:111]
	v_mfma_f32_16x16x32_bf16 v[104:107], v[160:163], v[196:199], v[104:107]
	v_mfma_f32_16x16x32_bf16 v[92:95], v[152:155], v[204:207], v[92:95]
	v_mfma_f32_16x16x32_bf16 v[88:91], v[160:163], v[204:207], v[88:91]
	v_mfma_f32_16x16x32_bf16 v[76:79], v[152:155], v[212:215], v[76:79]
	v_mfma_f32_16x16x32_bf16 v[72:75], v[160:163], v[212:215], v[72:75]
	v_mfma_f32_16x16x32_bf16 v[124:127], v[156:159], v[188:191], v[124:127]
	v_mfma_f32_16x16x32_bf16 v[120:123], v[164:167], v[188:191], v[120:123]
	v_mfma_f32_16x16x32_bf16 v[108:111], v[156:159], v[200:203], v[108:111]
	v_mfma_f32_16x16x32_bf16 v[104:107], v[164:167], v[200:203], v[104:107]
	v_mfma_f32_16x16x32_bf16 v[92:95], v[156:159], v[208:211], v[92:95]
	v_mfma_f32_16x16x32_bf16 v[88:91], v[164:167], v[208:211], v[88:91]
	v_mfma_f32_16x16x32_bf16 v[76:79], v[156:159], v[216:219], v[76:79]
	v_mfma_f32_16x16x32_bf16 v[72:75], v[164:167], v[216:219], v[72:75]
	s_setprio 0
	s_setprio 1
	v_mfma_f32_16x16x32_bf16 v[116:119], v[168:171], v[184:187], v[116:119]
	v_mfma_f32_16x16x32_bf16 v[112:115], v[176:179], v[184:187], v[112:115]
	v_mfma_f32_16x16x32_bf16 v[100:103], v[168:171], v[196:199], v[100:103]
	v_mfma_f32_16x16x32_bf16 v[96:99], v[176:179], v[196:199], v[96:99]
	v_mfma_f32_16x16x32_bf16 v[84:87], v[168:171], v[204:207], v[84:87]
	v_mfma_f32_16x16x32_bf16 v[80:83], v[176:179], v[204:207], v[80:83]
	v_mfma_f32_16x16x32_bf16 v[68:71], v[168:171], v[212:215], v[68:71]
	v_mfma_f32_16x16x32_bf16 v[64:67], v[176:179], v[212:215], v[64:67]
	v_mfma_f32_16x16x32_bf16 v[116:119], v[172:175], v[188:191], v[116:119]
	v_mfma_f32_16x16x32_bf16 v[112:115], v[180:183], v[188:191], v[112:115]
	v_mfma_f32_16x16x32_bf16 v[100:103], v[172:175], v[200:203], v[100:103]
	v_mfma_f32_16x16x32_bf16 v[96:99], v[180:183], v[200:203], v[96:99]
	v_mfma_f32_16x16x32_bf16 v[84:87], v[172:175], v[208:211], v[84:87]
	v_mfma_f32_16x16x32_bf16 v[80:83], v[180:183], v[208:211], v[80:83]
	v_mfma_f32_16x16x32_bf16 v[68:71], v[172:175], v[216:219], v[68:71]
	v_mfma_f32_16x16x32_bf16 v[64:67], v[180:183], v[216:219], v[64:67]
	s_setprio 0
	s_barrier
	s_add_i32 s24, s58, s39
	v_lshl_add_u64 v[192:193], s[28:29], 0, v[132:133]
	s_mov_b32 m0, s24
	ds_read_b128 v[184:187], v150 offset:16384
	ds_read_b128 v[188:191], v150 offset:17408
	ds_read_b128 v[196:199], v150 offset:18432
	ds_read_b128 v[200:203], v150 offset:19456
	ds_read_b128 v[204:207], v150 offset:20480
	ds_read_b128 v[208:211], v150 offset:21504
	ds_read_b128 v[212:215], v150 offset:22528
	ds_read_b128 v[216:219], v150 offset:23552
	global_load_lds_dwordx4 v[192:193], off
	s_add_i32 m0, s24, 0x2000
	s_add_u32 s24, s28, 0x30000
	v_lshl_add_u64 v[220:221], s[28:29], 0, v[128:129]
	s_addc_u32 s25, s29, 0
	s_add_i32 s80, s59, s39
	global_load_lds_dwordx4 v[220:221], off
	v_lshl_add_u64 v[222:223], s[24:25], 0, v[132:133]
	s_mov_b32 m0, s80
	v_lshl_add_u64 v[224:225], s[30:31], 0, v[130:131]
	global_load_lds_dwordx4 v[222:223], off
	v_lshl_add_u64 v[222:223], s[24:25], 0, v[128:129]
	s_add_i32 m0, s80, 0x2000
	s_nop 0
	global_load_lds_dwordx4 v[222:223], off
	v_lshl_add_u64 v[222:223], s[30:31], 0, v[134:135]
	s_waitcnt vmcnt(6)
	s_waitcnt lgkmcnt(0)
	s_barrier
	s_setprio 1
	s_waitcnt lgkmcnt(0)
	v_mfma_f32_16x16x32_bf16 v[60:63], v[152:155], v[184:187], v[60:63]
	v_mfma_f32_16x16x32_bf16 v[56:59], v[160:163], v[184:187], v[56:59]
	v_mfma_f32_16x16x32_bf16 v[44:47], v[152:155], v[196:199], v[44:47]
	v_mfma_f32_16x16x32_bf16 v[40:43], v[160:163], v[196:199], v[40:43]
	v_mfma_f32_16x16x32_bf16 v[28:31], v[152:155], v[204:207], v[28:31]
	v_mfma_f32_16x16x32_bf16 v[24:27], v[160:163], v[204:207], v[24:27]
	v_mfma_f32_16x16x32_bf16 v[12:15], v[152:155], v[212:215], v[12:15]
	v_mfma_f32_16x16x32_bf16 v[8:11], v[160:163], v[212:215], v[8:11]
	v_mfma_f32_16x16x32_bf16 v[60:63], v[156:159], v[188:191], v[60:63]
	v_mfma_f32_16x16x32_bf16 v[56:59], v[164:167], v[188:191], v[56:59]
	v_mfma_f32_16x16x32_bf16 v[44:47], v[156:159], v[200:203], v[44:47]
	v_mfma_f32_16x16x32_bf16 v[40:43], v[164:167], v[200:203], v[40:43]
	v_mfma_f32_16x16x32_bf16 v[28:31], v[156:159], v[208:211], v[28:31]
	v_mfma_f32_16x16x32_bf16 v[24:27], v[164:167], v[208:211], v[24:27]
	v_mfma_f32_16x16x32_bf16 v[12:15], v[156:159], v[216:219], v[12:15]
	v_mfma_f32_16x16x32_bf16 v[8:11], v[164:167], v[216:219], v[8:11]
	s_setprio 0
	s_setprio 1
	v_mfma_f32_16x16x32_bf16 v[52:55], v[168:171], v[184:187], v[52:55]
	v_mfma_f32_16x16x32_bf16 v[48:51], v[176:179], v[184:187], v[48:51]
	v_mfma_f32_16x16x32_bf16 v[36:39], v[168:171], v[196:199], v[36:39]
	v_mfma_f32_16x16x32_bf16 v[32:35], v[176:179], v[196:199], v[32:35]
	v_mfma_f32_16x16x32_bf16 v[20:23], v[168:171], v[204:207], v[20:23]
	v_mfma_f32_16x16x32_bf16 v[16:19], v[176:179], v[204:207], v[16:19]
	v_mfma_f32_16x16x32_bf16 v[4:7], v[168:171], v[212:215], v[4:7]
	v_mfma_f32_16x16x32_bf16 v[0:3], v[176:179], v[212:215], v[0:3]
	v_mfma_f32_16x16x32_bf16 v[52:55], v[172:175], v[188:191], v[52:55]
	v_mfma_f32_16x16x32_bf16 v[48:51], v[180:183], v[188:191], v[48:51]
	v_mfma_f32_16x16x32_bf16 v[36:39], v[172:175], v[200:203], v[36:39]
	v_mfma_f32_16x16x32_bf16 v[32:35], v[180:183], v[200:203], v[32:35]
	v_mfma_f32_16x16x32_bf16 v[20:23], v[172:175], v[208:211], v[20:23]
	v_mfma_f32_16x16x32_bf16 v[16:19], v[180:183], v[208:211], v[16:19]
	v_mfma_f32_16x16x32_bf16 v[4:7], v[172:175], v[216:219], v[4:7]
	v_mfma_f32_16x16x32_bf16 v[0:3], v[180:183], v[216:219], v[0:3]
	s_setprio 0
	s_barrier
	s_add_i32 s80, 0, 0x18000
	v_add_u32_e32 v151, s80, v142
	s_add_i32 s81, 0, 0x1c000
	ds_read_b128 v[152:155], v151
	ds_read_b128 v[156:159], v151 offset:1024
	ds_read_b128 v[160:163], v151 offset:2048
	ds_read_b128 v[164:167], v151 offset:3072
	v_add_u32_e32 v151, s81, v142
	ds_read_b128 v[168:171], v151
	ds_read_b128 v[172:175], v151 offset:1024
	ds_read_b128 v[176:179], v151 offset:2048
	ds_read_b128 v[180:183], v151 offset:3072
	s_add_u32 s24, s30, 0x30000
	s_addc_u32 s25, s31, 0
	v_lshl_add_u64 v[226:227], s[24:25], 0, v[134:135]
	ds_read_b128 v[184:187], v150 offset:32768
	ds_read_b128 v[188:191], v150 offset:33792
	ds_read_b128 v[196:199], v150 offset:34816
	ds_read_b128 v[200:203], v150 offset:35840
	ds_read_b128 v[204:207], v150 offset:36864
	ds_read_b128 v[208:211], v150 offset:37888
	ds_read_b128 v[212:215], v150 offset:38912
	ds_read_b128 v[216:219], v150 offset:39936
	s_mov_b32 m0, s40
	s_nop 0
	global_load_lds_dwordx4 v[222:223], off
	s_mov_b32 m0, s41
	s_nop 0
	global_load_lds_dwordx4 v[224:225], off
	s_mov_b32 m0, s42
	s_nop 0
	global_load_lds_dwordx4 v[226:227], off
	v_lshl_add_u64 v[226:227], s[24:25], 0, v[130:131]
	s_mov_b32 m0, s43
	s_nop 0
	global_load_lds_dwordx4 v[226:227], off
	s_waitcnt vmcnt(8)
	s_waitcnt lgkmcnt(0)
	s_barrier
	s_setprio 1
	s_waitcnt lgkmcnt(0)
	v_mfma_f32_16x16x32_bf16 v[124:127], v[152:155], v[184:187], v[124:127]
	v_mfma_f32_16x16x32_bf16 v[120:123], v[160:163], v[184:187], v[120:123]
	v_mfma_f32_16x16x32_bf16 v[108:111], v[152:155], v[196:199], v[108:111]
	v_mfma_f32_16x16x32_bf16 v[104:107], v[160:163], v[196:199], v[104:107]
	v_mfma_f32_16x16x32_bf16 v[92:95], v[152:155], v[204:207], v[92:95]
	v_mfma_f32_16x16x32_bf16 v[88:91], v[160:163], v[204:207], v[88:91]
	v_mfma_f32_16x16x32_bf16 v[76:79], v[152:155], v[212:215], v[76:79]
	v_mfma_f32_16x16x32_bf16 v[72:75], v[160:163], v[212:215], v[72:75]
	v_mfma_f32_16x16x32_bf16 v[124:127], v[156:159], v[188:191], v[124:127]
	v_mfma_f32_16x16x32_bf16 v[120:123], v[164:167], v[188:191], v[120:123]
	v_mfma_f32_16x16x32_bf16 v[108:111], v[156:159], v[200:203], v[108:111]
	v_mfma_f32_16x16x32_bf16 v[104:107], v[164:167], v[200:203], v[104:107]
	v_mfma_f32_16x16x32_bf16 v[92:95], v[156:159], v[208:211], v[92:95]
	v_mfma_f32_16x16x32_bf16 v[88:91], v[164:167], v[208:211], v[88:91]
	v_mfma_f32_16x16x32_bf16 v[76:79], v[156:159], v[216:219], v[76:79]
	v_mfma_f32_16x16x32_bf16 v[72:75], v[164:167], v[216:219], v[72:75]
	s_setprio 0
	s_setprio 1
	v_mfma_f32_16x16x32_bf16 v[116:119], v[168:171], v[184:187], v[116:119]
	v_mfma_f32_16x16x32_bf16 v[112:115], v[176:179], v[184:187], v[112:115]
	v_mfma_f32_16x16x32_bf16 v[100:103], v[168:171], v[196:199], v[100:103]
	v_mfma_f32_16x16x32_bf16 v[96:99], v[176:179], v[196:199], v[96:99]
	v_mfma_f32_16x16x32_bf16 v[84:87], v[168:171], v[204:207], v[84:87]
	v_mfma_f32_16x16x32_bf16 v[80:83], v[176:179], v[204:207], v[80:83]
	v_mfma_f32_16x16x32_bf16 v[68:71], v[168:171], v[212:215], v[68:71]
	v_mfma_f32_16x16x32_bf16 v[64:67], v[176:179], v[212:215], v[64:67]
	v_mfma_f32_16x16x32_bf16 v[116:119], v[172:175], v[188:191], v[116:119]
	v_mfma_f32_16x16x32_bf16 v[112:115], v[180:183], v[188:191], v[112:115]
	v_mfma_f32_16x16x32_bf16 v[100:103], v[172:175], v[200:203], v[100:103]
	v_mfma_f32_16x16x32_bf16 v[96:99], v[180:183], v[200:203], v[96:99]
	v_mfma_f32_16x16x32_bf16 v[84:87], v[172:175], v[208:211], v[84:87]
	v_mfma_f32_16x16x32_bf16 v[80:83], v[180:183], v[208:211], v[80:83]
	v_mfma_f32_16x16x32_bf16 v[68:71], v[172:175], v[216:219], v[68:71]
	v_mfma_f32_16x16x32_bf16 v[64:67], v[180:183], v[216:219], v[64:67]
	s_setprio 0
	s_barrier
	s_add_i32 s24, s80, s39
	v_lshl_add_u64 v[192:193], v[192:193], 0, s[16:17]
	s_mov_b32 m0, s24
	ds_read_b128 v[184:187], v150 offset:49152
	ds_read_b128 v[188:191], v150 offset:50176
	ds_read_b128 v[196:199], v150 offset:51200
	ds_read_b128 v[200:203], v150 offset:52224
	ds_read_b128 v[204:207], v150 offset:53248
	ds_read_b128 v[208:211], v150 offset:54272
	ds_read_b128 v[212:215], v150 offset:55296
	ds_read_b128 v[216:219], v150 offset:56320
	global_load_lds_dwordx4 v[192:193], off
	s_add_i32 m0, s24, 0x2000
	s_add_u32 s24, s28, 0x30080
	v_lshl_add_u64 v[192:193], v[220:221], 0, s[16:17]
	s_addc_u32 s25, s29, 0
	s_add_i32 s28, s81, s39
	global_load_lds_dwordx4 v[192:193], off
	v_lshl_add_u64 v[192:193], s[24:25], 0, v[132:133]
	s_mov_b32 m0, s28
	s_nop 0
	global_load_lds_dwordx4 v[192:193], off
	v_lshl_add_u64 v[192:193], s[24:25], 0, v[128:129]
	s_add_i32 m0, s28, 0x2000
	s_nop 0
	global_load_lds_dwordx4 v[192:193], off
	s_mov_b32 s99, 1
	s_waitcnt vmcnt(6)
	s_waitcnt lgkmcnt(0)
	s_barrier
	s_setprio 1
	s_waitcnt lgkmcnt(0)
	v_mfma_f32_16x16x32_bf16 v[60:63], v[152:155], v[184:187], v[60:63]
	v_mfma_f32_16x16x32_bf16 v[56:59], v[160:163], v[184:187], v[56:59]
	v_mfma_f32_16x16x32_bf16 v[44:47], v[152:155], v[196:199], v[44:47]
	v_mfma_f32_16x16x32_bf16 v[40:43], v[160:163], v[196:199], v[40:43]
	v_mfma_f32_16x16x32_bf16 v[28:31], v[152:155], v[204:207], v[28:31]
	v_mfma_f32_16x16x32_bf16 v[24:27], v[160:163], v[204:207], v[24:27]
	v_mfma_f32_16x16x32_bf16 v[12:15], v[152:155], v[212:215], v[12:15]
	v_mfma_f32_16x16x32_bf16 v[8:11], v[160:163], v[212:215], v[8:11]
	v_mfma_f32_16x16x32_bf16 v[60:63], v[156:159], v[188:191], v[60:63]
	v_mfma_f32_16x16x32_bf16 v[56:59], v[164:167], v[188:191], v[56:59]
	v_mfma_f32_16x16x32_bf16 v[44:47], v[156:159], v[200:203], v[44:47]
	v_mfma_f32_16x16x32_bf16 v[40:43], v[164:167], v[200:203], v[40:43]
	v_mfma_f32_16x16x32_bf16 v[28:31], v[156:159], v[208:211], v[28:31]
	v_mfma_f32_16x16x32_bf16 v[24:27], v[164:167], v[208:211], v[24:27]
	v_mfma_f32_16x16x32_bf16 v[12:15], v[156:159], v[216:219], v[12:15]
	v_mfma_f32_16x16x32_bf16 v[8:11], v[164:167], v[216:219], v[8:11]
	s_setprio 0
	s_setprio 1
	v_mfma_f32_16x16x32_bf16 v[52:55], v[168:171], v[184:187], v[52:55]
	v_mfma_f32_16x16x32_bf16 v[48:51], v[176:179], v[184:187], v[48:51]
	v_mfma_f32_16x16x32_bf16 v[36:39], v[168:171], v[196:199], v[36:39]
	v_mfma_f32_16x16x32_bf16 v[32:35], v[176:179], v[196:199], v[32:35]
	v_mfma_f32_16x16x32_bf16 v[20:23], v[168:171], v[204:207], v[20:23]
	v_mfma_f32_16x16x32_bf16 v[16:19], v[176:179], v[204:207], v[16:19]
	v_mfma_f32_16x16x32_bf16 v[4:7], v[168:171], v[212:215], v[4:7]
	v_mfma_f32_16x16x32_bf16 v[0:3], v[176:179], v[212:215], v[0:3]
	v_mfma_f32_16x16x32_bf16 v[52:55], v[172:175], v[188:191], v[52:55]
	v_mfma_f32_16x16x32_bf16 v[48:51], v[180:183], v[188:191], v[48:51]
	v_mfma_f32_16x16x32_bf16 v[36:39], v[172:175], v[200:203], v[36:39]
	v_mfma_f32_16x16x32_bf16 v[32:35], v[180:183], v[200:203], v[32:35]
	v_mfma_f32_16x16x32_bf16 v[20:23], v[172:175], v[208:211], v[20:23]
	v_mfma_f32_16x16x32_bf16 v[16:19], v[180:183], v[208:211], v[16:19]
	v_mfma_f32_16x16x32_bf16 v[4:7], v[172:175], v[216:219], v[4:7]
	v_mfma_f32_16x16x32_bf16 v[0:3], v[180:183], v[216:219], v[0:3]
	s_setprio 0
	s_barrier
	s_add_i32 s79, s79, 2
	s_add_u32 s73, s73, 0x100
	s_addc_u32 s78, s78, 0
	s_cmp_gt_u32 s79, 9
	s_mov_b64 s[24:25], s[26:27]
	s_cbranch_scc0 .LBB0_923
	v_lshl_add_u64 v[222:223], v[222:223], 0, s[16:17]
	s_mov_b32 m0, s45
	s_nop 0
	global_load_lds_dwordx4 v[222:223], off
	v_lshl_add_u64 v[224:225], v[224:225], 0, s[16:17]
	s_mov_b32 m0, s50
	s_nop 0
	global_load_lds_dwordx4 v[224:225], off
	s_and_b64 vcc, exec, s[18:19]
	s_cbranch_vccz .LBB0_926
	s_barrier

.LBB0_946:
	s_ashr_i32 s27, s26, 31
	s_lshl_b64 s[28:29], s[26:27], 19
	s_add_u32 s28, s43, s28
	s_addc_u32 s29, s44, s29
	s_and_b64 s[30:31], s[6:7], exec
	s_cselect_b32 s27, s29, s35
	s_cselect_b32 s81, s28, s34
	s_ashr_i32 s25, s24, 31
	s_lshl_b64 s[30:31], s[24:25], 19
	s_add_u32 s30, s45, s30
	s_addc_u32 s31, s51, s31
	s_and_b64 s[38:39], s[6:7], exec
	s_cselect_b32 s25, s31, s37
	s_cselect_b32 s82, s30, s36
	s_add_u32 s34, s34, 0x40080
	s_addc_u32 s35, s35, 0
	s_add_u32 s83, s36, 0x100
	v_mov_b32_e32 v0, 0
	s_addc_u32 s84, s37, 0
	s_mov_b32 s85, -2
	v_mov_b32_e32 v1, v0
	v_mov_b32_e32 v2, v0
	v_mov_b32_e32 v3, v0
	v_mov_b32_e32 v4, v0
	v_mov_b32_e32 v5, v0
	v_mov_b32_e32 v6, v0
	v_mov_b32_e32 v7, v0
	v_mov_b32_e32 v16, v0
	v_mov_b32_e32 v17, v0
	v_mov_b32_e32 v18, v0
	v_mov_b32_e32 v19, v0
	v_mov_b32_e32 v20, v0
	v_mov_b32_e32 v21, v0
	v_mov_b32_e32 v22, v0
	v_mov_b32_e32 v23, v0
	v_mov_b32_e32 v32, v0
	v_mov_b32_e32 v33, v0
	v_mov_b32_e32 v34, v0
	v_mov_b32_e32 v35, v0
	v_mov_b32_e32 v36, v0
	v_mov_b32_e32 v37, v0
	v_mov_b32_e32 v38, v0
	v_mov_b32_e32 v39, v0
	v_mov_b32_e32 v48, v0
	v_mov_b32_e32 v49, v0
	v_mov_b32_e32 v50, v0
	v_mov_b32_e32 v51, v0
	v_mov_b32_e32 v52, v0
	v_mov_b32_e32 v53, v0
	v_mov_b32_e32 v54, v0
	v_mov_b32_e32 v55, v0
	v_mov_b32_e32 v8, v0
	v_mov_b32_e32 v9, v0
	v_mov_b32_e32 v10, v0
	v_mov_b32_e32 v11, v0
	v_mov_b32_e32 v12, v0
	v_mov_b32_e32 v13, v0
	v_mov_b32_e32 v14, v0
	v_mov_b32_e32 v15, v0
	v_mov_b32_e32 v24, v0
	v_mov_b32_e32 v25, v0
	v_mov_b32_e32 v26, v0
	v_mov_b32_e32 v27, v0
	v_mov_b32_e32 v28, v0
	v_mov_b32_e32 v29, v0
	v_mov_b32_e32 v30, v0
	v_mov_b32_e32 v31, v0
	v_mov_b32_e32 v40, v0
	v_mov_b32_e32 v41, v0
	v_mov_b32_e32 v42, v0
	v_mov_b32_e32 v43, v0
	v_mov_b32_e32 v44, v0
	v_mov_b32_e32 v45, v0
	v_mov_b32_e32 v46, v0
	v_mov_b32_e32 v47, v0
	v_mov_b32_e32 v56, v0
	v_mov_b32_e32 v57, v0
	v_mov_b32_e32 v58, v0
	v_mov_b32_e32 v59, v0
	v_mov_b32_e32 v60, v0
	v_mov_b32_e32 v61, v0
	v_mov_b32_e32 v62, v0
	v_mov_b32_e32 v63, v0
	v_mov_b32_e32 v64, v0
	v_mov_b32_e32 v65, v0
	v_mov_b32_e32 v66, v0
	v_mov_b32_e32 v67, v0
	v_mov_b32_e32 v68, v0
	v_mov_b32_e32 v69, v0
	v_mov_b32_e32 v70, v0
	v_mov_b32_e32 v71, v0
	v_mov_b32_e32 v80, v0
	v_mov_b32_e32 v81, v0
	v_mov_b32_e32 v82, v0
	v_mov_b32_e32 v83, v0
	v_mov_b32_e32 v84, v0
	v_mov_b32_e32 v85, v0
	v_mov_b32_e32 v86, v0
	v_mov_b32_e32 v87, v0
	v_mov_b32_e32 v96, v0
	v_mov_b32_e32 v97, v0
	v_mov_b32_e32 v98, v0
	v_mov_b32_e32 v99, v0
	v_mov_b32_e32 v100, v0
	v_mov_b32_e32 v101, v0
	v_mov_b32_e32 v102, v0
	v_mov_b32_e32 v103, v0
	v_mov_b32_e32 v112, v0
	v_mov_b32_e32 v113, v0
	v_mov_b32_e32 v114, v0
	v_mov_b32_e32 v115, v0
	v_mov_b32_e32 v116, v0
	v_mov_b32_e32 v117, v0
	v_mov_b32_e32 v118, v0
	v_mov_b32_e32 v119, v0
	v_mov_b32_e32 v72, v0
	v_mov_b32_e32 v73, v0
	v_mov_b32_e32 v74, v0
	v_mov_b32_e32 v75, v0
	v_mov_b32_e32 v76, v0
	v_mov_b32_e32 v77, v0
	v_mov_b32_e32 v78, v0
	v_mov_b32_e32 v79, v0
	v_mov_b32_e32 v88, v0
	v_mov_b32_e32 v89, v0
	v_mov_b32_e32 v90, v0
	v_mov_b32_e32 v91, v0
	v_mov_b32_e32 v92, v0
	v_mov_b32_e32 v93, v0
	v_mov_b32_e32 v94, v0
	v_mov_b32_e32 v95, v0
	v_mov_b32_e32 v104, v0
	v_mov_b32_e32 v105, v0
	v_mov_b32_e32 v106, v0
	v_mov_b32_e32 v107, v0
	v_mov_b32_e32 v108, v0
	v_mov_b32_e32 v109, v0
	v_mov_b32_e32 v110, v0
	v_mov_b32_e32 v111, v0
	v_mov_b32_e32 v120, v0
	v_mov_b32_e32 v121, v0
	v_mov_b32_e32 v122, v0
	v_mov_b32_e32 v123, v0
	v_mov_b32_e32 v124, v0
	v_mov_b32_e32 v125, v0
	v_mov_b32_e32 v126, v0
	v_mov_b32_e32 v127, v0
	s_mov_b32 s99, 0
.LBB0_947:
	ds_read_b128 v[144:147], v153
	ds_read_b128 v[158:161], v153 offset:1024
	ds_read_b128 v[162:165], v153 offset:2048
	ds_read_b128 v[166:169], v153 offset:3072
	ds_read_b128 v[170:173], v154
	ds_read_b128 v[174:177], v154 offset:1024
	ds_read_b128 v[178:181], v154 offset:2048
	ds_read_b128 v[182:185], v154 offset:3072
	s_add_u32 s36, s34, 0xfffc0080
	s_addc_u32 s37, s35, -1
	s_cmp_eq_u32 s85, 12
	s_cselect_b32 s39, s27, s37
	s_cselect_b32 s38, s81, s36
	s_cselect_b32 s37, s25, s84
	s_cselect_b32 s36, s82, s83
	v_lshl_add_u64 v[148:149], s[34:35], 0, v[136:137]
	ds_read_b128 v[186:189], v155
	ds_read_b128 v[190:193], v155 offset:1024
	ds_read_b128 v[196:199], v155 offset:2048
	ds_read_b128 v[200:203], v155 offset:3072
	ds_read_b128 v[204:207], v155 offset:4096
	ds_read_b128 v[208:211], v155 offset:5120
	ds_read_b128 v[212:215], v155 offset:6144
	ds_read_b128 v[216:219], v155 offset:7168
	s_cmp_eq_u32 s99, 0
	s_cbranch_scc1 .Lkb_first_6
	v_lshl_add_u64 v[222:223], v[222:223], 0, s[20:21]
	s_mov_b32 m0, s70
	s_nop 0
	global_load_lds_dwordx4 v[222:223], off
	v_lshl_add_u64 v[224:225], v[224:225], 0, s[20:21]
	s_mov_b32 m0, s71
	s_nop 0
	global_load_lds_dwordx4 v[224:225], off
	s_branch .Lkb_join_6
.Lkb_first_6:
	s_add_i32 m0, s59, 0xc000
	s_nop 0
	global_load_lds_dwordx4 v[148:149], off
	global_load_lds_dwordx4 v[148:149], off
.Lkb_join_6:
	s_add_i32 m0, s59, 0xc000
	s_nop 0
	global_load_lds_dwordx4 v[148:149], off
	v_lshl_add_u64 v[148:149], s[34:35], 0, v[138:139]
	s_add_i32 m0, s59, 0xe000
	s_nop 0
	global_load_lds_dwordx4 v[148:149], off
	s_waitcnt vmcnt(8)
	s_waitcnt lgkmcnt(0)
	s_barrier
	s_setprio 1
	s_waitcnt lgkmcnt(0)
	v_mfma_f32_16x16x32_bf16 v[124:127], v[144:147], v[186:189], v[124:127]
	v_mfma_f32_16x16x32_bf16 v[120:123], v[162:165], v[186:189], v[120:123]
	v_mfma_f32_16x16x32_bf16 v[108:111], v[144:147], v[196:199], v[108:111]
	v_mfma_f32_16x16x32_bf16 v[104:107], v[162:165], v[196:199], v[104:107]
	v_mfma_f32_16x16x32_bf16 v[92:95], v[144:147], v[204:207], v[92:95]
	v_mfma_f32_16x16x32_bf16 v[88:91], v[162:165], v[204:207], v[88:91]
	v_mfma_f32_16x16x32_bf16 v[76:79], v[144:147], v[212:215], v[76:79]
	v_mfma_f32_16x16x32_bf16 v[72:75], v[162:165], v[212:215], v[72:75]
	v_mfma_f32_16x16x32_bf16 v[124:127], v[158:161], v[190:193], v[124:127]
	v_mfma_f32_16x16x32_bf16 v[120:123], v[166:169], v[190:193], v[120:123]
	v_mfma_f32_16x16x32_bf16 v[108:111], v[158:161], v[200:203], v[108:111]
	v_mfma_f32_16x16x32_bf16 v[104:107], v[166:169], v[200:203], v[104:107]
	v_mfma_f32_16x16x32_bf16 v[92:95], v[158:161], v[208:211], v[92:95]
	v_mfma_f32_16x16x32_bf16 v[88:91], v[166:169], v[208:211], v[88:91]
	v_mfma_f32_16x16x32_bf16 v[76:79], v[158:161], v[216:219], v[76:79]
	v_mfma_f32_16x16x32_bf16 v[72:75], v[166:169], v[216:219], v[72:75]
	s_setprio 0
	s_setprio 1
	v_mfma_f32_16x16x32_bf16 v[116:119], v[170:173], v[186:189], v[116:119]
	v_mfma_f32_16x16x32_bf16 v[112:115], v[178:181], v[186:189], v[112:115]
	v_mfma_f32_16x16x32_bf16 v[100:103], v[170:173], v[196:199], v[100:103]
	v_mfma_f32_16x16x32_bf16 v[96:99], v[178:181], v[196:199], v[96:99]
	v_mfma_f32_16x16x32_bf16 v[84:87], v[170:173], v[204:207], v[84:87]
	v_mfma_f32_16x16x32_bf16 v[80:83], v[178:181], v[204:207], v[80:83]
	v_mfma_f32_16x16x32_bf16 v[68:71], v[170:173], v[212:215], v[68:71]
	v_mfma_f32_16x16x32_bf16 v[64:67], v[178:181], v[212:215], v[64:67]
	v_mfma_f32_16x16x32_bf16 v[116:119], v[174:177], v[190:193], v[116:119]
	v_mfma_f32_16x16x32_bf16 v[112:115], v[182:185], v[190:193], v[112:115]
	v_mfma_f32_16x16x32_bf16 v[100:103], v[174:177], v[200:203], v[100:103]
	v_mfma_f32_16x16x32_bf16 v[96:99], v[182:185], v[200:203], v[96:99]
	v_mfma_f32_16x16x32_bf16 v[84:87], v[174:177], v[208:211], v[84:87]
	v_mfma_f32_16x16x32_bf16 v[80:83], v[182:185], v[208:211], v[80:83]
	v_mfma_f32_16x16x32_bf16 v[68:71], v[174:177], v[216:219], v[68:71]
	v_mfma_f32_16x16x32_bf16 v[64:67], v[182:185], v[216:219], v[64:67]
	s_setprio 0
	s_barrier
	s_add_i32 s86, s73, s58
	v_lshl_add_u64 v[148:149], s[36:37], 0, v[130:131]
	s_mov_b32 m0, s86
	ds_read_b128 v[186:189], v155 offset:16384
	ds_read_b128 v[190:193], v155 offset:17408
	ds_read_b128 v[196:199], v155 offset:18432
	ds_read_b128 v[200:203], v155 offset:19456
	ds_read_b128 v[204:207], v155 offset:20480
	ds_read_b128 v[208:211], v155 offset:21504
	ds_read_b128 v[212:215], v155 offset:22528
	ds_read_b128 v[216:219], v155 offset:23552
	global_load_lds_dwordx4 v[148:149], off
	s_add_i32 m0, s86, 0x2000
	s_add_u32 s86, s36, 0x40000
	v_lshl_add_u64 v[220:221], s[36:37], 0, v[134:135]
	s_addc_u32 s87, s37, 0
	s_add_i32 s88, s78, s58
	global_load_lds_dwordx4 v[220:221], off
	v_lshl_add_u64 v[222:223], s[86:87], 0, v[130:131]
	s_mov_b32 m0, s88
	v_lshl_add_u64 v[224:225], s[38:39], 0, v[132:133]
	global_load_lds_dwordx4 v[222:223], off
	v_lshl_add_u64 v[222:223], s[86:87], 0, v[134:135]
	s_add_i32 m0, s88, 0x2000
	s_nop 0
	global_load_lds_dwordx4 v[222:223], off
	v_lshl_add_u64 v[222:223], s[38:39], 0, v[128:129]
	s_waitcnt vmcnt(6)
	s_waitcnt lgkmcnt(0)
	s_barrier
	s_setprio 1
	s_waitcnt lgkmcnt(0)
	v_mfma_f32_16x16x32_bf16 v[60:63], v[144:147], v[186:189], v[60:63]
	v_mfma_f32_16x16x32_bf16 v[56:59], v[162:165], v[186:189], v[56:59]
	v_mfma_f32_16x16x32_bf16 v[44:47], v[144:147], v[196:199], v[44:47]
	v_mfma_f32_16x16x32_bf16 v[40:43], v[162:165], v[196:199], v[40:43]
	v_mfma_f32_16x16x32_bf16 v[28:31], v[144:147], v[204:207], v[28:31]
	v_mfma_f32_16x16x32_bf16 v[24:27], v[162:165], v[204:207], v[24:27]
	v_mfma_f32_16x16x32_bf16 v[12:15], v[144:147], v[212:215], v[12:15]
	v_mfma_f32_16x16x32_bf16 v[8:11], v[162:165], v[212:215], v[8:11]
	v_mfma_f32_16x16x32_bf16 v[60:63], v[158:161], v[190:193], v[60:63]
	v_mfma_f32_16x16x32_bf16 v[56:59], v[166:169], v[190:193], v[56:59]
	v_mfma_f32_16x16x32_bf16 v[44:47], v[158:161], v[200:203], v[44:47]
	v_mfma_f32_16x16x32_bf16 v[40:43], v[166:169], v[200:203], v[40:43]
	v_mfma_f32_16x16x32_bf16 v[28:31], v[158:161], v[208:211], v[28:31]
	v_mfma_f32_16x16x32_bf16 v[24:27], v[166:169], v[208:211], v[24:27]
	v_mfma_f32_16x16x32_bf16 v[12:15], v[158:161], v[216:219], v[12:15]
	v_mfma_f32_16x16x32_bf16 v[8:11], v[166:169], v[216:219], v[8:11]
	s_setprio 0
	s_setprio 1
	v_mfma_f32_16x16x32_bf16 v[52:55], v[170:173], v[186:189], v[52:55]
	v_mfma_f32_16x16x32_bf16 v[48:51], v[178:181], v[186:189], v[48:51]
	v_mfma_f32_16x16x32_bf16 v[36:39], v[170:173], v[196:199], v[36:39]
	v_mfma_f32_16x16x32_bf16 v[32:35], v[178:181], v[196:199], v[32:35]
	v_mfma_f32_16x16x32_bf16 v[20:23], v[170:173], v[204:207], v[20:23]
	v_mfma_f32_16x16x32_bf16 v[16:19], v[178:181], v[204:207], v[16:19]
	v_mfma_f32_16x16x32_bf16 v[4:7], v[170:173], v[212:215], v[4:7]
	v_mfma_f32_16x16x32_bf16 v[0:3], v[178:181], v[212:215], v[0:3]
	v_mfma_f32_16x16x32_bf16 v[52:55], v[174:177], v[190:193], v[52:55]
	v_mfma_f32_16x16x32_bf16 v[48:51], v[182:185], v[190:193], v[48:51]
	v_mfma_f32_16x16x32_bf16 v[36:39], v[174:177], v[200:203], v[36:39]
	v_mfma_f32_16x16x32_bf16 v[32:35], v[182:185], v[200:203], v[32:35]
	v_mfma_f32_16x16x32_bf16 v[20:23], v[174:177], v[208:211], v[20:23]
	v_mfma_f32_16x16x32_bf16 v[16:19], v[182:185], v[208:211], v[16:19]
	v_mfma_f32_16x16x32_bf16 v[4:7], v[174:177], v[216:219], v[4:7]
	v_mfma_f32_16x16x32_bf16 v[0:3], v[182:185], v[216:219], v[0:3]
	s_setprio 0
	s_barrier
	s_add_i32 s86, 0, 0x18000
	v_add_u32_e32 v157, s86, v151
	s_add_i32 s87, 0, 0x1c000
	ds_read_b128 v[144:147], v157
	ds_read_b128 v[158:161], v157 offset:1024
	ds_read_b128 v[162:165], v157 offset:2048
	ds_read_b128 v[166:169], v157 offset:3072
	v_add_u32_e32 v157, s87, v151
	ds_read_b128 v[170:173], v157
	ds_read_b128 v[174:177], v157 offset:1024
	ds_read_b128 v[178:181], v157 offset:2048
	ds_read_b128 v[182:185], v157 offset:3072
	s_add_u32 s38, s38, 0x40000
	s_addc_u32 s39, s39, 0
	v_lshl_add_u64 v[226:227], s[38:39], 0, v[128:129]
	ds_read_b128 v[186:189], v155 offset:32768
	ds_read_b128 v[190:193], v155 offset:33792
	ds_read_b128 v[196:199], v155 offset:34816
	ds_read_b128 v[200:203], v155 offset:35840
	ds_read_b128 v[204:207], v155 offset:36864
	ds_read_b128 v[208:211], v155 offset:37888
	ds_read_b128 v[212:215], v155 offset:38912
	ds_read_b128 v[216:219], v155 offset:39936
	s_mov_b32 m0, s59
	s_nop 0
	global_load_lds_dwordx4 v[222:223], off
	s_mov_b32 m0, s60
	s_nop 0
	global_load_lds_dwordx4 v[224:225], off
	s_mov_b32 m0, s61
	s_nop 0
	global_load_lds_dwordx4 v[226:227], off
	v_lshl_add_u64 v[226:227], s[38:39], 0, v[132:133]
	s_mov_b32 m0, s62
	s_nop 0
	global_load_lds_dwordx4 v[226:227], off
	s_waitcnt vmcnt(8)
	s_waitcnt lgkmcnt(0)
	s_barrier
	s_setprio 1
	s_waitcnt lgkmcnt(0)
	v_mfma_f32_16x16x32_bf16 v[124:127], v[144:147], v[186:189], v[124:127]
	v_mfma_f32_16x16x32_bf16 v[120:123], v[162:165], v[186:189], v[120:123]
	v_mfma_f32_16x16x32_bf16 v[108:111], v[144:147], v[196:199], v[108:111]
	v_mfma_f32_16x16x32_bf16 v[104:107], v[162:165], v[196:199], v[104:107]
	v_mfma_f32_16x16x32_bf16 v[92:95], v[144:147], v[204:207], v[92:95]
	v_mfma_f32_16x16x32_bf16 v[88:91], v[162:165], v[204:207], v[88:91]
	v_mfma_f32_16x16x32_bf16 v[76:79], v[144:147], v[212:215], v[76:79]
	v_mfma_f32_16x16x32_bf16 v[72:75], v[162:165], v[212:215], v[72:75]
	v_mfma_f32_16x16x32_bf16 v[124:127], v[158:161], v[190:193], v[124:127]
	v_mfma_f32_16x16x32_bf16 v[120:123], v[166:169], v[190:193], v[120:123]
	v_mfma_f32_16x16x32_bf16 v[108:111], v[158:161], v[200:203], v[108:111]
	v_mfma_f32_16x16x32_bf16 v[104:107], v[166:169], v[200:203], v[104:107]
	v_mfma_f32_16x16x32_bf16 v[92:95], v[158:161], v[208:211], v[92:95]
	v_mfma_f32_16x16x32_bf16 v[88:91], v[166:169], v[208:211], v[88:91]
	v_mfma_f32_16x16x32_bf16 v[76:79], v[158:161], v[216:219], v[76:79]
	v_mfma_f32_16x16x32_bf16 v[72:75], v[166:169], v[216:219], v[72:75]
	s_setprio 0
	s_setprio 1
	v_mfma_f32_16x16x32_bf16 v[116:119], v[170:173], v[186:189], v[116:119]
	v_mfma_f32_16x16x32_bf16 v[112:115], v[178:181], v[186:189], v[112:115]
	v_mfma_f32_16x16x32_bf16 v[100:103], v[170:173], v[196:199], v[100:103]
	v_mfma_f32_16x16x32_bf16 v[96:99], v[178:181], v[196:199], v[96:99]
	v_mfma_f32_16x16x32_bf16 v[84:87], v[170:173], v[204:207], v[84:87]
	v_mfma_f32_16x16x32_bf16 v[80:83], v[178:181], v[204:207], v[80:83]
	v_mfma_f32_16x16x32_bf16 v[68:71], v[170:173], v[212:215], v[68:71]
	v_mfma_f32_16x16x32_bf16 v[64:67], v[178:181], v[212:215], v[64:67]
	v_mfma_f32_16x16x32_bf16 v[116:119], v[174:177], v[190:193], v[116:119]
	v_mfma_f32_16x16x32_bf16 v[112:115], v[182:185], v[190:193], v[112:115]
	v_mfma_f32_16x16x32_bf16 v[100:103], v[174:177], v[200:203], v[100:103]
	v_mfma_f32_16x16x32_bf16 v[96:99], v[182:185], v[200:203], v[96:99]
	v_mfma_f32_16x16x32_bf16 v[84:87], v[174:177], v[208:211], v[84:87]
	v_mfma_f32_16x16x32_bf16 v[80:83], v[182:185], v[208:211], v[80:83]
	v_mfma_f32_16x16x32_bf16 v[68:71], v[174:177], v[216:219], v[68:71]
	v_mfma_f32_16x16x32_bf16 v[64:67], v[182:185], v[216:219], v[64:67]
	s_setprio 0
	s_barrier
	s_add_i32 s38, s86, s58
	v_lshl_add_u64 v[148:149], v[148:149], 0, s[20:21]
	s_mov_b32 m0, s38
	ds_read_b128 v[186:189], v155 offset:49152
	ds_read_b128 v[190:193], v155 offset:50176
	ds_read_b128 v[196:199], v155 offset:51200
	ds_read_b128 v[200:203], v155 offset:52224
	ds_read_b128 v[204:207], v155 offset:53248
	ds_read_b128 v[208:211], v155 offset:54272
	ds_read_b128 v[212:215], v155 offset:55296
	ds_read_b128 v[216:219], v155 offset:56320
	global_load_lds_dwordx4 v[148:149], off
	s_add_i32 m0, s38, 0x2000
	s_add_u32 s36, s36, 0x40080
	v_lshl_add_u64 v[148:149], v[220:221], 0, s[20:21]
	s_addc_u32 s37, s37, 0
	s_add_i32 s38, s87, s58
	global_load_lds_dwordx4 v[148:149], off
	v_lshl_add_u64 v[148:149], s[36:37], 0, v[130:131]
	s_mov_b32 m0, s38
	s_nop 0
	global_load_lds_dwordx4 v[148:149], off
	v_lshl_add_u64 v[148:149], s[36:37], 0, v[134:135]
	s_add_i32 m0, s38, 0x2000
	s_nop 0
	global_load_lds_dwordx4 v[148:149], off
	s_mov_b32 s99, 1
	s_waitcnt vmcnt(6)
	s_waitcnt lgkmcnt(0)
	s_barrier
	s_setprio 1
	s_waitcnt lgkmcnt(0)
	v_mfma_f32_16x16x32_bf16 v[60:63], v[144:147], v[186:189], v[60:63]
	v_mfma_f32_16x16x32_bf16 v[56:59], v[162:165], v[186:189], v[56:59]
	v_mfma_f32_16x16x32_bf16 v[44:47], v[144:147], v[196:199], v[44:47]
	v_mfma_f32_16x16x32_bf16 v[40:43], v[162:165], v[196:199], v[40:43]
	v_mfma_f32_16x16x32_bf16 v[28:31], v[144:147], v[204:207], v[28:31]
	v_mfma_f32_16x16x32_bf16 v[24:27], v[162:165], v[204:207], v[24:27]
	v_mfma_f32_16x16x32_bf16 v[12:15], v[144:147], v[212:215], v[12:15]
	v_mfma_f32_16x16x32_bf16 v[8:11], v[162:165], v[212:215], v[8:11]
	v_mfma_f32_16x16x32_bf16 v[60:63], v[158:161], v[190:193], v[60:63]
	v_mfma_f32_16x16x32_bf16 v[56:59], v[166:169], v[190:193], v[56:59]
	v_mfma_f32_16x16x32_bf16 v[44:47], v[158:161], v[200:203], v[44:47]
	v_mfma_f32_16x16x32_bf16 v[40:43], v[166:169], v[200:203], v[40:43]
	v_mfma_f32_16x16x32_bf16 v[28:31], v[158:161], v[208:211], v[28:31]
	v_mfma_f32_16x16x32_bf16 v[24:27], v[166:169], v[208:211], v[24:27]
	v_mfma_f32_16x16x32_bf16 v[12:15], v[158:161], v[216:219], v[12:15]
	v_mfma_f32_16x16x32_bf16 v[8:11], v[166:169], v[216:219], v[8:11]
	s_setprio 0
	s_setprio 1
	v_mfma_f32_16x16x32_bf16 v[52:55], v[170:173], v[186:189], v[52:55]
	v_mfma_f32_16x16x32_bf16 v[48:51], v[178:181], v[186:189], v[48:51]
	v_mfma_f32_16x16x32_bf16 v[36:39], v[170:173], v[196:199], v[36:39]
	v_mfma_f32_16x16x32_bf16 v[32:35], v[178:181], v[196:199], v[32:35]
	v_mfma_f32_16x16x32_bf16 v[20:23], v[170:173], v[204:207], v[20:23]
	v_mfma_f32_16x16x32_bf16 v[16:19], v[178:181], v[204:207], v[16:19]
	v_mfma_f32_16x16x32_bf16 v[4:7], v[170:173], v[212:215], v[4:7]
	v_mfma_f32_16x16x32_bf16 v[0:3], v[178:181], v[212:215], v[0:3]
	v_mfma_f32_16x16x32_bf16 v[52:55], v[174:177], v[190:193], v[52:55]
	v_mfma_f32_16x16x32_bf16 v[48:51], v[182:185], v[190:193], v[48:51]
	v_mfma_f32_16x16x32_bf16 v[36:39], v[174:177], v[200:203], v[36:39]
	v_mfma_f32_16x16x32_bf16 v[32:35], v[182:185], v[200:203], v[32:35]
	v_mfma_f32_16x16x32_bf16 v[20:23], v[174:177], v[208:211], v[20:23]
	v_mfma_f32_16x16x32_bf16 v[16:19], v[182:185], v[208:211], v[16:19]
	v_mfma_f32_16x16x32_bf16 v[4:7], v[174:177], v[216:219], v[4:7]
	v_mfma_f32_16x16x32_bf16 v[0:3], v[182:185], v[216:219], v[0:3]
	s_setprio 0
	s_barrier
	s_add_i32 s85, s85, 2
	s_add_u32 s34, s34, 0x100
	s_addc_u32 s35, s35, 0
	s_add_u32 s83, s83, 0x100
	s_addc_u32 s84, s84, 0
	s_cmp_gt_u32 s85, 13
	s_cbranch_scc0 .LBB0_947
	v_lshl_add_u64 v[222:223], v[222:223], 0, s[20:21]
	s_mov_b32 m0, s70
	s_nop 0
	global_load_lds_dwordx4 v[222:223], off
	v_lshl_add_u64 v[224:225], v[224:225], 0, s[20:21]
	s_mov_b32 m0, s71
	s_nop 0
	global_load_lds_dwordx4 v[224:225], off
	s_and_b64 vcc, exec, s[22:23]
	s_cbranch_vccz .LBB0_950
	s_barrier

.LBB0_1022:
	s_ashr_i32 s35, s34, 31
	s_lshl_b64 s[36:37], s[34:35], 18
	s_add_u32 s36, s0, s36
	s_addc_u32 s37, s1, s37
	s_and_b64 s[38:39], s[6:7], exec
	s_cselect_b32 s35, s37, s43
	s_cselect_b32 s83, s36, s42
	s_ashr_i32 s31, s30, 31
	s_lshl_b64 s[38:39], s[30:31], 18
	s_add_u32 s38, s60, s38
	s_addc_u32 s39, s61, s39
	s_and_b64 s[58:59], s[6:7], exec
	s_cselect_b32 s31, s39, s45
	s_cselect_b32 s84, s38, s44
	s_add_u32 s42, s42, 0x20080
	s_addc_u32 s43, s43, 0
	s_add_u32 s85, s44, 0x100
	v_mov_b32_e32 v0, 0
	s_addc_u32 s86, s45, 0
	s_mov_b32 s87, -2
	v_mov_b32_e32 v1, v0
	v_mov_b32_e32 v2, v0
	v_mov_b32_e32 v3, v0
	v_mov_b32_e32 v4, v0
	v_mov_b32_e32 v5, v0
	v_mov_b32_e32 v6, v0
	v_mov_b32_e32 v7, v0
	v_mov_b32_e32 v16, v0
	v_mov_b32_e32 v17, v0
	v_mov_b32_e32 v18, v0
	v_mov_b32_e32 v19, v0
	v_mov_b32_e32 v20, v0
	v_mov_b32_e32 v21, v0
	v_mov_b32_e32 v22, v0
	v_mov_b32_e32 v23, v0
	v_mov_b32_e32 v32, v0
	v_mov_b32_e32 v33, v0
	v_mov_b32_e32 v34, v0
	v_mov_b32_e32 v35, v0
	v_mov_b32_e32 v36, v0
	v_mov_b32_e32 v37, v0
	v_mov_b32_e32 v38, v0
	v_mov_b32_e32 v39, v0
	v_mov_b32_e32 v48, v0
	v_mov_b32_e32 v49, v0
	v_mov_b32_e32 v50, v0
	v_mov_b32_e32 v51, v0
	v_mov_b32_e32 v52, v0
	v_mov_b32_e32 v53, v0
	v_mov_b32_e32 v54, v0
	v_mov_b32_e32 v55, v0
	v_mov_b32_e32 v8, v0
	v_mov_b32_e32 v9, v0
	v_mov_b32_e32 v10, v0
	v_mov_b32_e32 v11, v0
	v_mov_b32_e32 v12, v0
	v_mov_b32_e32 v13, v0
	v_mov_b32_e32 v14, v0
	v_mov_b32_e32 v15, v0
	v_mov_b32_e32 v24, v0
	v_mov_b32_e32 v25, v0
	v_mov_b32_e32 v26, v0
	v_mov_b32_e32 v27, v0
	v_mov_b32_e32 v28, v0
	v_mov_b32_e32 v29, v0
	v_mov_b32_e32 v30, v0
	v_mov_b32_e32 v31, v0
	v_mov_b32_e32 v40, v0
	v_mov_b32_e32 v41, v0
	v_mov_b32_e32 v42, v0
	v_mov_b32_e32 v43, v0
	v_mov_b32_e32 v44, v0
	v_mov_b32_e32 v45, v0
	v_mov_b32_e32 v46, v0
	v_mov_b32_e32 v47, v0
	v_mov_b32_e32 v56, v0
	v_mov_b32_e32 v57, v0
	v_mov_b32_e32 v58, v0
	v_mov_b32_e32 v59, v0
	v_mov_b32_e32 v60, v0
	v_mov_b32_e32 v61, v0
	v_mov_b32_e32 v62, v0
	v_mov_b32_e32 v63, v0
	v_mov_b32_e32 v64, v0
	v_mov_b32_e32 v65, v0
	v_mov_b32_e32 v66, v0
	v_mov_b32_e32 v67, v0
	v_mov_b32_e32 v68, v0
	v_mov_b32_e32 v69, v0
	v_mov_b32_e32 v70, v0
	v_mov_b32_e32 v71, v0
	v_mov_b32_e32 v80, v0
	v_mov_b32_e32 v81, v0
	v_mov_b32_e32 v82, v0
	v_mov_b32_e32 v83, v0
	v_mov_b32_e32 v84, v0
	v_mov_b32_e32 v85, v0
	v_mov_b32_e32 v86, v0
	v_mov_b32_e32 v87, v0
	v_mov_b32_e32 v96, v0
	v_mov_b32_e32 v97, v0
	v_mov_b32_e32 v98, v0
	v_mov_b32_e32 v99, v0
	v_mov_b32_e32 v100, v0
	v_mov_b32_e32 v101, v0
	v_mov_b32_e32 v102, v0
	v_mov_b32_e32 v103, v0
	v_mov_b32_e32 v112, v0
	v_mov_b32_e32 v113, v0
	v_mov_b32_e32 v114, v0
	v_mov_b32_e32 v115, v0
	v_mov_b32_e32 v116, v0
	v_mov_b32_e32 v117, v0
	v_mov_b32_e32 v118, v0
	v_mov_b32_e32 v119, v0
	v_mov_b32_e32 v72, v0
	v_mov_b32_e32 v73, v0
	v_mov_b32_e32 v74, v0
	v_mov_b32_e32 v75, v0
	v_mov_b32_e32 v76, v0
	v_mov_b32_e32 v77, v0
	v_mov_b32_e32 v78, v0
	v_mov_b32_e32 v79, v0
	v_mov_b32_e32 v88, v0
	v_mov_b32_e32 v89, v0
	v_mov_b32_e32 v90, v0
	v_mov_b32_e32 v91, v0
	v_mov_b32_e32 v92, v0
	v_mov_b32_e32 v93, v0
	v_mov_b32_e32 v94, v0
	v_mov_b32_e32 v95, v0
	v_mov_b32_e32 v104, v0
	v_mov_b32_e32 v105, v0
	v_mov_b32_e32 v106, v0
	v_mov_b32_e32 v107, v0
	v_mov_b32_e32 v108, v0
	v_mov_b32_e32 v109, v0
	v_mov_b32_e32 v110, v0
	v_mov_b32_e32 v111, v0
	v_mov_b32_e32 v120, v0
	v_mov_b32_e32 v121, v0
	v_mov_b32_e32 v122, v0
	v_mov_b32_e32 v123, v0
	v_mov_b32_e32 v124, v0
	v_mov_b32_e32 v125, v0
	v_mov_b32_e32 v126, v0
	v_mov_b32_e32 v127, v0
	s_mov_b32 s99, 0
.LBB0_1023:
	ds_read_b128 v[144:147], v153
	ds_read_b128 v[156:159], v153 offset:1024
	ds_read_b128 v[160:163], v153 offset:2048
	ds_read_b128 v[164:167], v153 offset:3072
	ds_read_b128 v[168:171], v154
	ds_read_b128 v[172:175], v154 offset:1024
	ds_read_b128 v[176:179], v154 offset:2048
	ds_read_b128 v[180:183], v154 offset:3072
	s_add_u32 s44, s42, 0xfffe0080
	s_addc_u32 s45, s43, -1
	s_cmp_eq_u32 s87, 4
	s_cselect_b32 s59, s35, s45
	s_cselect_b32 s58, s83, s44
	s_cselect_b32 s45, s31, s86
	s_cselect_b32 s44, s84, s85
	v_lshl_add_u64 v[148:149], s[42:43], 0, v[136:137]
	ds_read_b128 v[184:187], v155
	ds_read_b128 v[188:191], v155 offset:1024
	ds_read_b128 v[196:199], v155 offset:2048
	ds_read_b128 v[200:203], v155 offset:3072
	ds_read_b128 v[204:207], v155 offset:4096
	ds_read_b128 v[208:211], v155 offset:5120
	ds_read_b128 v[212:215], v155 offset:6144
	ds_read_b128 v[216:219], v155 offset:7168
	s_cmp_eq_u32 s99, 0
	s_cbranch_scc1 .Lkb_first_7
	v_lshl_add_u64 v[220:221], v[220:221], 0, s[20:21]
	s_mov_b32 m0, s73
	s_nop 0
	global_load_lds_dwordx4 v[220:221], off
	v_lshl_add_u64 v[222:223], v[222:223], 0, s[20:21]
	s_mov_b32 m0, s78
	s_nop 0
	global_load_lds_dwordx4 v[222:223], off
	s_branch .Lkb_join_7
.Lkb_first_7:
	s_add_i32 m0, s41, 0xc000
	s_nop 0
	global_load_lds_dwordx4 v[148:149], off
	global_load_lds_dwordx4 v[148:149], off
.Lkb_join_7:
	s_add_i32 m0, s41, 0xc000
	s_nop 0
	global_load_lds_dwordx4 v[148:149], off
	v_lshl_add_u64 v[148:149], s[42:43], 0, v[138:139]
	s_add_i32 m0, s41, 0xe000
	s_nop 0
	global_load_lds_dwordx4 v[148:149], off
	s_waitcnt vmcnt(8)
	s_waitcnt lgkmcnt(0)
	s_barrier
	s_setprio 1
	s_waitcnt lgkmcnt(0)
	v_mfma_f32_16x16x32_bf16 v[124:127], v[144:147], v[184:187], v[124:127]
	v_mfma_f32_16x16x32_bf16 v[120:123], v[160:163], v[184:187], v[120:123]
	v_mfma_f32_16x16x32_bf16 v[108:111], v[144:147], v[196:199], v[108:111]
	v_mfma_f32_16x16x32_bf16 v[104:107], v[160:163], v[196:199], v[104:107]
	v_mfma_f32_16x16x32_bf16 v[92:95], v[144:147], v[204:207], v[92:95]
	v_mfma_f32_16x16x32_bf16 v[88:91], v[160:163], v[204:207], v[88:91]
	v_mfma_f32_16x16x32_bf16 v[76:79], v[144:147], v[212:215], v[76:79]
	v_mfma_f32_16x16x32_bf16 v[72:75], v[160:163], v[212:215], v[72:75]
	v_mfma_f32_16x16x32_bf16 v[124:127], v[156:159], v[188:191], v[124:127]
	v_mfma_f32_16x16x32_bf16 v[120:123], v[164:167], v[188:191], v[120:123]
	v_mfma_f32_16x16x32_bf16 v[108:111], v[156:159], v[200:203], v[108:111]
	v_mfma_f32_16x16x32_bf16 v[104:107], v[164:167], v[200:203], v[104:107]
	v_mfma_f32_16x16x32_bf16 v[92:95], v[156:159], v[208:211], v[92:95]
	v_mfma_f32_16x16x32_bf16 v[88:91], v[164:167], v[208:211], v[88:91]
	v_mfma_f32_16x16x32_bf16 v[76:79], v[156:159], v[216:219], v[76:79]
	v_mfma_f32_16x16x32_bf16 v[72:75], v[164:167], v[216:219], v[72:75]
	s_setprio 0
	s_setprio 1
	v_mfma_f32_16x16x32_bf16 v[116:119], v[168:171], v[184:187], v[116:119]
	v_mfma_f32_16x16x32_bf16 v[112:115], v[176:179], v[184:187], v[112:115]
	v_mfma_f32_16x16x32_bf16 v[100:103], v[168:171], v[196:199], v[100:103]
	v_mfma_f32_16x16x32_bf16 v[96:99], v[176:179], v[196:199], v[96:99]
	v_mfma_f32_16x16x32_bf16 v[84:87], v[168:171], v[204:207], v[84:87]
	v_mfma_f32_16x16x32_bf16 v[80:83], v[176:179], v[204:207], v[80:83]
	v_mfma_f32_16x16x32_bf16 v[68:71], v[168:171], v[212:215], v[68:71]
	v_mfma_f32_16x16x32_bf16 v[64:67], v[176:179], v[212:215], v[64:67]
	v_mfma_f32_16x16x32_bf16 v[116:119], v[172:175], v[188:191], v[116:119]
	v_mfma_f32_16x16x32_bf16 v[112:115], v[180:183], v[188:191], v[112:115]
	v_mfma_f32_16x16x32_bf16 v[100:103], v[172:175], v[200:203], v[100:103]
	v_mfma_f32_16x16x32_bf16 v[96:99], v[180:183], v[200:203], v[96:99]
	v_mfma_f32_16x16x32_bf16 v[84:87], v[172:175], v[208:211], v[84:87]
	v_mfma_f32_16x16x32_bf16 v[80:83], v[180:183], v[208:211], v[80:83]
	v_mfma_f32_16x16x32_bf16 v[68:71], v[172:175], v[216:219], v[68:71]
	v_mfma_f32_16x16x32_bf16 v[64:67], v[180:183], v[216:219], v[64:67]
	s_setprio 0
	s_barrier
	s_add_i32 s88, s80, s62
	v_lshl_add_u64 v[148:149], s[44:45], 0, v[130:131]
	s_mov_b32 m0, s88
	ds_read_b128 v[184:187], v155 offset:16384
	ds_read_b128 v[188:191], v155 offset:17408
	ds_read_b128 v[196:199], v155 offset:18432
	ds_read_b128 v[200:203], v155 offset:19456
	ds_read_b128 v[204:207], v155 offset:20480
	ds_read_b128 v[208:211], v155 offset:21504
	ds_read_b128 v[212:215], v155 offset:22528
	ds_read_b128 v[216:219], v155 offset:23552
	global_load_lds_dwordx4 v[148:149], off
	s_add_i32 m0, s88, 0x2000
	s_add_u32 s88, s44, 0x20000
	v_lshl_add_u64 v[192:193], s[44:45], 0, v[134:135]
	s_addc_u32 s89, s45, 0
	s_add_i32 s90, s81, s62
	global_load_lds_dwordx4 v[192:193], off
	v_lshl_add_u64 v[220:221], s[88:89], 0, v[130:131]
	s_mov_b32 m0, s90
	v_lshl_add_u64 v[222:223], s[58:59], 0, v[132:133]
	global_load_lds_dwordx4 v[220:221], off
	v_lshl_add_u64 v[220:221], s[88:89], 0, v[134:135]
	s_add_i32 m0, s90, 0x2000
	s_nop 0
	global_load_lds_dwordx4 v[220:221], off
	v_lshl_add_u64 v[220:221], s[58:59], 0, v[128:129]
	s_waitcnt vmcnt(6)
	s_waitcnt lgkmcnt(0)
	s_barrier
	s_setprio 1
	s_waitcnt lgkmcnt(0)
	v_mfma_f32_16x16x32_bf16 v[60:63], v[144:147], v[184:187], v[60:63]
	v_mfma_f32_16x16x32_bf16 v[56:59], v[160:163], v[184:187], v[56:59]
	v_mfma_f32_16x16x32_bf16 v[44:47], v[144:147], v[196:199], v[44:47]
	v_mfma_f32_16x16x32_bf16 v[40:43], v[160:163], v[196:199], v[40:43]
	v_mfma_f32_16x16x32_bf16 v[28:31], v[144:147], v[204:207], v[28:31]
	v_mfma_f32_16x16x32_bf16 v[24:27], v[160:163], v[204:207], v[24:27]
	v_mfma_f32_16x16x32_bf16 v[12:15], v[144:147], v[212:215], v[12:15]
	v_mfma_f32_16x16x32_bf16 v[8:11], v[160:163], v[212:215], v[8:11]
	v_mfma_f32_16x16x32_bf16 v[60:63], v[156:159], v[188:191], v[60:63]
	v_mfma_f32_16x16x32_bf16 v[56:59], v[164:167], v[188:191], v[56:59]
	v_mfma_f32_16x16x32_bf16 v[44:47], v[156:159], v[200:203], v[44:47]
	v_mfma_f32_16x16x32_bf16 v[40:43], v[164:167], v[200:203], v[40:43]
	v_mfma_f32_16x16x32_bf16 v[28:31], v[156:159], v[208:211], v[28:31]
	v_mfma_f32_16x16x32_bf16 v[24:27], v[164:167], v[208:211], v[24:27]
	v_mfma_f32_16x16x32_bf16 v[12:15], v[156:159], v[216:219], v[12:15]
	v_mfma_f32_16x16x32_bf16 v[8:11], v[164:167], v[216:219], v[8:11]
	s_setprio 0
	s_setprio 1
	v_mfma_f32_16x16x32_bf16 v[52:55], v[168:171], v[184:187], v[52:55]
	v_mfma_f32_16x16x32_bf16 v[48:51], v[176:179], v[184:187], v[48:51]
	v_mfma_f32_16x16x32_bf16 v[36:39], v[168:171], v[196:199], v[36:39]
	v_mfma_f32_16x16x32_bf16 v[32:35], v[176:179], v[196:199], v[32:35]
	v_mfma_f32_16x16x32_bf16 v[20:23], v[168:171], v[204:207], v[20:23]
	v_mfma_f32_16x16x32_bf16 v[16:19], v[176:179], v[204:207], v[16:19]
	v_mfma_f32_16x16x32_bf16 v[4:7], v[168:171], v[212:215], v[4:7]
	v_mfma_f32_16x16x32_bf16 v[0:3], v[176:179], v[212:215], v[0:3]
	v_mfma_f32_16x16x32_bf16 v[52:55], v[172:175], v[188:191], v[52:55]
	v_mfma_f32_16x16x32_bf16 v[48:51], v[180:183], v[188:191], v[48:51]
	v_mfma_f32_16x16x32_bf16 v[36:39], v[172:175], v[200:203], v[36:39]
	v_mfma_f32_16x16x32_bf16 v[32:35], v[180:183], v[200:203], v[32:35]
	v_mfma_f32_16x16x32_bf16 v[20:23], v[172:175], v[208:211], v[20:23]
	v_mfma_f32_16x16x32_bf16 v[16:19], v[180:183], v[208:211], v[16:19]
	v_mfma_f32_16x16x32_bf16 v[4:7], v[172:175], v[216:219], v[4:7]
	v_mfma_f32_16x16x32_bf16 v[0:3], v[180:183], v[216:219], v[0:3]
	s_setprio 0
	s_barrier
	s_add_i32 s88, 0, 0x18000
	s_add_i32 s89, 0, 0x1c000
	v_add_u32_e32 v164, s88, v151
	v_add_u32_e32 v180, s89, v151
	ds_read_b128 v[144:147], v164
	ds_read_b128 v[156:159], v164 offset:1024
	ds_read_b128 v[160:163], v164 offset:2048
	ds_read_b128 v[164:167], v164 offset:3072
	ds_read_b128 v[168:171], v180
	ds_read_b128 v[172:175], v180 offset:1024
	ds_read_b128 v[176:179], v180 offset:2048
	ds_read_b128 v[180:183], v180 offset:3072
	s_add_u32 s58, s58, 0x20000
	s_addc_u32 s59, s59, 0
	v_lshl_add_u64 v[224:225], s[58:59], 0, v[128:129]
	ds_read_b128 v[184:187], v155 offset:32768
	ds_read_b128 v[188:191], v155 offset:33792
	ds_read_b128 v[196:199], v155 offset:34816
	ds_read_b128 v[200:203], v155 offset:35840
	ds_read_b128 v[204:207], v155 offset:36864
	ds_read_b128 v[208:211], v155 offset:37888
	ds_read_b128 v[212:215], v155 offset:38912
	ds_read_b128 v[216:219], v155 offset:39936
	s_mov_b32 m0, s41
	s_nop 0
	global_load_lds_dwordx4 v[220:221], off
	s_mov_b32 m0, s63
	s_nop 0
	global_load_lds_dwordx4 v[222:223], off
	s_mov_b32 m0, s70
	s_nop 0
	global_load_lds_dwordx4 v[224:225], off
	v_lshl_add_u64 v[224:225], s[58:59], 0, v[132:133]
	s_mov_b32 m0, s71
	s_nop 0
	global_load_lds_dwordx4 v[224:225], off
	s_waitcnt vmcnt(8)
	s_waitcnt lgkmcnt(0)
	s_barrier
	s_setprio 1
	s_waitcnt lgkmcnt(0)
	v_mfma_f32_16x16x32_bf16 v[124:127], v[144:147], v[184:187], v[124:127]
	v_mfma_f32_16x16x32_bf16 v[120:123], v[160:163], v[184:187], v[120:123]
	v_mfma_f32_16x16x32_bf16 v[108:111], v[144:147], v[196:199], v[108:111]
	v_mfma_f32_16x16x32_bf16 v[104:107], v[160:163], v[196:199], v[104:107]
	v_mfma_f32_16x16x32_bf16 v[92:95], v[144:147], v[204:207], v[92:95]
	v_mfma_f32_16x16x32_bf16 v[88:91], v[160:163], v[204:207], v[88:91]
	v_mfma_f32_16x16x32_bf16 v[76:79], v[144:147], v[212:215], v[76:79]
	v_mfma_f32_16x16x32_bf16 v[72:75], v[160:163], v[212:215], v[72:75]
	v_mfma_f32_16x16x32_bf16 v[124:127], v[156:159], v[188:191], v[124:127]
	v_mfma_f32_16x16x32_bf16 v[120:123], v[164:167], v[188:191], v[120:123]
	v_mfma_f32_16x16x32_bf16 v[108:111], v[156:159], v[200:203], v[108:111]
	v_mfma_f32_16x16x32_bf16 v[104:107], v[164:167], v[200:203], v[104:107]
	v_mfma_f32_16x16x32_bf16 v[92:95], v[156:159], v[208:211], v[92:95]
	v_mfma_f32_16x16x32_bf16 v[88:91], v[164:167], v[208:211], v[88:91]
	v_mfma_f32_16x16x32_bf16 v[76:79], v[156:159], v[216:219], v[76:79]
	v_mfma_f32_16x16x32_bf16 v[72:75], v[164:167], v[216:219], v[72:75]
	s_setprio 0
	s_setprio 1
	v_mfma_f32_16x16x32_bf16 v[116:119], v[168:171], v[184:187], v[116:119]
	v_mfma_f32_16x16x32_bf16 v[112:115], v[176:179], v[184:187], v[112:115]
	v_mfma_f32_16x16x32_bf16 v[100:103], v[168:171], v[196:199], v[100:103]
	v_mfma_f32_16x16x32_bf16 v[96:99], v[176:179], v[196:199], v[96:99]
	v_mfma_f32_16x16x32_bf16 v[84:87], v[168:171], v[204:207], v[84:87]
	v_mfma_f32_16x16x32_bf16 v[80:83], v[176:179], v[204:207], v[80:83]
	v_mfma_f32_16x16x32_bf16 v[68:71], v[168:171], v[212:215], v[68:71]
	v_mfma_f32_16x16x32_bf16 v[64:67], v[176:179], v[212:215], v[64:67]
	v_mfma_f32_16x16x32_bf16 v[116:119], v[172:175], v[188:191], v[116:119]
	v_mfma_f32_16x16x32_bf16 v[112:115], v[180:183], v[188:191], v[112:115]
	v_mfma_f32_16x16x32_bf16 v[100:103], v[172:175], v[200:203], v[100:103]
	v_mfma_f32_16x16x32_bf16 v[96:99], v[180:183], v[200:203], v[96:99]
	v_mfma_f32_16x16x32_bf16 v[84:87], v[172:175], v[208:211], v[84:87]
	v_mfma_f32_16x16x32_bf16 v[80:83], v[180:183], v[208:211], v[80:83]
	v_mfma_f32_16x16x32_bf16 v[68:71], v[172:175], v[216:219], v[68:71]
	v_mfma_f32_16x16x32_bf16 v[64:67], v[180:183], v[216:219], v[64:67]
	s_setprio 0
	s_barrier
	s_add_i32 s58, s88, s62
	v_lshl_add_u64 v[148:149], v[148:149], 0, s[20:21]
	s_mov_b32 m0, s58
	ds_read_b128 v[184:187], v155 offset:49152
	ds_read_b128 v[188:191], v155 offset:50176
	ds_read_b128 v[196:199], v155 offset:51200
	ds_read_b128 v[200:203], v155 offset:52224
	ds_read_b128 v[204:207], v155 offset:53248
	ds_read_b128 v[208:211], v155 offset:54272
	ds_read_b128 v[212:215], v155 offset:55296
	ds_read_b128 v[216:219], v155 offset:56320
	global_load_lds_dwordx4 v[148:149], off
	s_add_i32 m0, s58, 0x2000
	s_add_u32 s44, s44, 0x20080
	v_lshl_add_u64 v[148:149], v[192:193], 0, s[20:21]
	s_addc_u32 s45, s45, 0
	s_add_i32 s58, s89, s62
	global_load_lds_dwordx4 v[148:149], off
	v_lshl_add_u64 v[148:149], s[44:45], 0, v[130:131]
	s_mov_b32 m0, s58
	s_nop 0
	global_load_lds_dwordx4 v[148:149], off
	v_lshl_add_u64 v[148:149], s[44:45], 0, v[134:135]
	s_add_i32 m0, s58, 0x2000
	s_nop 0
	global_load_lds_dwordx4 v[148:149], off
	s_mov_b32 s99, 1
	s_waitcnt vmcnt(6)
	s_waitcnt lgkmcnt(0)
	s_barrier
	s_setprio 1
	s_waitcnt lgkmcnt(0)
	v_mfma_f32_16x16x32_bf16 v[60:63], v[144:147], v[184:187], v[60:63]
	v_mfma_f32_16x16x32_bf16 v[56:59], v[160:163], v[184:187], v[56:59]
	v_mfma_f32_16x16x32_bf16 v[44:47], v[144:147], v[196:199], v[44:47]
	v_mfma_f32_16x16x32_bf16 v[40:43], v[160:163], v[196:199], v[40:43]
	v_mfma_f32_16x16x32_bf16 v[28:31], v[144:147], v[204:207], v[28:31]
	v_mfma_f32_16x16x32_bf16 v[24:27], v[160:163], v[204:207], v[24:27]
	v_mfma_f32_16x16x32_bf16 v[12:15], v[144:147], v[212:215], v[12:15]
	v_mfma_f32_16x16x32_bf16 v[8:11], v[160:163], v[212:215], v[8:11]
	v_mfma_f32_16x16x32_bf16 v[60:63], v[156:159], v[188:191], v[60:63]
	v_mfma_f32_16x16x32_bf16 v[56:59], v[164:167], v[188:191], v[56:59]
	v_mfma_f32_16x16x32_bf16 v[44:47], v[156:159], v[200:203], v[44:47]
	v_mfma_f32_16x16x32_bf16 v[40:43], v[164:167], v[200:203], v[40:43]
	v_mfma_f32_16x16x32_bf16 v[28:31], v[156:159], v[208:211], v[28:31]
	v_mfma_f32_16x16x32_bf16 v[24:27], v[164:167], v[208:211], v[24:27]
	v_mfma_f32_16x16x32_bf16 v[12:15], v[156:159], v[216:219], v[12:15]
	v_mfma_f32_16x16x32_bf16 v[8:11], v[164:167], v[216:219], v[8:11]
	s_setprio 0
	s_setprio 1
	v_mfma_f32_16x16x32_bf16 v[52:55], v[168:171], v[184:187], v[52:55]
	v_mfma_f32_16x16x32_bf16 v[48:51], v[176:179], v[184:187], v[48:51]
	v_mfma_f32_16x16x32_bf16 v[36:39], v[168:171], v[196:199], v[36:39]
	v_mfma_f32_16x16x32_bf16 v[32:35], v[176:179], v[196:199], v[32:35]
	v_mfma_f32_16x16x32_bf16 v[20:23], v[168:171], v[204:207], v[20:23]
	v_mfma_f32_16x16x32_bf16 v[16:19], v[176:179], v[204:207], v[16:19]
	v_mfma_f32_16x16x32_bf16 v[4:7], v[168:171], v[212:215], v[4:7]
	v_mfma_f32_16x16x32_bf16 v[0:3], v[176:179], v[212:215], v[0:3]
	v_mfma_f32_16x16x32_bf16 v[52:55], v[172:175], v[188:191], v[52:55]
	v_mfma_f32_16x16x32_bf16 v[48:51], v[180:183], v[188:191], v[48:51]
	v_mfma_f32_16x16x32_bf16 v[36:39], v[172:175], v[200:203], v[36:39]
	v_mfma_f32_16x16x32_bf16 v[32:35], v[180:183], v[200:203], v[32:35]
	v_mfma_f32_16x16x32_bf16 v[20:23], v[172:175], v[208:211], v[20:23]
	v_mfma_f32_16x16x32_bf16 v[16:19], v[180:183], v[208:211], v[16:19]
	v_mfma_f32_16x16x32_bf16 v[4:7], v[172:175], v[216:219], v[4:7]
	v_mfma_f32_16x16x32_bf16 v[0:3], v[180:183], v[216:219], v[0:3]
	s_setprio 0
	s_barrier
	s_add_i32 s87, s87, 2
	s_add_u32 s42, s42, 0x100
	s_addc_u32 s43, s43, 0
	s_add_u32 s85, s85, 0x100
	s_addc_u32 s86, s86, 0
	s_cmp_gt_u32 s87, 5
	s_cbranch_scc0 .LBB0_1023
	v_lshl_add_u64 v[220:221], v[220:221], 0, s[20:21]
	s_mov_b32 m0, s73
	s_nop 0
	global_load_lds_dwordx4 v[220:221], off
	v_lshl_add_u64 v[222:223], v[222:223], 0, s[20:21]
	s_mov_b32 m0, s78
	s_nop 0
	global_load_lds_dwordx4 v[222:223], off
	s_and_b64 vcc, exec, s[22:23]
	s_cbranch_vccz .LBB0_1026
	s_barrier

.LBB0_1420:
	s_ashr_i32 s29, s28, 31
	s_lshl_b64 s[34:35], s[28:29], 19
	s_add_u32 s34, s44, s34
	s_addc_u32 s35, s45, s35
	s_and_b64 s[0:1], s[0:1], exec
	s_cselect_b32 s25, s35, s43
	s_cselect_b32 s27, s34, s42
	s_add_u32 s0, s42, 0x40080
	s_addc_u32 s1, s43, 0
	s_add_u32 s29, s40, 0x100
	v_mov_b32_e32 v0, 0
	s_addc_u32 s82, s41, 0
	s_mov_b32 s83, -2
	v_mov_b32_e32 v1, v0
	v_mov_b32_e32 v2, v0
	v_mov_b32_e32 v3, v0
	v_mov_b32_e32 v4, v0
	v_mov_b32_e32 v5, v0
	v_mov_b32_e32 v6, v0
	v_mov_b32_e32 v7, v0
	v_mov_b32_e32 v16, v0
	v_mov_b32_e32 v17, v0
	v_mov_b32_e32 v18, v0
	v_mov_b32_e32 v19, v0
	v_mov_b32_e32 v20, v0
	v_mov_b32_e32 v21, v0
	v_mov_b32_e32 v22, v0
	v_mov_b32_e32 v23, v0
	v_mov_b32_e32 v32, v0
	v_mov_b32_e32 v33, v0
	v_mov_b32_e32 v34, v0
	v_mov_b32_e32 v35, v0
	v_mov_b32_e32 v36, v0
	v_mov_b32_e32 v37, v0
	v_mov_b32_e32 v38, v0
	v_mov_b32_e32 v39, v0
	v_mov_b32_e32 v48, v0
	v_mov_b32_e32 v49, v0
	v_mov_b32_e32 v50, v0
	v_mov_b32_e32 v51, v0
	v_mov_b32_e32 v52, v0
	v_mov_b32_e32 v53, v0
	v_mov_b32_e32 v54, v0
	v_mov_b32_e32 v55, v0
	v_mov_b32_e32 v8, v0
	v_mov_b32_e32 v9, v0
	v_mov_b32_e32 v10, v0
	v_mov_b32_e32 v11, v0
	v_mov_b32_e32 v12, v0
	v_mov_b32_e32 v13, v0
	v_mov_b32_e32 v14, v0
	v_mov_b32_e32 v15, v0
	v_mov_b32_e32 v24, v0
	v_mov_b32_e32 v25, v0
	v_mov_b32_e32 v26, v0
	v_mov_b32_e32 v27, v0
	v_mov_b32_e32 v28, v0
	v_mov_b32_e32 v29, v0
	v_mov_b32_e32 v30, v0
	v_mov_b32_e32 v31, v0
	v_mov_b32_e32 v40, v0
	v_mov_b32_e32 v41, v0
	v_mov_b32_e32 v42, v0
	v_mov_b32_e32 v43, v0
	v_mov_b32_e32 v44, v0
	v_mov_b32_e32 v45, v0
	v_mov_b32_e32 v46, v0
	v_mov_b32_e32 v47, v0
	v_mov_b32_e32 v56, v0
	v_mov_b32_e32 v57, v0
	v_mov_b32_e32 v58, v0
	v_mov_b32_e32 v59, v0
	v_mov_b32_e32 v60, v0
	v_mov_b32_e32 v61, v0
	v_mov_b32_e32 v62, v0
	v_mov_b32_e32 v63, v0
	v_mov_b32_e32 v64, v0
	v_mov_b32_e32 v65, v0
	v_mov_b32_e32 v66, v0
	v_mov_b32_e32 v67, v0
	v_mov_b32_e32 v68, v0
	v_mov_b32_e32 v69, v0
	v_mov_b32_e32 v70, v0
	v_mov_b32_e32 v71, v0
	v_mov_b32_e32 v80, v0
	v_mov_b32_e32 v81, v0
	v_mov_b32_e32 v82, v0
	v_mov_b32_e32 v83, v0
	v_mov_b32_e32 v84, v0
	v_mov_b32_e32 v85, v0
	v_mov_b32_e32 v86, v0
	v_mov_b32_e32 v87, v0
	v_mov_b32_e32 v96, v0
	v_mov_b32_e32 v97, v0
	v_mov_b32_e32 v98, v0
	v_mov_b32_e32 v99, v0
	v_mov_b32_e32 v100, v0
	v_mov_b32_e32 v101, v0
	v_mov_b32_e32 v102, v0
	v_mov_b32_e32 v103, v0
	v_mov_b32_e32 v112, v0
	v_mov_b32_e32 v113, v0
	v_mov_b32_e32 v114, v0
	v_mov_b32_e32 v115, v0
	v_mov_b32_e32 v116, v0
	v_mov_b32_e32 v117, v0
	v_mov_b32_e32 v118, v0
	v_mov_b32_e32 v119, v0
	v_mov_b32_e32 v72, v0
	v_mov_b32_e32 v73, v0
	v_mov_b32_e32 v74, v0
	v_mov_b32_e32 v75, v0
	v_mov_b32_e32 v76, v0
	v_mov_b32_e32 v77, v0
	v_mov_b32_e32 v78, v0
	v_mov_b32_e32 v79, v0
	v_mov_b32_e32 v88, v0
	v_mov_b32_e32 v89, v0
	v_mov_b32_e32 v90, v0
	v_mov_b32_e32 v91, v0
	v_mov_b32_e32 v92, v0
	v_mov_b32_e32 v93, v0
	v_mov_b32_e32 v94, v0
	v_mov_b32_e32 v95, v0
	v_mov_b32_e32 v104, v0
	v_mov_b32_e32 v105, v0
	v_mov_b32_e32 v106, v0
	v_mov_b32_e32 v107, v0
	v_mov_b32_e32 v108, v0
	v_mov_b32_e32 v109, v0
	v_mov_b32_e32 v110, v0
	v_mov_b32_e32 v111, v0
	v_mov_b32_e32 v120, v0
	v_mov_b32_e32 v121, v0
	v_mov_b32_e32 v122, v0
	v_mov_b32_e32 v123, v0
	v_mov_b32_e32 v124, v0
	v_mov_b32_e32 v125, v0
	v_mov_b32_e32 v126, v0
	v_mov_b32_e32 v127, v0
	s_mov_b32 s99, 0
.LBB0_1421:
	ds_read_b128 v[146:149], v155
	ds_read_b128 v[160:163], v155 offset:1024
	ds_read_b128 v[164:167], v155 offset:2048
	ds_read_b128 v[168:171], v155 offset:3072
	ds_read_b128 v[172:175], v156
	ds_read_b128 v[176:179], v156 offset:1024
	ds_read_b128 v[180:183], v156 offset:2048
	ds_read_b128 v[184:187], v156 offset:3072
	s_add_u32 s40, s0, 0xfffc0080
	s_addc_u32 s41, s1, -1
	s_cmp_eq_u32 s83, 12
	s_cselect_b32 s43, s25, s41
	s_cselect_b32 s42, s27, s40
	s_cselect_b32 s41, s31, s82
	s_cselect_b32 s40, s30, s29
	v_lshl_add_u64 v[150:151], s[0:1], 0, v[138:139]
	ds_read_b128 v[188:191], v157
	ds_read_b128 v[196:199], v157 offset:1024
	ds_read_b128 v[200:203], v157 offset:2048
	ds_read_b128 v[204:207], v157 offset:3072
	ds_read_b128 v[208:211], v157 offset:4096
	ds_read_b128 v[212:215], v157 offset:5120
	ds_read_b128 v[216:219], v157 offset:6144
	ds_read_b128 v[220:223], v157 offset:7168
	s_cmp_eq_u32 s99, 0
	s_cbranch_scc1 .Lkb_first_9
	v_lshl_add_u64 v[224:225], v[224:225], 0, s[20:21]
	s_mov_b32 m0, s70
	s_nop 0
	global_load_lds_dwordx4 v[224:225], off
	v_lshl_add_u64 v[226:227], v[226:227], 0, s[20:21]
	s_mov_b32 m0, s71
	s_nop 0
	global_load_lds_dwordx4 v[226:227], off
	s_branch .Lkb_join_9
.Lkb_first_9:
	s_add_i32 m0, s39, 0xc000
	s_nop 0
	global_load_lds_dwordx4 v[150:151], off
	global_load_lds_dwordx4 v[150:151], off
.Lkb_join_9:
	s_add_i32 m0, s39, 0xc000
	s_nop 0
	global_load_lds_dwordx4 v[150:151], off
	v_lshl_add_u64 v[150:151], s[0:1], 0, v[140:141]
	s_add_i32 m0, s39, 0xe000
	s_nop 0
	global_load_lds_dwordx4 v[150:151], off
	s_waitcnt vmcnt(8)
	s_waitcnt lgkmcnt(0)
	s_barrier
	s_setprio 1
	s_waitcnt lgkmcnt(0)
	v_mfma_f32_16x16x32_bf16 v[124:127], v[146:149], v[188:191], v[124:127]
	v_mfma_f32_16x16x32_bf16 v[120:123], v[164:167], v[188:191], v[120:123]
	v_mfma_f32_16x16x32_bf16 v[108:111], v[146:149], v[200:203], v[108:111]
	v_mfma_f32_16x16x32_bf16 v[104:107], v[164:167], v[200:203], v[104:107]
	v_mfma_f32_16x16x32_bf16 v[92:95], v[146:149], v[208:211], v[92:95]
	v_mfma_f32_16x16x32_bf16 v[88:91], v[164:167], v[208:211], v[88:91]
	v_mfma_f32_16x16x32_bf16 v[76:79], v[146:149], v[216:219], v[76:79]
	v_mfma_f32_16x16x32_bf16 v[72:75], v[164:167], v[216:219], v[72:75]
	v_mfma_f32_16x16x32_bf16 v[124:127], v[160:163], v[196:199], v[124:127]
	v_mfma_f32_16x16x32_bf16 v[120:123], v[168:171], v[196:199], v[120:123]
	v_mfma_f32_16x16x32_bf16 v[108:111], v[160:163], v[204:207], v[108:111]
	v_mfma_f32_16x16x32_bf16 v[104:107], v[168:171], v[204:207], v[104:107]
	v_mfma_f32_16x16x32_bf16 v[92:95], v[160:163], v[212:215], v[92:95]
	v_mfma_f32_16x16x32_bf16 v[88:91], v[168:171], v[212:215], v[88:91]
	v_mfma_f32_16x16x32_bf16 v[76:79], v[160:163], v[220:223], v[76:79]
	v_mfma_f32_16x16x32_bf16 v[72:75], v[168:171], v[220:223], v[72:75]
	s_setprio 0
	s_setprio 1
	v_mfma_f32_16x16x32_bf16 v[116:119], v[172:175], v[188:191], v[116:119]
	v_mfma_f32_16x16x32_bf16 v[112:115], v[180:183], v[188:191], v[112:115]
	v_mfma_f32_16x16x32_bf16 v[100:103], v[172:175], v[200:203], v[100:103]
	v_mfma_f32_16x16x32_bf16 v[96:99], v[180:183], v[200:203], v[96:99]
	v_mfma_f32_16x16x32_bf16 v[84:87], v[172:175], v[208:211], v[84:87]
	v_mfma_f32_16x16x32_bf16 v[80:83], v[180:183], v[208:211], v[80:83]
	v_mfma_f32_16x16x32_bf16 v[68:71], v[172:175], v[216:219], v[68:71]
	v_mfma_f32_16x16x32_bf16 v[64:67], v[180:183], v[216:219], v[64:67]
	v_mfma_f32_16x16x32_bf16 v[116:119], v[176:179], v[196:199], v[116:119]
	v_mfma_f32_16x16x32_bf16 v[112:115], v[184:187], v[196:199], v[112:115]
	v_mfma_f32_16x16x32_bf16 v[100:103], v[176:179], v[204:207], v[100:103]
	v_mfma_f32_16x16x32_bf16 v[96:99], v[184:187], v[204:207], v[96:99]
	v_mfma_f32_16x16x32_bf16 v[84:87], v[176:179], v[212:215], v[84:87]
	v_mfma_f32_16x16x32_bf16 v[80:83], v[184:187], v[212:215], v[80:83]
	v_mfma_f32_16x16x32_bf16 v[68:71], v[176:179], v[220:223], v[68:71]
	v_mfma_f32_16x16x32_bf16 v[64:67], v[184:187], v[220:223], v[64:67]
	s_setprio 0
	s_barrier
	s_add_i32 s84, s78, s60
	v_lshl_add_u64 v[150:151], s[40:41], 0, v[132:133]
	s_mov_b32 m0, s84
	ds_read_b128 v[188:191], v157 offset:16384
	ds_read_b128 v[196:199], v157 offset:17408
	ds_read_b128 v[200:203], v157 offset:18432
	ds_read_b128 v[204:207], v157 offset:19456
	ds_read_b128 v[208:211], v157 offset:20480
	ds_read_b128 v[212:215], v157 offset:21504
	ds_read_b128 v[216:219], v157 offset:22528
	ds_read_b128 v[220:223], v157 offset:23552
	global_load_lds_dwordx4 v[150:151], off
	s_add_i32 m0, s84, 0x2000
	s_add_u32 s84, s40, 0x40000
	v_lshl_add_u64 v[192:193], s[40:41], 0, v[136:137]
	s_addc_u32 s85, s41, 0
	s_add_i32 s86, s79, s60
	global_load_lds_dwordx4 v[192:193], off
	v_lshl_add_u64 v[224:225], s[84:85], 0, v[132:133]
	s_mov_b32 m0, s86
	v_lshl_add_u64 v[226:227], s[42:43], 0, v[134:135]
	global_load_lds_dwordx4 v[224:225], off
	v_lshl_add_u64 v[224:225], s[84:85], 0, v[136:137]
	s_add_i32 m0, s86, 0x2000
	s_nop 0
	global_load_lds_dwordx4 v[224:225], off
	v_lshl_add_u64 v[224:225], s[42:43], 0, v[130:131]
	s_waitcnt vmcnt(6)
	s_waitcnt lgkmcnt(0)
	s_barrier
	s_setprio 1
	s_waitcnt lgkmcnt(0)
	v_mfma_f32_16x16x32_bf16 v[60:63], v[146:149], v[188:191], v[60:63]
	v_mfma_f32_16x16x32_bf16 v[56:59], v[164:167], v[188:191], v[56:59]
	v_mfma_f32_16x16x32_bf16 v[44:47], v[146:149], v[200:203], v[44:47]
	v_mfma_f32_16x16x32_bf16 v[40:43], v[164:167], v[200:203], v[40:43]
	v_mfma_f32_16x16x32_bf16 v[28:31], v[146:149], v[208:211], v[28:31]
	v_mfma_f32_16x16x32_bf16 v[24:27], v[164:167], v[208:211], v[24:27]
	v_mfma_f32_16x16x32_bf16 v[12:15], v[146:149], v[216:219], v[12:15]
	v_mfma_f32_16x16x32_bf16 v[8:11], v[164:167], v[216:219], v[8:11]
	v_mfma_f32_16x16x32_bf16 v[60:63], v[160:163], v[196:199], v[60:63]
	v_mfma_f32_16x16x32_bf16 v[56:59], v[168:171], v[196:199], v[56:59]
	v_mfma_f32_16x16x32_bf16 v[44:47], v[160:163], v[204:207], v[44:47]
	v_mfma_f32_16x16x32_bf16 v[40:43], v[168:171], v[204:207], v[40:43]
	v_mfma_f32_16x16x32_bf16 v[28:31], v[160:163], v[212:215], v[28:31]
	v_mfma_f32_16x16x32_bf16 v[24:27], v[168:171], v[212:215], v[24:27]
	v_mfma_f32_16x16x32_bf16 v[12:15], v[160:163], v[220:223], v[12:15]
	v_mfma_f32_16x16x32_bf16 v[8:11], v[168:171], v[220:223], v[8:11]
	s_setprio 0
	s_setprio 1
	v_mfma_f32_16x16x32_bf16 v[52:55], v[172:175], v[188:191], v[52:55]
	v_mfma_f32_16x16x32_bf16 v[48:51], v[180:183], v[188:191], v[48:51]
	v_mfma_f32_16x16x32_bf16 v[36:39], v[172:175], v[200:203], v[36:39]
	v_mfma_f32_16x16x32_bf16 v[32:35], v[180:183], v[200:203], v[32:35]
	v_mfma_f32_16x16x32_bf16 v[20:23], v[172:175], v[208:211], v[20:23]
	v_mfma_f32_16x16x32_bf16 v[16:19], v[180:183], v[208:211], v[16:19]
	v_mfma_f32_16x16x32_bf16 v[4:7], v[172:175], v[216:219], v[4:7]
	v_mfma_f32_16x16x32_bf16 v[0:3], v[180:183], v[216:219], v[0:3]
	v_mfma_f32_16x16x32_bf16 v[52:55], v[176:179], v[196:199], v[52:55]
	v_mfma_f32_16x16x32_bf16 v[48:51], v[184:187], v[196:199], v[48:51]
	v_mfma_f32_16x16x32_bf16 v[36:39], v[176:179], v[204:207], v[36:39]
	v_mfma_f32_16x16x32_bf16 v[32:35], v[184:187], v[204:207], v[32:35]
	v_mfma_f32_16x16x32_bf16 v[20:23], v[176:179], v[212:215], v[20:23]
	v_mfma_f32_16x16x32_bf16 v[16:19], v[184:187], v[212:215], v[16:19]
	v_mfma_f32_16x16x32_bf16 v[4:7], v[176:179], v[220:223], v[4:7]
	v_mfma_f32_16x16x32_bf16 v[0:3], v[184:187], v[220:223], v[0:3]
	s_setprio 0
	s_barrier
	s_add_i32 s84, 0, 0x18000
	v_add_u32_e32 v159, s84, v153
	s_add_i32 s85, 0, 0x1c000
	ds_read_b128 v[146:149], v159
	ds_read_b128 v[160:163], v159 offset:1024
	ds_read_b128 v[164:167], v159 offset:2048
	ds_read_b128 v[168:171], v159 offset:3072
	v_add_u32_e32 v159, s85, v153
	ds_read_b128 v[172:175], v159
	ds_read_b128 v[176:179], v159 offset:1024
	ds_read_b128 v[180:183], v159 offset:2048
	ds_read_b128 v[184:187], v159 offset:3072
	s_add_u32 s42, s42, 0x40000
	s_addc_u32 s43, s43, 0
	v_lshl_add_u64 v[228:229], s[42:43], 0, v[130:131]
	ds_read_b128 v[188:191], v157 offset:32768
	ds_read_b128 v[196:199], v157 offset:33792
	ds_read_b128 v[200:203], v157 offset:34816
	ds_read_b128 v[204:207], v157 offset:35840
	ds_read_b128 v[208:211], v157 offset:36864
	ds_read_b128 v[212:215], v157 offset:37888
	ds_read_b128 v[216:219], v157 offset:38912
	ds_read_b128 v[220:223], v157 offset:39936
	s_mov_b32 m0, s39
	s_nop 0
	global_load_lds_dwordx4 v[224:225], off
	s_mov_b32 m0, s61
	s_nop 0
	global_load_lds_dwordx4 v[226:227], off
	s_mov_b32 m0, s62
	s_nop 0
	global_load_lds_dwordx4 v[228:229], off
	v_lshl_add_u64 v[228:229], s[42:43], 0, v[134:135]
	s_mov_b32 m0, s63
	s_nop 0
	global_load_lds_dwordx4 v[228:229], off
	s_waitcnt vmcnt(8)
	s_waitcnt lgkmcnt(0)
	s_barrier
	s_setprio 1
	s_waitcnt lgkmcnt(0)
	v_mfma_f32_16x16x32_bf16 v[124:127], v[146:149], v[188:191], v[124:127]
	v_mfma_f32_16x16x32_bf16 v[120:123], v[164:167], v[188:191], v[120:123]
	v_mfma_f32_16x16x32_bf16 v[108:111], v[146:149], v[200:203], v[108:111]
	v_mfma_f32_16x16x32_bf16 v[104:107], v[164:167], v[200:203], v[104:107]
	v_mfma_f32_16x16x32_bf16 v[92:95], v[146:149], v[208:211], v[92:95]
	v_mfma_f32_16x16x32_bf16 v[88:91], v[164:167], v[208:211], v[88:91]
	v_mfma_f32_16x16x32_bf16 v[76:79], v[146:149], v[216:219], v[76:79]
	v_mfma_f32_16x16x32_bf16 v[72:75], v[164:167], v[216:219], v[72:75]
	v_mfma_f32_16x16x32_bf16 v[124:127], v[160:163], v[196:199], v[124:127]
	v_mfma_f32_16x16x32_bf16 v[120:123], v[168:171], v[196:199], v[120:123]
	v_mfma_f32_16x16x32_bf16 v[108:111], v[160:163], v[204:207], v[108:111]
	v_mfma_f32_16x16x32_bf16 v[104:107], v[168:171], v[204:207], v[104:107]
	v_mfma_f32_16x16x32_bf16 v[92:95], v[160:163], v[212:215], v[92:95]
	v_mfma_f32_16x16x32_bf16 v[88:91], v[168:171], v[212:215], v[88:91]
	v_mfma_f32_16x16x32_bf16 v[76:79], v[160:163], v[220:223], v[76:79]
	v_mfma_f32_16x16x32_bf16 v[72:75], v[168:171], v[220:223], v[72:75]
	s_setprio 0
	s_setprio 1
	v_mfma_f32_16x16x32_bf16 v[116:119], v[172:175], v[188:191], v[116:119]
	v_mfma_f32_16x16x32_bf16 v[112:115], v[180:183], v[188:191], v[112:115]
	v_mfma_f32_16x16x32_bf16 v[100:103], v[172:175], v[200:203], v[100:103]
	v_mfma_f32_16x16x32_bf16 v[96:99], v[180:183], v[200:203], v[96:99]
	v_mfma_f32_16x16x32_bf16 v[84:87], v[172:175], v[208:211], v[84:87]
	v_mfma_f32_16x16x32_bf16 v[80:83], v[180:183], v[208:211], v[80:83]
	v_mfma_f32_16x16x32_bf16 v[68:71], v[172:175], v[216:219], v[68:71]
	v_mfma_f32_16x16x32_bf16 v[64:67], v[180:183], v[216:219], v[64:67]
	v_mfma_f32_16x16x32_bf16 v[116:119], v[176:179], v[196:199], v[116:119]
	v_mfma_f32_16x16x32_bf16 v[112:115], v[184:187], v[196:199], v[112:115]
	v_mfma_f32_16x16x32_bf16 v[100:103], v[176:179], v[204:207], v[100:103]
	v_mfma_f32_16x16x32_bf16 v[96:99], v[184:187], v[204:207], v[96:99]
	v_mfma_f32_16x16x32_bf16 v[84:87], v[176:179], v[212:215], v[84:87]
	v_mfma_f32_16x16x32_bf16 v[80:83], v[184:187], v[212:215], v[80:83]
	v_mfma_f32_16x16x32_bf16 v[68:71], v[176:179], v[220:223], v[68:71]
	v_mfma_f32_16x16x32_bf16 v[64:67], v[184:187], v[220:223], v[64:67]
	s_setprio 0
	s_barrier
	s_add_i32 s42, s84, s60
	v_lshl_add_u64 v[150:151], v[150:151], 0, s[20:21]
	s_mov_b32 m0, s42
	ds_read_b128 v[188:191], v157 offset:49152
	ds_read_b128 v[196:199], v157 offset:50176
	ds_read_b128 v[200:203], v157 offset:51200
	ds_read_b128 v[204:207], v157 offset:52224
	ds_read_b128 v[208:211], v157 offset:53248
	ds_read_b128 v[212:215], v157 offset:54272
	ds_read_b128 v[216:219], v157 offset:55296
	ds_read_b128 v[220:223], v157 offset:56320
	global_load_lds_dwordx4 v[150:151], off
	s_add_i32 m0, s42, 0x2000
	s_add_u32 s40, s40, 0x40080
	v_lshl_add_u64 v[150:151], v[192:193], 0, s[20:21]
	s_addc_u32 s41, s41, 0
	s_add_i32 s42, s85, s60
	global_load_lds_dwordx4 v[150:151], off
	v_lshl_add_u64 v[150:151], s[40:41], 0, v[132:133]
	s_mov_b32 m0, s42
	s_nop 0
	global_load_lds_dwordx4 v[150:151], off
	v_lshl_add_u64 v[150:151], s[40:41], 0, v[136:137]
	s_add_i32 m0, s42, 0x2000
	s_nop 0
	global_load_lds_dwordx4 v[150:151], off
	s_mov_b32 s99, 1
	s_waitcnt vmcnt(6)
	s_waitcnt lgkmcnt(0)
	s_barrier
	s_setprio 1
	s_waitcnt lgkmcnt(0)
	v_mfma_f32_16x16x32_bf16 v[60:63], v[146:149], v[188:191], v[60:63]
	v_mfma_f32_16x16x32_bf16 v[56:59], v[164:167], v[188:191], v[56:59]
	v_mfma_f32_16x16x32_bf16 v[44:47], v[146:149], v[200:203], v[44:47]
	v_mfma_f32_16x16x32_bf16 v[40:43], v[164:167], v[200:203], v[40:43]
	v_mfma_f32_16x16x32_bf16 v[28:31], v[146:149], v[208:211], v[28:31]
	v_mfma_f32_16x16x32_bf16 v[24:27], v[164:167], v[208:211], v[24:27]
	v_mfma_f32_16x16x32_bf16 v[12:15], v[146:149], v[216:219], v[12:15]
	v_mfma_f32_16x16x32_bf16 v[8:11], v[164:167], v[216:219], v[8:11]
	v_mfma_f32_16x16x32_bf16 v[60:63], v[160:163], v[196:199], v[60:63]
	v_mfma_f32_16x16x32_bf16 v[56:59], v[168:171], v[196:199], v[56:59]
	v_mfma_f32_16x16x32_bf16 v[44:47], v[160:163], v[204:207], v[44:47]
	v_mfma_f32_16x16x32_bf16 v[40:43], v[168:171], v[204:207], v[40:43]
	v_mfma_f32_16x16x32_bf16 v[28:31], v[160:163], v[212:215], v[28:31]
	v_mfma_f32_16x16x32_bf16 v[24:27], v[168:171], v[212:215], v[24:27]
	v_mfma_f32_16x16x32_bf16 v[12:15], v[160:163], v[220:223], v[12:15]
	v_mfma_f32_16x16x32_bf16 v[8:11], v[168:171], v[220:223], v[8:11]
	s_setprio 0
	s_setprio 1
	v_mfma_f32_16x16x32_bf16 v[52:55], v[172:175], v[188:191], v[52:55]
	v_mfma_f32_16x16x32_bf16 v[48:51], v[180:183], v[188:191], v[48:51]
	v_mfma_f32_16x16x32_bf16 v[36:39], v[172:175], v[200:203], v[36:39]
	v_mfma_f32_16x16x32_bf16 v[32:35], v[180:183], v[200:203], v[32:35]
	v_mfma_f32_16x16x32_bf16 v[20:23], v[172:175], v[208:211], v[20:23]
	v_mfma_f32_16x16x32_bf16 v[16:19], v[180:183], v[208:211], v[16:19]
	v_mfma_f32_16x16x32_bf16 v[4:7], v[172:175], v[216:219], v[4:7]
	v_mfma_f32_16x16x32_bf16 v[0:3], v[180:183], v[216:219], v[0:3]
	v_mfma_f32_16x16x32_bf16 v[52:55], v[176:179], v[196:199], v[52:55]
	v_mfma_f32_16x16x32_bf16 v[48:51], v[184:187], v[196:199], v[48:51]
	v_mfma_f32_16x16x32_bf16 v[36:39], v[176:179], v[204:207], v[36:39]
	v_mfma_f32_16x16x32_bf16 v[32:35], v[184:187], v[204:207], v[32:35]
	v_mfma_f32_16x16x32_bf16 v[20:23], v[176:179], v[212:215], v[20:23]
	v_mfma_f32_16x16x32_bf16 v[16:19], v[184:187], v[212:215], v[16:19]
	v_mfma_f32_16x16x32_bf16 v[4:7], v[176:179], v[220:223], v[4:7]
	v_mfma_f32_16x16x32_bf16 v[0:3], v[184:187], v[220:223], v[0:3]
	s_setprio 0
	s_barrier
	s_add_i32 s83, s83, 2
	s_add_u32 s0, s0, 0x100
	s_addc_u32 s1, s1, 0
	s_add_u32 s29, s29, 0x100
	s_addc_u32 s82, s82, 0
	s_cmp_gt_u32 s83, 13
	s_cbranch_scc0 .LBB0_1421
	v_lshl_add_u64 v[224:225], v[224:225], 0, s[20:21]
	s_mov_b32 m0, s70
	s_nop 0
	global_load_lds_dwordx4 v[224:225], off
	v_lshl_add_u64 v[226:227], v[226:227], 0, s[20:21]
	s_mov_b32 m0, s71
	s_nop 0
	global_load_lds_dwordx4 v[226:227], off
	s_and_b64 vcc, exec, s[22:23]
	s_cbranch_vccz .LBB0_1424
	s_barrier

.LBB0_1450:
	s_add_u32 s58, s58, 0x20080
	s_addc_u32 s59, s59, 0
	s_add_u32 s15, s62, 0x100
	v_mov_b32_e32 v0, 0
	s_addc_u32 s17, s63, 0
	s_mov_b32 s39, -2
	v_mov_b32_e32 v1, v0
	v_mov_b32_e32 v2, v0
	v_mov_b32_e32 v3, v0
	v_mov_b32_e32 v4, v0
	v_mov_b32_e32 v5, v0
	v_mov_b32_e32 v6, v0
	v_mov_b32_e32 v7, v0
	v_mov_b32_e32 v16, v0
	v_mov_b32_e32 v17, v0
	v_mov_b32_e32 v18, v0
	v_mov_b32_e32 v19, v0
	v_mov_b32_e32 v20, v0
	v_mov_b32_e32 v21, v0
	v_mov_b32_e32 v22, v0
	v_mov_b32_e32 v23, v0
	v_mov_b32_e32 v32, v0
	v_mov_b32_e32 v33, v0
	v_mov_b32_e32 v34, v0
	v_mov_b32_e32 v35, v0
	v_mov_b32_e32 v36, v0
	v_mov_b32_e32 v37, v0
	v_mov_b32_e32 v38, v0
	v_mov_b32_e32 v39, v0
	v_mov_b32_e32 v48, v0
	v_mov_b32_e32 v49, v0
	v_mov_b32_e32 v50, v0
	v_mov_b32_e32 v51, v0
	v_mov_b32_e32 v52, v0
	v_mov_b32_e32 v53, v0
	v_mov_b32_e32 v54, v0
	v_mov_b32_e32 v55, v0
	v_mov_b32_e32 v8, v0
	v_mov_b32_e32 v9, v0
	v_mov_b32_e32 v10, v0
	v_mov_b32_e32 v11, v0
	v_mov_b32_e32 v12, v0
	v_mov_b32_e32 v13, v0
	v_mov_b32_e32 v14, v0
	v_mov_b32_e32 v15, v0
	v_mov_b32_e32 v24, v0
	v_mov_b32_e32 v25, v0
	v_mov_b32_e32 v26, v0
	v_mov_b32_e32 v27, v0
	v_mov_b32_e32 v28, v0
	v_mov_b32_e32 v29, v0
	v_mov_b32_e32 v30, v0
	v_mov_b32_e32 v31, v0
	v_mov_b32_e32 v40, v0
	v_mov_b32_e32 v41, v0
	v_mov_b32_e32 v42, v0
	v_mov_b32_e32 v43, v0
	v_mov_b32_e32 v44, v0
	v_mov_b32_e32 v45, v0
	v_mov_b32_e32 v46, v0
	v_mov_b32_e32 v47, v0
	v_mov_b32_e32 v56, v0
	v_mov_b32_e32 v57, v0
	v_mov_b32_e32 v58, v0
	v_mov_b32_e32 v59, v0
	v_mov_b32_e32 v60, v0
	v_mov_b32_e32 v61, v0
	v_mov_b32_e32 v62, v0
	v_mov_b32_e32 v63, v0
	v_mov_b32_e32 v64, v0
	v_mov_b32_e32 v65, v0
	v_mov_b32_e32 v66, v0
	v_mov_b32_e32 v67, v0
	v_mov_b32_e32 v68, v0
	v_mov_b32_e32 v69, v0
	v_mov_b32_e32 v70, v0
	v_mov_b32_e32 v71, v0
	v_mov_b32_e32 v80, v0
	v_mov_b32_e32 v81, v0
	v_mov_b32_e32 v82, v0
	v_mov_b32_e32 v83, v0
	v_mov_b32_e32 v84, v0
	v_mov_b32_e32 v85, v0
	v_mov_b32_e32 v86, v0
	v_mov_b32_e32 v87, v0
	v_mov_b32_e32 v96, v0
	v_mov_b32_e32 v97, v0
	v_mov_b32_e32 v98, v0
	v_mov_b32_e32 v99, v0
	v_mov_b32_e32 v100, v0
	v_mov_b32_e32 v101, v0
	v_mov_b32_e32 v102, v0
	v_mov_b32_e32 v103, v0
	v_mov_b32_e32 v112, v0
	v_mov_b32_e32 v113, v0
	v_mov_b32_e32 v114, v0
	v_mov_b32_e32 v115, v0
	v_mov_b32_e32 v116, v0
	v_mov_b32_e32 v117, v0
	v_mov_b32_e32 v118, v0
	v_mov_b32_e32 v119, v0
	v_mov_b32_e32 v72, v0
	v_mov_b32_e32 v73, v0
	v_mov_b32_e32 v74, v0
	v_mov_b32_e32 v75, v0
	v_mov_b32_e32 v76, v0
	v_mov_b32_e32 v77, v0
	v_mov_b32_e32 v78, v0
	v_mov_b32_e32 v79, v0
	v_mov_b32_e32 v88, v0
	v_mov_b32_e32 v89, v0
	v_mov_b32_e32 v90, v0
	v_mov_b32_e32 v91, v0
	v_mov_b32_e32 v92, v0
	v_mov_b32_e32 v93, v0
	v_mov_b32_e32 v94, v0
	v_mov_b32_e32 v95, v0
	v_mov_b32_e32 v104, v0
	v_mov_b32_e32 v105, v0
	v_mov_b32_e32 v106, v0
	v_mov_b32_e32 v107, v0
	v_mov_b32_e32 v108, v0
	v_mov_b32_e32 v109, v0
	v_mov_b32_e32 v110, v0
	v_mov_b32_e32 v111, v0
	v_mov_b32_e32 v120, v0
	v_mov_b32_e32 v121, v0
	v_mov_b32_e32 v122, v0
	v_mov_b32_e32 v123, v0
	v_mov_b32_e32 v124, v0
	v_mov_b32_e32 v125, v0
	v_mov_b32_e32 v126, v0
	v_mov_b32_e32 v127, v0
	s_mov_b32 s99, 0
.LBB0_1451:
	ds_read_b128 v[144:147], v159
	ds_read_b128 v[148:151], v159 offset:1024
	ds_read_b128 v[152:155], v159 offset:2048
	ds_read_b128 v[162:165], v159 offset:3072
	ds_read_b128 v[166:169], v160
	ds_read_b128 v[170:173], v160 offset:1024
	ds_read_b128 v[174:177], v160 offset:2048
	ds_read_b128 v[178:181], v160 offset:3072
	s_add_u32 s41, s58, 0xfffe0080
	s_addc_u32 s43, s59, -1
	s_cmp_eq_u32 s39, 4
	s_cselect_b32 s71, s1, s43
	s_cselect_b32 s70, s0, s41
	s_cselect_b32 s63, s45, s17
	s_cselect_b32 s62, s44, s15
	v_lshl_add_u64 v[216:217], s[58:59], 0, v[136:137]
	ds_read_b128 v[182:185], v161
	ds_read_b128 v[186:189], v161 offset:1024
	ds_read_b128 v[190:193], v161 offset:2048
	ds_read_b128 v[196:199], v161 offset:3072
	ds_read_b128 v[200:203], v161 offset:4096
	ds_read_b128 v[204:207], v161 offset:5120
	ds_read_b128 v[208:211], v161 offset:6144
	ds_read_b128 v[212:215], v161 offset:7168
	s_cmp_eq_u32 s99, 0
	s_cbranch_scc1 .Lkb_first_10
	v_lshl_add_u64 v[220:221], v[220:221], 0, s[26:27]
	s_mov_b32 m0, s87
	s_nop 0
	global_load_lds_dwordx4 v[220:221], off
	v_lshl_add_u64 v[222:223], v[222:223], 0, s[26:27]
	s_mov_b32 m0, s88
	s_nop 0
	global_load_lds_dwordx4 v[222:223], off
	s_branch .Lkb_join_10
.Lkb_first_10:
	s_add_i32 m0, s83, 0xc000
	s_nop 0
	global_load_lds_dwordx4 v[216:217], off
	global_load_lds_dwordx4 v[216:217], off
.Lkb_join_10:
	s_add_i32 m0, s83, 0xc000
	s_nop 0
	global_load_lds_dwordx4 v[216:217], off
	v_lshl_add_u64 v[216:217], s[58:59], 0, v[138:139]
	s_add_i32 m0, s83, 0xe000
	s_nop 0
	global_load_lds_dwordx4 v[216:217], off
	s_waitcnt vmcnt(8)
	s_waitcnt lgkmcnt(0)
	s_barrier
	s_setprio 1
	s_waitcnt lgkmcnt(0)
	v_mfma_f32_16x16x32_bf16 v[124:127], v[144:147], v[182:185], v[124:127]
	v_mfma_f32_16x16x32_bf16 v[120:123], v[152:155], v[182:185], v[120:123]
	v_mfma_f32_16x16x32_bf16 v[108:111], v[144:147], v[190:193], v[108:111]
	v_mfma_f32_16x16x32_bf16 v[104:107], v[152:155], v[190:193], v[104:107]
	v_mfma_f32_16x16x32_bf16 v[92:95], v[144:147], v[200:203], v[92:95]
	v_mfma_f32_16x16x32_bf16 v[88:91], v[152:155], v[200:203], v[88:91]
	v_mfma_f32_16x16x32_bf16 v[76:79], v[144:147], v[208:211], v[76:79]
	v_mfma_f32_16x16x32_bf16 v[72:75], v[152:155], v[208:211], v[72:75]
	v_mfma_f32_16x16x32_bf16 v[124:127], v[148:151], v[186:189], v[124:127]
	v_mfma_f32_16x16x32_bf16 v[120:123], v[162:165], v[186:189], v[120:123]
	v_mfma_f32_16x16x32_bf16 v[108:111], v[148:151], v[196:199], v[108:111]
	v_mfma_f32_16x16x32_bf16 v[104:107], v[162:165], v[196:199], v[104:107]
	v_mfma_f32_16x16x32_bf16 v[92:95], v[148:151], v[204:207], v[92:95]
	v_mfma_f32_16x16x32_bf16 v[88:91], v[162:165], v[204:207], v[88:91]
	v_mfma_f32_16x16x32_bf16 v[76:79], v[148:151], v[212:215], v[76:79]
	v_mfma_f32_16x16x32_bf16 v[72:75], v[162:165], v[212:215], v[72:75]
	s_setprio 0
	s_setprio 1
	v_mfma_f32_16x16x32_bf16 v[116:119], v[166:169], v[182:185], v[116:119]
	v_mfma_f32_16x16x32_bf16 v[112:115], v[174:177], v[182:185], v[112:115]
	v_mfma_f32_16x16x32_bf16 v[100:103], v[166:169], v[190:193], v[100:103]
	v_mfma_f32_16x16x32_bf16 v[96:99], v[174:177], v[190:193], v[96:99]
	v_mfma_f32_16x16x32_bf16 v[84:87], v[166:169], v[200:203], v[84:87]
	v_mfma_f32_16x16x32_bf16 v[80:83], v[174:177], v[200:203], v[80:83]
	v_mfma_f32_16x16x32_bf16 v[68:71], v[166:169], v[208:211], v[68:71]
	v_mfma_f32_16x16x32_bf16 v[64:67], v[174:177], v[208:211], v[64:67]
	v_mfma_f32_16x16x32_bf16 v[116:119], v[170:173], v[186:189], v[116:119]
	v_mfma_f32_16x16x32_bf16 v[112:115], v[178:181], v[186:189], v[112:115]
	v_mfma_f32_16x16x32_bf16 v[100:103], v[170:173], v[196:199], v[100:103]
	v_mfma_f32_16x16x32_bf16 v[96:99], v[178:181], v[196:199], v[96:99]
	v_mfma_f32_16x16x32_bf16 v[84:87], v[170:173], v[204:207], v[84:87]
	v_mfma_f32_16x16x32_bf16 v[80:83], v[178:181], v[204:207], v[80:83]
	v_mfma_f32_16x16x32_bf16 v[68:71], v[170:173], v[212:215], v[68:71]
	v_mfma_f32_16x16x32_bf16 v[64:67], v[178:181], v[212:215], v[64:67]
	s_setprio 0
	s_barrier
	s_add_i32 s41, s90, s80
	v_lshl_add_u64 v[216:217], s[62:63], 0, v[130:131]
	s_mov_b32 m0, s41
	ds_read_b128 v[182:185], v161 offset:16384
	ds_read_b128 v[186:189], v161 offset:17408
	ds_read_b128 v[190:193], v161 offset:18432
	ds_read_b128 v[196:199], v161 offset:19456
	ds_read_b128 v[200:203], v161 offset:20480
	ds_read_b128 v[204:207], v161 offset:21504
	ds_read_b128 v[208:211], v161 offset:22528
	ds_read_b128 v[212:215], v161 offset:23552
	global_load_lds_dwordx4 v[216:217], off
	s_add_i32 m0, s41, 0x2000
	s_add_u32 s94, s62, 0x20000
	v_lshl_add_u64 v[218:219], s[62:63], 0, v[134:135]
	s_addc_u32 s95, s63, 0
	s_add_i32 s41, s91, s80
	global_load_lds_dwordx4 v[218:219], off
	v_lshl_add_u64 v[220:221], s[94:95], 0, v[130:131]
	s_mov_b32 m0, s41
	v_lshl_add_u64 v[222:223], s[70:71], 0, v[132:133]
	global_load_lds_dwordx4 v[220:221], off
	v_lshl_add_u64 v[220:221], s[94:95], 0, v[134:135]
	s_add_i32 m0, s41, 0x2000
	s_nop 0
	global_load_lds_dwordx4 v[220:221], off
	v_lshl_add_u64 v[220:221], s[70:71], 0, v[128:129]
	s_waitcnt vmcnt(6)
	s_waitcnt lgkmcnt(0)
	s_barrier
	s_setprio 1
	s_waitcnt lgkmcnt(0)
	v_mfma_f32_16x16x32_bf16 v[60:63], v[144:147], v[182:185], v[60:63]
	v_mfma_f32_16x16x32_bf16 v[56:59], v[152:155], v[182:185], v[56:59]
	v_mfma_f32_16x16x32_bf16 v[44:47], v[144:147], v[190:193], v[44:47]
	v_mfma_f32_16x16x32_bf16 v[40:43], v[152:155], v[190:193], v[40:43]
	v_mfma_f32_16x16x32_bf16 v[28:31], v[144:147], v[200:203], v[28:31]
	v_mfma_f32_16x16x32_bf16 v[24:27], v[152:155], v[200:203], v[24:27]
	v_mfma_f32_16x16x32_bf16 v[12:15], v[144:147], v[208:211], v[12:15]
	v_mfma_f32_16x16x32_bf16 v[8:11], v[152:155], v[208:211], v[8:11]
	v_mfma_f32_16x16x32_bf16 v[60:63], v[148:151], v[186:189], v[60:63]
	v_mfma_f32_16x16x32_bf16 v[56:59], v[162:165], v[186:189], v[56:59]
	v_mfma_f32_16x16x32_bf16 v[44:47], v[148:151], v[196:199], v[44:47]
	v_mfma_f32_16x16x32_bf16 v[40:43], v[162:165], v[196:199], v[40:43]
	v_mfma_f32_16x16x32_bf16 v[28:31], v[148:151], v[204:207], v[28:31]
	v_mfma_f32_16x16x32_bf16 v[24:27], v[162:165], v[204:207], v[24:27]
	v_mfma_f32_16x16x32_bf16 v[12:15], v[148:151], v[212:215], v[12:15]
	v_mfma_f32_16x16x32_bf16 v[8:11], v[162:165], v[212:215], v[8:11]
	s_setprio 0
	s_setprio 1
	v_mfma_f32_16x16x32_bf16 v[52:55], v[166:169], v[182:185], v[52:55]
	v_mfma_f32_16x16x32_bf16 v[48:51], v[174:177], v[182:185], v[48:51]
	v_mfma_f32_16x16x32_bf16 v[36:39], v[166:169], v[190:193], v[36:39]
	v_mfma_f32_16x16x32_bf16 v[32:35], v[174:177], v[190:193], v[32:35]
	v_mfma_f32_16x16x32_bf16 v[20:23], v[166:169], v[200:203], v[20:23]
	v_mfma_f32_16x16x32_bf16 v[16:19], v[174:177], v[200:203], v[16:19]
	v_mfma_f32_16x16x32_bf16 v[4:7], v[166:169], v[208:211], v[4:7]
	v_mfma_f32_16x16x32_bf16 v[0:3], v[174:177], v[208:211], v[0:3]
	v_mfma_f32_16x16x32_bf16 v[52:55], v[170:173], v[186:189], v[52:55]
	v_mfma_f32_16x16x32_bf16 v[48:51], v[178:181], v[186:189], v[48:51]
	v_mfma_f32_16x16x32_bf16 v[36:39], v[170:173], v[196:199], v[36:39]
	v_mfma_f32_16x16x32_bf16 v[32:35], v[178:181], v[196:199], v[32:35]
	v_mfma_f32_16x16x32_bf16 v[20:23], v[170:173], v[204:207], v[20:23]
	v_mfma_f32_16x16x32_bf16 v[16:19], v[178:181], v[204:207], v[16:19]
	v_mfma_f32_16x16x32_bf16 v[4:7], v[170:173], v[212:215], v[4:7]
	v_mfma_f32_16x16x32_bf16 v[0:3], v[178:181], v[212:215], v[0:3]
	s_setprio 0
	s_barrier
	s_add_i32 s41, 0, 0x18000
	s_add_i32 s43, 0, 0x1c000
	v_add_u32_e32 v162, s41, v157
	v_add_u32_e32 v178, s43, v157
	ds_read_b128 v[144:147], v162
	ds_read_b128 v[148:151], v162 offset:1024
	ds_read_b128 v[152:155], v162 offset:2048
	ds_read_b128 v[162:165], v162 offset:3072
	ds_read_b128 v[166:169], v178
	ds_read_b128 v[170:173], v178 offset:1024
	ds_read_b128 v[174:177], v178 offset:2048
	ds_read_b128 v[178:181], v178 offset:3072
	s_add_u32 s70, s70, 0x20000
	s_addc_u32 s71, s71, 0
	v_lshl_add_u64 v[224:225], s[70:71], 0, v[128:129]
	ds_read_b128 v[182:185], v161 offset:32768
	ds_read_b128 v[186:189], v161 offset:33792
	ds_read_b128 v[190:193], v161 offset:34816
	ds_read_b128 v[196:199], v161 offset:35840
	ds_read_b128 v[200:203], v161 offset:36864
	ds_read_b128 v[204:207], v161 offset:37888
	ds_read_b128 v[208:211], v161 offset:38912
	ds_read_b128 v[212:215], v161 offset:39936
	s_mov_b32 m0, s83
	s_nop 0
	global_load_lds_dwordx4 v[220:221], off
	s_mov_b32 m0, s84
	s_nop 0
	global_load_lds_dwordx4 v[222:223], off
	s_mov_b32 m0, s85
	s_nop 0
	global_load_lds_dwordx4 v[224:225], off
	v_lshl_add_u64 v[224:225], s[70:71], 0, v[132:133]
	s_mov_b32 m0, s86
	s_nop 0
	global_load_lds_dwordx4 v[224:225], off
	s_waitcnt vmcnt(8)
	s_waitcnt lgkmcnt(0)
	s_barrier
	s_setprio 1
	s_waitcnt lgkmcnt(0)
	v_mfma_f32_16x16x32_bf16 v[124:127], v[144:147], v[182:185], v[124:127]
	v_mfma_f32_16x16x32_bf16 v[120:123], v[152:155], v[182:185], v[120:123]
	v_mfma_f32_16x16x32_bf16 v[108:111], v[144:147], v[190:193], v[108:111]
	v_mfma_f32_16x16x32_bf16 v[104:107], v[152:155], v[190:193], v[104:107]
	v_mfma_f32_16x16x32_bf16 v[92:95], v[144:147], v[200:203], v[92:95]
	v_mfma_f32_16x16x32_bf16 v[88:91], v[152:155], v[200:203], v[88:91]
	v_mfma_f32_16x16x32_bf16 v[76:79], v[144:147], v[208:211], v[76:79]
	v_mfma_f32_16x16x32_bf16 v[72:75], v[152:155], v[208:211], v[72:75]
	v_mfma_f32_16x16x32_bf16 v[124:127], v[148:151], v[186:189], v[124:127]
	v_mfma_f32_16x16x32_bf16 v[120:123], v[162:165], v[186:189], v[120:123]
	v_mfma_f32_16x16x32_bf16 v[108:111], v[148:151], v[196:199], v[108:111]
	v_mfma_f32_16x16x32_bf16 v[104:107], v[162:165], v[196:199], v[104:107]
	v_mfma_f32_16x16x32_bf16 v[92:95], v[148:151], v[204:207], v[92:95]
	v_mfma_f32_16x16x32_bf16 v[88:91], v[162:165], v[204:207], v[88:91]
	v_mfma_f32_16x16x32_bf16 v[76:79], v[148:151], v[212:215], v[76:79]
	v_mfma_f32_16x16x32_bf16 v[72:75], v[162:165], v[212:215], v[72:75]
	s_setprio 0
	s_setprio 1
	v_mfma_f32_16x16x32_bf16 v[116:119], v[166:169], v[182:185], v[116:119]
	v_mfma_f32_16x16x32_bf16 v[112:115], v[174:177], v[182:185], v[112:115]
	v_mfma_f32_16x16x32_bf16 v[100:103], v[166:169], v[190:193], v[100:103]
	v_mfma_f32_16x16x32_bf16 v[96:99], v[174:177], v[190:193], v[96:99]
	v_mfma_f32_16x16x32_bf16 v[84:87], v[166:169], v[200:203], v[84:87]
	v_mfma_f32_16x16x32_bf16 v[80:83], v[174:177], v[200:203], v[80:83]
	v_mfma_f32_16x16x32_bf16 v[68:71], v[166:169], v[208:211], v[68:71]
	v_mfma_f32_16x16x32_bf16 v[64:67], v[174:177], v[208:211], v[64:67]
	v_mfma_f32_16x16x32_bf16 v[116:119], v[170:173], v[186:189], v[116:119]
	v_mfma_f32_16x16x32_bf16 v[112:115], v[178:181], v[186:189], v[112:115]
	v_mfma_f32_16x16x32_bf16 v[100:103], v[170:173], v[196:199], v[100:103]
	v_mfma_f32_16x16x32_bf16 v[96:99], v[178:181], v[196:199], v[96:99]
	v_mfma_f32_16x16x32_bf16 v[84:87], v[170:173], v[204:207], v[84:87]
	v_mfma_f32_16x16x32_bf16 v[80:83], v[178:181], v[204:207], v[80:83]
	v_mfma_f32_16x16x32_bf16 v[68:71], v[170:173], v[212:215], v[68:71]
	v_mfma_f32_16x16x32_bf16 v[64:67], v[178:181], v[212:215], v[64:67]
	s_setprio 0
	s_barrier
	s_add_i32 s41, s41, s80
	v_lshl_add_u64 v[216:217], v[216:217], 0, s[26:27]
	s_mov_b32 m0, s41
	ds_read_b128 v[182:185], v161 offset:49152
	ds_read_b128 v[186:189], v161 offset:50176
	ds_read_b128 v[190:193], v161 offset:51200
	ds_read_b128 v[196:199], v161 offset:52224
	ds_read_b128 v[200:203], v161 offset:53248
	ds_read_b128 v[204:207], v161 offset:54272
	ds_read_b128 v[208:211], v161 offset:55296
	ds_read_b128 v[212:215], v161 offset:56320
	global_load_lds_dwordx4 v[216:217], off
	s_add_i32 m0, s41, 0x2000
	s_add_u32 s62, s62, 0x20080
	v_lshl_add_u64 v[216:217], v[218:219], 0, s[26:27]
	s_addc_u32 s63, s63, 0
	s_add_i32 s41, s43, s80
	global_load_lds_dwordx4 v[216:217], off
	v_lshl_add_u64 v[216:217], s[62:63], 0, v[130:131]
	s_mov_b32 m0, s41
	s_nop 0
	global_load_lds_dwordx4 v[216:217], off
	v_lshl_add_u64 v[216:217], s[62:63], 0, v[134:135]
	s_add_i32 m0, s41, 0x2000
	s_nop 0
	global_load_lds_dwordx4 v[216:217], off
	s_mov_b32 s99, 1
	s_waitcnt vmcnt(6)
	s_waitcnt lgkmcnt(0)
	s_barrier
	s_setprio 1
	s_waitcnt lgkmcnt(0)
	v_mfma_f32_16x16x32_bf16 v[60:63], v[144:147], v[182:185], v[60:63]
	v_mfma_f32_16x16x32_bf16 v[56:59], v[152:155], v[182:185], v[56:59]
	v_mfma_f32_16x16x32_bf16 v[44:47], v[144:147], v[190:193], v[44:47]
	v_mfma_f32_16x16x32_bf16 v[40:43], v[152:155], v[190:193], v[40:43]
	v_mfma_f32_16x16x32_bf16 v[28:31], v[144:147], v[200:203], v[28:31]
	v_mfma_f32_16x16x32_bf16 v[24:27], v[152:155], v[200:203], v[24:27]
	v_mfma_f32_16x16x32_bf16 v[12:15], v[144:147], v[208:211], v[12:15]
	v_mfma_f32_16x16x32_bf16 v[8:11], v[152:155], v[208:211], v[8:11]
	v_mfma_f32_16x16x32_bf16 v[60:63], v[148:151], v[186:189], v[60:63]
	v_mfma_f32_16x16x32_bf16 v[56:59], v[162:165], v[186:189], v[56:59]
	v_mfma_f32_16x16x32_bf16 v[44:47], v[148:151], v[196:199], v[44:47]
	v_mfma_f32_16x16x32_bf16 v[40:43], v[162:165], v[196:199], v[40:43]
	v_mfma_f32_16x16x32_bf16 v[28:31], v[148:151], v[204:207], v[28:31]
	v_mfma_f32_16x16x32_bf16 v[24:27], v[162:165], v[204:207], v[24:27]
	v_mfma_f32_16x16x32_bf16 v[12:15], v[148:151], v[212:215], v[12:15]
	v_mfma_f32_16x16x32_bf16 v[8:11], v[162:165], v[212:215], v[8:11]
	s_setprio 0
	s_setprio 1
	v_mfma_f32_16x16x32_bf16 v[52:55], v[166:169], v[182:185], v[52:55]
	v_mfma_f32_16x16x32_bf16 v[48:51], v[174:177], v[182:185], v[48:51]
	v_mfma_f32_16x16x32_bf16 v[36:39], v[166:169], v[190:193], v[36:39]
	v_mfma_f32_16x16x32_bf16 v[32:35], v[174:177], v[190:193], v[32:35]
	v_mfma_f32_16x16x32_bf16 v[20:23], v[166:169], v[200:203], v[20:23]
	v_mfma_f32_16x16x32_bf16 v[16:19], v[174:177], v[200:203], v[16:19]
	v_mfma_f32_16x16x32_bf16 v[4:7], v[166:169], v[208:211], v[4:7]
	v_mfma_f32_16x16x32_bf16 v[0:3], v[174:177], v[208:211], v[0:3]
	v_mfma_f32_16x16x32_bf16 v[52:55], v[170:173], v[186:189], v[52:55]
	v_mfma_f32_16x16x32_bf16 v[48:51], v[178:181], v[186:189], v[48:51]
	v_mfma_f32_16x16x32_bf16 v[36:39], v[170:173], v[196:199], v[36:39]
	v_mfma_f32_16x16x32_bf16 v[32:35], v[178:181], v[196:199], v[32:35]
	v_mfma_f32_16x16x32_bf16 v[20:23], v[170:173], v[204:207], v[20:23]
	v_mfma_f32_16x16x32_bf16 v[16:19], v[178:181], v[204:207], v[16:19]
	v_mfma_f32_16x16x32_bf16 v[4:7], v[170:173], v[212:215], v[4:7]
	v_mfma_f32_16x16x32_bf16 v[0:3], v[178:181], v[212:215], v[0:3]
	s_setprio 0
	s_barrier
	s_add_i32 s39, s39, 2
	s_add_u32 s58, s58, 0x100
	s_addc_u32 s59, s59, 0
	s_add_u32 s15, s15, 0x100
	s_addc_u32 s17, s17, 0
	s_cmp_gt_u32 s39, 5
	s_cbranch_scc0 .LBB0_1451
	v_lshl_add_u64 v[220:221], v[220:221], 0, s[26:27]
	s_mov_b32 m0, s87
	s_nop 0
	global_load_lds_dwordx4 v[220:221], off
	v_lshl_add_u64 v[222:223], v[222:223], 0, s[26:27]
	s_mov_b32 m0, s88
	s_nop 0
	global_load_lds_dwordx4 v[222:223], off
	s_and_b64 vcc, exec, s[28:29]
	s_cbranch_vccz .LBB0_1454
	s_barrier

.LBB0_1624:
	s_ashr_i32 s31, s30, 31
	s_lshl_b64 s[34:35], s[30:31], 19
	s_add_u32 s34, s58, s34
	s_addc_u32 s35, s59, s35
	s_and_b64 s[36:37], s[14:15], exec
	s_cselect_b32 s31, s35, s41
	s_cselect_b32 s39, s34, s40
	s_ashr_i32 s29, s28, 31
	s_lshl_b64 s[36:37], s[28:29], 19
	s_add_u32 s36, s60, s36
	s_addc_u32 s37, s61, s37
	s_and_b64 s[44:45], s[14:15], exec
	s_cselect_b32 s29, s37, s43
	s_cselect_b32 s84, s36, s42
	s_add_u32 s40, s40, 0x40080
	s_addc_u32 s41, s41, 0
	s_add_u32 s85, s42, 0x100
	v_mov_b32_e32 v0, 0
	s_addc_u32 s86, s43, 0
	s_mov_b32 s87, -2
	s_waitcnt lgkmcnt(0)
	v_mov_b32_e32 v1, v0
	v_mov_b32_e32 v2, v0
	v_mov_b32_e32 v3, v0
	v_mov_b32_e32 v4, v0
	v_mov_b32_e32 v5, v0
	v_mov_b32_e32 v6, v0
	v_mov_b32_e32 v7, v0
	v_mov_b32_e32 v16, v0
	v_mov_b32_e32 v17, v0
	v_mov_b32_e32 v18, v0
	v_mov_b32_e32 v19, v0
	v_mov_b32_e32 v20, v0
	v_mov_b32_e32 v21, v0
	v_mov_b32_e32 v22, v0
	v_mov_b32_e32 v23, v0
	v_mov_b32_e32 v32, v0
	v_mov_b32_e32 v33, v0
	v_mov_b32_e32 v34, v0
	v_mov_b32_e32 v35, v0
	v_mov_b32_e32 v36, v0
	v_mov_b32_e32 v37, v0
	v_mov_b32_e32 v38, v0
	v_mov_b32_e32 v39, v0
	v_mov_b32_e32 v48, v0
	v_mov_b32_e32 v49, v0
	v_mov_b32_e32 v50, v0
	v_mov_b32_e32 v51, v0
	v_mov_b32_e32 v52, v0
	v_mov_b32_e32 v53, v0
	v_mov_b32_e32 v54, v0
	v_mov_b32_e32 v55, v0
	v_mov_b32_e32 v8, v0
	v_mov_b32_e32 v9, v0
	v_mov_b32_e32 v10, v0
	v_mov_b32_e32 v11, v0
	v_mov_b32_e32 v12, v0
	v_mov_b32_e32 v13, v0
	v_mov_b32_e32 v14, v0
	v_mov_b32_e32 v15, v0
	v_mov_b32_e32 v24, v0
	v_mov_b32_e32 v25, v0
	v_mov_b32_e32 v26, v0
	v_mov_b32_e32 v27, v0
	v_mov_b32_e32 v28, v0
	v_mov_b32_e32 v29, v0
	v_mov_b32_e32 v30, v0
	v_mov_b32_e32 v31, v0
	v_mov_b32_e32 v40, v0
	v_mov_b32_e32 v41, v0
	v_mov_b32_e32 v42, v0
	v_mov_b32_e32 v43, v0
	v_mov_b32_e32 v44, v0
	v_mov_b32_e32 v45, v0
	v_mov_b32_e32 v46, v0
	v_mov_b32_e32 v47, v0
	v_mov_b32_e32 v56, v0
	v_mov_b32_e32 v57, v0
	v_mov_b32_e32 v58, v0
	v_mov_b32_e32 v59, v0
	v_mov_b32_e32 v60, v0
	v_mov_b32_e32 v61, v0
	v_mov_b32_e32 v62, v0
	v_mov_b32_e32 v63, v0
	v_mov_b32_e32 v64, v0
	v_mov_b32_e32 v65, v0
	v_mov_b32_e32 v66, v0
	v_mov_b32_e32 v67, v0
	v_mov_b32_e32 v68, v0
	v_mov_b32_e32 v69, v0
	v_mov_b32_e32 v70, v0
	v_mov_b32_e32 v71, v0
	v_mov_b32_e32 v80, v0
	v_mov_b32_e32 v81, v0
	v_mov_b32_e32 v82, v0
	v_mov_b32_e32 v83, v0
	v_mov_b32_e32 v84, v0
	v_mov_b32_e32 v85, v0
	v_mov_b32_e32 v86, v0
	v_mov_b32_e32 v87, v0
	v_mov_b32_e32 v96, v0
	v_mov_b32_e32 v97, v0
	v_mov_b32_e32 v98, v0
	v_mov_b32_e32 v99, v0
	v_mov_b32_e32 v100, v0
	v_mov_b32_e32 v101, v0
	v_mov_b32_e32 v102, v0
	v_mov_b32_e32 v103, v0
	v_mov_b32_e32 v112, v0
	v_mov_b32_e32 v113, v0
	v_mov_b32_e32 v114, v0
	v_mov_b32_e32 v115, v0
	v_mov_b32_e32 v116, v0
	v_mov_b32_e32 v117, v0
	v_mov_b32_e32 v118, v0
	v_mov_b32_e32 v119, v0
	v_mov_b32_e32 v72, v0
	v_mov_b32_e32 v73, v0
	v_mov_b32_e32 v74, v0
	v_mov_b32_e32 v75, v0
	v_mov_b32_e32 v76, v0
	v_mov_b32_e32 v77, v0
	v_mov_b32_e32 v78, v0
	v_mov_b32_e32 v79, v0
	v_mov_b32_e32 v88, v0
	v_mov_b32_e32 v89, v0
	v_mov_b32_e32 v90, v0
	v_mov_b32_e32 v91, v0
	v_mov_b32_e32 v92, v0
	v_mov_b32_e32 v93, v0
	v_mov_b32_e32 v94, v0
	v_mov_b32_e32 v95, v0
	v_mov_b32_e32 v104, v0
	v_mov_b32_e32 v105, v0
	v_mov_b32_e32 v106, v0
	v_mov_b32_e32 v107, v0
	v_mov_b32_e32 v108, v0
	v_mov_b32_e32 v109, v0
	v_mov_b32_e32 v110, v0
	v_mov_b32_e32 v111, v0
	v_mov_b32_e32 v120, v0
	v_mov_b32_e32 v121, v0
	v_mov_b32_e32 v122, v0
	v_mov_b32_e32 v123, v0
	v_mov_b32_e32 v124, v0
	v_mov_b32_e32 v125, v0
	v_mov_b32_e32 v126, v0
	v_mov_b32_e32 v127, v0
	s_mov_b32 s99, 0
.LBB0_1625:
	ds_read_b128 v[144:147], v151
	ds_read_b128 v[156:159], v151 offset:1024
	ds_read_b128 v[160:163], v151 offset:2048
	ds_read_b128 v[164:167], v151 offset:3072
	ds_read_b128 v[168:171], v152
	ds_read_b128 v[172:175], v152 offset:1024
	ds_read_b128 v[176:179], v152 offset:2048
	ds_read_b128 v[180:183], v152 offset:3072
	s_add_u32 s42, s40, 0xfffc0080
	s_addc_u32 s43, s41, -1
	s_cmp_eq_u32 s87, 12
	s_cselect_b32 s45, s31, s43
	s_cselect_b32 s44, s39, s42
	s_cselect_b32 s43, s29, s86
	s_cselect_b32 s42, s84, s85
	v_lshl_add_u64 v[192:193], s[40:41], 0, v[136:137]
	ds_read_b128 v[184:187], v153
	ds_read_b128 v[188:191], v153 offset:1024
	ds_read_b128 v[196:199], v153 offset:2048
	ds_read_b128 v[200:203], v153 offset:3072
	ds_read_b128 v[204:207], v153 offset:4096
	ds_read_b128 v[208:211], v153 offset:5120
	ds_read_b128 v[212:215], v153 offset:6144
	ds_read_b128 v[216:219], v153 offset:7168
	s_cmp_eq_u32 s99, 0
	s_cbranch_scc1 .Lkb_first_11
	v_lshl_add_u64 v[222:223], v[222:223], 0, s[24:25]
	s_mov_b32 m0, s78
	s_nop 0
	global_load_lds_dwordx4 v[222:223], off
	v_lshl_add_u64 v[224:225], v[224:225], 0, s[24:25]
	s_mov_b32 m0, s79
	s_nop 0
	global_load_lds_dwordx4 v[224:225], off
	s_branch .Lkb_join_11
.Lkb_first_11:
	s_add_i32 m0, s63, 0xc000
	s_nop 0
	global_load_lds_dwordx4 v[192:193], off
	global_load_lds_dwordx4 v[192:193], off
.Lkb_join_11:
	s_add_i32 m0, s63, 0xc000
	s_nop 0
	global_load_lds_dwordx4 v[192:193], off
	v_lshl_add_u64 v[192:193], s[40:41], 0, v[138:139]
	s_add_i32 m0, s63, 0xe000
	s_nop 0
	global_load_lds_dwordx4 v[192:193], off
	s_waitcnt vmcnt(8)
	s_waitcnt lgkmcnt(0)
	s_barrier
	s_setprio 1
	s_waitcnt lgkmcnt(0)
	v_mfma_f32_16x16x32_bf16 v[124:127], v[144:147], v[184:187], v[124:127]
	v_mfma_f32_16x16x32_bf16 v[120:123], v[160:163], v[184:187], v[120:123]
	v_mfma_f32_16x16x32_bf16 v[108:111], v[144:147], v[196:199], v[108:111]
	v_mfma_f32_16x16x32_bf16 v[104:107], v[160:163], v[196:199], v[104:107]
	v_mfma_f32_16x16x32_bf16 v[92:95], v[144:147], v[204:207], v[92:95]
	v_mfma_f32_16x16x32_bf16 v[88:91], v[160:163], v[204:207], v[88:91]
	v_mfma_f32_16x16x32_bf16 v[76:79], v[144:147], v[212:215], v[76:79]
	v_mfma_f32_16x16x32_bf16 v[72:75], v[160:163], v[212:215], v[72:75]
	v_mfma_f32_16x16x32_bf16 v[124:127], v[156:159], v[188:191], v[124:127]
	v_mfma_f32_16x16x32_bf16 v[120:123], v[164:167], v[188:191], v[120:123]
	v_mfma_f32_16x16x32_bf16 v[108:111], v[156:159], v[200:203], v[108:111]
	v_mfma_f32_16x16x32_bf16 v[104:107], v[164:167], v[200:203], v[104:107]
	v_mfma_f32_16x16x32_bf16 v[92:95], v[156:159], v[208:211], v[92:95]
	v_mfma_f32_16x16x32_bf16 v[88:91], v[164:167], v[208:211], v[88:91]
	v_mfma_f32_16x16x32_bf16 v[76:79], v[156:159], v[216:219], v[76:79]
	v_mfma_f32_16x16x32_bf16 v[72:75], v[164:167], v[216:219], v[72:75]
	s_setprio 0
	s_setprio 1
	v_mfma_f32_16x16x32_bf16 v[116:119], v[168:171], v[184:187], v[116:119]
	v_mfma_f32_16x16x32_bf16 v[112:115], v[176:179], v[184:187], v[112:115]
	v_mfma_f32_16x16x32_bf16 v[100:103], v[168:171], v[196:199], v[100:103]
	v_mfma_f32_16x16x32_bf16 v[96:99], v[176:179], v[196:199], v[96:99]
	v_mfma_f32_16x16x32_bf16 v[84:87], v[168:171], v[204:207], v[84:87]
	v_mfma_f32_16x16x32_bf16 v[80:83], v[176:179], v[204:207], v[80:83]
	v_mfma_f32_16x16x32_bf16 v[68:71], v[168:171], v[212:215], v[68:71]
	v_mfma_f32_16x16x32_bf16 v[64:67], v[176:179], v[212:215], v[64:67]
	v_mfma_f32_16x16x32_bf16 v[116:119], v[172:175], v[188:191], v[116:119]
	v_mfma_f32_16x16x32_bf16 v[112:115], v[180:183], v[188:191], v[112:115]
	v_mfma_f32_16x16x32_bf16 v[100:103], v[172:175], v[200:203], v[100:103]
	v_mfma_f32_16x16x32_bf16 v[96:99], v[180:183], v[200:203], v[96:99]
	v_mfma_f32_16x16x32_bf16 v[84:87], v[172:175], v[208:211], v[84:87]
	v_mfma_f32_16x16x32_bf16 v[80:83], v[180:183], v[208:211], v[80:83]
	v_mfma_f32_16x16x32_bf16 v[68:71], v[172:175], v[216:219], v[68:71]
	v_mfma_f32_16x16x32_bf16 v[64:67], v[180:183], v[216:219], v[64:67]
	s_setprio 0
	s_barrier
	s_add_i32 s88, s81, s62
	v_lshl_add_u64 v[192:193], s[42:43], 0, v[130:131]
	s_mov_b32 m0, s88
	ds_read_b128 v[184:187], v153 offset:16384
	ds_read_b128 v[188:191], v153 offset:17408
	ds_read_b128 v[196:199], v153 offset:18432
	ds_read_b128 v[200:203], v153 offset:19456
	ds_read_b128 v[204:207], v153 offset:20480
	ds_read_b128 v[208:211], v153 offset:21504
	ds_read_b128 v[212:215], v153 offset:22528
	ds_read_b128 v[216:219], v153 offset:23552
	global_load_lds_dwordx4 v[192:193], off
	s_add_i32 m0, s88, 0x2000
	s_add_u32 s88, s42, 0x40000
	v_lshl_add_u64 v[220:221], s[42:43], 0, v[134:135]
	s_addc_u32 s89, s43, 0
	s_add_i32 s90, s82, s62
	global_load_lds_dwordx4 v[220:221], off
	v_lshl_add_u64 v[222:223], s[88:89], 0, v[130:131]
	s_mov_b32 m0, s90
	v_lshl_add_u64 v[224:225], s[44:45], 0, v[132:133]
	global_load_lds_dwordx4 v[222:223], off
	v_lshl_add_u64 v[222:223], s[88:89], 0, v[134:135]
	s_add_i32 m0, s90, 0x2000
	s_nop 0
	global_load_lds_dwordx4 v[222:223], off
	v_lshl_add_u64 v[222:223], s[44:45], 0, v[128:129]
	s_waitcnt vmcnt(6)
	s_waitcnt lgkmcnt(0)
	s_barrier
	s_setprio 1
	s_waitcnt lgkmcnt(0)
	v_mfma_f32_16x16x32_bf16 v[60:63], v[144:147], v[184:187], v[60:63]
	v_mfma_f32_16x16x32_bf16 v[56:59], v[160:163], v[184:187], v[56:59]
	v_mfma_f32_16x16x32_bf16 v[44:47], v[144:147], v[196:199], v[44:47]
	v_mfma_f32_16x16x32_bf16 v[40:43], v[160:163], v[196:199], v[40:43]
	v_mfma_f32_16x16x32_bf16 v[28:31], v[144:147], v[204:207], v[28:31]
	v_mfma_f32_16x16x32_bf16 v[24:27], v[160:163], v[204:207], v[24:27]
	v_mfma_f32_16x16x32_bf16 v[12:15], v[144:147], v[212:215], v[12:15]
	v_mfma_f32_16x16x32_bf16 v[8:11], v[160:163], v[212:215], v[8:11]
	v_mfma_f32_16x16x32_bf16 v[60:63], v[156:159], v[188:191], v[60:63]
	v_mfma_f32_16x16x32_bf16 v[56:59], v[164:167], v[188:191], v[56:59]
	v_mfma_f32_16x16x32_bf16 v[44:47], v[156:159], v[200:203], v[44:47]
	v_mfma_f32_16x16x32_bf16 v[40:43], v[164:167], v[200:203], v[40:43]
	v_mfma_f32_16x16x32_bf16 v[28:31], v[156:159], v[208:211], v[28:31]
	v_mfma_f32_16x16x32_bf16 v[24:27], v[164:167], v[208:211], v[24:27]
	v_mfma_f32_16x16x32_bf16 v[12:15], v[156:159], v[216:219], v[12:15]
	v_mfma_f32_16x16x32_bf16 v[8:11], v[164:167], v[216:219], v[8:11]
	s_setprio 0
	s_setprio 1
	v_mfma_f32_16x16x32_bf16 v[52:55], v[168:171], v[184:187], v[52:55]
	v_mfma_f32_16x16x32_bf16 v[48:51], v[176:179], v[184:187], v[48:51]
	v_mfma_f32_16x16x32_bf16 v[36:39], v[168:171], v[196:199], v[36:39]
	v_mfma_f32_16x16x32_bf16 v[32:35], v[176:179], v[196:199], v[32:35]
	v_mfma_f32_16x16x32_bf16 v[20:23], v[168:171], v[204:207], v[20:23]
	v_mfma_f32_16x16x32_bf16 v[16:19], v[176:179], v[204:207], v[16:19]
	v_mfma_f32_16x16x32_bf16 v[4:7], v[168:171], v[212:215], v[4:7]
	v_mfma_f32_16x16x32_bf16 v[0:3], v[176:179], v[212:215], v[0:3]
	v_mfma_f32_16x16x32_bf16 v[52:55], v[172:175], v[188:191], v[52:55]
	v_mfma_f32_16x16x32_bf16 v[48:51], v[180:183], v[188:191], v[48:51]
	v_mfma_f32_16x16x32_bf16 v[36:39], v[172:175], v[200:203], v[36:39]
	v_mfma_f32_16x16x32_bf16 v[32:35], v[180:183], v[200:203], v[32:35]
	v_mfma_f32_16x16x32_bf16 v[20:23], v[172:175], v[208:211], v[20:23]
	v_mfma_f32_16x16x32_bf16 v[16:19], v[180:183], v[208:211], v[16:19]
	v_mfma_f32_16x16x32_bf16 v[4:7], v[172:175], v[216:219], v[4:7]
	v_mfma_f32_16x16x32_bf16 v[0:3], v[180:183], v[216:219], v[0:3]
	s_setprio 0
	s_barrier
	s_add_i32 s88, 0, 0x18000
	v_add_u32_e32 v155, s88, v149
	s_add_i32 s89, 0, 0x1c000
	ds_read_b128 v[144:147], v155
	ds_read_b128 v[156:159], v155 offset:1024
	ds_read_b128 v[160:163], v155 offset:2048
	ds_read_b128 v[164:167], v155 offset:3072
	v_add_u32_e32 v155, s89, v149
	ds_read_b128 v[168:171], v155
	ds_read_b128 v[172:175], v155 offset:1024
	ds_read_b128 v[176:179], v155 offset:2048
	ds_read_b128 v[180:183], v155 offset:3072
	s_add_u32 s44, s44, 0x40000
	s_addc_u32 s45, s45, 0
	v_lshl_add_u64 v[226:227], s[44:45], 0, v[128:129]
	ds_read_b128 v[184:187], v153 offset:32768
	ds_read_b128 v[188:191], v153 offset:33792
	ds_read_b128 v[196:199], v153 offset:34816
	ds_read_b128 v[200:203], v153 offset:35840
	ds_read_b128 v[204:207], v153 offset:36864
	ds_read_b128 v[208:211], v153 offset:37888
	ds_read_b128 v[212:215], v153 offset:38912
	ds_read_b128 v[216:219], v153 offset:39936
	s_mov_b32 m0, s63
	s_nop 0
	global_load_lds_dwordx4 v[222:223], off
	s_mov_b32 m0, s70
	s_nop 0
	global_load_lds_dwordx4 v[224:225], off
	s_mov_b32 m0, s71
	s_nop 0
	global_load_lds_dwordx4 v[226:227], off
	v_lshl_add_u64 v[226:227], s[44:45], 0, v[132:133]
	s_mov_b32 m0, s72
	s_nop 0
	global_load_lds_dwordx4 v[226:227], off
	s_waitcnt vmcnt(8)
	s_waitcnt lgkmcnt(0)
	s_barrier
	s_setprio 1
	s_waitcnt lgkmcnt(0)
	v_mfma_f32_16x16x32_bf16 v[124:127], v[144:147], v[184:187], v[124:127]
	v_mfma_f32_16x16x32_bf16 v[120:123], v[160:163], v[184:187], v[120:123]
	v_mfma_f32_16x16x32_bf16 v[108:111], v[144:147], v[196:199], v[108:111]
	v_mfma_f32_16x16x32_bf16 v[104:107], v[160:163], v[196:199], v[104:107]
	v_mfma_f32_16x16x32_bf16 v[92:95], v[144:147], v[204:207], v[92:95]
	v_mfma_f32_16x16x32_bf16 v[88:91], v[160:163], v[204:207], v[88:91]
	v_mfma_f32_16x16x32_bf16 v[76:79], v[144:147], v[212:215], v[76:79]
	v_mfma_f32_16x16x32_bf16 v[72:75], v[160:163], v[212:215], v[72:75]
	v_mfma_f32_16x16x32_bf16 v[124:127], v[156:159], v[188:191], v[124:127]
	v_mfma_f32_16x16x32_bf16 v[120:123], v[164:167], v[188:191], v[120:123]
	v_mfma_f32_16x16x32_bf16 v[108:111], v[156:159], v[200:203], v[108:111]
	v_mfma_f32_16x16x32_bf16 v[104:107], v[164:167], v[200:203], v[104:107]
	v_mfma_f32_16x16x32_bf16 v[92:95], v[156:159], v[208:211], v[92:95]
	v_mfma_f32_16x16x32_bf16 v[88:91], v[164:167], v[208:211], v[88:91]
	v_mfma_f32_16x16x32_bf16 v[76:79], v[156:159], v[216:219], v[76:79]
	v_mfma_f32_16x16x32_bf16 v[72:75], v[164:167], v[216:219], v[72:75]
	s_setprio 0
	s_setprio 1
	v_mfma_f32_16x16x32_bf16 v[116:119], v[168:171], v[184:187], v[116:119]
	v_mfma_f32_16x16x32_bf16 v[112:115], v[176:179], v[184:187], v[112:115]
	v_mfma_f32_16x16x32_bf16 v[100:103], v[168:171], v[196:199], v[100:103]
	v_mfma_f32_16x16x32_bf16 v[96:99], v[176:179], v[196:199], v[96:99]
	v_mfma_f32_16x16x32_bf16 v[84:87], v[168:171], v[204:207], v[84:87]
	v_mfma_f32_16x16x32_bf16 v[80:83], v[176:179], v[204:207], v[80:83]
	v_mfma_f32_16x16x32_bf16 v[68:71], v[168:171], v[212:215], v[68:71]
	v_mfma_f32_16x16x32_bf16 v[64:67], v[176:179], v[212:215], v[64:67]
	v_mfma_f32_16x16x32_bf16 v[116:119], v[172:175], v[188:191], v[116:119]
	v_mfma_f32_16x16x32_bf16 v[112:115], v[180:183], v[188:191], v[112:115]
	v_mfma_f32_16x16x32_bf16 v[100:103], v[172:175], v[200:203], v[100:103]
	v_mfma_f32_16x16x32_bf16 v[96:99], v[180:183], v[200:203], v[96:99]
	v_mfma_f32_16x16x32_bf16 v[84:87], v[172:175], v[208:211], v[84:87]
	v_mfma_f32_16x16x32_bf16 v[80:83], v[180:183], v[208:211], v[80:83]
	v_mfma_f32_16x16x32_bf16 v[68:71], v[172:175], v[216:219], v[68:71]
	v_mfma_f32_16x16x32_bf16 v[64:67], v[180:183], v[216:219], v[64:67]
	s_setprio 0
	s_barrier
	s_add_i32 s44, s88, s62
	v_lshl_add_u64 v[192:193], v[192:193], 0, s[24:25]
	s_mov_b32 m0, s44
	ds_read_b128 v[184:187], v153 offset:49152
	ds_read_b128 v[188:191], v153 offset:50176
	ds_read_b128 v[196:199], v153 offset:51200
	ds_read_b128 v[200:203], v153 offset:52224
	ds_read_b128 v[204:207], v153 offset:53248
	ds_read_b128 v[208:211], v153 offset:54272
	ds_read_b128 v[212:215], v153 offset:55296
	ds_read_b128 v[216:219], v153 offset:56320
	global_load_lds_dwordx4 v[192:193], off
	s_add_i32 m0, s44, 0x2000
	s_add_u32 s42, s42, 0x40080
	v_lshl_add_u64 v[192:193], v[220:221], 0, s[24:25]
	s_addc_u32 s43, s43, 0
	s_add_i32 s44, s89, s62
	global_load_lds_dwordx4 v[192:193], off
	v_lshl_add_u64 v[192:193], s[42:43], 0, v[130:131]
	s_mov_b32 m0, s44
	s_nop 0
	global_load_lds_dwordx4 v[192:193], off
	v_lshl_add_u64 v[192:193], s[42:43], 0, v[134:135]
	s_add_i32 m0, s44, 0x2000
	s_nop 0
	global_load_lds_dwordx4 v[192:193], off
	s_mov_b32 s99, 1
	s_waitcnt vmcnt(6)
	s_waitcnt lgkmcnt(0)
	s_barrier
	s_setprio 1
	s_waitcnt lgkmcnt(0)
	v_mfma_f32_16x16x32_bf16 v[60:63], v[144:147], v[184:187], v[60:63]
	v_mfma_f32_16x16x32_bf16 v[56:59], v[160:163], v[184:187], v[56:59]
	v_mfma_f32_16x16x32_bf16 v[44:47], v[144:147], v[196:199], v[44:47]
	v_mfma_f32_16x16x32_bf16 v[40:43], v[160:163], v[196:199], v[40:43]
	v_mfma_f32_16x16x32_bf16 v[28:31], v[144:147], v[204:207], v[28:31]
	v_mfma_f32_16x16x32_bf16 v[24:27], v[160:163], v[204:207], v[24:27]
	v_mfma_f32_16x16x32_bf16 v[12:15], v[144:147], v[212:215], v[12:15]
	v_mfma_f32_16x16x32_bf16 v[8:11], v[160:163], v[212:215], v[8:11]
	v_mfma_f32_16x16x32_bf16 v[60:63], v[156:159], v[188:191], v[60:63]
	v_mfma_f32_16x16x32_bf16 v[56:59], v[164:167], v[188:191], v[56:59]
	v_mfma_f32_16x16x32_bf16 v[44:47], v[156:159], v[200:203], v[44:47]
	v_mfma_f32_16x16x32_bf16 v[40:43], v[164:167], v[200:203], v[40:43]
	v_mfma_f32_16x16x32_bf16 v[28:31], v[156:159], v[208:211], v[28:31]
	v_mfma_f32_16x16x32_bf16 v[24:27], v[164:167], v[208:211], v[24:27]
	v_mfma_f32_16x16x32_bf16 v[12:15], v[156:159], v[216:219], v[12:15]
	v_mfma_f32_16x16x32_bf16 v[8:11], v[164:167], v[216:219], v[8:11]
	s_setprio 0
	s_setprio 1
	v_mfma_f32_16x16x32_bf16 v[52:55], v[168:171], v[184:187], v[52:55]
	v_mfma_f32_16x16x32_bf16 v[48:51], v[176:179], v[184:187], v[48:51]
	v_mfma_f32_16x16x32_bf16 v[36:39], v[168:171], v[196:199], v[36:39]
	v_mfma_f32_16x16x32_bf16 v[32:35], v[176:179], v[196:199], v[32:35]
	v_mfma_f32_16x16x32_bf16 v[20:23], v[168:171], v[204:207], v[20:23]
	v_mfma_f32_16x16x32_bf16 v[16:19], v[176:179], v[204:207], v[16:19]
	v_mfma_f32_16x16x32_bf16 v[4:7], v[168:171], v[212:215], v[4:7]
	v_mfma_f32_16x16x32_bf16 v[0:3], v[176:179], v[212:215], v[0:3]
	v_mfma_f32_16x16x32_bf16 v[52:55], v[172:175], v[188:191], v[52:55]
	v_mfma_f32_16x16x32_bf16 v[48:51], v[180:183], v[188:191], v[48:51]
	v_mfma_f32_16x16x32_bf16 v[36:39], v[172:175], v[200:203], v[36:39]
	v_mfma_f32_16x16x32_bf16 v[32:35], v[180:183], v[200:203], v[32:35]
	v_mfma_f32_16x16x32_bf16 v[20:23], v[172:175], v[208:211], v[20:23]
	v_mfma_f32_16x16x32_bf16 v[16:19], v[180:183], v[208:211], v[16:19]
	v_mfma_f32_16x16x32_bf16 v[4:7], v[172:175], v[216:219], v[4:7]
	v_mfma_f32_16x16x32_bf16 v[0:3], v[180:183], v[216:219], v[0:3]
	s_setprio 0
	s_barrier
	s_add_i32 s87, s87, 2
	s_add_u32 s40, s40, 0x100
	s_addc_u32 s41, s41, 0
	s_add_u32 s85, s85, 0x100
	s_addc_u32 s86, s86, 0
	s_cmp_gt_u32 s87, 13
	s_cbranch_scc0 .LBB0_1625
	v_lshl_add_u64 v[222:223], v[222:223], 0, s[24:25]
	s_mov_b32 m0, s78
	s_nop 0
	global_load_lds_dwordx4 v[222:223], off
	v_lshl_add_u64 v[224:225], v[224:225], 0, s[24:25]
	s_mov_b32 m0, s79
	s_nop 0
	global_load_lds_dwordx4 v[224:225], off
	s_and_b64 vcc, exec, s[26:27]
	s_cbranch_vccz .LBB0_1628
	s_barrier

.LBB0_1708:
	s_ashr_i32 s27, s26, 31
	s_lshl_b64 s[28:29], s[26:27], 19
	s_add_u32 s28, s43, s28
	s_addc_u32 s29, s44, s29
	s_and_b64 s[30:31], s[14:15], exec
	s_cselect_b32 s27, s29, s37
	s_cselect_b32 s80, s28, s36
	s_ashr_i32 s25, s24, 31
	s_lshl_b64 s[30:31], s[24:25], 19
	s_add_u32 s30, s45, s30
	s_addc_u32 s31, s51, s31
	s_and_b64 s[40:41], s[14:15], exec
	s_cselect_b32 s25, s31, s39
	s_cselect_b32 s81, s30, s38
	s_add_u32 s36, s36, 0x40080
	s_addc_u32 s37, s37, 0
	s_add_u32 s82, s38, 0x100
	v_mov_b32_e32 v8, 0
	s_addc_u32 s83, s39, 0
	s_mov_b32 s84, -2
	v_mov_b32_e32 v9, v8
	v_mov_b32_e32 v10, v8
	v_mov_b32_e32 v11, v8
	v_mov_b32_e32 v12, v8
	v_mov_b32_e32 v13, v8
	v_mov_b32_e32 v14, v8
	v_mov_b32_e32 v15, v8
	v_mov_b32_e32 v24, v8
	v_mov_b32_e32 v25, v8
	v_mov_b32_e32 v26, v8
	v_mov_b32_e32 v27, v8
	v_mov_b32_e32 v28, v8
	v_mov_b32_e32 v29, v8
	v_mov_b32_e32 v30, v8
	v_mov_b32_e32 v31, v8
	v_mov_b32_e32 v40, v8
	v_mov_b32_e32 v41, v8
	v_mov_b32_e32 v42, v8
	v_mov_b32_e32 v43, v8
	v_mov_b32_e32 v44, v8
	v_mov_b32_e32 v45, v8
	v_mov_b32_e32 v46, v8
	v_mov_b32_e32 v47, v8
	v_mov_b32_e32 v56, v8
	v_mov_b32_e32 v57, v8
	v_mov_b32_e32 v58, v8
	v_mov_b32_e32 v59, v8
	v_mov_b32_e32 v60, v8
	v_mov_b32_e32 v61, v8
	v_mov_b32_e32 v62, v8
	v_mov_b32_e32 v63, v8
	v_mov_b32_e32 v0, v8
	v_mov_b32_e32 v1, v8
	v_mov_b32_e32 v2, v8
	v_mov_b32_e32 v3, v8
	v_mov_b32_e32 v4, v8
	v_mov_b32_e32 v5, v8
	v_mov_b32_e32 v6, v8
	v_mov_b32_e32 v7, v8
	v_mov_b32_e32 v16, v8
	v_mov_b32_e32 v17, v8
	v_mov_b32_e32 v18, v8
	v_mov_b32_e32 v19, v8
	v_mov_b32_e32 v20, v8
	v_mov_b32_e32 v21, v8
	v_mov_b32_e32 v22, v8
	v_mov_b32_e32 v23, v8
	v_mov_b32_e32 v32, v8
	v_mov_b32_e32 v33, v8
	v_mov_b32_e32 v34, v8
	v_mov_b32_e32 v35, v8
	v_mov_b32_e32 v36, v8
	v_mov_b32_e32 v37, v8
	v_mov_b32_e32 v38, v8
	v_mov_b32_e32 v39, v8
	v_mov_b32_e32 v48, v8
	v_mov_b32_e32 v49, v8
	v_mov_b32_e32 v50, v8
	v_mov_b32_e32 v51, v8
	v_mov_b32_e32 v52, v8
	v_mov_b32_e32 v53, v8
	v_mov_b32_e32 v54, v8
	v_mov_b32_e32 v55, v8
	v_mov_b32_e32 v72, v8
	v_mov_b32_e32 v73, v8
	v_mov_b32_e32 v74, v8
	v_mov_b32_e32 v75, v8
	v_mov_b32_e32 v76, v8
	v_mov_b32_e32 v77, v8
	v_mov_b32_e32 v78, v8
	v_mov_b32_e32 v79, v8
	v_mov_b32_e32 v88, v8
	v_mov_b32_e32 v89, v8
	v_mov_b32_e32 v90, v8
	v_mov_b32_e32 v91, v8
	v_mov_b32_e32 v92, v8
	v_mov_b32_e32 v93, v8
	v_mov_b32_e32 v94, v8
	v_mov_b32_e32 v95, v8
	v_mov_b32_e32 v104, v8
	v_mov_b32_e32 v105, v8
	v_mov_b32_e32 v106, v8
	v_mov_b32_e32 v107, v8
	v_mov_b32_e32 v108, v8
	v_mov_b32_e32 v109, v8
	v_mov_b32_e32 v110, v8
	v_mov_b32_e32 v111, v8
	v_mov_b32_e32 v120, v8
	v_mov_b32_e32 v121, v8
	v_mov_b32_e32 v122, v8
	v_mov_b32_e32 v123, v8
	v_mov_b32_e32 v124, v8
	v_mov_b32_e32 v125, v8
	v_mov_b32_e32 v126, v8
	v_mov_b32_e32 v127, v8
	v_mov_b32_e32 v64, v8
	v_mov_b32_e32 v65, v8
	v_mov_b32_e32 v66, v8
	v_mov_b32_e32 v67, v8
	v_mov_b32_e32 v68, v8
	v_mov_b32_e32 v69, v8
	v_mov_b32_e32 v70, v8
	v_mov_b32_e32 v71, v8
	v_mov_b32_e32 v80, v8
	v_mov_b32_e32 v81, v8
	v_mov_b32_e32 v82, v8
	v_mov_b32_e32 v83, v8
	v_mov_b32_e32 v84, v8
	v_mov_b32_e32 v85, v8
	v_mov_b32_e32 v86, v8
	v_mov_b32_e32 v87, v8
	v_mov_b32_e32 v96, v8
	v_mov_b32_e32 v97, v8
	v_mov_b32_e32 v98, v8
	v_mov_b32_e32 v99, v8
	v_mov_b32_e32 v100, v8
	v_mov_b32_e32 v101, v8
	v_mov_b32_e32 v102, v8
	v_mov_b32_e32 v103, v8
	v_mov_b32_e32 v112, v8
	v_mov_b32_e32 v113, v8
	v_mov_b32_e32 v114, v8
	v_mov_b32_e32 v115, v8
	v_mov_b32_e32 v116, v8
	v_mov_b32_e32 v117, v8
	v_mov_b32_e32 v118, v8
	v_mov_b32_e32 v119, v8
	s_mov_b32 s99, 0
.LBB0_1709:
	ds_read_b128 v[154:157], v149
	ds_read_b128 v[158:161], v149 offset:1024
	ds_read_b128 v[162:165], v149 offset:2048
	ds_read_b128 v[166:169], v149 offset:3072
	ds_read_b128 v[170:173], v150
	ds_read_b128 v[174:177], v150 offset:1024
	ds_read_b128 v[178:181], v150 offset:2048
	ds_read_b128 v[182:185], v150 offset:3072
	s_add_u32 s38, s36, 0xfffc0080
	s_addc_u32 s39, s37, -1
	s_cmp_eq_u32 s84, 12
	s_cselect_b32 s41, s27, s39
	s_cselect_b32 s40, s80, s38
	s_cselect_b32 s39, s25, s83
	s_cselect_b32 s38, s81, s82
	v_lshl_add_u64 v[144:145], s[36:37], 0, v[136:137]
	ds_read_b128 v[186:189], v151
	ds_read_b128 v[190:193], v151 offset:1024
	ds_read_b128 v[196:199], v151 offset:2048
	ds_read_b128 v[200:203], v151 offset:3072
	ds_read_b128 v[204:207], v151 offset:4096
	ds_read_b128 v[208:211], v151 offset:5120
	ds_read_b128 v[212:215], v151 offset:6144
	ds_read_b128 v[216:219], v151 offset:7168
	s_cmp_eq_u32 s99, 0
	s_cbranch_scc1 .Lkb_first_12
	v_lshl_add_u64 v[222:223], v[222:223], 0, s[20:21]
	s_mov_b32 m0, s62
	s_nop 0
	global_load_lds_dwordx4 v[222:223], off
	v_lshl_add_u64 v[224:225], v[224:225], 0, s[20:21]
	s_mov_b32 m0, s63
	s_nop 0
	global_load_lds_dwordx4 v[224:225], off
	s_branch .Lkb_join_12
.Lkb_first_12:
	s_add_i32 m0, s35, 0xc000
	s_nop 0
	global_load_lds_dwordx4 v[144:145], off
	global_load_lds_dwordx4 v[144:145], off
.Lkb_join_12:
	s_add_i32 m0, s35, 0xc000
	s_nop 0
	global_load_lds_dwordx4 v[144:145], off
	v_lshl_add_u64 v[144:145], s[36:37], 0, v[138:139]
	s_add_i32 m0, s35, 0xe000
	s_nop 0
	global_load_lds_dwordx4 v[144:145], off
	s_waitcnt vmcnt(8)
	s_waitcnt lgkmcnt(0)
	s_barrier
	s_setprio 1
	s_waitcnt lgkmcnt(0)
	v_mfma_f32_16x16x32_bf16 v[116:119], v[154:157], v[186:189], v[116:119]
	v_mfma_f32_16x16x32_bf16 v[112:115], v[162:165], v[186:189], v[112:115]
	v_mfma_f32_16x16x32_bf16 v[100:103], v[154:157], v[196:199], v[100:103]
	v_mfma_f32_16x16x32_bf16 v[96:99], v[162:165], v[196:199], v[96:99]
	v_mfma_f32_16x16x32_bf16 v[84:87], v[154:157], v[204:207], v[84:87]
	v_mfma_f32_16x16x32_bf16 v[80:83], v[162:165], v[204:207], v[80:83]
	v_mfma_f32_16x16x32_bf16 v[68:71], v[154:157], v[212:215], v[68:71]
	v_mfma_f32_16x16x32_bf16 v[64:67], v[162:165], v[212:215], v[64:67]
	v_mfma_f32_16x16x32_bf16 v[116:119], v[158:161], v[190:193], v[116:119]
	v_mfma_f32_16x16x32_bf16 v[112:115], v[166:169], v[190:193], v[112:115]
	v_mfma_f32_16x16x32_bf16 v[100:103], v[158:161], v[200:203], v[100:103]
	v_mfma_f32_16x16x32_bf16 v[96:99], v[166:169], v[200:203], v[96:99]
	v_mfma_f32_16x16x32_bf16 v[84:87], v[158:161], v[208:211], v[84:87]
	v_mfma_f32_16x16x32_bf16 v[80:83], v[166:169], v[208:211], v[80:83]
	v_mfma_f32_16x16x32_bf16 v[68:71], v[158:161], v[216:219], v[68:71]
	v_mfma_f32_16x16x32_bf16 v[64:67], v[166:169], v[216:219], v[64:67]
	s_setprio 0
	s_setprio 1
	v_mfma_f32_16x16x32_bf16 v[124:127], v[170:173], v[186:189], v[124:127]
	v_mfma_f32_16x16x32_bf16 v[120:123], v[178:181], v[186:189], v[120:123]
	v_mfma_f32_16x16x32_bf16 v[108:111], v[170:173], v[196:199], v[108:111]
	v_mfma_f32_16x16x32_bf16 v[104:107], v[178:181], v[196:199], v[104:107]
	v_mfma_f32_16x16x32_bf16 v[92:95], v[170:173], v[204:207], v[92:95]
	v_mfma_f32_16x16x32_bf16 v[88:91], v[178:181], v[204:207], v[88:91]
	v_mfma_f32_16x16x32_bf16 v[76:79], v[170:173], v[212:215], v[76:79]
	v_mfma_f32_16x16x32_bf16 v[72:75], v[178:181], v[212:215], v[72:75]
	v_mfma_f32_16x16x32_bf16 v[124:127], v[174:177], v[190:193], v[124:127]
	v_mfma_f32_16x16x32_bf16 v[120:123], v[182:185], v[190:193], v[120:123]
	v_mfma_f32_16x16x32_bf16 v[108:111], v[174:177], v[200:203], v[108:111]
	v_mfma_f32_16x16x32_bf16 v[104:107], v[182:185], v[200:203], v[104:107]
	v_mfma_f32_16x16x32_bf16 v[92:95], v[174:177], v[208:211], v[92:95]
	v_mfma_f32_16x16x32_bf16 v[88:91], v[182:185], v[208:211], v[88:91]
	v_mfma_f32_16x16x32_bf16 v[76:79], v[174:177], v[216:219], v[76:79]
	v_mfma_f32_16x16x32_bf16 v[72:75], v[182:185], v[216:219], v[72:75]
	s_setprio 0
	s_barrier
	s_add_i32 s85, s71, s56
	v_lshl_add_u64 v[144:145], s[38:39], 0, v[132:133]
	s_mov_b32 m0, s85
	ds_read_b128 v[186:189], v151 offset:16384
	ds_read_b128 v[190:193], v151 offset:17408
	ds_read_b128 v[196:199], v151 offset:18432
	ds_read_b128 v[200:203], v151 offset:19456
	ds_read_b128 v[204:207], v151 offset:20480
	ds_read_b128 v[208:211], v151 offset:21504
	ds_read_b128 v[212:215], v151 offset:22528
	ds_read_b128 v[216:219], v151 offset:23552
	global_load_lds_dwordx4 v[144:145], off
	s_add_i32 m0, s85, 0x2000
	s_add_u32 s86, s38, 0x40000
	v_lshl_add_u64 v[220:221], s[38:39], 0, v[128:129]
	s_addc_u32 s87, s39, 0
	s_add_i32 s85, s72, s56
	global_load_lds_dwordx4 v[220:221], off
	v_lshl_add_u64 v[222:223], s[86:87], 0, v[132:133]
	s_mov_b32 m0, s85
	v_lshl_add_u64 v[224:225], s[40:41], 0, v[130:131]
	global_load_lds_dwordx4 v[222:223], off
	v_lshl_add_u64 v[222:223], s[86:87], 0, v[128:129]
	s_add_i32 m0, s85, 0x2000
	s_nop 0
	global_load_lds_dwordx4 v[222:223], off
	v_lshl_add_u64 v[222:223], s[40:41], 0, v[134:135]
	s_waitcnt vmcnt(6)
	s_waitcnt lgkmcnt(0)
	s_barrier
	s_setprio 1
	s_waitcnt lgkmcnt(0)
	v_mfma_f32_16x16x32_bf16 v[52:55], v[154:157], v[186:189], v[52:55]
	v_mfma_f32_16x16x32_bf16 v[48:51], v[162:165], v[186:189], v[48:51]
	v_mfma_f32_16x16x32_bf16 v[36:39], v[154:157], v[196:199], v[36:39]
	v_mfma_f32_16x16x32_bf16 v[32:35], v[162:165], v[196:199], v[32:35]
	v_mfma_f32_16x16x32_bf16 v[20:23], v[154:157], v[204:207], v[20:23]
	v_mfma_f32_16x16x32_bf16 v[16:19], v[162:165], v[204:207], v[16:19]
	v_mfma_f32_16x16x32_bf16 v[4:7], v[154:157], v[212:215], v[4:7]
	v_mfma_f32_16x16x32_bf16 v[0:3], v[162:165], v[212:215], v[0:3]
	v_mfma_f32_16x16x32_bf16 v[52:55], v[158:161], v[190:193], v[52:55]
	v_mfma_f32_16x16x32_bf16 v[48:51], v[166:169], v[190:193], v[48:51]
	v_mfma_f32_16x16x32_bf16 v[36:39], v[158:161], v[200:203], v[36:39]
	v_mfma_f32_16x16x32_bf16 v[32:35], v[166:169], v[200:203], v[32:35]
	v_mfma_f32_16x16x32_bf16 v[20:23], v[158:161], v[208:211], v[20:23]
	v_mfma_f32_16x16x32_bf16 v[16:19], v[166:169], v[208:211], v[16:19]
	v_mfma_f32_16x16x32_bf16 v[4:7], v[158:161], v[216:219], v[4:7]
	v_mfma_f32_16x16x32_bf16 v[0:3], v[166:169], v[216:219], v[0:3]
	s_setprio 0
	s_setprio 1
	v_mfma_f32_16x16x32_bf16 v[60:63], v[170:173], v[186:189], v[60:63]
	v_mfma_f32_16x16x32_bf16 v[56:59], v[178:181], v[186:189], v[56:59]
	v_mfma_f32_16x16x32_bf16 v[44:47], v[170:173], v[196:199], v[44:47]
	v_mfma_f32_16x16x32_bf16 v[40:43], v[178:181], v[196:199], v[40:43]
	v_mfma_f32_16x16x32_bf16 v[28:31], v[170:173], v[204:207], v[28:31]
	v_mfma_f32_16x16x32_bf16 v[24:27], v[178:181], v[204:207], v[24:27]
	v_mfma_f32_16x16x32_bf16 v[12:15], v[170:173], v[212:215], v[12:15]
	v_mfma_f32_16x16x32_bf16 v[8:11], v[178:181], v[212:215], v[8:11]
	v_mfma_f32_16x16x32_bf16 v[60:63], v[174:177], v[190:193], v[60:63]
	v_mfma_f32_16x16x32_bf16 v[56:59], v[182:185], v[190:193], v[56:59]
	v_mfma_f32_16x16x32_bf16 v[44:47], v[174:177], v[200:203], v[44:47]
	v_mfma_f32_16x16x32_bf16 v[40:43], v[182:185], v[200:203], v[40:43]
	v_mfma_f32_16x16x32_bf16 v[28:31], v[174:177], v[208:211], v[28:31]
	v_mfma_f32_16x16x32_bf16 v[24:27], v[182:185], v[208:211], v[24:27]
	v_mfma_f32_16x16x32_bf16 v[12:15], v[174:177], v[216:219], v[12:15]
	v_mfma_f32_16x16x32_bf16 v[8:11], v[182:185], v[216:219], v[8:11]
	s_setprio 0
	s_barrier
	s_add_i32 s85, 0, 0x18000
	v_add_u32_e32 v153, s85, v147
	s_add_i32 s86, 0, 0x1c000
	ds_read_b128 v[154:157], v153
	ds_read_b128 v[158:161], v153 offset:1024
	ds_read_b128 v[162:165], v153 offset:2048
	ds_read_b128 v[166:169], v153 offset:3072
	v_add_u32_e32 v153, s86, v147
	ds_read_b128 v[170:173], v153
	ds_read_b128 v[174:177], v153 offset:1024
	ds_read_b128 v[178:181], v153 offset:2048
	ds_read_b128 v[182:185], v153 offset:3072
	s_add_u32 s40, s40, 0x40000
	s_addc_u32 s41, s41, 0
	v_lshl_add_u64 v[226:227], s[40:41], 0, v[134:135]
	ds_read_b128 v[186:189], v151 offset:32768
	ds_read_b128 v[190:193], v151 offset:33792
	ds_read_b128 v[196:199], v151 offset:34816
	ds_read_b128 v[200:203], v151 offset:35840
	ds_read_b128 v[204:207], v151 offset:36864
	ds_read_b128 v[208:211], v151 offset:37888
	ds_read_b128 v[212:215], v151 offset:38912
	ds_read_b128 v[216:219], v151 offset:39936
	s_mov_b32 m0, s35
	s_nop 0
	global_load_lds_dwordx4 v[222:223], off
	s_mov_b32 m0, s58
	s_nop 0
	global_load_lds_dwordx4 v[224:225], off
	s_mov_b32 m0, s59
	s_nop 0
	global_load_lds_dwordx4 v[226:227], off
	v_lshl_add_u64 v[226:227], s[40:41], 0, v[130:131]
	s_mov_b32 m0, s60
	s_nop 0
	global_load_lds_dwordx4 v[226:227], off
	s_waitcnt vmcnt(8)
	s_waitcnt lgkmcnt(0)
	s_barrier
	s_setprio 1
	s_waitcnt lgkmcnt(0)
	v_mfma_f32_16x16x32_bf16 v[116:119], v[154:157], v[186:189], v[116:119]
	v_mfma_f32_16x16x32_bf16 v[112:115], v[162:165], v[186:189], v[112:115]
	v_mfma_f32_16x16x32_bf16 v[100:103], v[154:157], v[196:199], v[100:103]
	v_mfma_f32_16x16x32_bf16 v[96:99], v[162:165], v[196:199], v[96:99]
	v_mfma_f32_16x16x32_bf16 v[84:87], v[154:157], v[204:207], v[84:87]
	v_mfma_f32_16x16x32_bf16 v[80:83], v[162:165], v[204:207], v[80:83]
	v_mfma_f32_16x16x32_bf16 v[68:71], v[154:157], v[212:215], v[68:71]
	v_mfma_f32_16x16x32_bf16 v[64:67], v[162:165], v[212:215], v[64:67]
	v_mfma_f32_16x16x32_bf16 v[116:119], v[158:161], v[190:193], v[116:119]
	v_mfma_f32_16x16x32_bf16 v[112:115], v[166:169], v[190:193], v[112:115]
	v_mfma_f32_16x16x32_bf16 v[100:103], v[158:161], v[200:203], v[100:103]
	v_mfma_f32_16x16x32_bf16 v[96:99], v[166:169], v[200:203], v[96:99]
	v_mfma_f32_16x16x32_bf16 v[84:87], v[158:161], v[208:211], v[84:87]
	v_mfma_f32_16x16x32_bf16 v[80:83], v[166:169], v[208:211], v[80:83]
	v_mfma_f32_16x16x32_bf16 v[68:71], v[158:161], v[216:219], v[68:71]
	v_mfma_f32_16x16x32_bf16 v[64:67], v[166:169], v[216:219], v[64:67]
	s_setprio 0
	s_setprio 1
	v_mfma_f32_16x16x32_bf16 v[124:127], v[170:173], v[186:189], v[124:127]
	v_mfma_f32_16x16x32_bf16 v[120:123], v[178:181], v[186:189], v[120:123]
	v_mfma_f32_16x16x32_bf16 v[108:111], v[170:173], v[196:199], v[108:111]
	v_mfma_f32_16x16x32_bf16 v[104:107], v[178:181], v[196:199], v[104:107]
	v_mfma_f32_16x16x32_bf16 v[92:95], v[170:173], v[204:207], v[92:95]
	v_mfma_f32_16x16x32_bf16 v[88:91], v[178:181], v[204:207], v[88:91]
	v_mfma_f32_16x16x32_bf16 v[76:79], v[170:173], v[212:215], v[76:79]
	v_mfma_f32_16x16x32_bf16 v[72:75], v[178:181], v[212:215], v[72:75]
	v_mfma_f32_16x16x32_bf16 v[124:127], v[174:177], v[190:193], v[124:127]
	v_mfma_f32_16x16x32_bf16 v[120:123], v[182:185], v[190:193], v[120:123]
	v_mfma_f32_16x16x32_bf16 v[108:111], v[174:177], v[200:203], v[108:111]
	v_mfma_f32_16x16x32_bf16 v[104:107], v[182:185], v[200:203], v[104:107]
	v_mfma_f32_16x16x32_bf16 v[92:95], v[174:177], v[208:211], v[92:95]
	v_mfma_f32_16x16x32_bf16 v[88:91], v[182:185], v[208:211], v[88:91]
	v_mfma_f32_16x16x32_bf16 v[76:79], v[174:177], v[216:219], v[76:79]
	v_mfma_f32_16x16x32_bf16 v[72:75], v[182:185], v[216:219], v[72:75]
	s_setprio 0
	s_barrier
	s_add_i32 s40, s85, s56
	v_lshl_add_u64 v[144:145], v[144:145], 0, s[20:21]
	s_mov_b32 m0, s40
	ds_read_b128 v[186:189], v151 offset:49152
	ds_read_b128 v[190:193], v151 offset:50176
	ds_read_b128 v[196:199], v151 offset:51200
	ds_read_b128 v[200:203], v151 offset:52224
	ds_read_b128 v[204:207], v151 offset:53248
	ds_read_b128 v[208:211], v151 offset:54272
	ds_read_b128 v[212:215], v151 offset:55296
	ds_read_b128 v[216:219], v151 offset:56320
	global_load_lds_dwordx4 v[144:145], off
	s_add_i32 m0, s40, 0x2000
	s_add_u32 s38, s38, 0x40080
	v_lshl_add_u64 v[144:145], v[220:221], 0, s[20:21]
	s_addc_u32 s39, s39, 0
	s_add_i32 s40, s86, s56
	global_load_lds_dwordx4 v[144:145], off
	v_lshl_add_u64 v[144:145], s[38:39], 0, v[132:133]
	s_mov_b32 m0, s40
	s_nop 0
	global_load_lds_dwordx4 v[144:145], off
	v_lshl_add_u64 v[144:145], s[38:39], 0, v[128:129]
	s_add_i32 m0, s40, 0x2000
	s_nop 0
	global_load_lds_dwordx4 v[144:145], off
	s_mov_b32 s99, 1
	s_waitcnt vmcnt(6)
	s_waitcnt lgkmcnt(0)
	s_barrier
	s_setprio 1
	s_waitcnt lgkmcnt(0)
	v_mfma_f32_16x16x32_bf16 v[52:55], v[154:157], v[186:189], v[52:55]
	v_mfma_f32_16x16x32_bf16 v[48:51], v[162:165], v[186:189], v[48:51]
	v_mfma_f32_16x16x32_bf16 v[36:39], v[154:157], v[196:199], v[36:39]
	v_mfma_f32_16x16x32_bf16 v[32:35], v[162:165], v[196:199], v[32:35]
	v_mfma_f32_16x16x32_bf16 v[20:23], v[154:157], v[204:207], v[20:23]
	v_mfma_f32_16x16x32_bf16 v[16:19], v[162:165], v[204:207], v[16:19]
	v_mfma_f32_16x16x32_bf16 v[4:7], v[154:157], v[212:215], v[4:7]
	v_mfma_f32_16x16x32_bf16 v[0:3], v[162:165], v[212:215], v[0:3]
	v_mfma_f32_16x16x32_bf16 v[52:55], v[158:161], v[190:193], v[52:55]
	v_mfma_f32_16x16x32_bf16 v[48:51], v[166:169], v[190:193], v[48:51]
	v_mfma_f32_16x16x32_bf16 v[36:39], v[158:161], v[200:203], v[36:39]
	v_mfma_f32_16x16x32_bf16 v[32:35], v[166:169], v[200:203], v[32:35]
	v_mfma_f32_16x16x32_bf16 v[20:23], v[158:161], v[208:211], v[20:23]
	v_mfma_f32_16x16x32_bf16 v[16:19], v[166:169], v[208:211], v[16:19]
	v_mfma_f32_16x16x32_bf16 v[4:7], v[158:161], v[216:219], v[4:7]
	v_mfma_f32_16x16x32_bf16 v[0:3], v[166:169], v[216:219], v[0:3]
	s_setprio 0
	s_setprio 1
	v_mfma_f32_16x16x32_bf16 v[60:63], v[170:173], v[186:189], v[60:63]
	v_mfma_f32_16x16x32_bf16 v[56:59], v[178:181], v[186:189], v[56:59]
	v_mfma_f32_16x16x32_bf16 v[44:47], v[170:173], v[196:199], v[44:47]
	v_mfma_f32_16x16x32_bf16 v[40:43], v[178:181], v[196:199], v[40:43]
	v_mfma_f32_16x16x32_bf16 v[28:31], v[170:173], v[204:207], v[28:31]
	v_mfma_f32_16x16x32_bf16 v[24:27], v[178:181], v[204:207], v[24:27]
	v_mfma_f32_16x16x32_bf16 v[12:15], v[170:173], v[212:215], v[12:15]
	v_mfma_f32_16x16x32_bf16 v[8:11], v[178:181], v[212:215], v[8:11]
	v_mfma_f32_16x16x32_bf16 v[60:63], v[174:177], v[190:193], v[60:63]
	v_mfma_f32_16x16x32_bf16 v[56:59], v[182:185], v[190:193], v[56:59]
	v_mfma_f32_16x16x32_bf16 v[44:47], v[174:177], v[200:203], v[44:47]
	v_mfma_f32_16x16x32_bf16 v[40:43], v[182:185], v[200:203], v[40:43]
	v_mfma_f32_16x16x32_bf16 v[28:31], v[174:177], v[208:211], v[28:31]
	v_mfma_f32_16x16x32_bf16 v[24:27], v[182:185], v[208:211], v[24:27]
	v_mfma_f32_16x16x32_bf16 v[12:15], v[174:177], v[216:219], v[12:15]
	v_mfma_f32_16x16x32_bf16 v[8:11], v[182:185], v[216:219], v[8:11]
	s_setprio 0
	s_barrier
	s_add_i32 s84, s84, 2
	s_add_u32 s36, s36, 0x100
	s_addc_u32 s37, s37, 0
	s_add_u32 s82, s82, 0x100
	s_addc_u32 s83, s83, 0
	s_cmp_gt_u32 s84, 13
	s_cbranch_scc0 .LBB0_1709
	v_lshl_add_u64 v[222:223], v[222:223], 0, s[20:21]
	s_mov_b32 m0, s62
	s_nop 0
	global_load_lds_dwordx4 v[222:223], off
	v_lshl_add_u64 v[224:225], v[224:225], 0, s[20:21]
	s_mov_b32 m0, s63
	s_nop 0
	global_load_lds_dwordx4 v[224:225], off
	s_and_b64 vcc, exec, s[22:23]
	s_cbranch_vccz .LBB0_1712
	s_barrier

.LBB0_1790:
	s_add_u32 s83, s38, 0x100
	v_mov_b32_e32 v0, 0
	s_addc_u32 s84, s39, 0
	s_mov_b32 s85, -2
	s_waitcnt lgkmcnt(0)
	v_mov_b32_e32 v1, v0
	v_mov_b32_e32 v2, v0
	v_mov_b32_e32 v3, v0
	v_mov_b32_e32 v4, v0
	v_mov_b32_e32 v5, v0
	v_mov_b32_e32 v6, v0
	v_mov_b32_e32 v7, v0
	v_mov_b32_e32 v16, v0
	v_mov_b32_e32 v17, v0
	v_mov_b32_e32 v18, v0
	v_mov_b32_e32 v19, v0
	v_mov_b32_e32 v20, v0
	v_mov_b32_e32 v21, v0
	v_mov_b32_e32 v22, v0
	v_mov_b32_e32 v23, v0
	v_mov_b32_e32 v32, v0
	v_mov_b32_e32 v33, v0
	v_mov_b32_e32 v34, v0
	v_mov_b32_e32 v35, v0
	v_mov_b32_e32 v36, v0
	v_mov_b32_e32 v37, v0
	v_mov_b32_e32 v38, v0
	v_mov_b32_e32 v39, v0
	v_mov_b32_e32 v48, v0
	v_mov_b32_e32 v49, v0
	v_mov_b32_e32 v50, v0
	v_mov_b32_e32 v51, v0
	v_mov_b32_e32 v52, v0
	v_mov_b32_e32 v53, v0
	v_mov_b32_e32 v54, v0
	v_mov_b32_e32 v55, v0
	v_mov_b32_e32 v8, v0
	v_mov_b32_e32 v9, v0
	v_mov_b32_e32 v10, v0
	v_mov_b32_e32 v11, v0
	v_mov_b32_e32 v12, v0
	v_mov_b32_e32 v13, v0
	v_mov_b32_e32 v14, v0
	v_mov_b32_e32 v15, v0
	v_mov_b32_e32 v24, v0
	v_mov_b32_e32 v25, v0
	v_mov_b32_e32 v26, v0
	v_mov_b32_e32 v27, v0
	v_mov_b32_e32 v28, v0
	v_mov_b32_e32 v29, v0
	v_mov_b32_e32 v30, v0
	v_mov_b32_e32 v31, v0
	v_mov_b32_e32 v40, v0
	v_mov_b32_e32 v41, v0
	v_mov_b32_e32 v42, v0
	v_mov_b32_e32 v43, v0
	v_mov_b32_e32 v44, v0
	v_mov_b32_e32 v45, v0
	v_mov_b32_e32 v46, v0
	v_mov_b32_e32 v47, v0
	v_mov_b32_e32 v56, v0
	v_mov_b32_e32 v57, v0
	v_mov_b32_e32 v58, v0
	v_mov_b32_e32 v59, v0
	v_mov_b32_e32 v60, v0
	v_mov_b32_e32 v61, v0
	v_mov_b32_e32 v62, v0
	v_mov_b32_e32 v63, v0
	v_mov_b32_e32 v64, v0
	v_mov_b32_e32 v65, v0
	v_mov_b32_e32 v66, v0
	v_mov_b32_e32 v67, v0
	v_mov_b32_e32 v68, v0
	v_mov_b32_e32 v69, v0
	v_mov_b32_e32 v70, v0
	v_mov_b32_e32 v71, v0
	v_mov_b32_e32 v80, v0
	v_mov_b32_e32 v81, v0
	v_mov_b32_e32 v82, v0
	v_mov_b32_e32 v83, v0
	v_mov_b32_e32 v84, v0
	v_mov_b32_e32 v85, v0
	v_mov_b32_e32 v86, v0
	v_mov_b32_e32 v87, v0
	v_mov_b32_e32 v96, v0
	v_mov_b32_e32 v97, v0
	v_mov_b32_e32 v98, v0
	v_mov_b32_e32 v99, v0
	v_mov_b32_e32 v100, v0
	v_mov_b32_e32 v101, v0
	v_mov_b32_e32 v102, v0
	v_mov_b32_e32 v103, v0
	v_mov_b32_e32 v112, v0
	v_mov_b32_e32 v113, v0
	v_mov_b32_e32 v114, v0
	v_mov_b32_e32 v115, v0
	v_mov_b32_e32 v116, v0
	v_mov_b32_e32 v117, v0
	v_mov_b32_e32 v118, v0
	v_mov_b32_e32 v119, v0
	v_mov_b32_e32 v72, v0
	v_mov_b32_e32 v73, v0
	v_mov_b32_e32 v74, v0
	v_mov_b32_e32 v75, v0
	v_mov_b32_e32 v76, v0
	v_mov_b32_e32 v77, v0
	v_mov_b32_e32 v78, v0
	v_mov_b32_e32 v79, v0
	v_mov_b32_e32 v88, v0
	v_mov_b32_e32 v89, v0
	v_mov_b32_e32 v90, v0
	v_mov_b32_e32 v91, v0
	v_mov_b32_e32 v92, v0
	v_mov_b32_e32 v93, v0
	v_mov_b32_e32 v94, v0
	v_mov_b32_e32 v95, v0
	v_mov_b32_e32 v104, v0
	v_mov_b32_e32 v105, v0
	v_mov_b32_e32 v106, v0
	v_mov_b32_e32 v107, v0
	v_mov_b32_e32 v108, v0
	v_mov_b32_e32 v109, v0
	v_mov_b32_e32 v110, v0
	v_mov_b32_e32 v111, v0
	v_mov_b32_e32 v120, v0
	v_mov_b32_e32 v121, v0
	v_mov_b32_e32 v122, v0
	v_mov_b32_e32 v123, v0
	v_mov_b32_e32 v124, v0
	v_mov_b32_e32 v125, v0
	v_mov_b32_e32 v126, v0
	v_mov_b32_e32 v127, v0
	s_mov_b32 s99, 0
.LBB0_1791:
	ds_read_b128 v[144:147], v151
	ds_read_b128 v[156:159], v151 offset:1024
	ds_read_b128 v[160:163], v151 offset:2048
	ds_read_b128 v[164:167], v151 offset:3072
	ds_read_b128 v[168:171], v152
	ds_read_b128 v[172:175], v152 offset:1024
	ds_read_b128 v[176:179], v152 offset:2048
	ds_read_b128 v[180:183], v152 offset:3072
	s_add_u32 s38, s36, 0x100
	s_addc_u32 s39, s37, 0
	s_cmp_eq_u32 s85, 40
	s_cselect_b32 s43, s1, s39
	s_cselect_b32 s42, s0, s38
	s_cselect_b32 s41, s35, s84
	s_cselect_b32 s40, s34, s83
	v_lshl_add_u64 v[192:193], s[36:37], 0, v[136:137]
	ds_read_b128 v[184:187], v153
	ds_read_b128 v[188:191], v153 offset:1024
	ds_read_b128 v[196:199], v153 offset:2048
	ds_read_b128 v[200:203], v153 offset:3072
	ds_read_b128 v[204:207], v153 offset:4096
	ds_read_b128 v[208:211], v153 offset:5120
	ds_read_b128 v[212:215], v153 offset:6144
	ds_read_b128 v[216:219], v153 offset:7168
	s_cmp_eq_u32 s99, 0
	s_cbranch_scc1 .Lkb_first_13
	v_lshl_add_u64 v[222:223], v[222:223], 0, s[28:29]
	s_mov_b32 m0, s70
	s_nop 0
	global_load_lds_dwordx4 v[222:223], off
	v_lshl_add_u64 v[224:225], v[224:225], 0, s[28:29]
	s_mov_b32 m0, s71
	s_nop 0
	global_load_lds_dwordx4 v[224:225], off
	s_branch .Lkb_join_13
.Lkb_first_13:
	s_add_i32 m0, s59, 0xc000
	s_nop 0
	global_load_lds_dwordx4 v[192:193], off
	global_load_lds_dwordx4 v[192:193], off
.Lkb_join_13:
	s_add_i32 m0, s59, 0xc000
	s_nop 0
	global_load_lds_dwordx4 v[192:193], off
	v_lshl_add_u64 v[192:193], s[36:37], 0, v[138:139]
	s_add_i32 m0, s59, 0xe000
	s_nop 0
	global_load_lds_dwordx4 v[192:193], off
	s_waitcnt vmcnt(8)
	s_waitcnt lgkmcnt(0)
	s_barrier
	s_setprio 1
	s_waitcnt lgkmcnt(0)
	v_mfma_f32_16x16x32_bf16 v[124:127], v[144:147], v[184:187], v[124:127]
	v_mfma_f32_16x16x32_bf16 v[120:123], v[160:163], v[184:187], v[120:123]
	v_mfma_f32_16x16x32_bf16 v[108:111], v[144:147], v[196:199], v[108:111]
	v_mfma_f32_16x16x32_bf16 v[104:107], v[160:163], v[196:199], v[104:107]
	v_mfma_f32_16x16x32_bf16 v[92:95], v[144:147], v[204:207], v[92:95]
	v_mfma_f32_16x16x32_bf16 v[88:91], v[160:163], v[204:207], v[88:91]
	v_mfma_f32_16x16x32_bf16 v[76:79], v[144:147], v[212:215], v[76:79]
	v_mfma_f32_16x16x32_bf16 v[72:75], v[160:163], v[212:215], v[72:75]
	v_mfma_f32_16x16x32_bf16 v[124:127], v[156:159], v[188:191], v[124:127]
	v_mfma_f32_16x16x32_bf16 v[120:123], v[164:167], v[188:191], v[120:123]
	v_mfma_f32_16x16x32_bf16 v[108:111], v[156:159], v[200:203], v[108:111]
	v_mfma_f32_16x16x32_bf16 v[104:107], v[164:167], v[200:203], v[104:107]
	v_mfma_f32_16x16x32_bf16 v[92:95], v[156:159], v[208:211], v[92:95]
	v_mfma_f32_16x16x32_bf16 v[88:91], v[164:167], v[208:211], v[88:91]
	v_mfma_f32_16x16x32_bf16 v[76:79], v[156:159], v[216:219], v[76:79]
	v_mfma_f32_16x16x32_bf16 v[72:75], v[164:167], v[216:219], v[72:75]
	s_setprio 0
	s_setprio 1
	v_mfma_f32_16x16x32_bf16 v[116:119], v[168:171], v[184:187], v[116:119]
	v_mfma_f32_16x16x32_bf16 v[112:115], v[176:179], v[184:187], v[112:115]
	v_mfma_f32_16x16x32_bf16 v[100:103], v[168:171], v[196:199], v[100:103]
	v_mfma_f32_16x16x32_bf16 v[96:99], v[176:179], v[196:199], v[96:99]
	v_mfma_f32_16x16x32_bf16 v[84:87], v[168:171], v[204:207], v[84:87]
	v_mfma_f32_16x16x32_bf16 v[80:83], v[176:179], v[204:207], v[80:83]
	v_mfma_f32_16x16x32_bf16 v[68:71], v[168:171], v[212:215], v[68:71]
	v_mfma_f32_16x16x32_bf16 v[64:67], v[176:179], v[212:215], v[64:67]
	v_mfma_f32_16x16x32_bf16 v[116:119], v[172:175], v[188:191], v[116:119]
	v_mfma_f32_16x16x32_bf16 v[112:115], v[180:183], v[188:191], v[112:115]
	v_mfma_f32_16x16x32_bf16 v[100:103], v[172:175], v[200:203], v[100:103]
	v_mfma_f32_16x16x32_bf16 v[96:99], v[180:183], v[200:203], v[96:99]
	v_mfma_f32_16x16x32_bf16 v[84:87], v[172:175], v[208:211], v[84:87]
	v_mfma_f32_16x16x32_bf16 v[80:83], v[180:183], v[208:211], v[80:83]
	v_mfma_f32_16x16x32_bf16 v[68:71], v[172:175], v[216:219], v[68:71]
	v_mfma_f32_16x16x32_bf16 v[64:67], v[180:183], v[216:219], v[64:67]
	s_setprio 0
	s_barrier
	s_add_i32 s36, s73, s58
	v_lshl_add_u64 v[192:193], s[40:41], 0, v[130:131]
	s_mov_b32 m0, s36
	ds_read_b128 v[184:187], v153 offset:16384
	ds_read_b128 v[188:191], v153 offset:17408
	ds_read_b128 v[196:199], v153 offset:18432
	ds_read_b128 v[200:203], v153 offset:19456
	ds_read_b128 v[204:207], v153 offset:20480
	ds_read_b128 v[208:211], v153 offset:21504
	ds_read_b128 v[212:215], v153 offset:22528
	ds_read_b128 v[216:219], v153 offset:23552
	global_load_lds_dwordx4 v[192:193], off
	s_add_i32 m0, s36, 0x2000
	s_add_u32 s36, s40, 0xb0000
	v_lshl_add_u64 v[220:221], s[40:41], 0, v[134:135]
	s_addc_u32 s37, s41, 0
	s_add_i32 s86, s78, s58
	global_load_lds_dwordx4 v[220:221], off
	v_lshl_add_u64 v[222:223], s[36:37], 0, v[130:131]
	s_mov_b32 m0, s86
	v_lshl_add_u64 v[224:225], s[42:43], 0, v[132:133]
	global_load_lds_dwordx4 v[222:223], off
	v_lshl_add_u64 v[222:223], s[36:37], 0, v[134:135]
	s_add_i32 m0, s86, 0x2000
	s_nop 0
	global_load_lds_dwordx4 v[222:223], off
	v_lshl_add_u64 v[222:223], s[42:43], 0, v[128:129]
	s_waitcnt vmcnt(6)
	s_waitcnt lgkmcnt(0)
	s_barrier
	s_setprio 1
	s_waitcnt lgkmcnt(0)
	v_mfma_f32_16x16x32_bf16 v[60:63], v[144:147], v[184:187], v[60:63]
	v_mfma_f32_16x16x32_bf16 v[56:59], v[160:163], v[184:187], v[56:59]
	v_mfma_f32_16x16x32_bf16 v[44:47], v[144:147], v[196:199], v[44:47]
	v_mfma_f32_16x16x32_bf16 v[40:43], v[160:163], v[196:199], v[40:43]
	v_mfma_f32_16x16x32_bf16 v[28:31], v[144:147], v[204:207], v[28:31]
	v_mfma_f32_16x16x32_bf16 v[24:27], v[160:163], v[204:207], v[24:27]
	v_mfma_f32_16x16x32_bf16 v[12:15], v[144:147], v[212:215], v[12:15]
	v_mfma_f32_16x16x32_bf16 v[8:11], v[160:163], v[212:215], v[8:11]
	v_mfma_f32_16x16x32_bf16 v[60:63], v[156:159], v[188:191], v[60:63]
	v_mfma_f32_16x16x32_bf16 v[56:59], v[164:167], v[188:191], v[56:59]
	v_mfma_f32_16x16x32_bf16 v[44:47], v[156:159], v[200:203], v[44:47]
	v_mfma_f32_16x16x32_bf16 v[40:43], v[164:167], v[200:203], v[40:43]
	v_mfma_f32_16x16x32_bf16 v[28:31], v[156:159], v[208:211], v[28:31]
	v_mfma_f32_16x16x32_bf16 v[24:27], v[164:167], v[208:211], v[24:27]
	v_mfma_f32_16x16x32_bf16 v[12:15], v[156:159], v[216:219], v[12:15]
	v_mfma_f32_16x16x32_bf16 v[8:11], v[164:167], v[216:219], v[8:11]
	s_setprio 0
	s_setprio 1
	v_mfma_f32_16x16x32_bf16 v[52:55], v[168:171], v[184:187], v[52:55]
	v_mfma_f32_16x16x32_bf16 v[48:51], v[176:179], v[184:187], v[48:51]
	v_mfma_f32_16x16x32_bf16 v[36:39], v[168:171], v[196:199], v[36:39]
	v_mfma_f32_16x16x32_bf16 v[32:35], v[176:179], v[196:199], v[32:35]
	v_mfma_f32_16x16x32_bf16 v[20:23], v[168:171], v[204:207], v[20:23]
	v_mfma_f32_16x16x32_bf16 v[16:19], v[176:179], v[204:207], v[16:19]
	v_mfma_f32_16x16x32_bf16 v[4:7], v[168:171], v[212:215], v[4:7]
	v_mfma_f32_16x16x32_bf16 v[0:3], v[176:179], v[212:215], v[0:3]
	v_mfma_f32_16x16x32_bf16 v[52:55], v[172:175], v[188:191], v[52:55]
	v_mfma_f32_16x16x32_bf16 v[48:51], v[180:183], v[188:191], v[48:51]
	v_mfma_f32_16x16x32_bf16 v[36:39], v[172:175], v[200:203], v[36:39]
	v_mfma_f32_16x16x32_bf16 v[32:35], v[180:183], v[200:203], v[32:35]
	v_mfma_f32_16x16x32_bf16 v[20:23], v[172:175], v[208:211], v[20:23]
	v_mfma_f32_16x16x32_bf16 v[16:19], v[180:183], v[208:211], v[16:19]
	v_mfma_f32_16x16x32_bf16 v[4:7], v[172:175], v[216:219], v[4:7]
	v_mfma_f32_16x16x32_bf16 v[0:3], v[180:183], v[216:219], v[0:3]
	s_setprio 0
	s_barrier
	s_add_i32 s86, 0, 0x18000
	v_add_u32_e32 v155, s86, v149
	s_add_i32 s87, 0, 0x1c000
	ds_read_b128 v[144:147], v155
	ds_read_b128 v[156:159], v155 offset:1024
	ds_read_b128 v[160:163], v155 offset:2048
	ds_read_b128 v[164:167], v155 offset:3072
	v_add_u32_e32 v155, s87, v149
	ds_read_b128 v[168:171], v155
	ds_read_b128 v[172:175], v155 offset:1024
	ds_read_b128 v[176:179], v155 offset:2048
	ds_read_b128 v[180:183], v155 offset:3072
	s_add_u32 s36, s42, 0xb0000
	s_addc_u32 s37, s43, 0
	v_lshl_add_u64 v[226:227], s[36:37], 0, v[128:129]
	ds_read_b128 v[184:187], v153 offset:32768
	ds_read_b128 v[188:191], v153 offset:33792
	ds_read_b128 v[196:199], v153 offset:34816
	ds_read_b128 v[200:203], v153 offset:35840
	ds_read_b128 v[204:207], v153 offset:36864
	ds_read_b128 v[208:211], v153 offset:37888
	ds_read_b128 v[212:215], v153 offset:38912
	ds_read_b128 v[216:219], v153 offset:39936
	s_mov_b32 m0, s59
	s_nop 0
	global_load_lds_dwordx4 v[222:223], off
	s_mov_b32 m0, s60
	s_nop 0
	global_load_lds_dwordx4 v[224:225], off
	s_mov_b32 m0, s61
	s_nop 0
	global_load_lds_dwordx4 v[226:227], off
	v_lshl_add_u64 v[226:227], s[36:37], 0, v[132:133]
	s_mov_b32 m0, s62
	s_nop 0
	global_load_lds_dwordx4 v[226:227], off
	s_waitcnt vmcnt(8)
	s_waitcnt lgkmcnt(0)
	s_barrier
	s_setprio 1
	s_waitcnt lgkmcnt(0)
	v_mfma_f32_16x16x32_bf16 v[124:127], v[144:147], v[184:187], v[124:127]
	v_mfma_f32_16x16x32_bf16 v[120:123], v[160:163], v[184:187], v[120:123]
	v_mfma_f32_16x16x32_bf16 v[108:111], v[144:147], v[196:199], v[108:111]
	v_mfma_f32_16x16x32_bf16 v[104:107], v[160:163], v[196:199], v[104:107]
	v_mfma_f32_16x16x32_bf16 v[92:95], v[144:147], v[204:207], v[92:95]
	v_mfma_f32_16x16x32_bf16 v[88:91], v[160:163], v[204:207], v[88:91]
	v_mfma_f32_16x16x32_bf16 v[76:79], v[144:147], v[212:215], v[76:79]
	v_mfma_f32_16x16x32_bf16 v[72:75], v[160:163], v[212:215], v[72:75]
	v_mfma_f32_16x16x32_bf16 v[124:127], v[156:159], v[188:191], v[124:127]
	v_mfma_f32_16x16x32_bf16 v[120:123], v[164:167], v[188:191], v[120:123]
	v_mfma_f32_16x16x32_bf16 v[108:111], v[156:159], v[200:203], v[108:111]
	v_mfma_f32_16x16x32_bf16 v[104:107], v[164:167], v[200:203], v[104:107]
	v_mfma_f32_16x16x32_bf16 v[92:95], v[156:159], v[208:211], v[92:95]
	v_mfma_f32_16x16x32_bf16 v[88:91], v[164:167], v[208:211], v[88:91]
	v_mfma_f32_16x16x32_bf16 v[76:79], v[156:159], v[216:219], v[76:79]
	v_mfma_f32_16x16x32_bf16 v[72:75], v[164:167], v[216:219], v[72:75]
	s_setprio 0
	s_setprio 1
	v_mfma_f32_16x16x32_bf16 v[116:119], v[168:171], v[184:187], v[116:119]
	v_mfma_f32_16x16x32_bf16 v[112:115], v[176:179], v[184:187], v[112:115]
	v_mfma_f32_16x16x32_bf16 v[100:103], v[168:171], v[196:199], v[100:103]
	v_mfma_f32_16x16x32_bf16 v[96:99], v[176:179], v[196:199], v[96:99]
	v_mfma_f32_16x16x32_bf16 v[84:87], v[168:171], v[204:207], v[84:87]
	v_mfma_f32_16x16x32_bf16 v[80:83], v[176:179], v[204:207], v[80:83]
	v_mfma_f32_16x16x32_bf16 v[68:71], v[168:171], v[212:215], v[68:71]
	v_mfma_f32_16x16x32_bf16 v[64:67], v[176:179], v[212:215], v[64:67]
	v_mfma_f32_16x16x32_bf16 v[116:119], v[172:175], v[188:191], v[116:119]
	v_mfma_f32_16x16x32_bf16 v[112:115], v[180:183], v[188:191], v[112:115]
	v_mfma_f32_16x16x32_bf16 v[100:103], v[172:175], v[200:203], v[100:103]
	v_mfma_f32_16x16x32_bf16 v[96:99], v[180:183], v[200:203], v[96:99]
	v_mfma_f32_16x16x32_bf16 v[84:87], v[172:175], v[208:211], v[84:87]
	v_mfma_f32_16x16x32_bf16 v[80:83], v[180:183], v[208:211], v[80:83]
	v_mfma_f32_16x16x32_bf16 v[68:71], v[172:175], v[216:219], v[68:71]
	v_mfma_f32_16x16x32_bf16 v[64:67], v[180:183], v[216:219], v[64:67]
	s_setprio 0
	s_barrier
	s_add_i32 s36, s86, s58
	v_lshl_add_u64 v[192:193], v[192:193], 0, s[28:29]
	s_mov_b32 m0, s36
	ds_read_b128 v[184:187], v153 offset:49152
	ds_read_b128 v[188:191], v153 offset:50176
	ds_read_b128 v[196:199], v153 offset:51200
	ds_read_b128 v[200:203], v153 offset:52224
	ds_read_b128 v[204:207], v153 offset:53248
	ds_read_b128 v[208:211], v153 offset:54272
	ds_read_b128 v[212:215], v153 offset:55296
	ds_read_b128 v[216:219], v153 offset:56320
	global_load_lds_dwordx4 v[192:193], off
	s_add_i32 m0, s36, 0x2000
	s_add_u32 s36, s40, 0xb0080
	v_lshl_add_u64 v[192:193], v[220:221], 0, s[28:29]
	s_addc_u32 s37, s41, 0
	s_add_i32 s40, s87, s58
	global_load_lds_dwordx4 v[192:193], off
	v_lshl_add_u64 v[192:193], s[36:37], 0, v[130:131]
	s_mov_b32 m0, s40
	s_nop 0
	global_load_lds_dwordx4 v[192:193], off
	v_lshl_add_u64 v[192:193], s[36:37], 0, v[134:135]
	s_add_i32 m0, s40, 0x2000
	s_nop 0
	global_load_lds_dwordx4 v[192:193], off
	s_mov_b32 s99, 1
	s_waitcnt vmcnt(6)
	s_waitcnt lgkmcnt(0)
	s_barrier
	s_setprio 1
	s_waitcnt lgkmcnt(0)
	v_mfma_f32_16x16x32_bf16 v[60:63], v[144:147], v[184:187], v[60:63]
	v_mfma_f32_16x16x32_bf16 v[56:59], v[160:163], v[184:187], v[56:59]
	v_mfma_f32_16x16x32_bf16 v[44:47], v[144:147], v[196:199], v[44:47]
	v_mfma_f32_16x16x32_bf16 v[40:43], v[160:163], v[196:199], v[40:43]
	v_mfma_f32_16x16x32_bf16 v[28:31], v[144:147], v[204:207], v[28:31]
	v_mfma_f32_16x16x32_bf16 v[24:27], v[160:163], v[204:207], v[24:27]
	v_mfma_f32_16x16x32_bf16 v[12:15], v[144:147], v[212:215], v[12:15]
	v_mfma_f32_16x16x32_bf16 v[8:11], v[160:163], v[212:215], v[8:11]
	v_mfma_f32_16x16x32_bf16 v[60:63], v[156:159], v[188:191], v[60:63]
	v_mfma_f32_16x16x32_bf16 v[56:59], v[164:167], v[188:191], v[56:59]
	v_mfma_f32_16x16x32_bf16 v[44:47], v[156:159], v[200:203], v[44:47]
	v_mfma_f32_16x16x32_bf16 v[40:43], v[164:167], v[200:203], v[40:43]
	v_mfma_f32_16x16x32_bf16 v[28:31], v[156:159], v[208:211], v[28:31]
	v_mfma_f32_16x16x32_bf16 v[24:27], v[164:167], v[208:211], v[24:27]
	v_mfma_f32_16x16x32_bf16 v[12:15], v[156:159], v[216:219], v[12:15]
	v_mfma_f32_16x16x32_bf16 v[8:11], v[164:167], v[216:219], v[8:11]
	s_setprio 0
	s_setprio 1
	v_mfma_f32_16x16x32_bf16 v[52:55], v[168:171], v[184:187], v[52:55]
	v_mfma_f32_16x16x32_bf16 v[48:51], v[176:179], v[184:187], v[48:51]
	v_mfma_f32_16x16x32_bf16 v[36:39], v[168:171], v[196:199], v[36:39]
	v_mfma_f32_16x16x32_bf16 v[32:35], v[176:179], v[196:199], v[32:35]
	v_mfma_f32_16x16x32_bf16 v[20:23], v[168:171], v[204:207], v[20:23]
	v_mfma_f32_16x16x32_bf16 v[16:19], v[176:179], v[204:207], v[16:19]
	v_mfma_f32_16x16x32_bf16 v[4:7], v[168:171], v[212:215], v[4:7]
	v_mfma_f32_16x16x32_bf16 v[0:3], v[176:179], v[212:215], v[0:3]
	v_mfma_f32_16x16x32_bf16 v[52:55], v[172:175], v[188:191], v[52:55]
	v_mfma_f32_16x16x32_bf16 v[48:51], v[180:183], v[188:191], v[48:51]
	v_mfma_f32_16x16x32_bf16 v[36:39], v[172:175], v[200:203], v[36:39]
	v_mfma_f32_16x16x32_bf16 v[32:35], v[180:183], v[200:203], v[32:35]
	v_mfma_f32_16x16x32_bf16 v[20:23], v[172:175], v[208:211], v[20:23]
	v_mfma_f32_16x16x32_bf16 v[16:19], v[180:183], v[208:211], v[16:19]
	v_mfma_f32_16x16x32_bf16 v[4:7], v[172:175], v[216:219], v[4:7]
	v_mfma_f32_16x16x32_bf16 v[0:3], v[180:183], v[216:219], v[0:3]
	s_setprio 0
	s_barrier
	s_add_i32 s85, s85, 2
	s_add_u32 s83, s83, 0x100
	s_addc_u32 s84, s84, 0
	s_cmp_gt_u32 s85, 41
	s_mov_b64 s[36:37], s[38:39]
	s_cbranch_scc0 .LBB0_1791
	v_lshl_add_u64 v[222:223], v[222:223], 0, s[28:29]
	s_mov_b32 m0, s70
	s_nop 0
	global_load_lds_dwordx4 v[222:223], off
	v_lshl_add_u64 v[224:225], v[224:225], 0, s[28:29]
	s_mov_b32 m0, s71
	s_nop 0
	global_load_lds_dwordx4 v[224:225], off
	s_and_b64 vcc, exec, s[30:31]
	s_cbranch_vccz .LBB0_1794
	s_barrier

.LBB0_2141:
	s_add_u32 s81, s38, 0x100
	v_mov_b32_e32 v0, 0
	s_addc_u32 s82, s39, 0
	s_mov_b32 s83, -2
	s_waitcnt lgkmcnt(0)
	v_mov_b32_e32 v1, v0
	v_mov_b32_e32 v2, v0
	v_mov_b32_e32 v3, v0
	v_mov_b32_e32 v4, v0
	v_mov_b32_e32 v5, v0
	v_mov_b32_e32 v6, v0
	v_mov_b32_e32 v7, v0
	v_mov_b32_e32 v16, v0
	v_mov_b32_e32 v17, v0
	v_mov_b32_e32 v18, v0
	v_mov_b32_e32 v19, v0
	v_mov_b32_e32 v20, v0
	v_mov_b32_e32 v21, v0
	v_mov_b32_e32 v22, v0
	v_mov_b32_e32 v23, v0
	v_mov_b32_e32 v32, v0
	v_mov_b32_e32 v33, v0
	v_mov_b32_e32 v34, v0
	v_mov_b32_e32 v35, v0
	v_mov_b32_e32 v36, v0
	v_mov_b32_e32 v37, v0
	v_mov_b32_e32 v38, v0
	v_mov_b32_e32 v39, v0
	v_mov_b32_e32 v48, v0
	v_mov_b32_e32 v49, v0
	v_mov_b32_e32 v50, v0
	v_mov_b32_e32 v51, v0
	v_mov_b32_e32 v52, v0
	v_mov_b32_e32 v53, v0
	v_mov_b32_e32 v54, v0
	v_mov_b32_e32 v55, v0
	v_mov_b32_e32 v8, v0
	v_mov_b32_e32 v9, v0
	v_mov_b32_e32 v10, v0
	v_mov_b32_e32 v11, v0
	v_mov_b32_e32 v12, v0
	v_mov_b32_e32 v13, v0
	v_mov_b32_e32 v14, v0
	v_mov_b32_e32 v15, v0
	v_mov_b32_e32 v24, v0
	v_mov_b32_e32 v25, v0
	v_mov_b32_e32 v26, v0
	v_mov_b32_e32 v27, v0
	v_mov_b32_e32 v28, v0
	v_mov_b32_e32 v29, v0
	v_mov_b32_e32 v30, v0
	v_mov_b32_e32 v31, v0
	v_mov_b32_e32 v40, v0
	v_mov_b32_e32 v41, v0
	v_mov_b32_e32 v42, v0
	v_mov_b32_e32 v43, v0
	v_mov_b32_e32 v44, v0
	v_mov_b32_e32 v45, v0
	v_mov_b32_e32 v46, v0
	v_mov_b32_e32 v47, v0
	v_mov_b32_e32 v56, v0
	v_mov_b32_e32 v57, v0
	v_mov_b32_e32 v58, v0
	v_mov_b32_e32 v59, v0
	v_mov_b32_e32 v60, v0
	v_mov_b32_e32 v61, v0
	v_mov_b32_e32 v62, v0
	v_mov_b32_e32 v63, v0
	v_mov_b32_e32 v64, v0
	v_mov_b32_e32 v65, v0
	v_mov_b32_e32 v66, v0
	v_mov_b32_e32 v67, v0
	v_mov_b32_e32 v68, v0
	v_mov_b32_e32 v69, v0
	v_mov_b32_e32 v70, v0
	v_mov_b32_e32 v71, v0
	v_mov_b32_e32 v80, v0
	v_mov_b32_e32 v81, v0
	v_mov_b32_e32 v82, v0
	v_mov_b32_e32 v83, v0
	v_mov_b32_e32 v84, v0
	v_mov_b32_e32 v85, v0
	v_mov_b32_e32 v86, v0
	v_mov_b32_e32 v87, v0
	v_mov_b32_e32 v96, v0
	v_mov_b32_e32 v97, v0
	v_mov_b32_e32 v98, v0
	v_mov_b32_e32 v99, v0
	v_mov_b32_e32 v100, v0
	v_mov_b32_e32 v101, v0
	v_mov_b32_e32 v102, v0
	v_mov_b32_e32 v103, v0
	v_mov_b32_e32 v112, v0
	v_mov_b32_e32 v113, v0
	v_mov_b32_e32 v114, v0
	v_mov_b32_e32 v115, v0
	v_mov_b32_e32 v116, v0
	v_mov_b32_e32 v117, v0
	v_mov_b32_e32 v118, v0
	v_mov_b32_e32 v119, v0
	v_mov_b32_e32 v72, v0
	v_mov_b32_e32 v73, v0
	v_mov_b32_e32 v74, v0
	v_mov_b32_e32 v75, v0
	v_mov_b32_e32 v76, v0
	v_mov_b32_e32 v77, v0
	v_mov_b32_e32 v78, v0
	v_mov_b32_e32 v79, v0
	v_mov_b32_e32 v88, v0
	v_mov_b32_e32 v89, v0
	v_mov_b32_e32 v90, v0
	v_mov_b32_e32 v91, v0
	v_mov_b32_e32 v92, v0
	v_mov_b32_e32 v93, v0
	v_mov_b32_e32 v94, v0
	v_mov_b32_e32 v95, v0
	v_mov_b32_e32 v104, v0
	v_mov_b32_e32 v105, v0
	v_mov_b32_e32 v106, v0
	v_mov_b32_e32 v107, v0
	v_mov_b32_e32 v108, v0
	v_mov_b32_e32 v109, v0
	v_mov_b32_e32 v110, v0
	v_mov_b32_e32 v111, v0
	v_mov_b32_e32 v120, v0
	v_mov_b32_e32 v121, v0
	v_mov_b32_e32 v122, v0
	v_mov_b32_e32 v123, v0
	v_mov_b32_e32 v124, v0
	v_mov_b32_e32 v125, v0
	v_mov_b32_e32 v126, v0
	v_mov_b32_e32 v127, v0
	s_mov_b32 s99, 0
.LBB0_2142:
	ds_read_b128 v[144:147], v151
	ds_read_b128 v[156:159], v151 offset:1024
	ds_read_b128 v[160:163], v151 offset:2048
	ds_read_b128 v[164:167], v151 offset:3072
	ds_read_b128 v[168:171], v152
	ds_read_b128 v[172:175], v152 offset:1024
	ds_read_b128 v[176:179], v152 offset:2048
	ds_read_b128 v[180:183], v152 offset:3072
	s_add_u32 s38, s36, 0x100
	s_addc_u32 s39, s37, 0
	s_cmp_eq_u32 s83, 40
	s_cselect_b32 s43, s1, s39
	s_cselect_b32 s42, s0, s38
	s_cselect_b32 s41, s35, s82
	s_cselect_b32 s40, s34, s81
	v_lshl_add_u64 v[192:193], s[36:37], 0, v[136:137]
	ds_read_b128 v[184:187], v153
	ds_read_b128 v[188:191], v153 offset:1024
	ds_read_b128 v[196:199], v153 offset:2048
	ds_read_b128 v[200:203], v153 offset:3072
	ds_read_b128 v[204:207], v153 offset:4096
	ds_read_b128 v[208:211], v153 offset:5120
	ds_read_b128 v[212:215], v153 offset:6144
	ds_read_b128 v[216:219], v153 offset:7168
	s_cmp_eq_u32 s99, 0
	s_cbranch_scc1 .Lkb_first_15
	v_lshl_add_u64 v[222:223], v[222:223], 0, s[28:29]
	s_mov_b32 m0, s62
	s_nop 0
	global_load_lds_dwordx4 v[222:223], off
	v_lshl_add_u64 v[224:225], v[224:225], 0, s[28:29]
	s_mov_b32 m0, s63
	s_nop 0
	global_load_lds_dwordx4 v[224:225], off
	s_branch .Lkb_join_15
.Lkb_first_15:
	s_add_i32 m0, s57, 0xc000
	s_nop 0
	global_load_lds_dwordx4 v[192:193], off
	global_load_lds_dwordx4 v[192:193], off
.Lkb_join_15:
	s_add_i32 m0, s57, 0xc000
	s_nop 0
	global_load_lds_dwordx4 v[192:193], off
	v_lshl_add_u64 v[192:193], s[36:37], 0, v[138:139]
	s_add_i32 m0, s57, 0xe000
	s_nop 0
	global_load_lds_dwordx4 v[192:193], off
	s_waitcnt vmcnt(8)
	s_waitcnt lgkmcnt(0)
	s_barrier
	s_setprio 1
	s_waitcnt lgkmcnt(0)
	v_mfma_f32_16x16x32_bf16 v[124:127], v[144:147], v[184:187], v[124:127]
	v_mfma_f32_16x16x32_bf16 v[120:123], v[160:163], v[184:187], v[120:123]
	v_mfma_f32_16x16x32_bf16 v[108:111], v[144:147], v[196:199], v[108:111]
	v_mfma_f32_16x16x32_bf16 v[104:107], v[160:163], v[196:199], v[104:107]
	v_mfma_f32_16x16x32_bf16 v[92:95], v[144:147], v[204:207], v[92:95]
	v_mfma_f32_16x16x32_bf16 v[88:91], v[160:163], v[204:207], v[88:91]
	v_mfma_f32_16x16x32_bf16 v[76:79], v[144:147], v[212:215], v[76:79]
	v_mfma_f32_16x16x32_bf16 v[72:75], v[160:163], v[212:215], v[72:75]
	v_mfma_f32_16x16x32_bf16 v[124:127], v[156:159], v[188:191], v[124:127]
	v_mfma_f32_16x16x32_bf16 v[120:123], v[164:167], v[188:191], v[120:123]
	v_mfma_f32_16x16x32_bf16 v[108:111], v[156:159], v[200:203], v[108:111]
	v_mfma_f32_16x16x32_bf16 v[104:107], v[164:167], v[200:203], v[104:107]
	v_mfma_f32_16x16x32_bf16 v[92:95], v[156:159], v[208:211], v[92:95]
	v_mfma_f32_16x16x32_bf16 v[88:91], v[164:167], v[208:211], v[88:91]
	v_mfma_f32_16x16x32_bf16 v[76:79], v[156:159], v[216:219], v[76:79]
	v_mfma_f32_16x16x32_bf16 v[72:75], v[164:167], v[216:219], v[72:75]
	s_setprio 0
	s_setprio 1
	v_mfma_f32_16x16x32_bf16 v[116:119], v[168:171], v[184:187], v[116:119]
	v_mfma_f32_16x16x32_bf16 v[112:115], v[176:179], v[184:187], v[112:115]
	v_mfma_f32_16x16x32_bf16 v[100:103], v[168:171], v[196:199], v[100:103]
	v_mfma_f32_16x16x32_bf16 v[96:99], v[176:179], v[196:199], v[96:99]
	v_mfma_f32_16x16x32_bf16 v[84:87], v[168:171], v[204:207], v[84:87]
	v_mfma_f32_16x16x32_bf16 v[80:83], v[176:179], v[204:207], v[80:83]
	v_mfma_f32_16x16x32_bf16 v[68:71], v[168:171], v[212:215], v[68:71]
	v_mfma_f32_16x16x32_bf16 v[64:67], v[176:179], v[212:215], v[64:67]
	v_mfma_f32_16x16x32_bf16 v[116:119], v[172:175], v[188:191], v[116:119]
	v_mfma_f32_16x16x32_bf16 v[112:115], v[180:183], v[188:191], v[112:115]
	v_mfma_f32_16x16x32_bf16 v[100:103], v[172:175], v[200:203], v[100:103]
	v_mfma_f32_16x16x32_bf16 v[96:99], v[180:183], v[200:203], v[96:99]
	v_mfma_f32_16x16x32_bf16 v[84:87], v[172:175], v[208:211], v[84:87]
	v_mfma_f32_16x16x32_bf16 v[80:83], v[180:183], v[208:211], v[80:83]
	v_mfma_f32_16x16x32_bf16 v[68:71], v[172:175], v[216:219], v[68:71]
	v_mfma_f32_16x16x32_bf16 v[64:67], v[180:183], v[216:219], v[64:67]
	s_setprio 0
	s_barrier
	s_add_i32 s36, s71, s56
	v_lshl_add_u64 v[192:193], s[40:41], 0, v[130:131]
	s_mov_b32 m0, s36
	ds_read_b128 v[184:187], v153 offset:16384
	ds_read_b128 v[188:191], v153 offset:17408
	ds_read_b128 v[196:199], v153 offset:18432
	ds_read_b128 v[200:203], v153 offset:19456
	ds_read_b128 v[204:207], v153 offset:20480
	ds_read_b128 v[208:211], v153 offset:21504
	ds_read_b128 v[212:215], v153 offset:22528
	ds_read_b128 v[216:219], v153 offset:23552
	global_load_lds_dwordx4 v[192:193], off
	s_add_i32 m0, s36, 0x2000
	s_add_u32 s36, s40, 0xb0000
	v_lshl_add_u64 v[220:221], s[40:41], 0, v[134:135]
	s_addc_u32 s37, s41, 0
	s_add_i32 s84, s72, s56
	global_load_lds_dwordx4 v[220:221], off
	v_lshl_add_u64 v[222:223], s[36:37], 0, v[130:131]
	s_mov_b32 m0, s84
	v_lshl_add_u64 v[224:225], s[42:43], 0, v[132:133]
	global_load_lds_dwordx4 v[222:223], off
	v_lshl_add_u64 v[222:223], s[36:37], 0, v[134:135]
	s_add_i32 m0, s84, 0x2000
	s_nop 0
	global_load_lds_dwordx4 v[222:223], off
	v_lshl_add_u64 v[222:223], s[42:43], 0, v[128:129]
	s_waitcnt vmcnt(6)
	s_waitcnt lgkmcnt(0)
	s_barrier
	s_setprio 1
	s_waitcnt lgkmcnt(0)
	v_mfma_f32_16x16x32_bf16 v[60:63], v[144:147], v[184:187], v[60:63]
	v_mfma_f32_16x16x32_bf16 v[56:59], v[160:163], v[184:187], v[56:59]
	v_mfma_f32_16x16x32_bf16 v[44:47], v[144:147], v[196:199], v[44:47]
	v_mfma_f32_16x16x32_bf16 v[40:43], v[160:163], v[196:199], v[40:43]
	v_mfma_f32_16x16x32_bf16 v[28:31], v[144:147], v[204:207], v[28:31]
	v_mfma_f32_16x16x32_bf16 v[24:27], v[160:163], v[204:207], v[24:27]
	v_mfma_f32_16x16x32_bf16 v[12:15], v[144:147], v[212:215], v[12:15]
	v_mfma_f32_16x16x32_bf16 v[8:11], v[160:163], v[212:215], v[8:11]
	v_mfma_f32_16x16x32_bf16 v[60:63], v[156:159], v[188:191], v[60:63]
	v_mfma_f32_16x16x32_bf16 v[56:59], v[164:167], v[188:191], v[56:59]
	v_mfma_f32_16x16x32_bf16 v[44:47], v[156:159], v[200:203], v[44:47]
	v_mfma_f32_16x16x32_bf16 v[40:43], v[164:167], v[200:203], v[40:43]
	v_mfma_f32_16x16x32_bf16 v[28:31], v[156:159], v[208:211], v[28:31]
	v_mfma_f32_16x16x32_bf16 v[24:27], v[164:167], v[208:211], v[24:27]
	v_mfma_f32_16x16x32_bf16 v[12:15], v[156:159], v[216:219], v[12:15]
	v_mfma_f32_16x16x32_bf16 v[8:11], v[164:167], v[216:219], v[8:11]
	s_setprio 0
	s_setprio 1
	v_mfma_f32_16x16x32_bf16 v[52:55], v[168:171], v[184:187], v[52:55]
	v_mfma_f32_16x16x32_bf16 v[48:51], v[176:179], v[184:187], v[48:51]
	v_mfma_f32_16x16x32_bf16 v[36:39], v[168:171], v[196:199], v[36:39]
	v_mfma_f32_16x16x32_bf16 v[32:35], v[176:179], v[196:199], v[32:35]
	v_mfma_f32_16x16x32_bf16 v[20:23], v[168:171], v[204:207], v[20:23]
	v_mfma_f32_16x16x32_bf16 v[16:19], v[176:179], v[204:207], v[16:19]
	v_mfma_f32_16x16x32_bf16 v[4:7], v[168:171], v[212:215], v[4:7]
	v_mfma_f32_16x16x32_bf16 v[0:3], v[176:179], v[212:215], v[0:3]
	v_mfma_f32_16x16x32_bf16 v[52:55], v[172:175], v[188:191], v[52:55]
	v_mfma_f32_16x16x32_bf16 v[48:51], v[180:183], v[188:191], v[48:51]
	v_mfma_f32_16x16x32_bf16 v[36:39], v[172:175], v[200:203], v[36:39]
	v_mfma_f32_16x16x32_bf16 v[32:35], v[180:183], v[200:203], v[32:35]
	v_mfma_f32_16x16x32_bf16 v[20:23], v[172:175], v[208:211], v[20:23]
	v_mfma_f32_16x16x32_bf16 v[16:19], v[180:183], v[208:211], v[16:19]
	v_mfma_f32_16x16x32_bf16 v[4:7], v[172:175], v[216:219], v[4:7]
	v_mfma_f32_16x16x32_bf16 v[0:3], v[180:183], v[216:219], v[0:3]
	s_setprio 0
	s_barrier
	s_add_i32 s84, 0, 0x18000
	v_add_u32_e32 v155, s84, v149
	s_add_i32 s85, 0, 0x1c000
	ds_read_b128 v[144:147], v155
	ds_read_b128 v[156:159], v155 offset:1024
	ds_read_b128 v[160:163], v155 offset:2048
	ds_read_b128 v[164:167], v155 offset:3072
	v_add_u32_e32 v155, s85, v149
	ds_read_b128 v[168:171], v155
	ds_read_b128 v[172:175], v155 offset:1024
	ds_read_b128 v[176:179], v155 offset:2048
	ds_read_b128 v[180:183], v155 offset:3072
	s_add_u32 s36, s42, 0xb0000
	s_addc_u32 s37, s43, 0
	v_lshl_add_u64 v[226:227], s[36:37], 0, v[128:129]
	ds_read_b128 v[184:187], v153 offset:32768
	ds_read_b128 v[188:191], v153 offset:33792
	ds_read_b128 v[196:199], v153 offset:34816
	ds_read_b128 v[200:203], v153 offset:35840
	ds_read_b128 v[204:207], v153 offset:36864
	ds_read_b128 v[208:211], v153 offset:37888
	ds_read_b128 v[212:215], v153 offset:38912
	ds_read_b128 v[216:219], v153 offset:39936
	s_mov_b32 m0, s57
	s_nop 0
	global_load_lds_dwordx4 v[222:223], off
	s_mov_b32 m0, s58
	s_nop 0
	global_load_lds_dwordx4 v[224:225], off
	s_mov_b32 m0, s59
	s_nop 0
	global_load_lds_dwordx4 v[226:227], off
	v_lshl_add_u64 v[226:227], s[36:37], 0, v[132:133]
	s_mov_b32 m0, s60
	s_nop 0
	global_load_lds_dwordx4 v[226:227], off
	s_waitcnt vmcnt(8)
	s_waitcnt lgkmcnt(0)
	s_barrier
	s_setprio 1
	s_waitcnt lgkmcnt(0)
	v_mfma_f32_16x16x32_bf16 v[124:127], v[144:147], v[184:187], v[124:127]
	v_mfma_f32_16x16x32_bf16 v[120:123], v[160:163], v[184:187], v[120:123]
	v_mfma_f32_16x16x32_bf16 v[108:111], v[144:147], v[196:199], v[108:111]
	v_mfma_f32_16x16x32_bf16 v[104:107], v[160:163], v[196:199], v[104:107]
	v_mfma_f32_16x16x32_bf16 v[92:95], v[144:147], v[204:207], v[92:95]
	v_mfma_f32_16x16x32_bf16 v[88:91], v[160:163], v[204:207], v[88:91]
	v_mfma_f32_16x16x32_bf16 v[76:79], v[144:147], v[212:215], v[76:79]
	v_mfma_f32_16x16x32_bf16 v[72:75], v[160:163], v[212:215], v[72:75]
	v_mfma_f32_16x16x32_bf16 v[124:127], v[156:159], v[188:191], v[124:127]
	v_mfma_f32_16x16x32_bf16 v[120:123], v[164:167], v[188:191], v[120:123]
	v_mfma_f32_16x16x32_bf16 v[108:111], v[156:159], v[200:203], v[108:111]
	v_mfma_f32_16x16x32_bf16 v[104:107], v[164:167], v[200:203], v[104:107]
	v_mfma_f32_16x16x32_bf16 v[92:95], v[156:159], v[208:211], v[92:95]
	v_mfma_f32_16x16x32_bf16 v[88:91], v[164:167], v[208:211], v[88:91]
	v_mfma_f32_16x16x32_bf16 v[76:79], v[156:159], v[216:219], v[76:79]
	v_mfma_f32_16x16x32_bf16 v[72:75], v[164:167], v[216:219], v[72:75]
	s_setprio 0
	s_setprio 1
	v_mfma_f32_16x16x32_bf16 v[116:119], v[168:171], v[184:187], v[116:119]
	v_mfma_f32_16x16x32_bf16 v[112:115], v[176:179], v[184:187], v[112:115]
	v_mfma_f32_16x16x32_bf16 v[100:103], v[168:171], v[196:199], v[100:103]
	v_mfma_f32_16x16x32_bf16 v[96:99], v[176:179], v[196:199], v[96:99]
	v_mfma_f32_16x16x32_bf16 v[84:87], v[168:171], v[204:207], v[84:87]
	v_mfma_f32_16x16x32_bf16 v[80:83], v[176:179], v[204:207], v[80:83]
	v_mfma_f32_16x16x32_bf16 v[68:71], v[168:171], v[212:215], v[68:71]
	v_mfma_f32_16x16x32_bf16 v[64:67], v[176:179], v[212:215], v[64:67]
	v_mfma_f32_16x16x32_bf16 v[116:119], v[172:175], v[188:191], v[116:119]
	v_mfma_f32_16x16x32_bf16 v[112:115], v[180:183], v[188:191], v[112:115]
	v_mfma_f32_16x16x32_bf16 v[100:103], v[172:175], v[200:203], v[100:103]
	v_mfma_f32_16x16x32_bf16 v[96:99], v[180:183], v[200:203], v[96:99]
	v_mfma_f32_16x16x32_bf16 v[84:87], v[172:175], v[208:211], v[84:87]
	v_mfma_f32_16x16x32_bf16 v[80:83], v[180:183], v[208:211], v[80:83]
	v_mfma_f32_16x16x32_bf16 v[68:71], v[172:175], v[216:219], v[68:71]
	v_mfma_f32_16x16x32_bf16 v[64:67], v[180:183], v[216:219], v[64:67]
	s_setprio 0
	s_barrier
	s_add_i32 s36, s84, s56
	v_lshl_add_u64 v[192:193], v[192:193], 0, s[28:29]
	s_mov_b32 m0, s36
	ds_read_b128 v[184:187], v153 offset:49152
	ds_read_b128 v[188:191], v153 offset:50176
	ds_read_b128 v[196:199], v153 offset:51200
	ds_read_b128 v[200:203], v153 offset:52224
	ds_read_b128 v[204:207], v153 offset:53248
	ds_read_b128 v[208:211], v153 offset:54272
	ds_read_b128 v[212:215], v153 offset:55296
	ds_read_b128 v[216:219], v153 offset:56320
	global_load_lds_dwordx4 v[192:193], off
	s_add_i32 m0, s36, 0x2000
	s_add_u32 s36, s40, 0xb0080
	v_lshl_add_u64 v[192:193], v[220:221], 0, s[28:29]
	s_addc_u32 s37, s41, 0
	s_add_i32 s40, s85, s56
	global_load_lds_dwordx4 v[192:193], off
	v_lshl_add_u64 v[192:193], s[36:37], 0, v[130:131]
	s_mov_b32 m0, s40
	s_nop 0
	global_load_lds_dwordx4 v[192:193], off
	v_lshl_add_u64 v[192:193], s[36:37], 0, v[134:135]
	s_add_i32 m0, s40, 0x2000
	s_nop 0
	global_load_lds_dwordx4 v[192:193], off
	s_mov_b32 s99, 1
	s_waitcnt vmcnt(6)
	s_waitcnt lgkmcnt(0)
	s_barrier
	s_setprio 1
	s_waitcnt lgkmcnt(0)
	v_mfma_f32_16x16x32_bf16 v[60:63], v[144:147], v[184:187], v[60:63]
	v_mfma_f32_16x16x32_bf16 v[56:59], v[160:163], v[184:187], v[56:59]
	v_mfma_f32_16x16x32_bf16 v[44:47], v[144:147], v[196:199], v[44:47]
	v_mfma_f32_16x16x32_bf16 v[40:43], v[160:163], v[196:199], v[40:43]
	v_mfma_f32_16x16x32_bf16 v[28:31], v[144:147], v[204:207], v[28:31]
	v_mfma_f32_16x16x32_bf16 v[24:27], v[160:163], v[204:207], v[24:27]
	v_mfma_f32_16x16x32_bf16 v[12:15], v[144:147], v[212:215], v[12:15]
	v_mfma_f32_16x16x32_bf16 v[8:11], v[160:163], v[212:215], v[8:11]
	v_mfma_f32_16x16x32_bf16 v[60:63], v[156:159], v[188:191], v[60:63]
	v_mfma_f32_16x16x32_bf16 v[56:59], v[164:167], v[188:191], v[56:59]
	v_mfma_f32_16x16x32_bf16 v[44:47], v[156:159], v[200:203], v[44:47]
	v_mfma_f32_16x16x32_bf16 v[40:43], v[164:167], v[200:203], v[40:43]
	v_mfma_f32_16x16x32_bf16 v[28:31], v[156:159], v[208:211], v[28:31]
	v_mfma_f32_16x16x32_bf16 v[24:27], v[164:167], v[208:211], v[24:27]
	v_mfma_f32_16x16x32_bf16 v[12:15], v[156:159], v[216:219], v[12:15]
	v_mfma_f32_16x16x32_bf16 v[8:11], v[164:167], v[216:219], v[8:11]
	s_setprio 0
	s_setprio 1
	v_mfma_f32_16x16x32_bf16 v[52:55], v[168:171], v[184:187], v[52:55]
	v_mfma_f32_16x16x32_bf16 v[48:51], v[176:179], v[184:187], v[48:51]
	v_mfma_f32_16x16x32_bf16 v[36:39], v[168:171], v[196:199], v[36:39]
	v_mfma_f32_16x16x32_bf16 v[32:35], v[176:179], v[196:199], v[32:35]
	v_mfma_f32_16x16x32_bf16 v[20:23], v[168:171], v[204:207], v[20:23]
	v_mfma_f32_16x16x32_bf16 v[16:19], v[176:179], v[204:207], v[16:19]
	v_mfma_f32_16x16x32_bf16 v[4:7], v[168:171], v[212:215], v[4:7]
	v_mfma_f32_16x16x32_bf16 v[0:3], v[176:179], v[212:215], v[0:3]
	v_mfma_f32_16x16x32_bf16 v[52:55], v[172:175], v[188:191], v[52:55]
	v_mfma_f32_16x16x32_bf16 v[48:51], v[180:183], v[188:191], v[48:51]
	v_mfma_f32_16x16x32_bf16 v[36:39], v[172:175], v[200:203], v[36:39]
	v_mfma_f32_16x16x32_bf16 v[32:35], v[180:183], v[200:203], v[32:35]
	v_mfma_f32_16x16x32_bf16 v[20:23], v[172:175], v[208:211], v[20:23]
	v_mfma_f32_16x16x32_bf16 v[16:19], v[180:183], v[208:211], v[16:19]
	v_mfma_f32_16x16x32_bf16 v[4:7], v[172:175], v[216:219], v[4:7]
	v_mfma_f32_16x16x32_bf16 v[0:3], v[180:183], v[216:219], v[0:3]
	s_setprio 0
	s_barrier
	s_add_i32 s83, s83, 2
	s_add_u32 s81, s81, 0x100
	s_addc_u32 s82, s82, 0
	s_cmp_gt_u32 s83, 41
	s_mov_b64 s[36:37], s[38:39]
	s_cbranch_scc0 .LBB0_2142
	v_lshl_add_u64 v[222:223], v[222:223], 0, s[28:29]
	s_mov_b32 m0, s62
	s_nop 0
	global_load_lds_dwordx4 v[222:223], off
	v_lshl_add_u64 v[224:225], v[224:225], 0, s[28:29]
	s_mov_b32 m0, s63
	s_nop 0
	global_load_lds_dwordx4 v[224:225], off
	s_and_b64 vcc, exec, s[30:31]
	s_cbranch_vccz .LBB0_2145
	s_barrier

.LBB0_2235:
	s_ashr_i32 s35, s34, 31
	s_lshl_b64 s[36:37], s[34:35], 19
	s_add_u32 s36, s52, s36
	s_addc_u32 s37, s53, s37
	s_and_b64 s[38:39], s[8:9], exec
	s_cselect_b32 s1, s37, s41
	s_cselect_b32 s15, s36, s40
	s_ashr_i32 s31, s30, 31
	s_lshl_b64 s[38:39], s[30:31], 19
	s_add_u32 s38, s56, s38
	s_addc_u32 s39, s57, s39
	s_and_b64 s[44:45], s[8:9], exec
	s_cselect_b32 s16, s39, s43
	s_cselect_b32 s31, s38, s42
	s_add_u32 s40, s40, 0x40080
	s_addc_u32 s41, s41, 0
	s_add_u32 s35, s42, 0x100
	v_mov_b32_e32 v0, 0
	s_addc_u32 s87, s43, 0
	s_mov_b32 s88, -2
	v_mov_b32_e32 v1, v0
	v_mov_b32_e32 v2, v0
	v_mov_b32_e32 v3, v0
	v_mov_b32_e32 v4, v0
	v_mov_b32_e32 v5, v0
	v_mov_b32_e32 v6, v0
	v_mov_b32_e32 v7, v0
	v_mov_b32_e32 v16, v0
	v_mov_b32_e32 v17, v0
	v_mov_b32_e32 v18, v0
	v_mov_b32_e32 v19, v0
	v_mov_b32_e32 v20, v0
	v_mov_b32_e32 v21, v0
	v_mov_b32_e32 v22, v0
	v_mov_b32_e32 v23, v0
	v_mov_b32_e32 v32, v0
	v_mov_b32_e32 v33, v0
	v_mov_b32_e32 v34, v0
	v_mov_b32_e32 v35, v0
	v_mov_b32_e32 v36, v0
	v_mov_b32_e32 v37, v0
	v_mov_b32_e32 v38, v0
	v_mov_b32_e32 v39, v0
	v_mov_b32_e32 v48, v0
	v_mov_b32_e32 v49, v0
	v_mov_b32_e32 v50, v0
	v_mov_b32_e32 v51, v0
	v_mov_b32_e32 v52, v0
	v_mov_b32_e32 v53, v0
	v_mov_b32_e32 v54, v0
	v_mov_b32_e32 v55, v0
	v_mov_b32_e32 v8, v0
	v_mov_b32_e32 v9, v0
	v_mov_b32_e32 v10, v0
	v_mov_b32_e32 v11, v0
	v_mov_b32_e32 v12, v0
	v_mov_b32_e32 v13, v0
	v_mov_b32_e32 v14, v0
	v_mov_b32_e32 v15, v0
	v_mov_b32_e32 v24, v0
	v_mov_b32_e32 v25, v0
	v_mov_b32_e32 v26, v0
	v_mov_b32_e32 v27, v0
	v_mov_b32_e32 v28, v0
	v_mov_b32_e32 v29, v0
	v_mov_b32_e32 v30, v0
	v_mov_b32_e32 v31, v0
	v_mov_b32_e32 v40, v0
	v_mov_b32_e32 v41, v0
	v_mov_b32_e32 v42, v0
	v_mov_b32_e32 v43, v0
	v_mov_b32_e32 v44, v0
	v_mov_b32_e32 v45, v0
	v_mov_b32_e32 v46, v0
	v_mov_b32_e32 v47, v0
	v_mov_b32_e32 v56, v0
	v_mov_b32_e32 v57, v0
	v_mov_b32_e32 v58, v0
	v_mov_b32_e32 v59, v0
	v_mov_b32_e32 v60, v0
	v_mov_b32_e32 v61, v0
	v_mov_b32_e32 v62, v0
	v_mov_b32_e32 v63, v0
	v_mov_b32_e32 v64, v0
	v_mov_b32_e32 v65, v0
	v_mov_b32_e32 v66, v0
	v_mov_b32_e32 v67, v0
	v_mov_b32_e32 v68, v0
	v_mov_b32_e32 v69, v0
	v_mov_b32_e32 v70, v0
	v_mov_b32_e32 v71, v0
	v_mov_b32_e32 v80, v0
	v_mov_b32_e32 v81, v0
	v_mov_b32_e32 v82, v0
	v_mov_b32_e32 v83, v0
	v_mov_b32_e32 v84, v0
	v_mov_b32_e32 v85, v0
	v_mov_b32_e32 v86, v0
	v_mov_b32_e32 v87, v0
	v_mov_b32_e32 v96, v0
	v_mov_b32_e32 v97, v0
	v_mov_b32_e32 v98, v0
	v_mov_b32_e32 v99, v0
	v_mov_b32_e32 v100, v0
	v_mov_b32_e32 v101, v0
	v_mov_b32_e32 v102, v0
	v_mov_b32_e32 v103, v0
	v_mov_b32_e32 v112, v0
	v_mov_b32_e32 v113, v0
	v_mov_b32_e32 v114, v0
	v_mov_b32_e32 v115, v0
	v_mov_b32_e32 v116, v0
	v_mov_b32_e32 v117, v0
	v_mov_b32_e32 v118, v0
	v_mov_b32_e32 v119, v0
	v_mov_b32_e32 v72, v0
	v_mov_b32_e32 v73, v0
	v_mov_b32_e32 v74, v0
	v_mov_b32_e32 v75, v0
	v_mov_b32_e32 v76, v0
	v_mov_b32_e32 v77, v0
	v_mov_b32_e32 v78, v0
	v_mov_b32_e32 v79, v0
	v_mov_b32_e32 v88, v0
	v_mov_b32_e32 v89, v0
	v_mov_b32_e32 v90, v0
	v_mov_b32_e32 v91, v0
	v_mov_b32_e32 v92, v0
	v_mov_b32_e32 v93, v0
	v_mov_b32_e32 v94, v0
	v_mov_b32_e32 v95, v0
	v_mov_b32_e32 v104, v0
	v_mov_b32_e32 v105, v0
	v_mov_b32_e32 v106, v0
	v_mov_b32_e32 v107, v0
	v_mov_b32_e32 v108, v0
	v_mov_b32_e32 v109, v0
	v_mov_b32_e32 v110, v0
	v_mov_b32_e32 v111, v0
	v_mov_b32_e32 v120, v0
	v_mov_b32_e32 v121, v0
	v_mov_b32_e32 v122, v0
	v_mov_b32_e32 v123, v0
	v_mov_b32_e32 v124, v0
	v_mov_b32_e32 v125, v0
	v_mov_b32_e32 v126, v0
	v_mov_b32_e32 v127, v0
	s_mov_b32 s99, 0
.LBB0_2236:
	ds_read_b128 v[152:155], v157
	ds_read_b128 v[162:165], v157 offset:1024
	ds_read_b128 v[166:169], v157 offset:2048
	ds_read_b128 v[170:173], v157 offset:3072
	ds_read_b128 v[174:177], v158
	ds_read_b128 v[178:181], v158 offset:1024
	ds_read_b128 v[182:185], v158 offset:2048
	ds_read_b128 v[186:189], v158 offset:3072
	s_add_u32 s42, s40, 0xfffc0080
	s_addc_u32 s43, s41, -1
	s_cmp_eq_u32 s88, 12
	s_cselect_b32 s45, s1, s43
	s_cselect_b32 s44, s15, s42
	s_cselect_b32 s43, s16, s87
	s_cselect_b32 s42, s31, s35
	v_lshl_add_u64 v[224:225], s[40:41], 0, v[144:145]
	ds_read_b128 v[190:193], v159
	ds_read_b128 v[196:199], v159 offset:1024
	ds_read_b128 v[200:203], v159 offset:2048
	ds_read_b128 v[204:207], v159 offset:3072
	ds_read_b128 v[208:211], v159 offset:4096
	ds_read_b128 v[212:215], v159 offset:5120
	ds_read_b128 v[216:219], v159 offset:6144
	ds_read_b128 v[220:223], v159 offset:7168
	s_cmp_eq_u32 s99, 0
	s_cbranch_scc1 .Lkb_first_16
	v_lshl_add_u64 v[228:229], v[228:229], 0, s[26:27]
	s_mov_b32 m0, s71
	s_nop 0
	global_load_lds_dwordx4 v[228:229], off
	v_lshl_add_u64 v[230:231], v[230:231], 0, s[26:27]
	s_mov_b32 m0, s72
	s_nop 0
	global_load_lds_dwordx4 v[230:231], off
	s_branch .Lkb_join_16
.Lkb_first_16:
	s_add_i32 m0, s59, 0xc000
	s_nop 0
	global_load_lds_dwordx4 v[224:225], off
	global_load_lds_dwordx4 v[224:225], off
.Lkb_join_16:
	s_add_i32 m0, s59, 0xc000
	s_nop 0
	global_load_lds_dwordx4 v[224:225], off
	v_lshl_add_u64 v[224:225], s[40:41], 0, v[146:147]
	s_add_i32 m0, s59, 0xe000
	s_nop 0
	global_load_lds_dwordx4 v[224:225], off
	s_waitcnt vmcnt(8)
	s_waitcnt lgkmcnt(0)
	s_barrier
	s_setprio 1
	s_waitcnt lgkmcnt(0)
	v_mfma_f32_16x16x32_bf16 v[124:127], v[152:155], v[190:193], v[124:127]
	v_mfma_f32_16x16x32_bf16 v[120:123], v[166:169], v[190:193], v[120:123]
	v_mfma_f32_16x16x32_bf16 v[108:111], v[152:155], v[200:203], v[108:111]
	v_mfma_f32_16x16x32_bf16 v[104:107], v[166:169], v[200:203], v[104:107]
	v_mfma_f32_16x16x32_bf16 v[92:95], v[152:155], v[208:211], v[92:95]
	v_mfma_f32_16x16x32_bf16 v[88:91], v[166:169], v[208:211], v[88:91]
	v_mfma_f32_16x16x32_bf16 v[76:79], v[152:155], v[216:219], v[76:79]
	v_mfma_f32_16x16x32_bf16 v[72:75], v[166:169], v[216:219], v[72:75]
	v_mfma_f32_16x16x32_bf16 v[124:127], v[162:165], v[196:199], v[124:127]
	v_mfma_f32_16x16x32_bf16 v[120:123], v[170:173], v[196:199], v[120:123]
	v_mfma_f32_16x16x32_bf16 v[108:111], v[162:165], v[204:207], v[108:111]
	v_mfma_f32_16x16x32_bf16 v[104:107], v[170:173], v[204:207], v[104:107]
	v_mfma_f32_16x16x32_bf16 v[92:95], v[162:165], v[212:215], v[92:95]
	v_mfma_f32_16x16x32_bf16 v[88:91], v[170:173], v[212:215], v[88:91]
	v_mfma_f32_16x16x32_bf16 v[76:79], v[162:165], v[220:223], v[76:79]
	v_mfma_f32_16x16x32_bf16 v[72:75], v[170:173], v[220:223], v[72:75]
	s_setprio 0
	s_setprio 1
	v_mfma_f32_16x16x32_bf16 v[116:119], v[174:177], v[190:193], v[116:119]
	v_mfma_f32_16x16x32_bf16 v[112:115], v[182:185], v[190:193], v[112:115]
	v_mfma_f32_16x16x32_bf16 v[100:103], v[174:177], v[200:203], v[100:103]
	v_mfma_f32_16x16x32_bf16 v[96:99], v[182:185], v[200:203], v[96:99]
	v_mfma_f32_16x16x32_bf16 v[84:87], v[174:177], v[208:211], v[84:87]
	v_mfma_f32_16x16x32_bf16 v[80:83], v[182:185], v[208:211], v[80:83]
	v_mfma_f32_16x16x32_bf16 v[68:71], v[174:177], v[216:219], v[68:71]
	v_mfma_f32_16x16x32_bf16 v[64:67], v[182:185], v[216:219], v[64:67]
	v_mfma_f32_16x16x32_bf16 v[116:119], v[178:181], v[196:199], v[116:119]
	v_mfma_f32_16x16x32_bf16 v[112:115], v[186:189], v[196:199], v[112:115]
	v_mfma_f32_16x16x32_bf16 v[100:103], v[178:181], v[204:207], v[100:103]
	v_mfma_f32_16x16x32_bf16 v[96:99], v[186:189], v[204:207], v[96:99]
	v_mfma_f32_16x16x32_bf16 v[84:87], v[178:181], v[212:215], v[84:87]
	v_mfma_f32_16x16x32_bf16 v[80:83], v[186:189], v[212:215], v[80:83]
	v_mfma_f32_16x16x32_bf16 v[68:71], v[178:181], v[220:223], v[68:71]
	v_mfma_f32_16x16x32_bf16 v[64:67], v[186:189], v[220:223], v[64:67]
	s_setprio 0
	s_barrier
	s_add_i32 s89, s78, s58
	v_lshl_add_u64 v[224:225], s[42:43], 0, v[130:131]
	s_mov_b32 m0, s89
	ds_read_b128 v[190:193], v159 offset:16384
	ds_read_b128 v[196:199], v159 offset:17408
	ds_read_b128 v[200:203], v159 offset:18432
	ds_read_b128 v[204:207], v159 offset:19456
	ds_read_b128 v[208:211], v159 offset:20480
	ds_read_b128 v[212:215], v159 offset:21504
	ds_read_b128 v[216:219], v159 offset:22528
	ds_read_b128 v[220:223], v159 offset:23552
	global_load_lds_dwordx4 v[224:225], off
	s_add_i32 m0, s89, 0x2000
	s_add_u32 s90, s42, 0x40000
	v_lshl_add_u64 v[226:227], s[42:43], 0, v[134:135]
	s_addc_u32 s91, s43, 0
	s_add_i32 s89, s79, s58
	global_load_lds_dwordx4 v[226:227], off
	v_lshl_add_u64 v[228:229], s[90:91], 0, v[130:131]
	s_mov_b32 m0, s89
	v_lshl_add_u64 v[230:231], s[44:45], 0, v[132:133]
	global_load_lds_dwordx4 v[228:229], off
	v_lshl_add_u64 v[228:229], s[90:91], 0, v[134:135]
	s_add_i32 m0, s89, 0x2000
	s_nop 0
	global_load_lds_dwordx4 v[228:229], off
	v_lshl_add_u64 v[228:229], s[44:45], 0, v[128:129]
	s_waitcnt vmcnt(6)
	s_waitcnt lgkmcnt(0)
	s_barrier
	s_setprio 1
	s_waitcnt lgkmcnt(0)
	v_mfma_f32_16x16x32_bf16 v[60:63], v[152:155], v[190:193], v[60:63]
	v_mfma_f32_16x16x32_bf16 v[56:59], v[166:169], v[190:193], v[56:59]
	v_mfma_f32_16x16x32_bf16 v[44:47], v[152:155], v[200:203], v[44:47]
	v_mfma_f32_16x16x32_bf16 v[40:43], v[166:169], v[200:203], v[40:43]
	v_mfma_f32_16x16x32_bf16 v[28:31], v[152:155], v[208:211], v[28:31]
	v_mfma_f32_16x16x32_bf16 v[24:27], v[166:169], v[208:211], v[24:27]
	v_mfma_f32_16x16x32_bf16 v[12:15], v[152:155], v[216:219], v[12:15]
	v_mfma_f32_16x16x32_bf16 v[8:11], v[166:169], v[216:219], v[8:11]
	v_mfma_f32_16x16x32_bf16 v[60:63], v[162:165], v[196:199], v[60:63]
	v_mfma_f32_16x16x32_bf16 v[56:59], v[170:173], v[196:199], v[56:59]
	v_mfma_f32_16x16x32_bf16 v[44:47], v[162:165], v[204:207], v[44:47]
	v_mfma_f32_16x16x32_bf16 v[40:43], v[170:173], v[204:207], v[40:43]
	v_mfma_f32_16x16x32_bf16 v[28:31], v[162:165], v[212:215], v[28:31]
	v_mfma_f32_16x16x32_bf16 v[24:27], v[170:173], v[212:215], v[24:27]
	v_mfma_f32_16x16x32_bf16 v[12:15], v[162:165], v[220:223], v[12:15]
	v_mfma_f32_16x16x32_bf16 v[8:11], v[170:173], v[220:223], v[8:11]
	s_setprio 0
	s_setprio 1
	v_mfma_f32_16x16x32_bf16 v[52:55], v[174:177], v[190:193], v[52:55]
	v_mfma_f32_16x16x32_bf16 v[48:51], v[182:185], v[190:193], v[48:51]
	v_mfma_f32_16x16x32_bf16 v[36:39], v[174:177], v[200:203], v[36:39]
	v_mfma_f32_16x16x32_bf16 v[32:35], v[182:185], v[200:203], v[32:35]
	v_mfma_f32_16x16x32_bf16 v[20:23], v[174:177], v[208:211], v[20:23]
	v_mfma_f32_16x16x32_bf16 v[16:19], v[182:185], v[208:211], v[16:19]
	v_mfma_f32_16x16x32_bf16 v[4:7], v[174:177], v[216:219], v[4:7]
	v_mfma_f32_16x16x32_bf16 v[0:3], v[182:185], v[216:219], v[0:3]
	v_mfma_f32_16x16x32_bf16 v[52:55], v[178:181], v[196:199], v[52:55]
	v_mfma_f32_16x16x32_bf16 v[48:51], v[186:189], v[196:199], v[48:51]
	v_mfma_f32_16x16x32_bf16 v[36:39], v[178:181], v[204:207], v[36:39]
	v_mfma_f32_16x16x32_bf16 v[32:35], v[186:189], v[204:207], v[32:35]
	v_mfma_f32_16x16x32_bf16 v[20:23], v[178:181], v[212:215], v[20:23]
	v_mfma_f32_16x16x32_bf16 v[16:19], v[186:189], v[212:215], v[16:19]
	v_mfma_f32_16x16x32_bf16 v[4:7], v[178:181], v[220:223], v[4:7]
	v_mfma_f32_16x16x32_bf16 v[0:3], v[186:189], v[220:223], v[0:3]
	s_setprio 0
	s_barrier
	s_add_i32 s89, 0, 0x18000
	v_add_u32_e32 v136, s89, v141
	s_add_i32 s90, 0, 0x1c000
	ds_read_b128 v[152:155], v136
	ds_read_b128 v[162:165], v136 offset:1024
	ds_read_b128 v[166:169], v136 offset:2048
	ds_read_b128 v[170:173], v136 offset:3072
	v_add_u32_e32 v136, s90, v141
	ds_read_b128 v[174:177], v136
	ds_read_b128 v[178:181], v136 offset:1024
	ds_read_b128 v[182:185], v136 offset:2048
	ds_read_b128 v[186:189], v136 offset:3072
	s_add_u32 s44, s44, 0x40000
	s_addc_u32 s45, s45, 0
	v_lshl_add_u64 v[232:233], s[44:45], 0, v[128:129]
	ds_read_b128 v[190:193], v159 offset:32768
	ds_read_b128 v[196:199], v159 offset:33792
	ds_read_b128 v[200:203], v159 offset:34816
	ds_read_b128 v[204:207], v159 offset:35840
	ds_read_b128 v[208:211], v159 offset:36864
	ds_read_b128 v[212:215], v159 offset:37888
	ds_read_b128 v[216:219], v159 offset:38912
	ds_read_b128 v[220:223], v159 offset:39936
	s_mov_b32 m0, s59
	s_nop 0
	global_load_lds_dwordx4 v[228:229], off
	s_mov_b32 m0, s60
	s_nop 0
	global_load_lds_dwordx4 v[230:231], off
	s_mov_b32 m0, s61
	s_nop 0
	global_load_lds_dwordx4 v[232:233], off
	v_lshl_add_u64 v[232:233], s[44:45], 0, v[132:133]
	s_mov_b32 m0, s62
	s_nop 0
	global_load_lds_dwordx4 v[232:233], off
	s_waitcnt vmcnt(8)
	s_waitcnt lgkmcnt(0)
	s_barrier
	s_setprio 1
	s_waitcnt lgkmcnt(0)
	v_mfma_f32_16x16x32_bf16 v[124:127], v[152:155], v[190:193], v[124:127]
	v_mfma_f32_16x16x32_bf16 v[120:123], v[166:169], v[190:193], v[120:123]
	v_mfma_f32_16x16x32_bf16 v[108:111], v[152:155], v[200:203], v[108:111]
	v_mfma_f32_16x16x32_bf16 v[104:107], v[166:169], v[200:203], v[104:107]
	v_mfma_f32_16x16x32_bf16 v[92:95], v[152:155], v[208:211], v[92:95]
	v_mfma_f32_16x16x32_bf16 v[88:91], v[166:169], v[208:211], v[88:91]
	v_mfma_f32_16x16x32_bf16 v[76:79], v[152:155], v[216:219], v[76:79]
	v_mfma_f32_16x16x32_bf16 v[72:75], v[166:169], v[216:219], v[72:75]
	v_mfma_f32_16x16x32_bf16 v[124:127], v[162:165], v[196:199], v[124:127]
	v_mfma_f32_16x16x32_bf16 v[120:123], v[170:173], v[196:199], v[120:123]
	v_mfma_f32_16x16x32_bf16 v[108:111], v[162:165], v[204:207], v[108:111]
	v_mfma_f32_16x16x32_bf16 v[104:107], v[170:173], v[204:207], v[104:107]
	v_mfma_f32_16x16x32_bf16 v[92:95], v[162:165], v[212:215], v[92:95]
	v_mfma_f32_16x16x32_bf16 v[88:91], v[170:173], v[212:215], v[88:91]
	v_mfma_f32_16x16x32_bf16 v[76:79], v[162:165], v[220:223], v[76:79]
	v_mfma_f32_16x16x32_bf16 v[72:75], v[170:173], v[220:223], v[72:75]
	s_setprio 0
	s_setprio 1
	v_mfma_f32_16x16x32_bf16 v[116:119], v[174:177], v[190:193], v[116:119]
	v_mfma_f32_16x16x32_bf16 v[112:115], v[182:185], v[190:193], v[112:115]
	v_mfma_f32_16x16x32_bf16 v[100:103], v[174:177], v[200:203], v[100:103]
	v_mfma_f32_16x16x32_bf16 v[96:99], v[182:185], v[200:203], v[96:99]
	v_mfma_f32_16x16x32_bf16 v[84:87], v[174:177], v[208:211], v[84:87]
	v_mfma_f32_16x16x32_bf16 v[80:83], v[182:185], v[208:211], v[80:83]
	v_mfma_f32_16x16x32_bf16 v[68:71], v[174:177], v[216:219], v[68:71]
	v_mfma_f32_16x16x32_bf16 v[64:67], v[182:185], v[216:219], v[64:67]
	v_mfma_f32_16x16x32_bf16 v[116:119], v[178:181], v[196:199], v[116:119]
	v_mfma_f32_16x16x32_bf16 v[112:115], v[186:189], v[196:199], v[112:115]
	v_mfma_f32_16x16x32_bf16 v[100:103], v[178:181], v[204:207], v[100:103]
	v_mfma_f32_16x16x32_bf16 v[96:99], v[186:189], v[204:207], v[96:99]
	v_mfma_f32_16x16x32_bf16 v[84:87], v[178:181], v[212:215], v[84:87]
	v_mfma_f32_16x16x32_bf16 v[80:83], v[186:189], v[212:215], v[80:83]
	v_mfma_f32_16x16x32_bf16 v[68:71], v[178:181], v[220:223], v[68:71]
	v_mfma_f32_16x16x32_bf16 v[64:67], v[186:189], v[220:223], v[64:67]
	s_setprio 0
	s_barrier
	s_add_i32 s44, s89, s58
	v_lshl_add_u64 v[224:225], v[224:225], 0, s[26:27]
	s_mov_b32 m0, s44
	ds_read_b128 v[190:193], v159 offset:49152
	ds_read_b128 v[196:199], v159 offset:50176
	ds_read_b128 v[200:203], v159 offset:51200
	ds_read_b128 v[204:207], v159 offset:52224
	ds_read_b128 v[208:211], v159 offset:53248
	ds_read_b128 v[212:215], v159 offset:54272
	ds_read_b128 v[216:219], v159 offset:55296
	ds_read_b128 v[220:223], v159 offset:56320
	global_load_lds_dwordx4 v[224:225], off
	s_add_i32 m0, s44, 0x2000
	s_add_u32 s42, s42, 0x40080
	v_lshl_add_u64 v[224:225], v[226:227], 0, s[26:27]
	s_addc_u32 s43, s43, 0
	s_add_i32 s44, s90, s58
	global_load_lds_dwordx4 v[224:225], off
	v_lshl_add_u64 v[224:225], s[42:43], 0, v[130:131]
	s_mov_b32 m0, s44
	s_nop 0
	global_load_lds_dwordx4 v[224:225], off
	v_lshl_add_u64 v[224:225], s[42:43], 0, v[134:135]
	s_add_i32 m0, s44, 0x2000
	s_nop 0
	global_load_lds_dwordx4 v[224:225], off
	s_mov_b32 s99, 1
	s_waitcnt vmcnt(6)
	s_waitcnt lgkmcnt(0)
	s_barrier
	s_setprio 1
	s_waitcnt lgkmcnt(0)
	v_mfma_f32_16x16x32_bf16 v[60:63], v[152:155], v[190:193], v[60:63]
	v_mfma_f32_16x16x32_bf16 v[56:59], v[166:169], v[190:193], v[56:59]
	v_mfma_f32_16x16x32_bf16 v[44:47], v[152:155], v[200:203], v[44:47]
	v_mfma_f32_16x16x32_bf16 v[40:43], v[166:169], v[200:203], v[40:43]
	v_mfma_f32_16x16x32_bf16 v[28:31], v[152:155], v[208:211], v[28:31]
	v_mfma_f32_16x16x32_bf16 v[24:27], v[166:169], v[208:211], v[24:27]
	v_mfma_f32_16x16x32_bf16 v[12:15], v[152:155], v[216:219], v[12:15]
	v_mfma_f32_16x16x32_bf16 v[8:11], v[166:169], v[216:219], v[8:11]
	v_mfma_f32_16x16x32_bf16 v[60:63], v[162:165], v[196:199], v[60:63]
	v_mfma_f32_16x16x32_bf16 v[56:59], v[170:173], v[196:199], v[56:59]
	v_mfma_f32_16x16x32_bf16 v[44:47], v[162:165], v[204:207], v[44:47]
	v_mfma_f32_16x16x32_bf16 v[40:43], v[170:173], v[204:207], v[40:43]
	v_mfma_f32_16x16x32_bf16 v[28:31], v[162:165], v[212:215], v[28:31]
	v_mfma_f32_16x16x32_bf16 v[24:27], v[170:173], v[212:215], v[24:27]
	v_mfma_f32_16x16x32_bf16 v[12:15], v[162:165], v[220:223], v[12:15]
	v_mfma_f32_16x16x32_bf16 v[8:11], v[170:173], v[220:223], v[8:11]
	s_setprio 0
	s_setprio 1
	v_mfma_f32_16x16x32_bf16 v[52:55], v[174:177], v[190:193], v[52:55]
	v_mfma_f32_16x16x32_bf16 v[48:51], v[182:185], v[190:193], v[48:51]
	v_mfma_f32_16x16x32_bf16 v[36:39], v[174:177], v[200:203], v[36:39]
	v_mfma_f32_16x16x32_bf16 v[32:35], v[182:185], v[200:203], v[32:35]
	v_mfma_f32_16x16x32_bf16 v[20:23], v[174:177], v[208:211], v[20:23]
	v_mfma_f32_16x16x32_bf16 v[16:19], v[182:185], v[208:211], v[16:19]
	v_mfma_f32_16x16x32_bf16 v[4:7], v[174:177], v[216:219], v[4:7]
	v_mfma_f32_16x16x32_bf16 v[0:3], v[182:185], v[216:219], v[0:3]
	v_mfma_f32_16x16x32_bf16 v[52:55], v[178:181], v[196:199], v[52:55]
	v_mfma_f32_16x16x32_bf16 v[48:51], v[186:189], v[196:199], v[48:51]
	v_mfma_f32_16x16x32_bf16 v[36:39], v[178:181], v[204:207], v[36:39]
	v_mfma_f32_16x16x32_bf16 v[32:35], v[186:189], v[204:207], v[32:35]
	v_mfma_f32_16x16x32_bf16 v[20:23], v[178:181], v[212:215], v[20:23]
	v_mfma_f32_16x16x32_bf16 v[16:19], v[186:189], v[212:215], v[16:19]
	v_mfma_f32_16x16x32_bf16 v[4:7], v[178:181], v[220:223], v[4:7]
	v_mfma_f32_16x16x32_bf16 v[0:3], v[186:189], v[220:223], v[0:3]
	s_setprio 0
	s_barrier
	s_add_i32 s88, s88, 2
	s_add_u32 s40, s40, 0x100
	s_addc_u32 s41, s41, 0
	s_add_u32 s35, s35, 0x100
	s_addc_u32 s87, s87, 0
	s_cmp_gt_u32 s88, 13
	s_cbranch_scc0 .LBB0_2236
	v_lshl_add_u64 v[228:229], v[228:229], 0, s[26:27]
	s_mov_b32 m0, s71
	s_nop 0
	global_load_lds_dwordx4 v[228:229], off
	v_lshl_add_u64 v[230:231], v[230:231], 0, s[26:27]
	s_mov_b32 m0, s72
	s_nop 0
	global_load_lds_dwordx4 v[230:231], off
	s_and_b64 vcc, exec, s[28:29]
	s_cbranch_vccz .LBB0_2239
	s_barrier

.LBB0_2369:
	s_lshl_b64 s[34:35], s[26:27], 18
	s_add_u32 s17, s52, s34
	s_addc_u32 s27, s53, s35
	s_and_b64 s[34:35], s[28:29], exec
	s_cselect_b32 s35, s27, s39
	s_cselect_b32 s34, s17, s38
	s_add_u32 s17, s38, 0x100
	v_mov_b32_e32 v0, 0
	s_addc_u32 s27, s39, 0
	s_mov_b32 s81, -2
	v_mov_b32_e32 v1, v0
	v_mov_b32_e32 v2, v0
	v_mov_b32_e32 v3, v0
	v_mov_b32_e32 v4, v0
	v_mov_b32_e32 v5, v0
	v_mov_b32_e32 v6, v0
	v_mov_b32_e32 v7, v0
	v_mov_b32_e32 v8, v0
	v_mov_b32_e32 v9, v0
	v_mov_b32_e32 v10, v0
	v_mov_b32_e32 v11, v0
	v_mov_b32_e32 v12, v0
	v_mov_b32_e32 v13, v0
	v_mov_b32_e32 v14, v0
	v_mov_b32_e32 v15, v0
	v_mov_b32_e32 v20, v0
	v_mov_b32_e32 v21, v0
	v_mov_b32_e32 v22, v0
	v_mov_b32_e32 v23, v0
	v_mov_b32_e32 v28, v0
	v_mov_b32_e32 v29, v0
	v_mov_b32_e32 v30, v0
	v_mov_b32_e32 v31, v0
	v_mov_b32_e32 v36, v0
	v_mov_b32_e32 v37, v0
	v_mov_b32_e32 v38, v0
	v_mov_b32_e32 v39, v0
	v_mov_b32_e32 v44, v0
	v_mov_b32_e32 v45, v0
	v_mov_b32_e32 v46, v0
	v_mov_b32_e32 v47, v0
	v_mov_b32_e32 v16, v0
	v_mov_b32_e32 v17, v0
	v_mov_b32_e32 v18, v0
	v_mov_b32_e32 v19, v0
	v_mov_b32_e32 v24, v0
	v_mov_b32_e32 v25, v0
	v_mov_b32_e32 v26, v0
	v_mov_b32_e32 v27, v0
	v_mov_b32_e32 v32, v0
	v_mov_b32_e32 v33, v0
	v_mov_b32_e32 v34, v0
	v_mov_b32_e32 v35, v0
	v_mov_b32_e32 v40, v0
	v_mov_b32_e32 v41, v0
	v_mov_b32_e32 v42, v0
	v_mov_b32_e32 v43, v0
	v_mov_b32_e32 v48, v0
	v_mov_b32_e32 v49, v0
	v_mov_b32_e32 v50, v0
	v_mov_b32_e32 v51, v0
	v_mov_b32_e32 v52, v0
	v_mov_b32_e32 v53, v0
	v_mov_b32_e32 v54, v0
	v_mov_b32_e32 v55, v0
	v_mov_b32_e32 v56, v0
	v_mov_b32_e32 v57, v0
	v_mov_b32_e32 v58, v0
	v_mov_b32_e32 v59, v0
	v_mov_b32_e32 v60, v0
	v_mov_b32_e32 v61, v0
	v_mov_b32_e32 v62, v0
	v_mov_b32_e32 v63, v0
	v_mov_b32_e32 v64, v0
	v_mov_b32_e32 v65, v0
	v_mov_b32_e32 v66, v0
	v_mov_b32_e32 v67, v0
	v_mov_b32_e32 v68, v0
	v_mov_b32_e32 v69, v0
	v_mov_b32_e32 v70, v0
	v_mov_b32_e32 v71, v0
	v_mov_b32_e32 v72, v0
	v_mov_b32_e32 v73, v0
	v_mov_b32_e32 v74, v0
	v_mov_b32_e32 v75, v0
	v_mov_b32_e32 v76, v0
	v_mov_b32_e32 v77, v0
	v_mov_b32_e32 v78, v0
	v_mov_b32_e32 v79, v0
	v_mov_b32_e32 v84, v0
	v_mov_b32_e32 v85, v0
	v_mov_b32_e32 v86, v0
	v_mov_b32_e32 v87, v0
	v_mov_b32_e32 v92, v0
	v_mov_b32_e32 v93, v0
	v_mov_b32_e32 v94, v0
	v_mov_b32_e32 v95, v0
	v_mov_b32_e32 v100, v0
	v_mov_b32_e32 v101, v0
	v_mov_b32_e32 v102, v0
	v_mov_b32_e32 v103, v0
	v_mov_b32_e32 v108, v0
	v_mov_b32_e32 v109, v0
	v_mov_b32_e32 v110, v0
	v_mov_b32_e32 v111, v0
	v_mov_b32_e32 v80, v0
	v_mov_b32_e32 v81, v0
	v_mov_b32_e32 v82, v0
	v_mov_b32_e32 v83, v0
	v_mov_b32_e32 v88, v0
	v_mov_b32_e32 v89, v0
	v_mov_b32_e32 v90, v0
	v_mov_b32_e32 v91, v0
	v_mov_b32_e32 v96, v0
	v_mov_b32_e32 v97, v0
	v_mov_b32_e32 v98, v0
	v_mov_b32_e32 v99, v0
	v_mov_b32_e32 v104, v0
	v_mov_b32_e32 v105, v0
	v_mov_b32_e32 v106, v0
	v_mov_b32_e32 v107, v0
	v_mov_b32_e32 v112, v0
	v_mov_b32_e32 v113, v0
	v_mov_b32_e32 v114, v0
	v_mov_b32_e32 v115, v0
	v_mov_b32_e32 v116, v0
	v_mov_b32_e32 v117, v0
	v_mov_b32_e32 v118, v0
	v_mov_b32_e32 v119, v0
	v_mov_b32_e32 v120, v0
	v_mov_b32_e32 v121, v0
	v_mov_b32_e32 v122, v0
	v_mov_b32_e32 v123, v0
	v_mov_b32_e32 v124, v0
	v_mov_b32_e32 v125, v0
	v_mov_b32_e32 v126, v0
	v_mov_b32_e32 v127, v0
	s_mov_b32 s99, 0
.LBB0_2370:
	ds_read_b128 v[148:151], v144
	ds_read_b128 v[152:155], v144 offset:1024
	ds_read_b128 v[156:159], v144 offset:2048
	ds_read_b128 v[160:163], v144 offset:3072
	ds_read_b128 v[164:167], v145
	ds_read_b128 v[168:171], v145 offset:1024
	ds_read_b128 v[172:175], v145 offset:2048
	ds_read_b128 v[176:179], v145 offset:3072
	s_add_u32 s38, s36, 0x100
	s_addc_u32 s39, s37, 0
	s_cmp_eq_u32 s81, 4
	s_cselect_b32 s43, s31, s39
	s_cselect_b32 s42, s30, s38
	s_cselect_b32 s41, s35, s27
	s_cselect_b32 s40, s34, s17
	v_lshl_add_u64 v[192:193], s[36:37], 0, v[138:139]
	ds_read_b128 v[180:183], v146
	ds_read_b128 v[184:187], v146 offset:1024
	ds_read_b128 v[188:191], v146 offset:2048
	ds_read_b128 v[196:199], v146 offset:3072
	ds_read_b128 v[200:203], v146 offset:4096
	ds_read_b128 v[204:207], v146 offset:5120
	ds_read_b128 v[208:211], v146 offset:6144
	ds_read_b128 v[212:215], v146 offset:7168
	s_cmp_eq_u32 s99, 0
	s_cbranch_scc1 .Lkb_first_17
	v_lshl_add_u64 v[218:219], v[218:219], 0, s[14:15]
	s_mov_b32 m0, s62
	s_nop 0
	global_load_lds_dwordx4 v[218:219], off
	v_lshl_add_u64 v[220:221], v[220:221], 0, s[14:15]
	s_mov_b32 m0, s63
	s_nop 0
	global_load_lds_dwordx4 v[220:221], off
	s_branch .Lkb_join_17
.Lkb_first_17:
	s_add_i32 m0, s55, 0xc000
	s_nop 0
	global_load_lds_dwordx4 v[192:193], off
	global_load_lds_dwordx4 v[192:193], off
.Lkb_join_17:
	s_add_i32 m0, s55, 0xc000
	s_nop 0
	global_load_lds_dwordx4 v[192:193], off
	v_lshl_add_u64 v[192:193], s[36:37], 0, v[140:141]
	s_add_i32 m0, s55, 0xe000
	s_nop 0
	global_load_lds_dwordx4 v[192:193], off
	s_waitcnt vmcnt(8)
	s_waitcnt lgkmcnt(0)
	s_barrier
	s_setprio 1
	s_waitcnt lgkmcnt(0)
	v_mfma_f32_16x16x32_bf16 v[124:127], v[148:151], v[180:183], v[124:127]
	v_mfma_f32_16x16x32_bf16 v[120:123], v[156:159], v[180:183], v[120:123]
	v_mfma_f32_16x16x32_bf16 v[116:119], v[148:151], v[188:191], v[116:119]
	v_mfma_f32_16x16x32_bf16 v[112:115], v[156:159], v[188:191], v[112:115]
	v_mfma_f32_16x16x32_bf16 v[104:107], v[148:151], v[200:203], v[104:107]
	v_mfma_f32_16x16x32_bf16 v[96:99], v[156:159], v[200:203], v[96:99]
	v_mfma_f32_16x16x32_bf16 v[88:91], v[148:151], v[208:211], v[88:91]
	v_mfma_f32_16x16x32_bf16 v[80:83], v[156:159], v[208:211], v[80:83]
	v_mfma_f32_16x16x32_bf16 v[124:127], v[152:155], v[184:187], v[124:127]
	v_mfma_f32_16x16x32_bf16 v[120:123], v[160:163], v[184:187], v[120:123]
	v_mfma_f32_16x16x32_bf16 v[116:119], v[152:155], v[196:199], v[116:119]
	v_mfma_f32_16x16x32_bf16 v[112:115], v[160:163], v[196:199], v[112:115]
	v_mfma_f32_16x16x32_bf16 v[104:107], v[152:155], v[204:207], v[104:107]
	v_mfma_f32_16x16x32_bf16 v[96:99], v[160:163], v[204:207], v[96:99]
	v_mfma_f32_16x16x32_bf16 v[88:91], v[152:155], v[212:215], v[88:91]
	v_mfma_f32_16x16x32_bf16 v[80:83], v[160:163], v[212:215], v[80:83]
	s_setprio 0
	s_setprio 1
	v_mfma_f32_16x16x32_bf16 v[108:111], v[164:167], v[180:183], v[108:111]
	v_mfma_f32_16x16x32_bf16 v[100:103], v[172:175], v[180:183], v[100:103]
	v_mfma_f32_16x16x32_bf16 v[92:95], v[164:167], v[188:191], v[92:95]
	v_mfma_f32_16x16x32_bf16 v[84:87], v[172:175], v[188:191], v[84:87]
	v_mfma_f32_16x16x32_bf16 v[76:79], v[164:167], v[200:203], v[76:79]
	v_mfma_f32_16x16x32_bf16 v[72:75], v[172:175], v[200:203], v[72:75]
	v_mfma_f32_16x16x32_bf16 v[68:71], v[164:167], v[208:211], v[68:71]
	v_mfma_f32_16x16x32_bf16 v[64:67], v[172:175], v[208:211], v[64:67]
	v_mfma_f32_16x16x32_bf16 v[108:111], v[168:171], v[184:187], v[108:111]
	v_mfma_f32_16x16x32_bf16 v[100:103], v[176:179], v[184:187], v[100:103]
	v_mfma_f32_16x16x32_bf16 v[92:95], v[168:171], v[196:199], v[92:95]
	v_mfma_f32_16x16x32_bf16 v[84:87], v[176:179], v[196:199], v[84:87]
	v_mfma_f32_16x16x32_bf16 v[76:79], v[168:171], v[204:207], v[76:79]
	v_mfma_f32_16x16x32_bf16 v[72:75], v[176:179], v[204:207], v[72:75]
	v_mfma_f32_16x16x32_bf16 v[68:71], v[168:171], v[212:215], v[68:71]
	v_mfma_f32_16x16x32_bf16 v[64:67], v[176:179], v[212:215], v[64:67]
	s_setprio 0
	s_barrier
	s_add_i32 s36, s71, s54
	v_lshl_add_u64 v[192:193], s[40:41], 0, v[132:133]
	s_mov_b32 m0, s36
	ds_read_b128 v[180:183], v146 offset:16384
	ds_read_b128 v[184:187], v146 offset:17408
	ds_read_b128 v[188:191], v146 offset:18432
	ds_read_b128 v[196:199], v146 offset:19456
	ds_read_b128 v[200:203], v146 offset:20480
	ds_read_b128 v[204:207], v146 offset:21504
	ds_read_b128 v[208:211], v146 offset:22528
	ds_read_b128 v[212:215], v146 offset:23552
	global_load_lds_dwordx4 v[192:193], off
	s_add_i32 m0, s36, 0x2000
	s_add_u32 s36, s40, 0x20000
	v_lshl_add_u64 v[216:217], s[40:41], 0, v[128:129]
	s_addc_u32 s37, s41, 0
	s_add_i32 s82, s72, s54
	global_load_lds_dwordx4 v[216:217], off
	v_lshl_add_u64 v[218:219], s[36:37], 0, v[132:133]
	s_mov_b32 m0, s82
	v_lshl_add_u64 v[220:221], s[42:43], 0, v[130:131]
	global_load_lds_dwordx4 v[218:219], off
	v_lshl_add_u64 v[218:219], s[36:37], 0, v[128:129]
	s_add_i32 m0, s82, 0x2000
	s_nop 0
	global_load_lds_dwordx4 v[218:219], off
	v_lshl_add_u64 v[218:219], s[42:43], 0, v[134:135]
	s_waitcnt vmcnt(6)
	s_waitcnt lgkmcnt(0)
	s_barrier
	s_setprio 1
	s_waitcnt lgkmcnt(0)
	v_mfma_f32_16x16x32_bf16 v[60:63], v[148:151], v[180:183], v[60:63]
	v_mfma_f32_16x16x32_bf16 v[56:59], v[156:159], v[180:183], v[56:59]
	v_mfma_f32_16x16x32_bf16 v[52:55], v[148:151], v[188:191], v[52:55]
	v_mfma_f32_16x16x32_bf16 v[48:51], v[156:159], v[188:191], v[48:51]
	v_mfma_f32_16x16x32_bf16 v[40:43], v[148:151], v[200:203], v[40:43]
	v_mfma_f32_16x16x32_bf16 v[32:35], v[156:159], v[200:203], v[32:35]
	v_mfma_f32_16x16x32_bf16 v[24:27], v[148:151], v[208:211], v[24:27]
	v_mfma_f32_16x16x32_bf16 v[16:19], v[156:159], v[208:211], v[16:19]
	v_mfma_f32_16x16x32_bf16 v[60:63], v[152:155], v[184:187], v[60:63]
	v_mfma_f32_16x16x32_bf16 v[56:59], v[160:163], v[184:187], v[56:59]
	v_mfma_f32_16x16x32_bf16 v[52:55], v[152:155], v[196:199], v[52:55]
	v_mfma_f32_16x16x32_bf16 v[48:51], v[160:163], v[196:199], v[48:51]
	v_mfma_f32_16x16x32_bf16 v[40:43], v[152:155], v[204:207], v[40:43]
	v_mfma_f32_16x16x32_bf16 v[32:35], v[160:163], v[204:207], v[32:35]
	v_mfma_f32_16x16x32_bf16 v[24:27], v[152:155], v[212:215], v[24:27]
	v_mfma_f32_16x16x32_bf16 v[16:19], v[160:163], v[212:215], v[16:19]
	s_setprio 0
	s_setprio 1
	v_mfma_f32_16x16x32_bf16 v[44:47], v[164:167], v[180:183], v[44:47]
	v_mfma_f32_16x16x32_bf16 v[36:39], v[172:175], v[180:183], v[36:39]
	v_mfma_f32_16x16x32_bf16 v[28:31], v[164:167], v[188:191], v[28:31]
	v_mfma_f32_16x16x32_bf16 v[20:23], v[172:175], v[188:191], v[20:23]
	v_mfma_f32_16x16x32_bf16 v[12:15], v[164:167], v[200:203], v[12:15]
	v_mfma_f32_16x16x32_bf16 v[8:11], v[172:175], v[200:203], v[8:11]
	v_mfma_f32_16x16x32_bf16 v[4:7], v[164:167], v[208:211], v[4:7]
	v_mfma_f32_16x16x32_bf16 v[0:3], v[172:175], v[208:211], v[0:3]
	v_mfma_f32_16x16x32_bf16 v[44:47], v[168:171], v[184:187], v[44:47]
	v_mfma_f32_16x16x32_bf16 v[36:39], v[176:179], v[184:187], v[36:39]
	v_mfma_f32_16x16x32_bf16 v[28:31], v[168:171], v[196:199], v[28:31]
	v_mfma_f32_16x16x32_bf16 v[20:23], v[176:179], v[196:199], v[20:23]
	v_mfma_f32_16x16x32_bf16 v[12:15], v[168:171], v[204:207], v[12:15]
	v_mfma_f32_16x16x32_bf16 v[8:11], v[176:179], v[204:207], v[8:11]
	v_mfma_f32_16x16x32_bf16 v[4:7], v[168:171], v[212:215], v[4:7]
	v_mfma_f32_16x16x32_bf16 v[0:3], v[176:179], v[212:215], v[0:3]
	s_setprio 0
	s_barrier
	s_add_i32 s82, 0, 0x18000
	v_add_u32_e32 v147, s82, v143
	s_add_i32 s83, 0, 0x1c000
	ds_read_b128 v[148:151], v147
	ds_read_b128 v[152:155], v147 offset:1024
	ds_read_b128 v[156:159], v147 offset:2048
	ds_read_b128 v[160:163], v147 offset:3072
	v_add_u32_e32 v147, s83, v143
	ds_read_b128 v[164:167], v147
	ds_read_b128 v[168:171], v147 offset:1024
	ds_read_b128 v[172:175], v147 offset:2048
	ds_read_b128 v[176:179], v147 offset:3072
	s_add_u32 s36, s42, 0x30000
	s_addc_u32 s37, s43, 0
	v_lshl_add_u64 v[222:223], s[36:37], 0, v[134:135]
	ds_read_b128 v[180:183], v146 offset:32768
	ds_read_b128 v[184:187], v146 offset:33792
	ds_read_b128 v[188:191], v146 offset:34816
	ds_read_b128 v[196:199], v146 offset:35840
	ds_read_b128 v[200:203], v146 offset:36864
	ds_read_b128 v[204:207], v146 offset:37888
	ds_read_b128 v[208:211], v146 offset:38912
	ds_read_b128 v[212:215], v146 offset:39936
	s_mov_b32 m0, s55
	s_nop 0
	global_load_lds_dwordx4 v[218:219], off
	s_mov_b32 m0, s56
	s_nop 0
	global_load_lds_dwordx4 v[220:221], off
	s_mov_b32 m0, s57
	s_nop 0
	global_load_lds_dwordx4 v[222:223], off
	v_lshl_add_u64 v[222:223], s[36:37], 0, v[130:131]
	s_mov_b32 m0, s58
	s_nop 0
	global_load_lds_dwordx4 v[222:223], off
	s_waitcnt vmcnt(8)
	s_waitcnt lgkmcnt(0)
	s_barrier
	s_setprio 1
	s_waitcnt lgkmcnt(0)
	v_mfma_f32_16x16x32_bf16 v[124:127], v[148:151], v[180:183], v[124:127]
	v_mfma_f32_16x16x32_bf16 v[120:123], v[156:159], v[180:183], v[120:123]
	v_mfma_f32_16x16x32_bf16 v[116:119], v[148:151], v[188:191], v[116:119]
	v_mfma_f32_16x16x32_bf16 v[112:115], v[156:159], v[188:191], v[112:115]
	v_mfma_f32_16x16x32_bf16 v[104:107], v[148:151], v[200:203], v[104:107]
	v_mfma_f32_16x16x32_bf16 v[96:99], v[156:159], v[200:203], v[96:99]
	v_mfma_f32_16x16x32_bf16 v[88:91], v[148:151], v[208:211], v[88:91]
	v_mfma_f32_16x16x32_bf16 v[80:83], v[156:159], v[208:211], v[80:83]
	v_mfma_f32_16x16x32_bf16 v[124:127], v[152:155], v[184:187], v[124:127]
	v_mfma_f32_16x16x32_bf16 v[120:123], v[160:163], v[184:187], v[120:123]
	v_mfma_f32_16x16x32_bf16 v[116:119], v[152:155], v[196:199], v[116:119]
	v_mfma_f32_16x16x32_bf16 v[112:115], v[160:163], v[196:199], v[112:115]
	v_mfma_f32_16x16x32_bf16 v[104:107], v[152:155], v[204:207], v[104:107]
	v_mfma_f32_16x16x32_bf16 v[96:99], v[160:163], v[204:207], v[96:99]
	v_mfma_f32_16x16x32_bf16 v[88:91], v[152:155], v[212:215], v[88:91]
	v_mfma_f32_16x16x32_bf16 v[80:83], v[160:163], v[212:215], v[80:83]
	s_setprio 0
	s_setprio 1
	v_mfma_f32_16x16x32_bf16 v[108:111], v[164:167], v[180:183], v[108:111]
	v_mfma_f32_16x16x32_bf16 v[100:103], v[172:175], v[180:183], v[100:103]
	v_mfma_f32_16x16x32_bf16 v[92:95], v[164:167], v[188:191], v[92:95]
	v_mfma_f32_16x16x32_bf16 v[84:87], v[172:175], v[188:191], v[84:87]
	v_mfma_f32_16x16x32_bf16 v[76:79], v[164:167], v[200:203], v[76:79]
	v_mfma_f32_16x16x32_bf16 v[72:75], v[172:175], v[200:203], v[72:75]
	v_mfma_f32_16x16x32_bf16 v[68:71], v[164:167], v[208:211], v[68:71]
	v_mfma_f32_16x16x32_bf16 v[64:67], v[172:175], v[208:211], v[64:67]
	v_mfma_f32_16x16x32_bf16 v[108:111], v[168:171], v[184:187], v[108:111]
	v_mfma_f32_16x16x32_bf16 v[100:103], v[176:179], v[184:187], v[100:103]
	v_mfma_f32_16x16x32_bf16 v[92:95], v[168:171], v[196:199], v[92:95]
	v_mfma_f32_16x16x32_bf16 v[84:87], v[176:179], v[196:199], v[84:87]
	v_mfma_f32_16x16x32_bf16 v[76:79], v[168:171], v[204:207], v[76:79]
	v_mfma_f32_16x16x32_bf16 v[72:75], v[176:179], v[204:207], v[72:75]
	v_mfma_f32_16x16x32_bf16 v[68:71], v[168:171], v[212:215], v[68:71]
	v_mfma_f32_16x16x32_bf16 v[64:67], v[176:179], v[212:215], v[64:67]
	s_setprio 0
	s_barrier
	s_add_i32 s36, s82, s54
	v_lshl_add_u64 v[192:193], v[192:193], 0, s[14:15]
	s_mov_b32 m0, s36
	ds_read_b128 v[180:183], v146 offset:49152
	ds_read_b128 v[184:187], v146 offset:50176
	ds_read_b128 v[188:191], v146 offset:51200
	ds_read_b128 v[196:199], v146 offset:52224
	ds_read_b128 v[200:203], v146 offset:53248
	ds_read_b128 v[204:207], v146 offset:54272
	ds_read_b128 v[208:211], v146 offset:55296
	ds_read_b128 v[212:215], v146 offset:56320
	global_load_lds_dwordx4 v[192:193], off
	s_add_i32 m0, s36, 0x2000
	s_add_u32 s36, s40, 0x20080
	v_lshl_add_u64 v[192:193], v[216:217], 0, s[14:15]
	s_addc_u32 s37, s41, 0
	s_add_i32 s40, s83, s54
	global_load_lds_dwordx4 v[192:193], off
	v_lshl_add_u64 v[192:193], s[36:37], 0, v[132:133]
	s_mov_b32 m0, s40
	s_nop 0
	global_load_lds_dwordx4 v[192:193], off
	v_lshl_add_u64 v[192:193], s[36:37], 0, v[128:129]
	s_add_i32 m0, s40, 0x2000
	s_nop 0
	global_load_lds_dwordx4 v[192:193], off
	s_mov_b32 s99, 1
	s_waitcnt vmcnt(6)
	s_waitcnt lgkmcnt(0)
	s_barrier
	s_setprio 1
	s_waitcnt lgkmcnt(0)
	v_mfma_f32_16x16x32_bf16 v[60:63], v[148:151], v[180:183], v[60:63]
	v_mfma_f32_16x16x32_bf16 v[56:59], v[156:159], v[180:183], v[56:59]
	v_mfma_f32_16x16x32_bf16 v[52:55], v[148:151], v[188:191], v[52:55]
	v_mfma_f32_16x16x32_bf16 v[48:51], v[156:159], v[188:191], v[48:51]
	v_mfma_f32_16x16x32_bf16 v[40:43], v[148:151], v[200:203], v[40:43]
	v_mfma_f32_16x16x32_bf16 v[32:35], v[156:159], v[200:203], v[32:35]
	v_mfma_f32_16x16x32_bf16 v[24:27], v[148:151], v[208:211], v[24:27]
	v_mfma_f32_16x16x32_bf16 v[16:19], v[156:159], v[208:211], v[16:19]
	v_mfma_f32_16x16x32_bf16 v[60:63], v[152:155], v[184:187], v[60:63]
	v_mfma_f32_16x16x32_bf16 v[56:59], v[160:163], v[184:187], v[56:59]
	v_mfma_f32_16x16x32_bf16 v[52:55], v[152:155], v[196:199], v[52:55]
	v_mfma_f32_16x16x32_bf16 v[48:51], v[160:163], v[196:199], v[48:51]
	v_mfma_f32_16x16x32_bf16 v[40:43], v[152:155], v[204:207], v[40:43]
	v_mfma_f32_16x16x32_bf16 v[32:35], v[160:163], v[204:207], v[32:35]
	v_mfma_f32_16x16x32_bf16 v[24:27], v[152:155], v[212:215], v[24:27]
	v_mfma_f32_16x16x32_bf16 v[16:19], v[160:163], v[212:215], v[16:19]
	s_setprio 0
	s_setprio 1
	v_mfma_f32_16x16x32_bf16 v[44:47], v[164:167], v[180:183], v[44:47]
	v_mfma_f32_16x16x32_bf16 v[36:39], v[172:175], v[180:183], v[36:39]
	v_mfma_f32_16x16x32_bf16 v[28:31], v[164:167], v[188:191], v[28:31]
	v_mfma_f32_16x16x32_bf16 v[20:23], v[172:175], v[188:191], v[20:23]
	v_mfma_f32_16x16x32_bf16 v[12:15], v[164:167], v[200:203], v[12:15]
	v_mfma_f32_16x16x32_bf16 v[8:11], v[172:175], v[200:203], v[8:11]
	v_mfma_f32_16x16x32_bf16 v[4:7], v[164:167], v[208:211], v[4:7]
	v_mfma_f32_16x16x32_bf16 v[0:3], v[172:175], v[208:211], v[0:3]
	v_mfma_f32_16x16x32_bf16 v[44:47], v[168:171], v[184:187], v[44:47]
	v_mfma_f32_16x16x32_bf16 v[36:39], v[176:179], v[184:187], v[36:39]
	v_mfma_f32_16x16x32_bf16 v[28:31], v[168:171], v[196:199], v[28:31]
	v_mfma_f32_16x16x32_bf16 v[20:23], v[176:179], v[196:199], v[20:23]
	v_mfma_f32_16x16x32_bf16 v[12:15], v[168:171], v[204:207], v[12:15]
	v_mfma_f32_16x16x32_bf16 v[8:11], v[176:179], v[204:207], v[8:11]
	v_mfma_f32_16x16x32_bf16 v[4:7], v[168:171], v[212:215], v[4:7]
	v_mfma_f32_16x16x32_bf16 v[0:3], v[176:179], v[212:215], v[0:3]
	s_setprio 0
	s_barrier
	s_add_i32 s81, s81, 2
	s_add_u32 s17, s17, 0x100
	s_addc_u32 s27, s27, 0
	s_cmp_gt_u32 s81, 5
	s_mov_b64 s[36:37], s[38:39]
	s_cbranch_scc0 .LBB0_2370
	v_lshl_add_u64 v[218:219], v[218:219], 0, s[14:15]
	s_mov_b32 m0, s62
	s_nop 0
	global_load_lds_dwordx4 v[218:219], off
	v_lshl_add_u64 v[220:221], v[220:221], 0, s[14:15]
	s_mov_b32 m0, s63
	s_nop 0
	global_load_lds_dwordx4 v[220:221], off
	s_and_b64 vcc, exec, s[18:19]
	s_cbranch_vccz .LBB0_2373
	s_barrier

.LBB0_2395:
	s_ashr_i32 s27, s26, 31
	s_lshl_b64 s[28:29], s[26:27], 19
	s_add_u32 s28, s43, s28
	s_addc_u32 s29, s44, s29
	s_and_b64 s[30:31], s[8:9], exec
	s_cselect_b32 s27, s29, s35
	s_cselect_b32 s71, s28, s34
	s_ashr_i32 s25, s24, 31
	s_lshl_b64 s[30:31], s[24:25], 19
	s_add_u32 s30, s45, s30
	s_addc_u32 s31, s51, s31
	s_and_b64 s[38:39], s[8:9], exec
	s_cselect_b32 s25, s31, s37
	s_cselect_b32 s72, s30, s36
	s_add_u32 s34, s34, 0x40080
	s_addc_u32 s35, s35, 0
	s_add_u32 s73, s36, 0x100
	v_mov_b32_e32 v0, 0
	s_addc_u32 s77, s37, 0
	s_mov_b32 s78, -2
	v_mov_b32_e32 v1, v0
	v_mov_b32_e32 v2, v0
	v_mov_b32_e32 v3, v0
	v_mov_b32_e32 v4, v0
	v_mov_b32_e32 v5, v0
	v_mov_b32_e32 v6, v0
	v_mov_b32_e32 v7, v0
	v_mov_b32_e32 v16, v0
	v_mov_b32_e32 v17, v0
	v_mov_b32_e32 v18, v0
	v_mov_b32_e32 v19, v0
	v_mov_b32_e32 v20, v0
	v_mov_b32_e32 v21, v0
	v_mov_b32_e32 v22, v0
	v_mov_b32_e32 v23, v0
	v_mov_b32_e32 v32, v0
	v_mov_b32_e32 v33, v0
	v_mov_b32_e32 v34, v0
	v_mov_b32_e32 v35, v0
	v_mov_b32_e32 v36, v0
	v_mov_b32_e32 v37, v0
	v_mov_b32_e32 v38, v0
	v_mov_b32_e32 v39, v0
	v_mov_b32_e32 v48, v0
	v_mov_b32_e32 v49, v0
	v_mov_b32_e32 v50, v0
	v_mov_b32_e32 v51, v0
	v_mov_b32_e32 v52, v0
	v_mov_b32_e32 v53, v0
	v_mov_b32_e32 v54, v0
	v_mov_b32_e32 v55, v0
	v_mov_b32_e32 v8, v0
	v_mov_b32_e32 v9, v0
	v_mov_b32_e32 v10, v0
	v_mov_b32_e32 v11, v0
	v_mov_b32_e32 v12, v0
	v_mov_b32_e32 v13, v0
	v_mov_b32_e32 v14, v0
	v_mov_b32_e32 v15, v0
	v_mov_b32_e32 v24, v0
	v_mov_b32_e32 v25, v0
	v_mov_b32_e32 v26, v0
	v_mov_b32_e32 v27, v0
	v_mov_b32_e32 v28, v0
	v_mov_b32_e32 v29, v0
	v_mov_b32_e32 v30, v0
	v_mov_b32_e32 v31, v0
	v_mov_b32_e32 v40, v0
	v_mov_b32_e32 v41, v0
	v_mov_b32_e32 v42, v0
	v_mov_b32_e32 v43, v0
	v_mov_b32_e32 v44, v0
	v_mov_b32_e32 v45, v0
	v_mov_b32_e32 v46, v0
	v_mov_b32_e32 v47, v0
	v_mov_b32_e32 v56, v0
	v_mov_b32_e32 v57, v0
	v_mov_b32_e32 v58, v0
	v_mov_b32_e32 v59, v0
	v_mov_b32_e32 v60, v0
	v_mov_b32_e32 v61, v0
	v_mov_b32_e32 v62, v0
	v_mov_b32_e32 v63, v0
	v_mov_b32_e32 v64, v0
	v_mov_b32_e32 v65, v0
	v_mov_b32_e32 v66, v0
	v_mov_b32_e32 v67, v0
	v_mov_b32_e32 v68, v0
	v_mov_b32_e32 v69, v0
	v_mov_b32_e32 v70, v0
	v_mov_b32_e32 v71, v0
	v_mov_b32_e32 v80, v0
	v_mov_b32_e32 v81, v0
	v_mov_b32_e32 v82, v0
	v_mov_b32_e32 v83, v0
	v_mov_b32_e32 v84, v0
	v_mov_b32_e32 v85, v0
	v_mov_b32_e32 v86, v0
	v_mov_b32_e32 v87, v0
	v_mov_b32_e32 v96, v0
	v_mov_b32_e32 v97, v0
	v_mov_b32_e32 v98, v0
	v_mov_b32_e32 v99, v0
	v_mov_b32_e32 v100, v0
	v_mov_b32_e32 v101, v0
	v_mov_b32_e32 v102, v0
	v_mov_b32_e32 v103, v0
	v_mov_b32_e32 v112, v0
	v_mov_b32_e32 v113, v0
	v_mov_b32_e32 v114, v0
	v_mov_b32_e32 v115, v0
	v_mov_b32_e32 v116, v0
	v_mov_b32_e32 v117, v0
	v_mov_b32_e32 v118, v0
	v_mov_b32_e32 v119, v0
	v_mov_b32_e32 v72, v0
	v_mov_b32_e32 v73, v0
	v_mov_b32_e32 v74, v0
	v_mov_b32_e32 v75, v0
	v_mov_b32_e32 v76, v0
	v_mov_b32_e32 v77, v0
	v_mov_b32_e32 v78, v0
	v_mov_b32_e32 v79, v0
	v_mov_b32_e32 v88, v0
	v_mov_b32_e32 v89, v0
	v_mov_b32_e32 v90, v0
	v_mov_b32_e32 v91, v0
	v_mov_b32_e32 v92, v0
	v_mov_b32_e32 v93, v0
	v_mov_b32_e32 v94, v0
	v_mov_b32_e32 v95, v0
	v_mov_b32_e32 v104, v0
	v_mov_b32_e32 v105, v0
	v_mov_b32_e32 v106, v0
	v_mov_b32_e32 v107, v0
	v_mov_b32_e32 v108, v0
	v_mov_b32_e32 v109, v0
	v_mov_b32_e32 v110, v0
	v_mov_b32_e32 v111, v0
	v_mov_b32_e32 v120, v0
	v_mov_b32_e32 v121, v0
	v_mov_b32_e32 v122, v0
	v_mov_b32_e32 v123, v0
	v_mov_b32_e32 v124, v0
	v_mov_b32_e32 v125, v0
	v_mov_b32_e32 v126, v0
	v_mov_b32_e32 v127, v0
	s_mov_b32 s99, 0
.LBB0_2396:
	ds_read_b128 v[144:147], v153
	ds_read_b128 v[158:161], v153 offset:1024
	ds_read_b128 v[162:165], v153 offset:2048
	ds_read_b128 v[166:169], v153 offset:3072
	ds_read_b128 v[170:173], v154
	ds_read_b128 v[174:177], v154 offset:1024
	ds_read_b128 v[178:181], v154 offset:2048
	ds_read_b128 v[182:185], v154 offset:3072
	s_add_u32 s36, s34, 0xfffc0080
	s_addc_u32 s37, s35, -1
	s_cmp_eq_u32 s78, 12
	s_cselect_b32 s39, s27, s37
	s_cselect_b32 s38, s71, s36
	s_cselect_b32 s37, s25, s77
	s_cselect_b32 s36, s72, s73
	v_lshl_add_u64 v[148:149], s[34:35], 0, v[136:137]
	ds_read_b128 v[186:189], v155
	ds_read_b128 v[190:193], v155 offset:1024
	ds_read_b128 v[196:199], v155 offset:2048
	ds_read_b128 v[200:203], v155 offset:3072
	ds_read_b128 v[204:207], v155 offset:4096
	ds_read_b128 v[208:211], v155 offset:5120
	ds_read_b128 v[212:215], v155 offset:6144
	ds_read_b128 v[216:219], v155 offset:7168
	s_cmp_eq_u32 s99, 0
	s_cbranch_scc1 .Lkb_first_18
	v_lshl_add_u64 v[222:223], v[222:223], 0, s[20:21]
	s_mov_b32 m0, s58
	s_nop 0
	global_load_lds_dwordx4 v[222:223], off
	v_lshl_add_u64 v[224:225], v[224:225], 0, s[20:21]
	s_mov_b32 m0, s59
	s_nop 0
	global_load_lds_dwordx4 v[224:225], off
	s_branch .Lkb_join_18
.Lkb_first_18:
	s_add_i32 m0, s53, 0xc000
	s_nop 0
	global_load_lds_dwordx4 v[148:149], off
	global_load_lds_dwordx4 v[148:149], off
.Lkb_join_18:
	s_add_i32 m0, s53, 0xc000
	s_nop 0
	global_load_lds_dwordx4 v[148:149], off
	v_lshl_add_u64 v[148:149], s[34:35], 0, v[138:139]
	s_add_i32 m0, s53, 0xe000
	s_nop 0
	global_load_lds_dwordx4 v[148:149], off
	s_waitcnt vmcnt(8)
	s_waitcnt lgkmcnt(0)
	s_barrier
	s_setprio 1
	s_waitcnt lgkmcnt(0)
	v_mfma_f32_16x16x32_bf16 v[124:127], v[144:147], v[186:189], v[124:127]
	v_mfma_f32_16x16x32_bf16 v[120:123], v[162:165], v[186:189], v[120:123]
	v_mfma_f32_16x16x32_bf16 v[108:111], v[144:147], v[196:199], v[108:111]
	v_mfma_f32_16x16x32_bf16 v[104:107], v[162:165], v[196:199], v[104:107]
	v_mfma_f32_16x16x32_bf16 v[92:95], v[144:147], v[204:207], v[92:95]
	v_mfma_f32_16x16x32_bf16 v[88:91], v[162:165], v[204:207], v[88:91]
	v_mfma_f32_16x16x32_bf16 v[76:79], v[144:147], v[212:215], v[76:79]
	v_mfma_f32_16x16x32_bf16 v[72:75], v[162:165], v[212:215], v[72:75]
	v_mfma_f32_16x16x32_bf16 v[124:127], v[158:161], v[190:193], v[124:127]
	v_mfma_f32_16x16x32_bf16 v[120:123], v[166:169], v[190:193], v[120:123]
	v_mfma_f32_16x16x32_bf16 v[108:111], v[158:161], v[200:203], v[108:111]
	v_mfma_f32_16x16x32_bf16 v[104:107], v[166:169], v[200:203], v[104:107]
	v_mfma_f32_16x16x32_bf16 v[92:95], v[158:161], v[208:211], v[92:95]
	v_mfma_f32_16x16x32_bf16 v[88:91], v[166:169], v[208:211], v[88:91]
	v_mfma_f32_16x16x32_bf16 v[76:79], v[158:161], v[216:219], v[76:79]
	v_mfma_f32_16x16x32_bf16 v[72:75], v[166:169], v[216:219], v[72:75]
	s_setprio 0
	s_setprio 1
	v_mfma_f32_16x16x32_bf16 v[116:119], v[170:173], v[186:189], v[116:119]
	v_mfma_f32_16x16x32_bf16 v[112:115], v[178:181], v[186:189], v[112:115]
	v_mfma_f32_16x16x32_bf16 v[100:103], v[170:173], v[196:199], v[100:103]
	v_mfma_f32_16x16x32_bf16 v[96:99], v[178:181], v[196:199], v[96:99]
	v_mfma_f32_16x16x32_bf16 v[84:87], v[170:173], v[204:207], v[84:87]
	v_mfma_f32_16x16x32_bf16 v[80:83], v[178:181], v[204:207], v[80:83]
	v_mfma_f32_16x16x32_bf16 v[68:71], v[170:173], v[212:215], v[68:71]
	v_mfma_f32_16x16x32_bf16 v[64:67], v[178:181], v[212:215], v[64:67]
	v_mfma_f32_16x16x32_bf16 v[116:119], v[174:177], v[190:193], v[116:119]
	v_mfma_f32_16x16x32_bf16 v[112:115], v[182:185], v[190:193], v[112:115]
	v_mfma_f32_16x16x32_bf16 v[100:103], v[174:177], v[200:203], v[100:103]
	v_mfma_f32_16x16x32_bf16 v[96:99], v[182:185], v[200:203], v[96:99]
	v_mfma_f32_16x16x32_bf16 v[84:87], v[174:177], v[208:211], v[84:87]
	v_mfma_f32_16x16x32_bf16 v[80:83], v[182:185], v[208:211], v[80:83]
	v_mfma_f32_16x16x32_bf16 v[68:71], v[174:177], v[216:219], v[68:71]
	v_mfma_f32_16x16x32_bf16 v[64:67], v[182:185], v[216:219], v[64:67]
	s_setprio 0
	s_barrier
	s_add_i32 s79, s61, s52
	v_lshl_add_u64 v[148:149], s[36:37], 0, v[130:131]
	s_mov_b32 m0, s79
	ds_read_b128 v[186:189], v155 offset:16384
	ds_read_b128 v[190:193], v155 offset:17408
	ds_read_b128 v[196:199], v155 offset:18432
	ds_read_b128 v[200:203], v155 offset:19456
	ds_read_b128 v[204:207], v155 offset:20480
	ds_read_b128 v[208:211], v155 offset:21504
	ds_read_b128 v[212:215], v155 offset:22528
	ds_read_b128 v[216:219], v155 offset:23552
	global_load_lds_dwordx4 v[148:149], off
	s_add_i32 m0, s79, 0x2000
	s_add_u32 s80, s36, 0x40000
	v_lshl_add_u64 v[220:221], s[36:37], 0, v[134:135]
	s_addc_u32 s81, s37, 0
	s_add_i32 s79, s62, s52
	global_load_lds_dwordx4 v[220:221], off
	v_lshl_add_u64 v[222:223], s[80:81], 0, v[130:131]
	s_mov_b32 m0, s79
	v_lshl_add_u64 v[224:225], s[38:39], 0, v[132:133]
	global_load_lds_dwordx4 v[222:223], off
	v_lshl_add_u64 v[222:223], s[80:81], 0, v[134:135]
	s_add_i32 m0, s79, 0x2000
	s_nop 0
	global_load_lds_dwordx4 v[222:223], off
	v_lshl_add_u64 v[222:223], s[38:39], 0, v[128:129]
	s_waitcnt vmcnt(6)
	s_waitcnt lgkmcnt(0)
	s_barrier
	s_setprio 1
	s_waitcnt lgkmcnt(0)
	v_mfma_f32_16x16x32_bf16 v[60:63], v[144:147], v[186:189], v[60:63]
	v_mfma_f32_16x16x32_bf16 v[56:59], v[162:165], v[186:189], v[56:59]
	v_mfma_f32_16x16x32_bf16 v[44:47], v[144:147], v[196:199], v[44:47]
	v_mfma_f32_16x16x32_bf16 v[40:43], v[162:165], v[196:199], v[40:43]
	v_mfma_f32_16x16x32_bf16 v[28:31], v[144:147], v[204:207], v[28:31]
	v_mfma_f32_16x16x32_bf16 v[24:27], v[162:165], v[204:207], v[24:27]
	v_mfma_f32_16x16x32_bf16 v[12:15], v[144:147], v[212:215], v[12:15]
	v_mfma_f32_16x16x32_bf16 v[8:11], v[162:165], v[212:215], v[8:11]
	v_mfma_f32_16x16x32_bf16 v[60:63], v[158:161], v[190:193], v[60:63]
	v_mfma_f32_16x16x32_bf16 v[56:59], v[166:169], v[190:193], v[56:59]
	v_mfma_f32_16x16x32_bf16 v[44:47], v[158:161], v[200:203], v[44:47]
	v_mfma_f32_16x16x32_bf16 v[40:43], v[166:169], v[200:203], v[40:43]
	v_mfma_f32_16x16x32_bf16 v[28:31], v[158:161], v[208:211], v[28:31]
	v_mfma_f32_16x16x32_bf16 v[24:27], v[166:169], v[208:211], v[24:27]
	v_mfma_f32_16x16x32_bf16 v[12:15], v[158:161], v[216:219], v[12:15]
	v_mfma_f32_16x16x32_bf16 v[8:11], v[166:169], v[216:219], v[8:11]
	s_setprio 0
	s_setprio 1
	v_mfma_f32_16x16x32_bf16 v[52:55], v[170:173], v[186:189], v[52:55]
	v_mfma_f32_16x16x32_bf16 v[48:51], v[178:181], v[186:189], v[48:51]
	v_mfma_f32_16x16x32_bf16 v[36:39], v[170:173], v[196:199], v[36:39]
	v_mfma_f32_16x16x32_bf16 v[32:35], v[178:181], v[196:199], v[32:35]
	v_mfma_f32_16x16x32_bf16 v[20:23], v[170:173], v[204:207], v[20:23]
	v_mfma_f32_16x16x32_bf16 v[16:19], v[178:181], v[204:207], v[16:19]
	v_mfma_f32_16x16x32_bf16 v[4:7], v[170:173], v[212:215], v[4:7]
	v_mfma_f32_16x16x32_bf16 v[0:3], v[178:181], v[212:215], v[0:3]
	v_mfma_f32_16x16x32_bf16 v[52:55], v[174:177], v[190:193], v[52:55]
	v_mfma_f32_16x16x32_bf16 v[48:51], v[182:185], v[190:193], v[48:51]
	v_mfma_f32_16x16x32_bf16 v[36:39], v[174:177], v[200:203], v[36:39]
	v_mfma_f32_16x16x32_bf16 v[32:35], v[182:185], v[200:203], v[32:35]
	v_mfma_f32_16x16x32_bf16 v[20:23], v[174:177], v[208:211], v[20:23]
	v_mfma_f32_16x16x32_bf16 v[16:19], v[182:185], v[208:211], v[16:19]
	v_mfma_f32_16x16x32_bf16 v[4:7], v[174:177], v[216:219], v[4:7]
	v_mfma_f32_16x16x32_bf16 v[0:3], v[182:185], v[216:219], v[0:3]
	s_setprio 0
	s_barrier
	s_add_i32 s79, 0, 0x18000
	v_add_u32_e32 v157, s79, v151
	s_add_i32 s80, 0, 0x1c000
	ds_read_b128 v[144:147], v157
	ds_read_b128 v[158:161], v157 offset:1024
	ds_read_b128 v[162:165], v157 offset:2048
	ds_read_b128 v[166:169], v157 offset:3072
	v_add_u32_e32 v157, s80, v151
	ds_read_b128 v[170:173], v157
	ds_read_b128 v[174:177], v157 offset:1024
	ds_read_b128 v[178:181], v157 offset:2048
	ds_read_b128 v[182:185], v157 offset:3072
	s_add_u32 s38, s38, 0x40000
	s_addc_u32 s39, s39, 0
	v_lshl_add_u64 v[226:227], s[38:39], 0, v[128:129]
	ds_read_b128 v[186:189], v155 offset:32768
	ds_read_b128 v[190:193], v155 offset:33792
	ds_read_b128 v[196:199], v155 offset:34816
	ds_read_b128 v[200:203], v155 offset:35840
	ds_read_b128 v[204:207], v155 offset:36864
	ds_read_b128 v[208:211], v155 offset:37888
	ds_read_b128 v[212:215], v155 offset:38912
	ds_read_b128 v[216:219], v155 offset:39936
	s_mov_b32 m0, s53
	s_nop 0
	global_load_lds_dwordx4 v[222:223], off
	s_mov_b32 m0, s54
	s_nop 0
	global_load_lds_dwordx4 v[224:225], off
	s_mov_b32 m0, s55
	s_nop 0
	global_load_lds_dwordx4 v[226:227], off
	v_lshl_add_u64 v[226:227], s[38:39], 0, v[132:133]
	s_mov_b32 m0, s56
	s_nop 0
	global_load_lds_dwordx4 v[226:227], off
	s_waitcnt vmcnt(8)
	s_waitcnt lgkmcnt(0)
	s_barrier
	s_setprio 1
	s_waitcnt lgkmcnt(0)
	v_mfma_f32_16x16x32_bf16 v[124:127], v[144:147], v[186:189], v[124:127]
	v_mfma_f32_16x16x32_bf16 v[120:123], v[162:165], v[186:189], v[120:123]
	v_mfma_f32_16x16x32_bf16 v[108:111], v[144:147], v[196:199], v[108:111]
	v_mfma_f32_16x16x32_bf16 v[104:107], v[162:165], v[196:199], v[104:107]
	v_mfma_f32_16x16x32_bf16 v[92:95], v[144:147], v[204:207], v[92:95]
	v_mfma_f32_16x16x32_bf16 v[88:91], v[162:165], v[204:207], v[88:91]
	v_mfma_f32_16x16x32_bf16 v[76:79], v[144:147], v[212:215], v[76:79]
	v_mfma_f32_16x16x32_bf16 v[72:75], v[162:165], v[212:215], v[72:75]
	v_mfma_f32_16x16x32_bf16 v[124:127], v[158:161], v[190:193], v[124:127]
	v_mfma_f32_16x16x32_bf16 v[120:123], v[166:169], v[190:193], v[120:123]
	v_mfma_f32_16x16x32_bf16 v[108:111], v[158:161], v[200:203], v[108:111]
	v_mfma_f32_16x16x32_bf16 v[104:107], v[166:169], v[200:203], v[104:107]
	v_mfma_f32_16x16x32_bf16 v[92:95], v[158:161], v[208:211], v[92:95]
	v_mfma_f32_16x16x32_bf16 v[88:91], v[166:169], v[208:211], v[88:91]
	v_mfma_f32_16x16x32_bf16 v[76:79], v[158:161], v[216:219], v[76:79]
	v_mfma_f32_16x16x32_bf16 v[72:75], v[166:169], v[216:219], v[72:75]
	s_setprio 0
	s_setprio 1
	v_mfma_f32_16x16x32_bf16 v[116:119], v[170:173], v[186:189], v[116:119]
	v_mfma_f32_16x16x32_bf16 v[112:115], v[178:181], v[186:189], v[112:115]
	v_mfma_f32_16x16x32_bf16 v[100:103], v[170:173], v[196:199], v[100:103]
	v_mfma_f32_16x16x32_bf16 v[96:99], v[178:181], v[196:199], v[96:99]
	v_mfma_f32_16x16x32_bf16 v[84:87], v[170:173], v[204:207], v[84:87]
	v_mfma_f32_16x16x32_bf16 v[80:83], v[178:181], v[204:207], v[80:83]
	v_mfma_f32_16x16x32_bf16 v[68:71], v[170:173], v[212:215], v[68:71]
	v_mfma_f32_16x16x32_bf16 v[64:67], v[178:181], v[212:215], v[64:67]
	v_mfma_f32_16x16x32_bf16 v[116:119], v[174:177], v[190:193], v[116:119]
	v_mfma_f32_16x16x32_bf16 v[112:115], v[182:185], v[190:193], v[112:115]
	v_mfma_f32_16x16x32_bf16 v[100:103], v[174:177], v[200:203], v[100:103]
	v_mfma_f32_16x16x32_bf16 v[96:99], v[182:185], v[200:203], v[96:99]
	v_mfma_f32_16x16x32_bf16 v[84:87], v[174:177], v[208:211], v[84:87]
	v_mfma_f32_16x16x32_bf16 v[80:83], v[182:185], v[208:211], v[80:83]
	v_mfma_f32_16x16x32_bf16 v[68:71], v[174:177], v[216:219], v[68:71]
	v_mfma_f32_16x16x32_bf16 v[64:67], v[182:185], v[216:219], v[64:67]
	s_setprio 0
	s_barrier
	s_add_i32 s38, s79, s52
	v_lshl_add_u64 v[148:149], v[148:149], 0, s[20:21]
	s_mov_b32 m0, s38
	ds_read_b128 v[186:189], v155 offset:49152
	ds_read_b128 v[190:193], v155 offset:50176
	ds_read_b128 v[196:199], v155 offset:51200
	ds_read_b128 v[200:203], v155 offset:52224
	ds_read_b128 v[204:207], v155 offset:53248
	ds_read_b128 v[208:211], v155 offset:54272
	ds_read_b128 v[212:215], v155 offset:55296
	ds_read_b128 v[216:219], v155 offset:56320
	global_load_lds_dwordx4 v[148:149], off
	s_add_i32 m0, s38, 0x2000
	s_add_u32 s36, s36, 0x40080
	v_lshl_add_u64 v[148:149], v[220:221], 0, s[20:21]
	s_addc_u32 s37, s37, 0
	s_add_i32 s38, s80, s52
	global_load_lds_dwordx4 v[148:149], off
	v_lshl_add_u64 v[148:149], s[36:37], 0, v[130:131]
	s_mov_b32 m0, s38
	s_nop 0
	global_load_lds_dwordx4 v[148:149], off
	v_lshl_add_u64 v[148:149], s[36:37], 0, v[134:135]
	s_add_i32 m0, s38, 0x2000
	s_nop 0
	global_load_lds_dwordx4 v[148:149], off
	s_mov_b32 s99, 1
	s_waitcnt vmcnt(6)
	s_waitcnt lgkmcnt(0)
	s_barrier
	s_setprio 1
	s_waitcnt lgkmcnt(0)
	v_mfma_f32_16x16x32_bf16 v[60:63], v[144:147], v[186:189], v[60:63]
	v_mfma_f32_16x16x32_bf16 v[56:59], v[162:165], v[186:189], v[56:59]
	v_mfma_f32_16x16x32_bf16 v[44:47], v[144:147], v[196:199], v[44:47]
	v_mfma_f32_16x16x32_bf16 v[40:43], v[162:165], v[196:199], v[40:43]
	v_mfma_f32_16x16x32_bf16 v[28:31], v[144:147], v[204:207], v[28:31]
	v_mfma_f32_16x16x32_bf16 v[24:27], v[162:165], v[204:207], v[24:27]
	v_mfma_f32_16x16x32_bf16 v[12:15], v[144:147], v[212:215], v[12:15]
	v_mfma_f32_16x16x32_bf16 v[8:11], v[162:165], v[212:215], v[8:11]
	v_mfma_f32_16x16x32_bf16 v[60:63], v[158:161], v[190:193], v[60:63]
	v_mfma_f32_16x16x32_bf16 v[56:59], v[166:169], v[190:193], v[56:59]
	v_mfma_f32_16x16x32_bf16 v[44:47], v[158:161], v[200:203], v[44:47]
	v_mfma_f32_16x16x32_bf16 v[40:43], v[166:169], v[200:203], v[40:43]
	v_mfma_f32_16x16x32_bf16 v[28:31], v[158:161], v[208:211], v[28:31]
	v_mfma_f32_16x16x32_bf16 v[24:27], v[166:169], v[208:211], v[24:27]
	v_mfma_f32_16x16x32_bf16 v[12:15], v[158:161], v[216:219], v[12:15]
	v_mfma_f32_16x16x32_bf16 v[8:11], v[166:169], v[216:219], v[8:11]
	s_setprio 0
	s_setprio 1
	v_mfma_f32_16x16x32_bf16 v[52:55], v[170:173], v[186:189], v[52:55]
	v_mfma_f32_16x16x32_bf16 v[48:51], v[178:181], v[186:189], v[48:51]
	v_mfma_f32_16x16x32_bf16 v[36:39], v[170:173], v[196:199], v[36:39]
	v_mfma_f32_16x16x32_bf16 v[32:35], v[178:181], v[196:199], v[32:35]
	v_mfma_f32_16x16x32_bf16 v[20:23], v[170:173], v[204:207], v[20:23]
	v_mfma_f32_16x16x32_bf16 v[16:19], v[178:181], v[204:207], v[16:19]
	v_mfma_f32_16x16x32_bf16 v[4:7], v[170:173], v[212:215], v[4:7]
	v_mfma_f32_16x16x32_bf16 v[0:3], v[178:181], v[212:215], v[0:3]
	v_mfma_f32_16x16x32_bf16 v[52:55], v[174:177], v[190:193], v[52:55]
	v_mfma_f32_16x16x32_bf16 v[48:51], v[182:185], v[190:193], v[48:51]
	v_mfma_f32_16x16x32_bf16 v[36:39], v[174:177], v[200:203], v[36:39]
	v_mfma_f32_16x16x32_bf16 v[32:35], v[182:185], v[200:203], v[32:35]
	v_mfma_f32_16x16x32_bf16 v[20:23], v[174:177], v[208:211], v[20:23]
	v_mfma_f32_16x16x32_bf16 v[16:19], v[182:185], v[208:211], v[16:19]
	v_mfma_f32_16x16x32_bf16 v[4:7], v[174:177], v[216:219], v[4:7]
	v_mfma_f32_16x16x32_bf16 v[0:3], v[182:185], v[216:219], v[0:3]
	s_setprio 0
	s_barrier
	s_add_i32 s78, s78, 2
	s_add_u32 s34, s34, 0x100
	s_addc_u32 s35, s35, 0
	s_add_u32 s73, s73, 0x100
	s_addc_u32 s77, s77, 0
	s_cmp_gt_u32 s78, 13
	s_cbranch_scc0 .LBB0_2396
	v_lshl_add_u64 v[222:223], v[222:223], 0, s[20:21]
	s_mov_b32 m0, s58
	s_nop 0
	global_load_lds_dwordx4 v[222:223], off
	v_lshl_add_u64 v[224:225], v[224:225], 0, s[20:21]
	s_mov_b32 m0, s59
	s_nop 0
	global_load_lds_dwordx4 v[224:225], off
	s_and_b64 vcc, exec, s[22:23]
	s_cbranch_vccz .LBB0_2399
	s_barrier

.LBB0_2532:
	s_add_u32 s60, s26, 0x100
	v_mov_b32_e32 v0, 0
	s_addc_u32 s61, s27, 0
	s_mov_b32 s62, -2
	v_mov_b32_e32 v1, v0
	v_mov_b32_e32 v2, v0
	v_mov_b32_e32 v3, v0
	v_mov_b32_e32 v4, v0
	v_mov_b32_e32 v5, v0
	v_mov_b32_e32 v6, v0
	v_mov_b32_e32 v7, v0
	v_mov_b32_e32 v16, v0
	v_mov_b32_e32 v17, v0
	v_mov_b32_e32 v18, v0
	v_mov_b32_e32 v19, v0
	v_mov_b32_e32 v20, v0
	v_mov_b32_e32 v21, v0
	v_mov_b32_e32 v22, v0
	v_mov_b32_e32 v23, v0
	v_mov_b32_e32 v32, v0
	v_mov_b32_e32 v33, v0
	v_mov_b32_e32 v34, v0
	v_mov_b32_e32 v35, v0
	v_mov_b32_e32 v36, v0
	v_mov_b32_e32 v37, v0
	v_mov_b32_e32 v38, v0
	v_mov_b32_e32 v39, v0
	v_mov_b32_e32 v48, v0
	v_mov_b32_e32 v49, v0
	v_mov_b32_e32 v50, v0
	v_mov_b32_e32 v51, v0
	v_mov_b32_e32 v52, v0
	v_mov_b32_e32 v53, v0
	v_mov_b32_e32 v54, v0
	v_mov_b32_e32 v55, v0
	v_mov_b32_e32 v8, v0
	v_mov_b32_e32 v9, v0
	v_mov_b32_e32 v10, v0
	v_mov_b32_e32 v11, v0
	v_mov_b32_e32 v12, v0
	v_mov_b32_e32 v13, v0
	v_mov_b32_e32 v14, v0
	v_mov_b32_e32 v15, v0
	v_mov_b32_e32 v24, v0
	v_mov_b32_e32 v25, v0
	v_mov_b32_e32 v26, v0
	v_mov_b32_e32 v27, v0
	v_mov_b32_e32 v28, v0
	v_mov_b32_e32 v29, v0
	v_mov_b32_e32 v30, v0
	v_mov_b32_e32 v31, v0
	v_mov_b32_e32 v40, v0
	v_mov_b32_e32 v41, v0
	v_mov_b32_e32 v42, v0
	v_mov_b32_e32 v43, v0
	v_mov_b32_e32 v44, v0
	v_mov_b32_e32 v45, v0
	v_mov_b32_e32 v46, v0
	v_mov_b32_e32 v47, v0
	v_mov_b32_e32 v56, v0
	v_mov_b32_e32 v57, v0
	v_mov_b32_e32 v58, v0
	v_mov_b32_e32 v59, v0
	v_mov_b32_e32 v60, v0
	v_mov_b32_e32 v61, v0
	v_mov_b32_e32 v62, v0
	v_mov_b32_e32 v63, v0
	v_mov_b32_e32 v64, v0
	v_mov_b32_e32 v65, v0
	v_mov_b32_e32 v66, v0
	v_mov_b32_e32 v67, v0
	v_mov_b32_e32 v68, v0
	v_mov_b32_e32 v69, v0
	v_mov_b32_e32 v70, v0
	v_mov_b32_e32 v71, v0
	v_mov_b32_e32 v80, v0
	v_mov_b32_e32 v81, v0
	v_mov_b32_e32 v82, v0
	v_mov_b32_e32 v83, v0
	v_mov_b32_e32 v84, v0
	v_mov_b32_e32 v85, v0
	v_mov_b32_e32 v86, v0
	v_mov_b32_e32 v87, v0
	v_mov_b32_e32 v96, v0
	v_mov_b32_e32 v97, v0
	v_mov_b32_e32 v98, v0
	v_mov_b32_e32 v99, v0
	v_mov_b32_e32 v100, v0
	v_mov_b32_e32 v101, v0
	v_mov_b32_e32 v102, v0
	v_mov_b32_e32 v103, v0
	v_mov_b32_e32 v112, v0
	v_mov_b32_e32 v113, v0
	v_mov_b32_e32 v114, v0
	v_mov_b32_e32 v115, v0
	v_mov_b32_e32 v116, v0
	v_mov_b32_e32 v117, v0
	v_mov_b32_e32 v118, v0
	v_mov_b32_e32 v119, v0
	v_mov_b32_e32 v72, v0
	v_mov_b32_e32 v73, v0
	v_mov_b32_e32 v74, v0
	v_mov_b32_e32 v75, v0
	v_mov_b32_e32 v76, v0
	v_mov_b32_e32 v77, v0
	v_mov_b32_e32 v78, v0
	v_mov_b32_e32 v79, v0
	v_mov_b32_e32 v88, v0
	v_mov_b32_e32 v89, v0
	v_mov_b32_e32 v90, v0
	v_mov_b32_e32 v91, v0
	v_mov_b32_e32 v92, v0
	v_mov_b32_e32 v93, v0
	v_mov_b32_e32 v94, v0
	v_mov_b32_e32 v95, v0
	v_mov_b32_e32 v104, v0
	v_mov_b32_e32 v105, v0
	v_mov_b32_e32 v106, v0
	v_mov_b32_e32 v107, v0
	v_mov_b32_e32 v108, v0
	v_mov_b32_e32 v109, v0
	v_mov_b32_e32 v110, v0
	v_mov_b32_e32 v111, v0
	v_mov_b32_e32 v120, v0
	v_mov_b32_e32 v121, v0
	v_mov_b32_e32 v122, v0
	v_mov_b32_e32 v123, v0
	v_mov_b32_e32 v124, v0
	v_mov_b32_e32 v125, v0
	v_mov_b32_e32 v126, v0
	v_mov_b32_e32 v127, v0
	s_mov_b32 s99, 0
.LBB0_2533:
	ds_read_b128 v[152:155], v148
	ds_read_b128 v[156:159], v148 offset:1024
	ds_read_b128 v[160:163], v148 offset:2048
	ds_read_b128 v[164:167], v148 offset:3072
	ds_read_b128 v[168:171], v149
	ds_read_b128 v[172:175], v149 offset:1024
	ds_read_b128 v[176:179], v149 offset:2048
	ds_read_b128 v[180:183], v149 offset:3072
	s_add_u32 s26, s24, 0x100
	s_addc_u32 s27, s25, 0
	s_cmp_eq_u32 s62, 8
	s_cselect_b32 s31, s21, s27
	s_cselect_b32 s30, s20, s26
	s_cselect_b32 s29, s23, s61
	s_cselect_b32 s28, s22, s60
	v_lshl_add_u64 v[192:193], s[24:25], 0, v[138:139]
	ds_read_b128 v[184:187], v150
	ds_read_b128 v[188:191], v150 offset:1024
	ds_read_b128 v[196:199], v150 offset:2048
	ds_read_b128 v[200:203], v150 offset:3072
	ds_read_b128 v[204:207], v150 offset:4096
	ds_read_b128 v[208:211], v150 offset:5120
	ds_read_b128 v[212:215], v150 offset:6144
	ds_read_b128 v[216:219], v150 offset:7168
	s_cmp_eq_u32 s99, 0
	s_cbranch_scc1 .Lkb_first_19
	v_lshl_add_u64 v[222:223], v[222:223], 0, s[16:17]
	s_mov_b32 m0, s45
	s_nop 0
	global_load_lds_dwordx4 v[222:223], off
	v_lshl_add_u64 v[224:225], v[224:225], 0, s[16:17]
	s_mov_b32 m0, s48
	s_nop 0
	global_load_lds_dwordx4 v[224:225], off
	s_branch .Lkb_join_19
.Lkb_first_19:
	s_mov_b32 m0, s53
	s_nop 0
	global_load_lds_dwordx4 v[192:193], off
	global_load_lds_dwordx4 v[192:193], off
.Lkb_join_19:
	s_mov_b32 m0, s53
	s_nop 0
	global_load_lds_dwordx4 v[192:193], off
	v_lshl_add_u64 v[192:193], s[24:25], 0, v[140:141]
	s_add_i32 m0, s40, 0xe000
	s_nop 0
	global_load_lds_dwordx4 v[192:193], off
	s_waitcnt vmcnt(8)
	s_waitcnt lgkmcnt(0)
	s_barrier
	s_setprio 1
	s_waitcnt lgkmcnt(0)
	v_mfma_f32_16x16x32_bf16 v[124:127], v[152:155], v[184:187], v[124:127]
	v_mfma_f32_16x16x32_bf16 v[120:123], v[160:163], v[184:187], v[120:123]
	v_mfma_f32_16x16x32_bf16 v[108:111], v[152:155], v[196:199], v[108:111]
	v_mfma_f32_16x16x32_bf16 v[104:107], v[160:163], v[196:199], v[104:107]
	v_mfma_f32_16x16x32_bf16 v[92:95], v[152:155], v[204:207], v[92:95]
	v_mfma_f32_16x16x32_bf16 v[88:91], v[160:163], v[204:207], v[88:91]
	v_mfma_f32_16x16x32_bf16 v[76:79], v[152:155], v[212:215], v[76:79]
	v_mfma_f32_16x16x32_bf16 v[72:75], v[160:163], v[212:215], v[72:75]
	v_mfma_f32_16x16x32_bf16 v[124:127], v[156:159], v[188:191], v[124:127]
	v_mfma_f32_16x16x32_bf16 v[120:123], v[164:167], v[188:191], v[120:123]
	v_mfma_f32_16x16x32_bf16 v[108:111], v[156:159], v[200:203], v[108:111]
	v_mfma_f32_16x16x32_bf16 v[104:107], v[164:167], v[200:203], v[104:107]
	v_mfma_f32_16x16x32_bf16 v[92:95], v[156:159], v[208:211], v[92:95]
	v_mfma_f32_16x16x32_bf16 v[88:91], v[164:167], v[208:211], v[88:91]
	v_mfma_f32_16x16x32_bf16 v[76:79], v[156:159], v[216:219], v[76:79]
	v_mfma_f32_16x16x32_bf16 v[72:75], v[164:167], v[216:219], v[72:75]
	s_setprio 0
	s_setprio 1
	v_mfma_f32_16x16x32_bf16 v[116:119], v[168:171], v[184:187], v[116:119]
	v_mfma_f32_16x16x32_bf16 v[112:115], v[176:179], v[184:187], v[112:115]
	v_mfma_f32_16x16x32_bf16 v[100:103], v[168:171], v[196:199], v[100:103]
	v_mfma_f32_16x16x32_bf16 v[96:99], v[176:179], v[196:199], v[96:99]
	v_mfma_f32_16x16x32_bf16 v[84:87], v[168:171], v[204:207], v[84:87]
	v_mfma_f32_16x16x32_bf16 v[80:83], v[176:179], v[204:207], v[80:83]
	v_mfma_f32_16x16x32_bf16 v[68:71], v[168:171], v[212:215], v[68:71]
	v_mfma_f32_16x16x32_bf16 v[64:67], v[176:179], v[212:215], v[64:67]
	v_mfma_f32_16x16x32_bf16 v[116:119], v[172:175], v[188:191], v[116:119]
	v_mfma_f32_16x16x32_bf16 v[112:115], v[180:183], v[188:191], v[112:115]
	v_mfma_f32_16x16x32_bf16 v[100:103], v[172:175], v[200:203], v[100:103]
	v_mfma_f32_16x16x32_bf16 v[96:99], v[180:183], v[200:203], v[96:99]
	v_mfma_f32_16x16x32_bf16 v[84:87], v[172:175], v[208:211], v[84:87]
	v_mfma_f32_16x16x32_bf16 v[80:83], v[180:183], v[208:211], v[80:83]
	v_mfma_f32_16x16x32_bf16 v[68:71], v[172:175], v[216:219], v[68:71]
	v_mfma_f32_16x16x32_bf16 v[64:67], v[180:183], v[216:219], v[64:67]
	s_setprio 0
	s_barrier
	s_add_i32 s24, s51, s39
	v_lshl_add_u64 v[192:193], s[28:29], 0, v[132:133]
	s_mov_b32 m0, s24
	ds_read_b128 v[184:187], v150 offset:16384
	ds_read_b128 v[188:191], v150 offset:17408
	ds_read_b128 v[196:199], v150 offset:18432
	ds_read_b128 v[200:203], v150 offset:19456
	ds_read_b128 v[204:207], v150 offset:20480
	ds_read_b128 v[208:211], v150 offset:21504
	ds_read_b128 v[212:215], v150 offset:22528
	ds_read_b128 v[216:219], v150 offset:23552
	global_load_lds_dwordx4 v[192:193], off
	s_add_i32 m0, s24, 0x2000
	s_add_u32 s24, s28, 0x30000
	v_lshl_add_u64 v[220:221], s[28:29], 0, v[128:129]
	s_addc_u32 s25, s29, 0
	s_add_i32 s63, s52, s39
	global_load_lds_dwordx4 v[220:221], off
	v_lshl_add_u64 v[222:223], s[24:25], 0, v[132:133]
	s_mov_b32 m0, s63
	v_lshl_add_u64 v[224:225], s[30:31], 0, v[130:131]
	global_load_lds_dwordx4 v[222:223], off
	v_lshl_add_u64 v[222:223], s[24:25], 0, v[128:129]
	s_add_i32 m0, s63, 0x2000
	s_nop 0
	global_load_lds_dwordx4 v[222:223], off
	v_lshl_add_u64 v[222:223], s[30:31], 0, v[134:135]
	s_waitcnt vmcnt(6)
	s_waitcnt lgkmcnt(0)
	s_barrier
	s_setprio 1
	s_waitcnt lgkmcnt(0)
	v_mfma_f32_16x16x32_bf16 v[60:63], v[152:155], v[184:187], v[60:63]
	v_mfma_f32_16x16x32_bf16 v[56:59], v[160:163], v[184:187], v[56:59]
	v_mfma_f32_16x16x32_bf16 v[44:47], v[152:155], v[196:199], v[44:47]
	v_mfma_f32_16x16x32_bf16 v[40:43], v[160:163], v[196:199], v[40:43]
	v_mfma_f32_16x16x32_bf16 v[28:31], v[152:155], v[204:207], v[28:31]
	v_mfma_f32_16x16x32_bf16 v[24:27], v[160:163], v[204:207], v[24:27]
	v_mfma_f32_16x16x32_bf16 v[12:15], v[152:155], v[212:215], v[12:15]
	v_mfma_f32_16x16x32_bf16 v[8:11], v[160:163], v[212:215], v[8:11]
	v_mfma_f32_16x16x32_bf16 v[60:63], v[156:159], v[188:191], v[60:63]
	v_mfma_f32_16x16x32_bf16 v[56:59], v[164:167], v[188:191], v[56:59]
	v_mfma_f32_16x16x32_bf16 v[44:47], v[156:159], v[200:203], v[44:47]
	v_mfma_f32_16x16x32_bf16 v[40:43], v[164:167], v[200:203], v[40:43]
	v_mfma_f32_16x16x32_bf16 v[28:31], v[156:159], v[208:211], v[28:31]
	v_mfma_f32_16x16x32_bf16 v[24:27], v[164:167], v[208:211], v[24:27]
	v_mfma_f32_16x16x32_bf16 v[12:15], v[156:159], v[216:219], v[12:15]
	v_mfma_f32_16x16x32_bf16 v[8:11], v[164:167], v[216:219], v[8:11]
	s_setprio 0
	s_setprio 1
	v_mfma_f32_16x16x32_bf16 v[52:55], v[168:171], v[184:187], v[52:55]
	v_mfma_f32_16x16x32_bf16 v[48:51], v[176:179], v[184:187], v[48:51]
	v_mfma_f32_16x16x32_bf16 v[36:39], v[168:171], v[196:199], v[36:39]
	v_mfma_f32_16x16x32_bf16 v[32:35], v[176:179], v[196:199], v[32:35]
	v_mfma_f32_16x16x32_bf16 v[20:23], v[168:171], v[204:207], v[20:23]
	v_mfma_f32_16x16x32_bf16 v[16:19], v[176:179], v[204:207], v[16:19]
	v_mfma_f32_16x16x32_bf16 v[4:7], v[168:171], v[212:215], v[4:7]
	v_mfma_f32_16x16x32_bf16 v[0:3], v[176:179], v[212:215], v[0:3]
	v_mfma_f32_16x16x32_bf16 v[52:55], v[172:175], v[188:191], v[52:55]
	v_mfma_f32_16x16x32_bf16 v[48:51], v[180:183], v[188:191], v[48:51]
	v_mfma_f32_16x16x32_bf16 v[36:39], v[172:175], v[200:203], v[36:39]
	v_mfma_f32_16x16x32_bf16 v[32:35], v[180:183], v[200:203], v[32:35]
	v_mfma_f32_16x16x32_bf16 v[20:23], v[172:175], v[208:211], v[20:23]
	v_mfma_f32_16x16x32_bf16 v[16:19], v[180:183], v[208:211], v[16:19]
	v_mfma_f32_16x16x32_bf16 v[4:7], v[172:175], v[216:219], v[4:7]
	v_mfma_f32_16x16x32_bf16 v[0:3], v[180:183], v[216:219], v[0:3]
	s_setprio 0
	s_barrier
	s_add_i32 s63, 0, 0x18000
	v_add_u32_e32 v151, s63, v142
	s_add_i32 s70, 0, 0x1c000
	ds_read_b128 v[152:155], v151
	ds_read_b128 v[156:159], v151 offset:1024
	ds_read_b128 v[160:163], v151 offset:2048
	ds_read_b128 v[164:167], v151 offset:3072
	v_add_u32_e32 v151, s70, v142
	ds_read_b128 v[168:171], v151
	ds_read_b128 v[172:175], v151 offset:1024
	ds_read_b128 v[176:179], v151 offset:2048
	ds_read_b128 v[180:183], v151 offset:3072
	s_add_u32 s24, s30, 0x30000
	s_addc_u32 s25, s31, 0
	v_lshl_add_u64 v[226:227], s[24:25], 0, v[134:135]
	ds_read_b128 v[184:187], v150 offset:32768
	ds_read_b128 v[188:191], v150 offset:33792
	ds_read_b128 v[196:199], v150 offset:34816
	ds_read_b128 v[200:203], v150 offset:35840
	ds_read_b128 v[204:207], v150 offset:36864
	ds_read_b128 v[208:211], v150 offset:37888
	ds_read_b128 v[212:215], v150 offset:38912
	ds_read_b128 v[216:219], v150 offset:39936
	s_mov_b32 m0, s40
	s_nop 0
	global_load_lds_dwordx4 v[222:223], off
	s_mov_b32 m0, s41
	s_nop 0
	global_load_lds_dwordx4 v[224:225], off
	s_mov_b32 m0, s42
	s_nop 0
	global_load_lds_dwordx4 v[226:227], off
	v_lshl_add_u64 v[226:227], s[24:25], 0, v[130:131]
	s_mov_b32 m0, s43
	s_nop 0
	global_load_lds_dwordx4 v[226:227], off
	s_waitcnt vmcnt(8)
	s_waitcnt lgkmcnt(0)
	s_barrier
	s_setprio 1
	s_waitcnt lgkmcnt(0)
	v_mfma_f32_16x16x32_bf16 v[124:127], v[152:155], v[184:187], v[124:127]
	v_mfma_f32_16x16x32_bf16 v[120:123], v[160:163], v[184:187], v[120:123]
	v_mfma_f32_16x16x32_bf16 v[108:111], v[152:155], v[196:199], v[108:111]
	v_mfma_f32_16x16x32_bf16 v[104:107], v[160:163], v[196:199], v[104:107]
	v_mfma_f32_16x16x32_bf16 v[92:95], v[152:155], v[204:207], v[92:95]
	v_mfma_f32_16x16x32_bf16 v[88:91], v[160:163], v[204:207], v[88:91]
	v_mfma_f32_16x16x32_bf16 v[76:79], v[152:155], v[212:215], v[76:79]
	v_mfma_f32_16x16x32_bf16 v[72:75], v[160:163], v[212:215], v[72:75]
	v_mfma_f32_16x16x32_bf16 v[124:127], v[156:159], v[188:191], v[124:127]
	v_mfma_f32_16x16x32_bf16 v[120:123], v[164:167], v[188:191], v[120:123]
	v_mfma_f32_16x16x32_bf16 v[108:111], v[156:159], v[200:203], v[108:111]
	v_mfma_f32_16x16x32_bf16 v[104:107], v[164:167], v[200:203], v[104:107]
	v_mfma_f32_16x16x32_bf16 v[92:95], v[156:159], v[208:211], v[92:95]
	v_mfma_f32_16x16x32_bf16 v[88:91], v[164:167], v[208:211], v[88:91]
	v_mfma_f32_16x16x32_bf16 v[76:79], v[156:159], v[216:219], v[76:79]
	v_mfma_f32_16x16x32_bf16 v[72:75], v[164:167], v[216:219], v[72:75]
	s_setprio 0
	s_setprio 1
	v_mfma_f32_16x16x32_bf16 v[116:119], v[168:171], v[184:187], v[116:119]
	v_mfma_f32_16x16x32_bf16 v[112:115], v[176:179], v[184:187], v[112:115]
	v_mfma_f32_16x16x32_bf16 v[100:103], v[168:171], v[196:199], v[100:103]
	v_mfma_f32_16x16x32_bf16 v[96:99], v[176:179], v[196:199], v[96:99]
	v_mfma_f32_16x16x32_bf16 v[84:87], v[168:171], v[204:207], v[84:87]
	v_mfma_f32_16x16x32_bf16 v[80:83], v[176:179], v[204:207], v[80:83]
	v_mfma_f32_16x16x32_bf16 v[68:71], v[168:171], v[212:215], v[68:71]
	v_mfma_f32_16x16x32_bf16 v[64:67], v[176:179], v[212:215], v[64:67]
	v_mfma_f32_16x16x32_bf16 v[116:119], v[172:175], v[188:191], v[116:119]
	v_mfma_f32_16x16x32_bf16 v[112:115], v[180:183], v[188:191], v[112:115]
	v_mfma_f32_16x16x32_bf16 v[100:103], v[172:175], v[200:203], v[100:103]
	v_mfma_f32_16x16x32_bf16 v[96:99], v[180:183], v[200:203], v[96:99]
	v_mfma_f32_16x16x32_bf16 v[84:87], v[172:175], v[208:211], v[84:87]
	v_mfma_f32_16x16x32_bf16 v[80:83], v[180:183], v[208:211], v[80:83]
	v_mfma_f32_16x16x32_bf16 v[68:71], v[172:175], v[216:219], v[68:71]
	v_mfma_f32_16x16x32_bf16 v[64:67], v[180:183], v[216:219], v[64:67]
	s_setprio 0
	s_barrier
	s_add_i32 s24, s63, s39
	v_lshl_add_u64 v[192:193], v[192:193], 0, s[16:17]
	s_mov_b32 m0, s24
	ds_read_b128 v[184:187], v150 offset:49152
	ds_read_b128 v[188:191], v150 offset:50176
	ds_read_b128 v[196:199], v150 offset:51200
	ds_read_b128 v[200:203], v150 offset:52224
	ds_read_b128 v[204:207], v150 offset:53248
	ds_read_b128 v[208:211], v150 offset:54272
	ds_read_b128 v[212:215], v150 offset:55296
	ds_read_b128 v[216:219], v150 offset:56320
	global_load_lds_dwordx4 v[192:193], off
	s_add_i32 m0, s24, 0x2000
	s_add_u32 s24, s28, 0x30080
	v_lshl_add_u64 v[192:193], v[220:221], 0, s[16:17]
	s_addc_u32 s25, s29, 0
	s_add_i32 s28, s70, s39
	global_load_lds_dwordx4 v[192:193], off
	v_lshl_add_u64 v[192:193], s[24:25], 0, v[132:133]
	s_mov_b32 m0, s28
	s_nop 0
	global_load_lds_dwordx4 v[192:193], off
	v_lshl_add_u64 v[192:193], s[24:25], 0, v[128:129]
	s_add_i32 m0, s28, 0x2000
	s_nop 0
	global_load_lds_dwordx4 v[192:193], off
	s_mov_b32 s99, 1
	s_waitcnt vmcnt(6)
	s_waitcnt lgkmcnt(0)
	s_barrier
	s_setprio 1
	s_waitcnt lgkmcnt(0)
	v_mfma_f32_16x16x32_bf16 v[60:63], v[152:155], v[184:187], v[60:63]
	v_mfma_f32_16x16x32_bf16 v[56:59], v[160:163], v[184:187], v[56:59]
	v_mfma_f32_16x16x32_bf16 v[44:47], v[152:155], v[196:199], v[44:47]
	v_mfma_f32_16x16x32_bf16 v[40:43], v[160:163], v[196:199], v[40:43]
	v_mfma_f32_16x16x32_bf16 v[28:31], v[152:155], v[204:207], v[28:31]
	v_mfma_f32_16x16x32_bf16 v[24:27], v[160:163], v[204:207], v[24:27]
	v_mfma_f32_16x16x32_bf16 v[12:15], v[152:155], v[212:215], v[12:15]
	v_mfma_f32_16x16x32_bf16 v[8:11], v[160:163], v[212:215], v[8:11]
	v_mfma_f32_16x16x32_bf16 v[60:63], v[156:159], v[188:191], v[60:63]
	v_mfma_f32_16x16x32_bf16 v[56:59], v[164:167], v[188:191], v[56:59]
	v_mfma_f32_16x16x32_bf16 v[44:47], v[156:159], v[200:203], v[44:47]
	v_mfma_f32_16x16x32_bf16 v[40:43], v[164:167], v[200:203], v[40:43]
	v_mfma_f32_16x16x32_bf16 v[28:31], v[156:159], v[208:211], v[28:31]
	v_mfma_f32_16x16x32_bf16 v[24:27], v[164:167], v[208:211], v[24:27]
	v_mfma_f32_16x16x32_bf16 v[12:15], v[156:159], v[216:219], v[12:15]
	v_mfma_f32_16x16x32_bf16 v[8:11], v[164:167], v[216:219], v[8:11]
	s_setprio 0
	s_setprio 1
	v_mfma_f32_16x16x32_bf16 v[52:55], v[168:171], v[184:187], v[52:55]
	v_mfma_f32_16x16x32_bf16 v[48:51], v[176:179], v[184:187], v[48:51]
	v_mfma_f32_16x16x32_bf16 v[36:39], v[168:171], v[196:199], v[36:39]
	v_mfma_f32_16x16x32_bf16 v[32:35], v[176:179], v[196:199], v[32:35]
	v_mfma_f32_16x16x32_bf16 v[20:23], v[168:171], v[204:207], v[20:23]
	v_mfma_f32_16x16x32_bf16 v[16:19], v[176:179], v[204:207], v[16:19]
	v_mfma_f32_16x16x32_bf16 v[4:7], v[168:171], v[212:215], v[4:7]
	v_mfma_f32_16x16x32_bf16 v[0:3], v[176:179], v[212:215], v[0:3]
	v_mfma_f32_16x16x32_bf16 v[52:55], v[172:175], v[188:191], v[52:55]
	v_mfma_f32_16x16x32_bf16 v[48:51], v[180:183], v[188:191], v[48:51]
	v_mfma_f32_16x16x32_bf16 v[36:39], v[172:175], v[200:203], v[36:39]
	v_mfma_f32_16x16x32_bf16 v[32:35], v[180:183], v[200:203], v[32:35]
	v_mfma_f32_16x16x32_bf16 v[20:23], v[172:175], v[208:211], v[20:23]
	v_mfma_f32_16x16x32_bf16 v[16:19], v[180:183], v[208:211], v[16:19]
	v_mfma_f32_16x16x32_bf16 v[4:7], v[172:175], v[216:219], v[4:7]
	v_mfma_f32_16x16x32_bf16 v[0:3], v[180:183], v[216:219], v[0:3]
	s_setprio 0
	s_barrier
	s_add_i32 s62, s62, 2
	s_add_u32 s60, s60, 0x100
	s_addc_u32 s61, s61, 0
	s_cmp_gt_u32 s62, 9
	s_mov_b64 s[24:25], s[26:27]
	s_cbranch_scc0 .LBB0_2533
	v_lshl_add_u64 v[222:223], v[222:223], 0, s[16:17]
	s_mov_b32 m0, s45
	s_nop 0
	global_load_lds_dwordx4 v[222:223], off
	v_lshl_add_u64 v[224:225], v[224:225], 0, s[16:17]
	s_mov_b32 m0, s48
	s_nop 0
	global_load_lds_dwordx4 v[224:225], off
	s_and_b64 vcc, exec, s[18:19]
	s_cbranch_vccz .LBB0_2536
	s_barrier

.LBB0_2556:
	s_ashr_i32 s27, s26, 31
	s_lshl_b64 s[28:29], s[26:27], 19
	s_add_u32 s28, s43, s28
	s_addc_u32 s29, s44, s29
	s_and_b64 s[30:31], s[8:9], exec
	s_cselect_b32 s27, s29, s35
	s_cselect_b32 s63, s28, s34
	s_ashr_i32 s25, s24, 31
	s_lshl_b64 s[30:31], s[24:25], 19
	s_add_u32 s30, s45, s30
	s_addc_u32 s31, s48, s31
	s_and_b64 s[38:39], s[8:9], exec
	s_cselect_b32 s25, s31, s37
	s_cselect_b32 s70, s30, s36
	s_add_u32 s34, s34, 0x40080
	s_addc_u32 s35, s35, 0
	s_add_u32 s71, s36, 0x100
	v_mov_b32_e32 v0, 0
	s_addc_u32 s72, s37, 0
	s_mov_b32 s73, -2
	v_mov_b32_e32 v1, v0
	v_mov_b32_e32 v2, v0
	v_mov_b32_e32 v3, v0
	v_mov_b32_e32 v4, v0
	v_mov_b32_e32 v5, v0
	v_mov_b32_e32 v6, v0
	v_mov_b32_e32 v7, v0
	v_mov_b32_e32 v16, v0
	v_mov_b32_e32 v17, v0
	v_mov_b32_e32 v18, v0
	v_mov_b32_e32 v19, v0
	v_mov_b32_e32 v20, v0
	v_mov_b32_e32 v21, v0
	v_mov_b32_e32 v22, v0
	v_mov_b32_e32 v23, v0
	v_mov_b32_e32 v32, v0
	v_mov_b32_e32 v33, v0
	v_mov_b32_e32 v34, v0
	v_mov_b32_e32 v35, v0
	v_mov_b32_e32 v36, v0
	v_mov_b32_e32 v37, v0
	v_mov_b32_e32 v38, v0
	v_mov_b32_e32 v39, v0
	v_mov_b32_e32 v48, v0
	v_mov_b32_e32 v49, v0
	v_mov_b32_e32 v50, v0
	v_mov_b32_e32 v51, v0
	v_mov_b32_e32 v52, v0
	v_mov_b32_e32 v53, v0
	v_mov_b32_e32 v54, v0
	v_mov_b32_e32 v55, v0
	v_mov_b32_e32 v8, v0
	v_mov_b32_e32 v9, v0
	v_mov_b32_e32 v10, v0
	v_mov_b32_e32 v11, v0
	v_mov_b32_e32 v12, v0
	v_mov_b32_e32 v13, v0
	v_mov_b32_e32 v14, v0
	v_mov_b32_e32 v15, v0
	v_mov_b32_e32 v24, v0
	v_mov_b32_e32 v25, v0
	v_mov_b32_e32 v26, v0
	v_mov_b32_e32 v27, v0
	v_mov_b32_e32 v28, v0
	v_mov_b32_e32 v29, v0
	v_mov_b32_e32 v30, v0
	v_mov_b32_e32 v31, v0
	v_mov_b32_e32 v40, v0
	v_mov_b32_e32 v41, v0
	v_mov_b32_e32 v42, v0
	v_mov_b32_e32 v43, v0
	v_mov_b32_e32 v44, v0
	v_mov_b32_e32 v45, v0
	v_mov_b32_e32 v46, v0
	v_mov_b32_e32 v47, v0
	v_mov_b32_e32 v56, v0
	v_mov_b32_e32 v57, v0
	v_mov_b32_e32 v58, v0
	v_mov_b32_e32 v59, v0
	v_mov_b32_e32 v60, v0
	v_mov_b32_e32 v61, v0
	v_mov_b32_e32 v62, v0
	v_mov_b32_e32 v63, v0
	v_mov_b32_e32 v64, v0
	v_mov_b32_e32 v65, v0
	v_mov_b32_e32 v66, v0
	v_mov_b32_e32 v67, v0
	v_mov_b32_e32 v68, v0
	v_mov_b32_e32 v69, v0
	v_mov_b32_e32 v70, v0
	v_mov_b32_e32 v71, v0
	v_mov_b32_e32 v80, v0
	v_mov_b32_e32 v81, v0
	v_mov_b32_e32 v82, v0
	v_mov_b32_e32 v83, v0
	v_mov_b32_e32 v84, v0
	v_mov_b32_e32 v85, v0
	v_mov_b32_e32 v86, v0
	v_mov_b32_e32 v87, v0
	v_mov_b32_e32 v96, v0
	v_mov_b32_e32 v97, v0
	v_mov_b32_e32 v98, v0
	v_mov_b32_e32 v99, v0
	v_mov_b32_e32 v100, v0
	v_mov_b32_e32 v101, v0
	v_mov_b32_e32 v102, v0
	v_mov_b32_e32 v103, v0
	v_mov_b32_e32 v112, v0
	v_mov_b32_e32 v113, v0
	v_mov_b32_e32 v114, v0
	v_mov_b32_e32 v115, v0
	v_mov_b32_e32 v116, v0
	v_mov_b32_e32 v117, v0
	v_mov_b32_e32 v118, v0
	v_mov_b32_e32 v119, v0
	v_mov_b32_e32 v72, v0
	v_mov_b32_e32 v73, v0
	v_mov_b32_e32 v74, v0
	v_mov_b32_e32 v75, v0
	v_mov_b32_e32 v76, v0
	v_mov_b32_e32 v77, v0
	v_mov_b32_e32 v78, v0
	v_mov_b32_e32 v79, v0
	v_mov_b32_e32 v88, v0
	v_mov_b32_e32 v89, v0
	v_mov_b32_e32 v90, v0
	v_mov_b32_e32 v91, v0
	v_mov_b32_e32 v92, v0
	v_mov_b32_e32 v93, v0
	v_mov_b32_e32 v94, v0
	v_mov_b32_e32 v95, v0
	v_mov_b32_e32 v104, v0
	v_mov_b32_e32 v105, v0
	v_mov_b32_e32 v106, v0
	v_mov_b32_e32 v107, v0
	v_mov_b32_e32 v108, v0
	v_mov_b32_e32 v109, v0
	v_mov_b32_e32 v110, v0
	v_mov_b32_e32 v111, v0
	v_mov_b32_e32 v120, v0
	v_mov_b32_e32 v121, v0
	v_mov_b32_e32 v122, v0
	v_mov_b32_e32 v123, v0
	v_mov_b32_e32 v124, v0
	v_mov_b32_e32 v125, v0
	v_mov_b32_e32 v126, v0
	v_mov_b32_e32 v127, v0
	s_mov_b32 s99, 0
.LBB0_2557:
	ds_read_b128 v[144:147], v153
	ds_read_b128 v[158:161], v153 offset:1024
	ds_read_b128 v[162:165], v153 offset:2048
	ds_read_b128 v[166:169], v153 offset:3072
	ds_read_b128 v[170:173], v154
	ds_read_b128 v[174:177], v154 offset:1024
	ds_read_b128 v[178:181], v154 offset:2048
	ds_read_b128 v[182:185], v154 offset:3072
	s_add_u32 s36, s34, 0xfffc0080
	s_addc_u32 s37, s35, -1
	s_cmp_eq_u32 s73, 12
	s_cselect_b32 s39, s27, s37
	s_cselect_b32 s38, s63, s36
	s_cselect_b32 s37, s25, s72
	s_cselect_b32 s36, s70, s71
	v_lshl_add_u64 v[148:149], s[34:35], 0, v[136:137]
	ds_read_b128 v[186:189], v155
	ds_read_b128 v[190:193], v155 offset:1024
	ds_read_b128 v[196:199], v155 offset:2048
	ds_read_b128 v[200:203], v155 offset:3072
	ds_read_b128 v[204:207], v155 offset:4096
	ds_read_b128 v[208:211], v155 offset:5120
	ds_read_b128 v[212:215], v155 offset:6144
	ds_read_b128 v[216:219], v155 offset:7168
	s_cmp_eq_u32 s99, 0
	s_cbranch_scc1 .Lkb_first_20
	v_lshl_add_u64 v[222:223], v[222:223], 0, s[20:21]
	s_mov_b32 m0, s56
	s_nop 0
	global_load_lds_dwordx4 v[222:223], off
	v_lshl_add_u64 v[224:225], v[224:225], 0, s[20:21]
	s_mov_b32 m0, s57
	s_nop 0
	global_load_lds_dwordx4 v[224:225], off
	s_branch .Lkb_join_20
.Lkb_first_20:
	s_add_i32 m0, s51, 0xc000
	s_nop 0
	global_load_lds_dwordx4 v[148:149], off
	global_load_lds_dwordx4 v[148:149], off
.Lkb_join_20:
	s_add_i32 m0, s51, 0xc000
	s_nop 0
	global_load_lds_dwordx4 v[148:149], off
	v_lshl_add_u64 v[148:149], s[34:35], 0, v[138:139]
	s_add_i32 m0, s51, 0xe000
	s_nop 0
	global_load_lds_dwordx4 v[148:149], off
	s_waitcnt vmcnt(8)
	s_waitcnt lgkmcnt(0)
	s_barrier
	s_setprio 1
	s_waitcnt lgkmcnt(0)
	v_mfma_f32_16x16x32_bf16 v[124:127], v[144:147], v[186:189], v[124:127]
	v_mfma_f32_16x16x32_bf16 v[120:123], v[162:165], v[186:189], v[120:123]
	v_mfma_f32_16x16x32_bf16 v[108:111], v[144:147], v[196:199], v[108:111]
	v_mfma_f32_16x16x32_bf16 v[104:107], v[162:165], v[196:199], v[104:107]
	v_mfma_f32_16x16x32_bf16 v[92:95], v[144:147], v[204:207], v[92:95]
	v_mfma_f32_16x16x32_bf16 v[88:91], v[162:165], v[204:207], v[88:91]
	v_mfma_f32_16x16x32_bf16 v[76:79], v[144:147], v[212:215], v[76:79]
	v_mfma_f32_16x16x32_bf16 v[72:75], v[162:165], v[212:215], v[72:75]
	v_mfma_f32_16x16x32_bf16 v[124:127], v[158:161], v[190:193], v[124:127]
	v_mfma_f32_16x16x32_bf16 v[120:123], v[166:169], v[190:193], v[120:123]
	v_mfma_f32_16x16x32_bf16 v[108:111], v[158:161], v[200:203], v[108:111]
	v_mfma_f32_16x16x32_bf16 v[104:107], v[166:169], v[200:203], v[104:107]
	v_mfma_f32_16x16x32_bf16 v[92:95], v[158:161], v[208:211], v[92:95]
	v_mfma_f32_16x16x32_bf16 v[88:91], v[166:169], v[208:211], v[88:91]
	v_mfma_f32_16x16x32_bf16 v[76:79], v[158:161], v[216:219], v[76:79]
	v_mfma_f32_16x16x32_bf16 v[72:75], v[166:169], v[216:219], v[72:75]
	s_setprio 0
	s_setprio 1
	v_mfma_f32_16x16x32_bf16 v[116:119], v[170:173], v[186:189], v[116:119]
	v_mfma_f32_16x16x32_bf16 v[112:115], v[178:181], v[186:189], v[112:115]
	v_mfma_f32_16x16x32_bf16 v[100:103], v[170:173], v[196:199], v[100:103]
	v_mfma_f32_16x16x32_bf16 v[96:99], v[178:181], v[196:199], v[96:99]
	v_mfma_f32_16x16x32_bf16 v[84:87], v[170:173], v[204:207], v[84:87]
	v_mfma_f32_16x16x32_bf16 v[80:83], v[178:181], v[204:207], v[80:83]
	v_mfma_f32_16x16x32_bf16 v[68:71], v[170:173], v[212:215], v[68:71]
	v_mfma_f32_16x16x32_bf16 v[64:67], v[178:181], v[212:215], v[64:67]
	v_mfma_f32_16x16x32_bf16 v[116:119], v[174:177], v[190:193], v[116:119]
	v_mfma_f32_16x16x32_bf16 v[112:115], v[182:185], v[190:193], v[112:115]
	v_mfma_f32_16x16x32_bf16 v[100:103], v[174:177], v[200:203], v[100:103]
	v_mfma_f32_16x16x32_bf16 v[96:99], v[182:185], v[200:203], v[96:99]
	v_mfma_f32_16x16x32_bf16 v[84:87], v[174:177], v[208:211], v[84:87]
	v_mfma_f32_16x16x32_bf16 v[80:83], v[182:185], v[208:211], v[80:83]
	v_mfma_f32_16x16x32_bf16 v[68:71], v[174:177], v[216:219], v[68:71]
	v_mfma_f32_16x16x32_bf16 v[64:67], v[182:185], v[216:219], v[64:67]
	s_setprio 0
	s_barrier
	s_add_i32 s77, s59, s49
	v_lshl_add_u64 v[148:149], s[36:37], 0, v[130:131]
	s_mov_b32 m0, s77
	ds_read_b128 v[186:189], v155 offset:16384
	ds_read_b128 v[190:193], v155 offset:17408
	ds_read_b128 v[196:199], v155 offset:18432
	ds_read_b128 v[200:203], v155 offset:19456
	ds_read_b128 v[204:207], v155 offset:20480
	ds_read_b128 v[208:211], v155 offset:21504
	ds_read_b128 v[212:215], v155 offset:22528
	ds_read_b128 v[216:219], v155 offset:23552
	global_load_lds_dwordx4 v[148:149], off
	s_add_i32 m0, s77, 0x2000
	s_add_u32 s78, s36, 0x40000
	v_lshl_add_u64 v[220:221], s[36:37], 0, v[134:135]
	s_addc_u32 s79, s37, 0
	s_add_i32 s77, s60, s49
	global_load_lds_dwordx4 v[220:221], off
	v_lshl_add_u64 v[222:223], s[78:79], 0, v[130:131]
	s_mov_b32 m0, s77
	v_lshl_add_u64 v[224:225], s[38:39], 0, v[132:133]
	global_load_lds_dwordx4 v[222:223], off
	v_lshl_add_u64 v[222:223], s[78:79], 0, v[134:135]
	s_add_i32 m0, s77, 0x2000
	s_nop 0
	global_load_lds_dwordx4 v[222:223], off
	v_lshl_add_u64 v[222:223], s[38:39], 0, v[128:129]
	s_waitcnt vmcnt(6)
	s_waitcnt lgkmcnt(0)
	s_barrier
	s_setprio 1
	s_waitcnt lgkmcnt(0)
	v_mfma_f32_16x16x32_bf16 v[60:63], v[144:147], v[186:189], v[60:63]
	v_mfma_f32_16x16x32_bf16 v[56:59], v[162:165], v[186:189], v[56:59]
	v_mfma_f32_16x16x32_bf16 v[44:47], v[144:147], v[196:199], v[44:47]
	v_mfma_f32_16x16x32_bf16 v[40:43], v[162:165], v[196:199], v[40:43]
	v_mfma_f32_16x16x32_bf16 v[28:31], v[144:147], v[204:207], v[28:31]
	v_mfma_f32_16x16x32_bf16 v[24:27], v[162:165], v[204:207], v[24:27]
	v_mfma_f32_16x16x32_bf16 v[12:15], v[144:147], v[212:215], v[12:15]
	v_mfma_f32_16x16x32_bf16 v[8:11], v[162:165], v[212:215], v[8:11]
	v_mfma_f32_16x16x32_bf16 v[60:63], v[158:161], v[190:193], v[60:63]
	v_mfma_f32_16x16x32_bf16 v[56:59], v[166:169], v[190:193], v[56:59]
	v_mfma_f32_16x16x32_bf16 v[44:47], v[158:161], v[200:203], v[44:47]
	v_mfma_f32_16x16x32_bf16 v[40:43], v[166:169], v[200:203], v[40:43]
	v_mfma_f32_16x16x32_bf16 v[28:31], v[158:161], v[208:211], v[28:31]
	v_mfma_f32_16x16x32_bf16 v[24:27], v[166:169], v[208:211], v[24:27]
	v_mfma_f32_16x16x32_bf16 v[12:15], v[158:161], v[216:219], v[12:15]
	v_mfma_f32_16x16x32_bf16 v[8:11], v[166:169], v[216:219], v[8:11]
	s_setprio 0
	s_setprio 1
	v_mfma_f32_16x16x32_bf16 v[52:55], v[170:173], v[186:189], v[52:55]
	v_mfma_f32_16x16x32_bf16 v[48:51], v[178:181], v[186:189], v[48:51]
	v_mfma_f32_16x16x32_bf16 v[36:39], v[170:173], v[196:199], v[36:39]
	v_mfma_f32_16x16x32_bf16 v[32:35], v[178:181], v[196:199], v[32:35]
	v_mfma_f32_16x16x32_bf16 v[20:23], v[170:173], v[204:207], v[20:23]
	v_mfma_f32_16x16x32_bf16 v[16:19], v[178:181], v[204:207], v[16:19]
	v_mfma_f32_16x16x32_bf16 v[4:7], v[170:173], v[212:215], v[4:7]
	v_mfma_f32_16x16x32_bf16 v[0:3], v[178:181], v[212:215], v[0:3]
	v_mfma_f32_16x16x32_bf16 v[52:55], v[174:177], v[190:193], v[52:55]
	v_mfma_f32_16x16x32_bf16 v[48:51], v[182:185], v[190:193], v[48:51]
	v_mfma_f32_16x16x32_bf16 v[36:39], v[174:177], v[200:203], v[36:39]
	v_mfma_f32_16x16x32_bf16 v[32:35], v[182:185], v[200:203], v[32:35]
	v_mfma_f32_16x16x32_bf16 v[20:23], v[174:177], v[208:211], v[20:23]
	v_mfma_f32_16x16x32_bf16 v[16:19], v[182:185], v[208:211], v[16:19]
	v_mfma_f32_16x16x32_bf16 v[4:7], v[174:177], v[216:219], v[4:7]
	v_mfma_f32_16x16x32_bf16 v[0:3], v[182:185], v[216:219], v[0:3]
	s_setprio 0
	s_barrier
	s_add_i32 s77, 0, 0x18000
	v_add_u32_e32 v157, s77, v151
	s_add_i32 s78, 0, 0x1c000
	ds_read_b128 v[144:147], v157
	ds_read_b128 v[158:161], v157 offset:1024
	ds_read_b128 v[162:165], v157 offset:2048
	ds_read_b128 v[166:169], v157 offset:3072
	v_add_u32_e32 v157, s78, v151
	ds_read_b128 v[170:173], v157
	ds_read_b128 v[174:177], v157 offset:1024
	ds_read_b128 v[178:181], v157 offset:2048
	ds_read_b128 v[182:185], v157 offset:3072
	s_add_u32 s38, s38, 0x40000
	s_addc_u32 s39, s39, 0
	v_lshl_add_u64 v[226:227], s[38:39], 0, v[128:129]
	ds_read_b128 v[186:189], v155 offset:32768
	ds_read_b128 v[190:193], v155 offset:33792
	ds_read_b128 v[196:199], v155 offset:34816
	ds_read_b128 v[200:203], v155 offset:35840
	ds_read_b128 v[204:207], v155 offset:36864
	ds_read_b128 v[208:211], v155 offset:37888
	ds_read_b128 v[212:215], v155 offset:38912
	ds_read_b128 v[216:219], v155 offset:39936
	s_mov_b32 m0, s51
	s_nop 0
	global_load_lds_dwordx4 v[222:223], off
	s_mov_b32 m0, s52
	s_nop 0
	global_load_lds_dwordx4 v[224:225], off
	s_mov_b32 m0, s53
	s_nop 0
	global_load_lds_dwordx4 v[226:227], off
	v_lshl_add_u64 v[226:227], s[38:39], 0, v[132:133]
	s_mov_b32 m0, s54
	s_nop 0
	global_load_lds_dwordx4 v[226:227], off
	s_waitcnt vmcnt(8)
	s_waitcnt lgkmcnt(0)
	s_barrier
	s_setprio 1
	s_waitcnt lgkmcnt(0)
	v_mfma_f32_16x16x32_bf16 v[124:127], v[144:147], v[186:189], v[124:127]
	v_mfma_f32_16x16x32_bf16 v[120:123], v[162:165], v[186:189], v[120:123]
	v_mfma_f32_16x16x32_bf16 v[108:111], v[144:147], v[196:199], v[108:111]
	v_mfma_f32_16x16x32_bf16 v[104:107], v[162:165], v[196:199], v[104:107]
	v_mfma_f32_16x16x32_bf16 v[92:95], v[144:147], v[204:207], v[92:95]
	v_mfma_f32_16x16x32_bf16 v[88:91], v[162:165], v[204:207], v[88:91]
	v_mfma_f32_16x16x32_bf16 v[76:79], v[144:147], v[212:215], v[76:79]
	v_mfma_f32_16x16x32_bf16 v[72:75], v[162:165], v[212:215], v[72:75]
	v_mfma_f32_16x16x32_bf16 v[124:127], v[158:161], v[190:193], v[124:127]
	v_mfma_f32_16x16x32_bf16 v[120:123], v[166:169], v[190:193], v[120:123]
	v_mfma_f32_16x16x32_bf16 v[108:111], v[158:161], v[200:203], v[108:111]
	v_mfma_f32_16x16x32_bf16 v[104:107], v[166:169], v[200:203], v[104:107]
	v_mfma_f32_16x16x32_bf16 v[92:95], v[158:161], v[208:211], v[92:95]
	v_mfma_f32_16x16x32_bf16 v[88:91], v[166:169], v[208:211], v[88:91]
	v_mfma_f32_16x16x32_bf16 v[76:79], v[158:161], v[216:219], v[76:79]
	v_mfma_f32_16x16x32_bf16 v[72:75], v[166:169], v[216:219], v[72:75]
	s_setprio 0
	s_setprio 1
	v_mfma_f32_16x16x32_bf16 v[116:119], v[170:173], v[186:189], v[116:119]
	v_mfma_f32_16x16x32_bf16 v[112:115], v[178:181], v[186:189], v[112:115]
	v_mfma_f32_16x16x32_bf16 v[100:103], v[170:173], v[196:199], v[100:103]
	v_mfma_f32_16x16x32_bf16 v[96:99], v[178:181], v[196:199], v[96:99]
	v_mfma_f32_16x16x32_bf16 v[84:87], v[170:173], v[204:207], v[84:87]
	v_mfma_f32_16x16x32_bf16 v[80:83], v[178:181], v[204:207], v[80:83]
	v_mfma_f32_16x16x32_bf16 v[68:71], v[170:173], v[212:215], v[68:71]
	v_mfma_f32_16x16x32_bf16 v[64:67], v[178:181], v[212:215], v[64:67]
	v_mfma_f32_16x16x32_bf16 v[116:119], v[174:177], v[190:193], v[116:119]
	v_mfma_f32_16x16x32_bf16 v[112:115], v[182:185], v[190:193], v[112:115]
	v_mfma_f32_16x16x32_bf16 v[100:103], v[174:177], v[200:203], v[100:103]
	v_mfma_f32_16x16x32_bf16 v[96:99], v[182:185], v[200:203], v[96:99]
	v_mfma_f32_16x16x32_bf16 v[84:87], v[174:177], v[208:211], v[84:87]
	v_mfma_f32_16x16x32_bf16 v[80:83], v[182:185], v[208:211], v[80:83]
	v_mfma_f32_16x16x32_bf16 v[68:71], v[174:177], v[216:219], v[68:71]
	v_mfma_f32_16x16x32_bf16 v[64:67], v[182:185], v[216:219], v[64:67]
	s_setprio 0
	s_barrier
	s_add_i32 s38, s77, s49
	v_lshl_add_u64 v[148:149], v[148:149], 0, s[20:21]
	s_mov_b32 m0, s38
	ds_read_b128 v[186:189], v155 offset:49152
	ds_read_b128 v[190:193], v155 offset:50176
	ds_read_b128 v[196:199], v155 offset:51200
	ds_read_b128 v[200:203], v155 offset:52224
	ds_read_b128 v[204:207], v155 offset:53248
	ds_read_b128 v[208:211], v155 offset:54272
	ds_read_b128 v[212:215], v155 offset:55296
	ds_read_b128 v[216:219], v155 offset:56320
	global_load_lds_dwordx4 v[148:149], off
	s_add_i32 m0, s38, 0x2000
	s_add_u32 s36, s36, 0x40080
	v_lshl_add_u64 v[148:149], v[220:221], 0, s[20:21]
	s_addc_u32 s37, s37, 0
	s_add_i32 s38, s78, s49
	global_load_lds_dwordx4 v[148:149], off
	v_lshl_add_u64 v[148:149], s[36:37], 0, v[130:131]
	s_mov_b32 m0, s38
	s_nop 0
	global_load_lds_dwordx4 v[148:149], off
	v_lshl_add_u64 v[148:149], s[36:37], 0, v[134:135]
	s_add_i32 m0, s38, 0x2000
	s_nop 0
	global_load_lds_dwordx4 v[148:149], off
	s_mov_b32 s99, 1
	s_waitcnt vmcnt(6)
	s_waitcnt lgkmcnt(0)
	s_barrier
	s_setprio 1
	s_waitcnt lgkmcnt(0)
	v_mfma_f32_16x16x32_bf16 v[60:63], v[144:147], v[186:189], v[60:63]
	v_mfma_f32_16x16x32_bf16 v[56:59], v[162:165], v[186:189], v[56:59]
	v_mfma_f32_16x16x32_bf16 v[44:47], v[144:147], v[196:199], v[44:47]
	v_mfma_f32_16x16x32_bf16 v[40:43], v[162:165], v[196:199], v[40:43]
	v_mfma_f32_16x16x32_bf16 v[28:31], v[144:147], v[204:207], v[28:31]
	v_mfma_f32_16x16x32_bf16 v[24:27], v[162:165], v[204:207], v[24:27]
	v_mfma_f32_16x16x32_bf16 v[12:15], v[144:147], v[212:215], v[12:15]
	v_mfma_f32_16x16x32_bf16 v[8:11], v[162:165], v[212:215], v[8:11]
	v_mfma_f32_16x16x32_bf16 v[60:63], v[158:161], v[190:193], v[60:63]
	v_mfma_f32_16x16x32_bf16 v[56:59], v[166:169], v[190:193], v[56:59]
	v_mfma_f32_16x16x32_bf16 v[44:47], v[158:161], v[200:203], v[44:47]
	v_mfma_f32_16x16x32_bf16 v[40:43], v[166:169], v[200:203], v[40:43]
	v_mfma_f32_16x16x32_bf16 v[28:31], v[158:161], v[208:211], v[28:31]
	v_mfma_f32_16x16x32_bf16 v[24:27], v[166:169], v[208:211], v[24:27]
	v_mfma_f32_16x16x32_bf16 v[12:15], v[158:161], v[216:219], v[12:15]
	v_mfma_f32_16x16x32_bf16 v[8:11], v[166:169], v[216:219], v[8:11]
	s_setprio 0
	s_setprio 1
	v_mfma_f32_16x16x32_bf16 v[52:55], v[170:173], v[186:189], v[52:55]
	v_mfma_f32_16x16x32_bf16 v[48:51], v[178:181], v[186:189], v[48:51]
	v_mfma_f32_16x16x32_bf16 v[36:39], v[170:173], v[196:199], v[36:39]
	v_mfma_f32_16x16x32_bf16 v[32:35], v[178:181], v[196:199], v[32:35]
	v_mfma_f32_16x16x32_bf16 v[20:23], v[170:173], v[204:207], v[20:23]
	v_mfma_f32_16x16x32_bf16 v[16:19], v[178:181], v[204:207], v[16:19]
	v_mfma_f32_16x16x32_bf16 v[4:7], v[170:173], v[212:215], v[4:7]
	v_mfma_f32_16x16x32_bf16 v[0:3], v[178:181], v[212:215], v[0:3]
	v_mfma_f32_16x16x32_bf16 v[52:55], v[174:177], v[190:193], v[52:55]
	v_mfma_f32_16x16x32_bf16 v[48:51], v[182:185], v[190:193], v[48:51]
	v_mfma_f32_16x16x32_bf16 v[36:39], v[174:177], v[200:203], v[36:39]
	v_mfma_f32_16x16x32_bf16 v[32:35], v[182:185], v[200:203], v[32:35]
	v_mfma_f32_16x16x32_bf16 v[20:23], v[174:177], v[208:211], v[20:23]
	v_mfma_f32_16x16x32_bf16 v[16:19], v[182:185], v[208:211], v[16:19]
	v_mfma_f32_16x16x32_bf16 v[4:7], v[174:177], v[216:219], v[4:7]
	v_mfma_f32_16x16x32_bf16 v[0:3], v[182:185], v[216:219], v[0:3]
	s_setprio 0
	s_barrier
	s_add_i32 s73, s73, 2
	s_add_u32 s34, s34, 0x100
	s_addc_u32 s35, s35, 0
	s_add_u32 s71, s71, 0x100
	s_addc_u32 s72, s72, 0
	s_cmp_gt_u32 s73, 13
	s_cbranch_scc0 .LBB0_2557
	v_lshl_add_u64 v[222:223], v[222:223], 0, s[20:21]
	s_mov_b32 m0, s56
	s_nop 0
	global_load_lds_dwordx4 v[222:223], off
	v_lshl_add_u64 v[224:225], v[224:225], 0, s[20:21]
	s_mov_b32 m0, s57
	s_nop 0
	global_load_lds_dwordx4 v[224:225], off
	s_and_b64 vcc, exec, s[22:23]
	s_cbranch_vccz .LBB0_2560
	s_barrier

.LBB0_2632:
	s_ashr_i32 s31, s30, 31
	s_lshl_b64 s[34:35], s[30:31], 18
	s_add_u32 s34, s0, s34
	s_addc_u32 s35, s1, s35
	s_and_b64 s[36:37], s[8:9], exec
	s_cselect_b32 s31, s35, s41
	s_cselect_b32 s63, s34, s40
	s_ashr_i32 s29, s28, 31
	s_lshl_b64 s[36:37], s[28:29], 18
	s_add_u32 s36, s49, s36
	s_addc_u32 s37, s51, s37
	s_and_b64 s[44:45], s[8:9], exec
	s_cselect_b32 s29, s37, s43
	s_cselect_b32 s70, s36, s42
	s_add_u32 s40, s40, 0x20080
	s_addc_u32 s41, s41, 0
	s_add_u32 s71, s42, 0x100
	v_mov_b32_e32 v0, 0
	s_addc_u32 s72, s43, 0
	s_mov_b32 s73, -2
	v_mov_b32_e32 v1, v0
	v_mov_b32_e32 v2, v0
	v_mov_b32_e32 v3, v0
	v_mov_b32_e32 v4, v0
	v_mov_b32_e32 v5, v0
	v_mov_b32_e32 v6, v0
	v_mov_b32_e32 v7, v0
	v_mov_b32_e32 v16, v0
	v_mov_b32_e32 v17, v0
	v_mov_b32_e32 v18, v0
	v_mov_b32_e32 v19, v0
	v_mov_b32_e32 v20, v0
	v_mov_b32_e32 v21, v0
	v_mov_b32_e32 v22, v0
	v_mov_b32_e32 v23, v0
	v_mov_b32_e32 v32, v0
	v_mov_b32_e32 v33, v0
	v_mov_b32_e32 v34, v0
	v_mov_b32_e32 v35, v0
	v_mov_b32_e32 v36, v0
	v_mov_b32_e32 v37, v0
	v_mov_b32_e32 v38, v0
	v_mov_b32_e32 v39, v0
	v_mov_b32_e32 v48, v0
	v_mov_b32_e32 v49, v0
	v_mov_b32_e32 v50, v0
	v_mov_b32_e32 v51, v0
	v_mov_b32_e32 v52, v0
	v_mov_b32_e32 v53, v0
	v_mov_b32_e32 v54, v0
	v_mov_b32_e32 v55, v0
	v_mov_b32_e32 v8, v0
	v_mov_b32_e32 v9, v0
	v_mov_b32_e32 v10, v0
	v_mov_b32_e32 v11, v0
	v_mov_b32_e32 v12, v0
	v_mov_b32_e32 v13, v0
	v_mov_b32_e32 v14, v0
	v_mov_b32_e32 v15, v0
	v_mov_b32_e32 v24, v0
	v_mov_b32_e32 v25, v0
	v_mov_b32_e32 v26, v0
	v_mov_b32_e32 v27, v0
	v_mov_b32_e32 v28, v0
	v_mov_b32_e32 v29, v0
	v_mov_b32_e32 v30, v0
	v_mov_b32_e32 v31, v0
	v_mov_b32_e32 v40, v0
	v_mov_b32_e32 v41, v0
	v_mov_b32_e32 v42, v0
	v_mov_b32_e32 v43, v0
	v_mov_b32_e32 v44, v0
	v_mov_b32_e32 v45, v0
	v_mov_b32_e32 v46, v0
	v_mov_b32_e32 v47, v0
	v_mov_b32_e32 v56, v0
	v_mov_b32_e32 v57, v0
	v_mov_b32_e32 v58, v0
	v_mov_b32_e32 v59, v0
	v_mov_b32_e32 v60, v0
	v_mov_b32_e32 v61, v0
	v_mov_b32_e32 v62, v0
	v_mov_b32_e32 v63, v0
	v_mov_b32_e32 v64, v0
	v_mov_b32_e32 v65, v0
	v_mov_b32_e32 v66, v0
	v_mov_b32_e32 v67, v0
	v_mov_b32_e32 v68, v0
	v_mov_b32_e32 v69, v0
	v_mov_b32_e32 v70, v0
	v_mov_b32_e32 v71, v0
	v_mov_b32_e32 v80, v0
	v_mov_b32_e32 v81, v0
	v_mov_b32_e32 v82, v0
	v_mov_b32_e32 v83, v0
	v_mov_b32_e32 v84, v0
	v_mov_b32_e32 v85, v0
	v_mov_b32_e32 v86, v0
	v_mov_b32_e32 v87, v0
	v_mov_b32_e32 v96, v0
	v_mov_b32_e32 v97, v0
	v_mov_b32_e32 v98, v0
	v_mov_b32_e32 v99, v0
	v_mov_b32_e32 v100, v0
	v_mov_b32_e32 v101, v0
	v_mov_b32_e32 v102, v0
	v_mov_b32_e32 v103, v0
	v_mov_b32_e32 v112, v0
	v_mov_b32_e32 v113, v0
	v_mov_b32_e32 v114, v0
	v_mov_b32_e32 v115, v0
	v_mov_b32_e32 v116, v0
	v_mov_b32_e32 v117, v0
	v_mov_b32_e32 v118, v0
	v_mov_b32_e32 v119, v0
	v_mov_b32_e32 v72, v0
	v_mov_b32_e32 v73, v0
	v_mov_b32_e32 v74, v0
	v_mov_b32_e32 v75, v0
	v_mov_b32_e32 v76, v0
	v_mov_b32_e32 v77, v0
	v_mov_b32_e32 v78, v0
	v_mov_b32_e32 v79, v0
	v_mov_b32_e32 v88, v0
	v_mov_b32_e32 v89, v0
	v_mov_b32_e32 v90, v0
	v_mov_b32_e32 v91, v0
	v_mov_b32_e32 v92, v0
	v_mov_b32_e32 v93, v0
	v_mov_b32_e32 v94, v0
	v_mov_b32_e32 v95, v0
	v_mov_b32_e32 v104, v0
	v_mov_b32_e32 v105, v0
	v_mov_b32_e32 v106, v0
	v_mov_b32_e32 v107, v0
	v_mov_b32_e32 v108, v0
	v_mov_b32_e32 v109, v0
	v_mov_b32_e32 v110, v0
	v_mov_b32_e32 v111, v0
	v_mov_b32_e32 v120, v0
	v_mov_b32_e32 v121, v0
	v_mov_b32_e32 v122, v0
	v_mov_b32_e32 v123, v0
	v_mov_b32_e32 v124, v0
	v_mov_b32_e32 v125, v0
	v_mov_b32_e32 v126, v0
	v_mov_b32_e32 v127, v0
	s_mov_b32 s99, 0
.LBB0_2633:
	ds_read_b128 v[144:147], v153
	ds_read_b128 v[156:159], v153 offset:1024
	ds_read_b128 v[160:163], v153 offset:2048
	ds_read_b128 v[164:167], v153 offset:3072
	ds_read_b128 v[168:171], v154
	ds_read_b128 v[172:175], v154 offset:1024
	ds_read_b128 v[176:179], v154 offset:2048
	ds_read_b128 v[180:183], v154 offset:3072
	s_add_u32 s42, s40, 0xfffe0080
	s_addc_u32 s43, s41, -1
	s_cmp_eq_u32 s73, 4
	s_cselect_b32 s45, s31, s43
	s_cselect_b32 s44, s63, s42
	s_cselect_b32 s43, s29, s72
	s_cselect_b32 s42, s70, s71
	v_lshl_add_u64 v[148:149], s[40:41], 0, v[136:137]
	ds_read_b128 v[184:187], v155
	ds_read_b128 v[188:191], v155 offset:1024
	ds_read_b128 v[196:199], v155 offset:2048
	ds_read_b128 v[200:203], v155 offset:3072
	ds_read_b128 v[204:207], v155 offset:4096
	ds_read_b128 v[208:211], v155 offset:5120
	ds_read_b128 v[212:215], v155 offset:6144
	ds_read_b128 v[216:219], v155 offset:7168
	s_cmp_eq_u32 s99, 0
	s_cbranch_scc1 .Lkb_first_21
	v_lshl_add_u64 v[220:221], v[220:221], 0, s[18:19]
	s_mov_b32 m0, s57
	s_nop 0
	global_load_lds_dwordx4 v[220:221], off
	v_lshl_add_u64 v[222:223], v[222:223], 0, s[18:19]
	s_mov_b32 m0, s58
	s_nop 0
	global_load_lds_dwordx4 v[222:223], off
	s_branch .Lkb_join_21
.Lkb_first_21:
	s_add_i32 m0, s39, 0xc000
	s_nop 0
	global_load_lds_dwordx4 v[148:149], off
	global_load_lds_dwordx4 v[148:149], off
.Lkb_join_21:
	s_add_i32 m0, s39, 0xc000
	s_nop 0
	global_load_lds_dwordx4 v[148:149], off
	v_lshl_add_u64 v[148:149], s[40:41], 0, v[138:139]
	s_add_i32 m0, s39, 0xe000
	s_nop 0
	global_load_lds_dwordx4 v[148:149], off
	s_waitcnt vmcnt(8)
	s_waitcnt lgkmcnt(0)
	s_barrier
	s_setprio 1
	s_waitcnt lgkmcnt(0)
	v_mfma_f32_16x16x32_bf16 v[124:127], v[144:147], v[184:187], v[124:127]
	v_mfma_f32_16x16x32_bf16 v[120:123], v[160:163], v[184:187], v[120:123]
	v_mfma_f32_16x16x32_bf16 v[108:111], v[144:147], v[196:199], v[108:111]
	v_mfma_f32_16x16x32_bf16 v[104:107], v[160:163], v[196:199], v[104:107]
	v_mfma_f32_16x16x32_bf16 v[92:95], v[144:147], v[204:207], v[92:95]
	v_mfma_f32_16x16x32_bf16 v[88:91], v[160:163], v[204:207], v[88:91]
	v_mfma_f32_16x16x32_bf16 v[76:79], v[144:147], v[212:215], v[76:79]
	v_mfma_f32_16x16x32_bf16 v[72:75], v[160:163], v[212:215], v[72:75]
	v_mfma_f32_16x16x32_bf16 v[124:127], v[156:159], v[188:191], v[124:127]
	v_mfma_f32_16x16x32_bf16 v[120:123], v[164:167], v[188:191], v[120:123]
	v_mfma_f32_16x16x32_bf16 v[108:111], v[156:159], v[200:203], v[108:111]
	v_mfma_f32_16x16x32_bf16 v[104:107], v[164:167], v[200:203], v[104:107]
	v_mfma_f32_16x16x32_bf16 v[92:95], v[156:159], v[208:211], v[92:95]
	v_mfma_f32_16x16x32_bf16 v[88:91], v[164:167], v[208:211], v[88:91]
	v_mfma_f32_16x16x32_bf16 v[76:79], v[156:159], v[216:219], v[76:79]
	v_mfma_f32_16x16x32_bf16 v[72:75], v[164:167], v[216:219], v[72:75]
	s_setprio 0
	s_setprio 1
	v_mfma_f32_16x16x32_bf16 v[116:119], v[168:171], v[184:187], v[116:119]
	v_mfma_f32_16x16x32_bf16 v[112:115], v[176:179], v[184:187], v[112:115]
	v_mfma_f32_16x16x32_bf16 v[100:103], v[168:171], v[196:199], v[100:103]
	v_mfma_f32_16x16x32_bf16 v[96:99], v[176:179], v[196:199], v[96:99]
	v_mfma_f32_16x16x32_bf16 v[84:87], v[168:171], v[204:207], v[84:87]
	v_mfma_f32_16x16x32_bf16 v[80:83], v[176:179], v[204:207], v[80:83]
	v_mfma_f32_16x16x32_bf16 v[68:71], v[168:171], v[212:215], v[68:71]
	v_mfma_f32_16x16x32_bf16 v[64:67], v[176:179], v[212:215], v[64:67]
	v_mfma_f32_16x16x32_bf16 v[116:119], v[172:175], v[188:191], v[116:119]
	v_mfma_f32_16x16x32_bf16 v[112:115], v[180:183], v[188:191], v[112:115]
	v_mfma_f32_16x16x32_bf16 v[100:103], v[172:175], v[200:203], v[100:103]
	v_mfma_f32_16x16x32_bf16 v[96:99], v[180:183], v[200:203], v[96:99]
	v_mfma_f32_16x16x32_bf16 v[84:87], v[172:175], v[208:211], v[84:87]
	v_mfma_f32_16x16x32_bf16 v[80:83], v[180:183], v[208:211], v[80:83]
	v_mfma_f32_16x16x32_bf16 v[68:71], v[172:175], v[216:219], v[68:71]
	v_mfma_f32_16x16x32_bf16 v[64:67], v[180:183], v[216:219], v[64:67]
	s_setprio 0
	s_barrier
	s_add_i32 s77, s60, s52
	v_lshl_add_u64 v[148:149], s[42:43], 0, v[130:131]
	s_mov_b32 m0, s77
	ds_read_b128 v[184:187], v155 offset:16384
	ds_read_b128 v[188:191], v155 offset:17408
	ds_read_b128 v[196:199], v155 offset:18432
	ds_read_b128 v[200:203], v155 offset:19456
	ds_read_b128 v[204:207], v155 offset:20480
	ds_read_b128 v[208:211], v155 offset:21504
	ds_read_b128 v[212:215], v155 offset:22528
	ds_read_b128 v[216:219], v155 offset:23552
	global_load_lds_dwordx4 v[148:149], off
	s_add_i32 m0, s77, 0x2000
	s_add_u32 s78, s42, 0x20000
	v_lshl_add_u64 v[192:193], s[42:43], 0, v[134:135]
	s_addc_u32 s79, s43, 0
	s_add_i32 s77, s61, s52
	global_load_lds_dwordx4 v[192:193], off
	v_lshl_add_u64 v[220:221], s[78:79], 0, v[130:131]
	s_mov_b32 m0, s77
	v_lshl_add_u64 v[222:223], s[44:45], 0, v[132:133]
	global_load_lds_dwordx4 v[220:221], off
	v_lshl_add_u64 v[220:221], s[78:79], 0, v[134:135]
	s_add_i32 m0, s77, 0x2000
	s_nop 0
	global_load_lds_dwordx4 v[220:221], off
	v_lshl_add_u64 v[220:221], s[44:45], 0, v[128:129]
	s_waitcnt vmcnt(6)
	s_waitcnt lgkmcnt(0)
	s_barrier
	s_setprio 1
	s_waitcnt lgkmcnt(0)
	v_mfma_f32_16x16x32_bf16 v[60:63], v[144:147], v[184:187], v[60:63]
	v_mfma_f32_16x16x32_bf16 v[56:59], v[160:163], v[184:187], v[56:59]
	v_mfma_f32_16x16x32_bf16 v[44:47], v[144:147], v[196:199], v[44:47]
	v_mfma_f32_16x16x32_bf16 v[40:43], v[160:163], v[196:199], v[40:43]
	v_mfma_f32_16x16x32_bf16 v[28:31], v[144:147], v[204:207], v[28:31]
	v_mfma_f32_16x16x32_bf16 v[24:27], v[160:163], v[204:207], v[24:27]
	v_mfma_f32_16x16x32_bf16 v[12:15], v[144:147], v[212:215], v[12:15]
	v_mfma_f32_16x16x32_bf16 v[8:11], v[160:163], v[212:215], v[8:11]
	v_mfma_f32_16x16x32_bf16 v[60:63], v[156:159], v[188:191], v[60:63]
	v_mfma_f32_16x16x32_bf16 v[56:59], v[164:167], v[188:191], v[56:59]
	v_mfma_f32_16x16x32_bf16 v[44:47], v[156:159], v[200:203], v[44:47]
	v_mfma_f32_16x16x32_bf16 v[40:43], v[164:167], v[200:203], v[40:43]
	v_mfma_f32_16x16x32_bf16 v[28:31], v[156:159], v[208:211], v[28:31]
	v_mfma_f32_16x16x32_bf16 v[24:27], v[164:167], v[208:211], v[24:27]
	v_mfma_f32_16x16x32_bf16 v[12:15], v[156:159], v[216:219], v[12:15]
	v_mfma_f32_16x16x32_bf16 v[8:11], v[164:167], v[216:219], v[8:11]
	s_setprio 0
	s_setprio 1
	v_mfma_f32_16x16x32_bf16 v[52:55], v[168:171], v[184:187], v[52:55]
	v_mfma_f32_16x16x32_bf16 v[48:51], v[176:179], v[184:187], v[48:51]
	v_mfma_f32_16x16x32_bf16 v[36:39], v[168:171], v[196:199], v[36:39]
	v_mfma_f32_16x16x32_bf16 v[32:35], v[176:179], v[196:199], v[32:35]
	v_mfma_f32_16x16x32_bf16 v[20:23], v[168:171], v[204:207], v[20:23]
	v_mfma_f32_16x16x32_bf16 v[16:19], v[176:179], v[204:207], v[16:19]
	v_mfma_f32_16x16x32_bf16 v[4:7], v[168:171], v[212:215], v[4:7]
	v_mfma_f32_16x16x32_bf16 v[0:3], v[176:179], v[212:215], v[0:3]
	v_mfma_f32_16x16x32_bf16 v[52:55], v[172:175], v[188:191], v[52:55]
	v_mfma_f32_16x16x32_bf16 v[48:51], v[180:183], v[188:191], v[48:51]
	v_mfma_f32_16x16x32_bf16 v[36:39], v[172:175], v[200:203], v[36:39]
	v_mfma_f32_16x16x32_bf16 v[32:35], v[180:183], v[200:203], v[32:35]
	v_mfma_f32_16x16x32_bf16 v[20:23], v[172:175], v[208:211], v[20:23]
	v_mfma_f32_16x16x32_bf16 v[16:19], v[180:183], v[208:211], v[16:19]
	v_mfma_f32_16x16x32_bf16 v[4:7], v[172:175], v[216:219], v[4:7]
	v_mfma_f32_16x16x32_bf16 v[0:3], v[180:183], v[216:219], v[0:3]
	s_setprio 0
	s_barrier
	s_add_i32 s77, 0, 0x18000
	s_add_i32 s78, 0, 0x1c000
	v_add_u32_e32 v164, s77, v151
	v_add_u32_e32 v180, s78, v151
	ds_read_b128 v[144:147], v164
	ds_read_b128 v[156:159], v164 offset:1024
	ds_read_b128 v[160:163], v164 offset:2048
	ds_read_b128 v[164:167], v164 offset:3072
	ds_read_b128 v[168:171], v180
	ds_read_b128 v[172:175], v180 offset:1024
	ds_read_b128 v[176:179], v180 offset:2048
	ds_read_b128 v[180:183], v180 offset:3072
	s_add_u32 s44, s44, 0x20000
	s_addc_u32 s45, s45, 0
	v_lshl_add_u64 v[224:225], s[44:45], 0, v[128:129]
	ds_read_b128 v[184:187], v155 offset:32768
	ds_read_b128 v[188:191], v155 offset:33792
	ds_read_b128 v[196:199], v155 offset:34816
	ds_read_b128 v[200:203], v155 offset:35840
	ds_read_b128 v[204:207], v155 offset:36864
	ds_read_b128 v[208:211], v155 offset:37888
	ds_read_b128 v[212:215], v155 offset:38912
	ds_read_b128 v[216:219], v155 offset:39936
	s_mov_b32 m0, s39
	s_nop 0
	global_load_lds_dwordx4 v[220:221], off
	s_mov_b32 m0, s53
	s_nop 0
	global_load_lds_dwordx4 v[222:223], off
	s_mov_b32 m0, s54
	s_nop 0
	global_load_lds_dwordx4 v[224:225], off
	v_lshl_add_u64 v[224:225], s[44:45], 0, v[132:133]
	s_mov_b32 m0, s55
	s_nop 0
	global_load_lds_dwordx4 v[224:225], off
	s_waitcnt vmcnt(8)
	s_waitcnt lgkmcnt(0)
	s_barrier
	s_setprio 1
	s_waitcnt lgkmcnt(0)
	v_mfma_f32_16x16x32_bf16 v[124:127], v[144:147], v[184:187], v[124:127]
	v_mfma_f32_16x16x32_bf16 v[120:123], v[160:163], v[184:187], v[120:123]
	v_mfma_f32_16x16x32_bf16 v[108:111], v[144:147], v[196:199], v[108:111]
	v_mfma_f32_16x16x32_bf16 v[104:107], v[160:163], v[196:199], v[104:107]
	v_mfma_f32_16x16x32_bf16 v[92:95], v[144:147], v[204:207], v[92:95]
	v_mfma_f32_16x16x32_bf16 v[88:91], v[160:163], v[204:207], v[88:91]
	v_mfma_f32_16x16x32_bf16 v[76:79], v[144:147], v[212:215], v[76:79]
	v_mfma_f32_16x16x32_bf16 v[72:75], v[160:163], v[212:215], v[72:75]
	v_mfma_f32_16x16x32_bf16 v[124:127], v[156:159], v[188:191], v[124:127]
	v_mfma_f32_16x16x32_bf16 v[120:123], v[164:167], v[188:191], v[120:123]
	v_mfma_f32_16x16x32_bf16 v[108:111], v[156:159], v[200:203], v[108:111]
	v_mfma_f32_16x16x32_bf16 v[104:107], v[164:167], v[200:203], v[104:107]
	v_mfma_f32_16x16x32_bf16 v[92:95], v[156:159], v[208:211], v[92:95]
	v_mfma_f32_16x16x32_bf16 v[88:91], v[164:167], v[208:211], v[88:91]
	v_mfma_f32_16x16x32_bf16 v[76:79], v[156:159], v[216:219], v[76:79]
	v_mfma_f32_16x16x32_bf16 v[72:75], v[164:167], v[216:219], v[72:75]
	s_setprio 0
	s_setprio 1
	v_mfma_f32_16x16x32_bf16 v[116:119], v[168:171], v[184:187], v[116:119]
	v_mfma_f32_16x16x32_bf16 v[112:115], v[176:179], v[184:187], v[112:115]
	v_mfma_f32_16x16x32_bf16 v[100:103], v[168:171], v[196:199], v[100:103]
	v_mfma_f32_16x16x32_bf16 v[96:99], v[176:179], v[196:199], v[96:99]
	v_mfma_f32_16x16x32_bf16 v[84:87], v[168:171], v[204:207], v[84:87]
	v_mfma_f32_16x16x32_bf16 v[80:83], v[176:179], v[204:207], v[80:83]
	v_mfma_f32_16x16x32_bf16 v[68:71], v[168:171], v[212:215], v[68:71]
	v_mfma_f32_16x16x32_bf16 v[64:67], v[176:179], v[212:215], v[64:67]
	v_mfma_f32_16x16x32_bf16 v[116:119], v[172:175], v[188:191], v[116:119]
	v_mfma_f32_16x16x32_bf16 v[112:115], v[180:183], v[188:191], v[112:115]
	v_mfma_f32_16x16x32_bf16 v[100:103], v[172:175], v[200:203], v[100:103]
	v_mfma_f32_16x16x32_bf16 v[96:99], v[180:183], v[200:203], v[96:99]
	v_mfma_f32_16x16x32_bf16 v[84:87], v[172:175], v[208:211], v[84:87]
	v_mfma_f32_16x16x32_bf16 v[80:83], v[180:183], v[208:211], v[80:83]
	v_mfma_f32_16x16x32_bf16 v[68:71], v[172:175], v[216:219], v[68:71]
	v_mfma_f32_16x16x32_bf16 v[64:67], v[180:183], v[216:219], v[64:67]
	s_setprio 0
	s_barrier
	s_add_i32 s44, s77, s52
	v_lshl_add_u64 v[148:149], v[148:149], 0, s[18:19]
	s_mov_b32 m0, s44
	ds_read_b128 v[184:187], v155 offset:49152
	ds_read_b128 v[188:191], v155 offset:50176
	ds_read_b128 v[196:199], v155 offset:51200
	ds_read_b128 v[200:203], v155 offset:52224
	ds_read_b128 v[204:207], v155 offset:53248
	ds_read_b128 v[208:211], v155 offset:54272
	ds_read_b128 v[212:215], v155 offset:55296
	ds_read_b128 v[216:219], v155 offset:56320
	global_load_lds_dwordx4 v[148:149], off
	s_add_i32 m0, s44, 0x2000
	s_add_u32 s42, s42, 0x20080
	v_lshl_add_u64 v[148:149], v[192:193], 0, s[18:19]
	s_addc_u32 s43, s43, 0
	s_add_i32 s44, s78, s52
	global_load_lds_dwordx4 v[148:149], off
	v_lshl_add_u64 v[148:149], s[42:43], 0, v[130:131]
	s_mov_b32 m0, s44
	s_nop 0
	global_load_lds_dwordx4 v[148:149], off
	v_lshl_add_u64 v[148:149], s[42:43], 0, v[134:135]
	s_add_i32 m0, s44, 0x2000
	s_nop 0
	global_load_lds_dwordx4 v[148:149], off
	s_mov_b32 s99, 1
	s_waitcnt vmcnt(6)
	s_waitcnt lgkmcnt(0)
	s_barrier
	s_setprio 1
	s_waitcnt lgkmcnt(0)
	v_mfma_f32_16x16x32_bf16 v[60:63], v[144:147], v[184:187], v[60:63]
	v_mfma_f32_16x16x32_bf16 v[56:59], v[160:163], v[184:187], v[56:59]
	v_mfma_f32_16x16x32_bf16 v[44:47], v[144:147], v[196:199], v[44:47]
	v_mfma_f32_16x16x32_bf16 v[40:43], v[160:163], v[196:199], v[40:43]
	v_mfma_f32_16x16x32_bf16 v[28:31], v[144:147], v[204:207], v[28:31]
	v_mfma_f32_16x16x32_bf16 v[24:27], v[160:163], v[204:207], v[24:27]
	v_mfma_f32_16x16x32_bf16 v[12:15], v[144:147], v[212:215], v[12:15]
	v_mfma_f32_16x16x32_bf16 v[8:11], v[160:163], v[212:215], v[8:11]
	v_mfma_f32_16x16x32_bf16 v[60:63], v[156:159], v[188:191], v[60:63]
	v_mfma_f32_16x16x32_bf16 v[56:59], v[164:167], v[188:191], v[56:59]
	v_mfma_f32_16x16x32_bf16 v[44:47], v[156:159], v[200:203], v[44:47]
	v_mfma_f32_16x16x32_bf16 v[40:43], v[164:167], v[200:203], v[40:43]
	v_mfma_f32_16x16x32_bf16 v[28:31], v[156:159], v[208:211], v[28:31]
	v_mfma_f32_16x16x32_bf16 v[24:27], v[164:167], v[208:211], v[24:27]
	v_mfma_f32_16x16x32_bf16 v[12:15], v[156:159], v[216:219], v[12:15]
	v_mfma_f32_16x16x32_bf16 v[8:11], v[164:167], v[216:219], v[8:11]
	s_setprio 0
	s_setprio 1
	v_mfma_f32_16x16x32_bf16 v[52:55], v[168:171], v[184:187], v[52:55]
	v_mfma_f32_16x16x32_bf16 v[48:51], v[176:179], v[184:187], v[48:51]
	v_mfma_f32_16x16x32_bf16 v[36:39], v[168:171], v[196:199], v[36:39]
	v_mfma_f32_16x16x32_bf16 v[32:35], v[176:179], v[196:199], v[32:35]
	v_mfma_f32_16x16x32_bf16 v[20:23], v[168:171], v[204:207], v[20:23]
	v_mfma_f32_16x16x32_bf16 v[16:19], v[176:179], v[204:207], v[16:19]
	v_mfma_f32_16x16x32_bf16 v[4:7], v[168:171], v[212:215], v[4:7]
	v_mfma_f32_16x16x32_bf16 v[0:3], v[176:179], v[212:215], v[0:3]
	v_mfma_f32_16x16x32_bf16 v[52:55], v[172:175], v[188:191], v[52:55]
	v_mfma_f32_16x16x32_bf16 v[48:51], v[180:183], v[188:191], v[48:51]
	v_mfma_f32_16x16x32_bf16 v[36:39], v[172:175], v[200:203], v[36:39]
	v_mfma_f32_16x16x32_bf16 v[32:35], v[180:183], v[200:203], v[32:35]
	v_mfma_f32_16x16x32_bf16 v[20:23], v[172:175], v[208:211], v[20:23]
	v_mfma_f32_16x16x32_bf16 v[16:19], v[180:183], v[208:211], v[16:19]
	v_mfma_f32_16x16x32_bf16 v[4:7], v[172:175], v[216:219], v[4:7]
	v_mfma_f32_16x16x32_bf16 v[0:3], v[180:183], v[216:219], v[0:3]
	s_setprio 0
	s_barrier
	s_add_i32 s73, s73, 2
	s_add_u32 s40, s40, 0x100
	s_addc_u32 s41, s41, 0
	s_add_u32 s71, s71, 0x100
	s_addc_u32 s72, s72, 0
	s_cmp_gt_u32 s73, 5
	s_cbranch_scc0 .LBB0_2633
	v_lshl_add_u64 v[220:221], v[220:221], 0, s[18:19]
	s_mov_b32 m0, s57
	s_nop 0
	global_load_lds_dwordx4 v[220:221], off
	v_lshl_add_u64 v[222:223], v[222:223], 0, s[18:19]
	s_mov_b32 m0, s58
	s_nop 0
	global_load_lds_dwordx4 v[222:223], off
	s_and_b64 vcc, exec, s[20:21]
	s_cbranch_vccz .LBB0_2636
	s_barrier

.LBB0_2656:
	s_ashr_i32 s25, s24, 31
	s_lshl_b64 s[26:27], s[24:25], 19
	s_add_u32 s26, s41, s26
	s_addc_u32 s27, s42, s27
	s_and_b64 s[28:29], s[8:9], exec
	s_cselect_b32 s25, s27, s31
	s_cselect_b32 s60, s26, s30
	s_ashr_i32 s23, s22, 31
	s_lshl_b64 s[28:29], s[22:23], 19
	s_add_u32 s28, s43, s28
	s_addc_u32 s29, s44, s29
	s_and_b64 s[36:37], s[8:9], exec
	s_cselect_b32 s23, s29, s35
	s_cselect_b32 s61, s28, s34
	s_add_u32 s30, s30, 0x40080
	s_addc_u32 s31, s31, 0
	s_add_u32 s62, s34, 0x100
	v_mov_b32_e32 v0, 0
	s_addc_u32 s63, s35, 0
	s_mov_b32 s70, -2
	v_mov_b32_e32 v1, v0
	v_mov_b32_e32 v2, v0
	v_mov_b32_e32 v3, v0
	v_mov_b32_e32 v4, v0
	v_mov_b32_e32 v5, v0
	v_mov_b32_e32 v6, v0
	v_mov_b32_e32 v7, v0
	v_mov_b32_e32 v16, v0
	v_mov_b32_e32 v17, v0
	v_mov_b32_e32 v18, v0
	v_mov_b32_e32 v19, v0
	v_mov_b32_e32 v20, v0
	v_mov_b32_e32 v21, v0
	v_mov_b32_e32 v22, v0
	v_mov_b32_e32 v23, v0
	v_mov_b32_e32 v32, v0
	v_mov_b32_e32 v33, v0
	v_mov_b32_e32 v34, v0
	v_mov_b32_e32 v35, v0
	v_mov_b32_e32 v36, v0
	v_mov_b32_e32 v37, v0
	v_mov_b32_e32 v38, v0
	v_mov_b32_e32 v39, v0
	v_mov_b32_e32 v48, v0
	v_mov_b32_e32 v49, v0
	v_mov_b32_e32 v50, v0
	v_mov_b32_e32 v51, v0
	v_mov_b32_e32 v52, v0
	v_mov_b32_e32 v53, v0
	v_mov_b32_e32 v54, v0
	v_mov_b32_e32 v55, v0
	v_mov_b32_e32 v8, v0
	v_mov_b32_e32 v9, v0
	v_mov_b32_e32 v10, v0
	v_mov_b32_e32 v11, v0
	v_mov_b32_e32 v12, v0
	v_mov_b32_e32 v13, v0
	v_mov_b32_e32 v14, v0
	v_mov_b32_e32 v15, v0
	v_mov_b32_e32 v24, v0
	v_mov_b32_e32 v25, v0
	v_mov_b32_e32 v26, v0
	v_mov_b32_e32 v27, v0
	v_mov_b32_e32 v28, v0
	v_mov_b32_e32 v29, v0
	v_mov_b32_e32 v30, v0
	v_mov_b32_e32 v31, v0
	v_mov_b32_e32 v40, v0
	v_mov_b32_e32 v41, v0
	v_mov_b32_e32 v42, v0
	v_mov_b32_e32 v43, v0
	v_mov_b32_e32 v44, v0
	v_mov_b32_e32 v45, v0
	v_mov_b32_e32 v46, v0
	v_mov_b32_e32 v47, v0
	v_mov_b32_e32 v56, v0
	v_mov_b32_e32 v57, v0
	v_mov_b32_e32 v58, v0
	v_mov_b32_e32 v59, v0
	v_mov_b32_e32 v60, v0
	v_mov_b32_e32 v61, v0
	v_mov_b32_e32 v62, v0
	v_mov_b32_e32 v63, v0
	v_mov_b32_e32 v64, v0
	v_mov_b32_e32 v65, v0
	v_mov_b32_e32 v66, v0
	v_mov_b32_e32 v67, v0
	v_mov_b32_e32 v68, v0
	v_mov_b32_e32 v69, v0
	v_mov_b32_e32 v70, v0
	v_mov_b32_e32 v71, v0
	v_mov_b32_e32 v80, v0
	v_mov_b32_e32 v81, v0
	v_mov_b32_e32 v82, v0
	v_mov_b32_e32 v83, v0
	v_mov_b32_e32 v84, v0
	v_mov_b32_e32 v85, v0
	v_mov_b32_e32 v86, v0
	v_mov_b32_e32 v87, v0
	v_mov_b32_e32 v96, v0
	v_mov_b32_e32 v97, v0
	v_mov_b32_e32 v98, v0
	v_mov_b32_e32 v99, v0
	v_mov_b32_e32 v100, v0
	v_mov_b32_e32 v101, v0
	v_mov_b32_e32 v102, v0
	v_mov_b32_e32 v103, v0
	v_mov_b32_e32 v112, v0
	v_mov_b32_e32 v113, v0
	v_mov_b32_e32 v114, v0
	v_mov_b32_e32 v115, v0
	v_mov_b32_e32 v116, v0
	v_mov_b32_e32 v117, v0
	v_mov_b32_e32 v118, v0
	v_mov_b32_e32 v119, v0
	v_mov_b32_e32 v72, v0
	v_mov_b32_e32 v73, v0
	v_mov_b32_e32 v74, v0
	v_mov_b32_e32 v75, v0
	v_mov_b32_e32 v76, v0
	v_mov_b32_e32 v77, v0
	v_mov_b32_e32 v78, v0
	v_mov_b32_e32 v79, v0
	v_mov_b32_e32 v88, v0
	v_mov_b32_e32 v89, v0
	v_mov_b32_e32 v90, v0
	v_mov_b32_e32 v91, v0
	v_mov_b32_e32 v92, v0
	v_mov_b32_e32 v93, v0
	v_mov_b32_e32 v94, v0
	v_mov_b32_e32 v95, v0
	v_mov_b32_e32 v104, v0
	v_mov_b32_e32 v105, v0
	v_mov_b32_e32 v106, v0
	v_mov_b32_e32 v107, v0
	v_mov_b32_e32 v108, v0
	v_mov_b32_e32 v109, v0
	v_mov_b32_e32 v110, v0
	v_mov_b32_e32 v111, v0
	v_mov_b32_e32 v120, v0
	v_mov_b32_e32 v121, v0
	v_mov_b32_e32 v122, v0
	v_mov_b32_e32 v123, v0
	v_mov_b32_e32 v124, v0
	v_mov_b32_e32 v125, v0
	v_mov_b32_e32 v126, v0
	v_mov_b32_e32 v127, v0
	s_mov_b32 s99, 0
.LBB0_2657:
	ds_read_b128 v[144:147], v153
	ds_read_b128 v[158:161], v153 offset:1024
	ds_read_b128 v[162:165], v153 offset:2048
	ds_read_b128 v[166:169], v153 offset:3072
	ds_read_b128 v[170:173], v154
	ds_read_b128 v[174:177], v154 offset:1024
	ds_read_b128 v[178:181], v154 offset:2048
	ds_read_b128 v[182:185], v154 offset:3072
	s_add_u32 s34, s30, 0xfffc0080
	s_addc_u32 s35, s31, -1
	s_cmp_eq_u32 s70, 12
	s_cselect_b32 s37, s25, s35
	s_cselect_b32 s36, s60, s34
	s_cselect_b32 s35, s23, s63
	s_cselect_b32 s34, s61, s62
	v_lshl_add_u64 v[148:149], s[30:31], 0, v[136:137]
	ds_read_b128 v[186:189], v155
	ds_read_b128 v[190:193], v155 offset:1024
	ds_read_b128 v[196:199], v155 offset:2048
	ds_read_b128 v[200:203], v155 offset:3072
	ds_read_b128 v[204:207], v155 offset:4096
	ds_read_b128 v[208:211], v155 offset:5120
	ds_read_b128 v[212:215], v155 offset:6144
	ds_read_b128 v[216:219], v155 offset:7168
	s_cmp_eq_u32 s99, 0
	s_cbranch_scc1 .Lkb_first_22
	v_lshl_add_u64 v[222:223], v[222:223], 0, s[18:19]
	s_mov_b32 m0, s53
	s_nop 0
	global_load_lds_dwordx4 v[222:223], off
	v_lshl_add_u64 v[224:225], v[224:225], 0, s[18:19]
	s_mov_b32 m0, s54
	s_nop 0
	global_load_lds_dwordx4 v[224:225], off
	s_branch .Lkb_join_22
.Lkb_first_22:
	s_add_i32 m0, s48, 0xc000
	s_nop 0
	global_load_lds_dwordx4 v[148:149], off
	global_load_lds_dwordx4 v[148:149], off
.Lkb_join_22:
	s_add_i32 m0, s48, 0xc000
	s_nop 0
	global_load_lds_dwordx4 v[148:149], off
	v_lshl_add_u64 v[148:149], s[30:31], 0, v[138:139]
	s_add_i32 m0, s48, 0xe000
	s_nop 0
	global_load_lds_dwordx4 v[148:149], off
	s_waitcnt vmcnt(8)
	s_waitcnt lgkmcnt(0)
	s_barrier
	s_setprio 1
	s_waitcnt lgkmcnt(0)
	v_mfma_f32_16x16x32_bf16 v[124:127], v[144:147], v[186:189], v[124:127]
	v_mfma_f32_16x16x32_bf16 v[120:123], v[162:165], v[186:189], v[120:123]
	v_mfma_f32_16x16x32_bf16 v[108:111], v[144:147], v[196:199], v[108:111]
	v_mfma_f32_16x16x32_bf16 v[104:107], v[162:165], v[196:199], v[104:107]
	v_mfma_f32_16x16x32_bf16 v[92:95], v[144:147], v[204:207], v[92:95]
	v_mfma_f32_16x16x32_bf16 v[88:91], v[162:165], v[204:207], v[88:91]
	v_mfma_f32_16x16x32_bf16 v[76:79], v[144:147], v[212:215], v[76:79]
	v_mfma_f32_16x16x32_bf16 v[72:75], v[162:165], v[212:215], v[72:75]
	v_mfma_f32_16x16x32_bf16 v[124:127], v[158:161], v[190:193], v[124:127]
	v_mfma_f32_16x16x32_bf16 v[120:123], v[166:169], v[190:193], v[120:123]
	v_mfma_f32_16x16x32_bf16 v[108:111], v[158:161], v[200:203], v[108:111]
	v_mfma_f32_16x16x32_bf16 v[104:107], v[166:169], v[200:203], v[104:107]
	v_mfma_f32_16x16x32_bf16 v[92:95], v[158:161], v[208:211], v[92:95]
	v_mfma_f32_16x16x32_bf16 v[88:91], v[166:169], v[208:211], v[88:91]
	v_mfma_f32_16x16x32_bf16 v[76:79], v[158:161], v[216:219], v[76:79]
	v_mfma_f32_16x16x32_bf16 v[72:75], v[166:169], v[216:219], v[72:75]
	s_setprio 0
	s_setprio 1
	v_mfma_f32_16x16x32_bf16 v[116:119], v[170:173], v[186:189], v[116:119]
	v_mfma_f32_16x16x32_bf16 v[112:115], v[178:181], v[186:189], v[112:115]
	v_mfma_f32_16x16x32_bf16 v[100:103], v[170:173], v[196:199], v[100:103]
	v_mfma_f32_16x16x32_bf16 v[96:99], v[178:181], v[196:199], v[96:99]
	v_mfma_f32_16x16x32_bf16 v[84:87], v[170:173], v[204:207], v[84:87]
	v_mfma_f32_16x16x32_bf16 v[80:83], v[178:181], v[204:207], v[80:83]
	v_mfma_f32_16x16x32_bf16 v[68:71], v[170:173], v[212:215], v[68:71]
	v_mfma_f32_16x16x32_bf16 v[64:67], v[178:181], v[212:215], v[64:67]
	v_mfma_f32_16x16x32_bf16 v[116:119], v[174:177], v[190:193], v[116:119]
	v_mfma_f32_16x16x32_bf16 v[112:115], v[182:185], v[190:193], v[112:115]
	v_mfma_f32_16x16x32_bf16 v[100:103], v[174:177], v[200:203], v[100:103]
	v_mfma_f32_16x16x32_bf16 v[96:99], v[182:185], v[200:203], v[96:99]
	v_mfma_f32_16x16x32_bf16 v[84:87], v[174:177], v[208:211], v[84:87]
	v_mfma_f32_16x16x32_bf16 v[80:83], v[182:185], v[208:211], v[80:83]
	v_mfma_f32_16x16x32_bf16 v[68:71], v[174:177], v[216:219], v[68:71]
	v_mfma_f32_16x16x32_bf16 v[64:67], v[182:185], v[216:219], v[64:67]
	s_setprio 0
	s_barrier
	s_add_i32 s71, s56, s45
	v_lshl_add_u64 v[148:149], s[34:35], 0, v[130:131]
	s_mov_b32 m0, s71
	ds_read_b128 v[186:189], v155 offset:16384
	ds_read_b128 v[190:193], v155 offset:17408
	ds_read_b128 v[196:199], v155 offset:18432
	ds_read_b128 v[200:203], v155 offset:19456
	ds_read_b128 v[204:207], v155 offset:20480
	ds_read_b128 v[208:211], v155 offset:21504
	ds_read_b128 v[212:215], v155 offset:22528
	ds_read_b128 v[216:219], v155 offset:23552
	global_load_lds_dwordx4 v[148:149], off
	s_add_i32 m0, s71, 0x2000
	s_add_u32 s72, s34, 0x40000
	v_lshl_add_u64 v[220:221], s[34:35], 0, v[134:135]
	s_addc_u32 s73, s35, 0
	s_add_i32 s71, s57, s45
	global_load_lds_dwordx4 v[220:221], off
	v_lshl_add_u64 v[222:223], s[72:73], 0, v[130:131]
	s_mov_b32 m0, s71
	v_lshl_add_u64 v[224:225], s[36:37], 0, v[132:133]
	global_load_lds_dwordx4 v[222:223], off
	v_lshl_add_u64 v[222:223], s[72:73], 0, v[134:135]
	s_add_i32 m0, s71, 0x2000
	s_nop 0
	global_load_lds_dwordx4 v[222:223], off
	v_lshl_add_u64 v[222:223], s[36:37], 0, v[128:129]
	s_waitcnt vmcnt(6)
	s_waitcnt lgkmcnt(0)
	s_barrier
	s_setprio 1
	s_waitcnt lgkmcnt(0)
	v_mfma_f32_16x16x32_bf16 v[60:63], v[144:147], v[186:189], v[60:63]
	v_mfma_f32_16x16x32_bf16 v[56:59], v[162:165], v[186:189], v[56:59]
	v_mfma_f32_16x16x32_bf16 v[44:47], v[144:147], v[196:199], v[44:47]
	v_mfma_f32_16x16x32_bf16 v[40:43], v[162:165], v[196:199], v[40:43]
	v_mfma_f32_16x16x32_bf16 v[28:31], v[144:147], v[204:207], v[28:31]
	v_mfma_f32_16x16x32_bf16 v[24:27], v[162:165], v[204:207], v[24:27]
	v_mfma_f32_16x16x32_bf16 v[12:15], v[144:147], v[212:215], v[12:15]
	v_mfma_f32_16x16x32_bf16 v[8:11], v[162:165], v[212:215], v[8:11]
	v_mfma_f32_16x16x32_bf16 v[60:63], v[158:161], v[190:193], v[60:63]
	v_mfma_f32_16x16x32_bf16 v[56:59], v[166:169], v[190:193], v[56:59]
	v_mfma_f32_16x16x32_bf16 v[44:47], v[158:161], v[200:203], v[44:47]
	v_mfma_f32_16x16x32_bf16 v[40:43], v[166:169], v[200:203], v[40:43]
	v_mfma_f32_16x16x32_bf16 v[28:31], v[158:161], v[208:211], v[28:31]
	v_mfma_f32_16x16x32_bf16 v[24:27], v[166:169], v[208:211], v[24:27]
	v_mfma_f32_16x16x32_bf16 v[12:15], v[158:161], v[216:219], v[12:15]
	v_mfma_f32_16x16x32_bf16 v[8:11], v[166:169], v[216:219], v[8:11]
	s_setprio 0
	s_setprio 1
	v_mfma_f32_16x16x32_bf16 v[52:55], v[170:173], v[186:189], v[52:55]
	v_mfma_f32_16x16x32_bf16 v[48:51], v[178:181], v[186:189], v[48:51]
	v_mfma_f32_16x16x32_bf16 v[36:39], v[170:173], v[196:199], v[36:39]
	v_mfma_f32_16x16x32_bf16 v[32:35], v[178:181], v[196:199], v[32:35]
	v_mfma_f32_16x16x32_bf16 v[20:23], v[170:173], v[204:207], v[20:23]
	v_mfma_f32_16x16x32_bf16 v[16:19], v[178:181], v[204:207], v[16:19]
	v_mfma_f32_16x16x32_bf16 v[4:7], v[170:173], v[212:215], v[4:7]
	v_mfma_f32_16x16x32_bf16 v[0:3], v[178:181], v[212:215], v[0:3]
	v_mfma_f32_16x16x32_bf16 v[52:55], v[174:177], v[190:193], v[52:55]
	v_mfma_f32_16x16x32_bf16 v[48:51], v[182:185], v[190:193], v[48:51]
	v_mfma_f32_16x16x32_bf16 v[36:39], v[174:177], v[200:203], v[36:39]
	v_mfma_f32_16x16x32_bf16 v[32:35], v[182:185], v[200:203], v[32:35]
	v_mfma_f32_16x16x32_bf16 v[20:23], v[174:177], v[208:211], v[20:23]
	v_mfma_f32_16x16x32_bf16 v[16:19], v[182:185], v[208:211], v[16:19]
	v_mfma_f32_16x16x32_bf16 v[4:7], v[174:177], v[216:219], v[4:7]
	v_mfma_f32_16x16x32_bf16 v[0:3], v[182:185], v[216:219], v[0:3]
	s_setprio 0
	s_barrier
	s_add_i32 s71, 0, 0x18000
	v_add_u32_e32 v157, s71, v151
	s_add_i32 s72, 0, 0x1c000
	ds_read_b128 v[144:147], v157
	ds_read_b128 v[158:161], v157 offset:1024
	ds_read_b128 v[162:165], v157 offset:2048
	ds_read_b128 v[166:169], v157 offset:3072
	v_add_u32_e32 v157, s72, v151
	ds_read_b128 v[170:173], v157
	ds_read_b128 v[174:177], v157 offset:1024
	ds_read_b128 v[178:181], v157 offset:2048
	ds_read_b128 v[182:185], v157 offset:3072
	s_add_u32 s36, s36, 0x40000
	s_addc_u32 s37, s37, 0
	v_lshl_add_u64 v[226:227], s[36:37], 0, v[128:129]
	ds_read_b128 v[186:189], v155 offset:32768
	ds_read_b128 v[190:193], v155 offset:33792
	ds_read_b128 v[196:199], v155 offset:34816
	ds_read_b128 v[200:203], v155 offset:35840
	ds_read_b128 v[204:207], v155 offset:36864
	ds_read_b128 v[208:211], v155 offset:37888
	ds_read_b128 v[212:215], v155 offset:38912
	ds_read_b128 v[216:219], v155 offset:39936
	s_mov_b32 m0, s48
	s_nop 0
	global_load_lds_dwordx4 v[222:223], off
	s_mov_b32 m0, s49
	s_nop 0
	global_load_lds_dwordx4 v[224:225], off
	s_mov_b32 m0, s50
	s_nop 0
	global_load_lds_dwordx4 v[226:227], off
	v_lshl_add_u64 v[226:227], s[36:37], 0, v[132:133]
	s_mov_b32 m0, s51
	s_nop 0
	global_load_lds_dwordx4 v[226:227], off
	s_waitcnt vmcnt(8)
	s_waitcnt lgkmcnt(0)
	s_barrier
	s_setprio 1
	s_waitcnt lgkmcnt(0)
	v_mfma_f32_16x16x32_bf16 v[124:127], v[144:147], v[186:189], v[124:127]
	v_mfma_f32_16x16x32_bf16 v[120:123], v[162:165], v[186:189], v[120:123]
	v_mfma_f32_16x16x32_bf16 v[108:111], v[144:147], v[196:199], v[108:111]
	v_mfma_f32_16x16x32_bf16 v[104:107], v[162:165], v[196:199], v[104:107]
	v_mfma_f32_16x16x32_bf16 v[92:95], v[144:147], v[204:207], v[92:95]
	v_mfma_f32_16x16x32_bf16 v[88:91], v[162:165], v[204:207], v[88:91]
	v_mfma_f32_16x16x32_bf16 v[76:79], v[144:147], v[212:215], v[76:79]
	v_mfma_f32_16x16x32_bf16 v[72:75], v[162:165], v[212:215], v[72:75]
	v_mfma_f32_16x16x32_bf16 v[124:127], v[158:161], v[190:193], v[124:127]
	v_mfma_f32_16x16x32_bf16 v[120:123], v[166:169], v[190:193], v[120:123]
	v_mfma_f32_16x16x32_bf16 v[108:111], v[158:161], v[200:203], v[108:111]
	v_mfma_f32_16x16x32_bf16 v[104:107], v[166:169], v[200:203], v[104:107]
	v_mfma_f32_16x16x32_bf16 v[92:95], v[158:161], v[208:211], v[92:95]
	v_mfma_f32_16x16x32_bf16 v[88:91], v[166:169], v[208:211], v[88:91]
	v_mfma_f32_16x16x32_bf16 v[76:79], v[158:161], v[216:219], v[76:79]
	v_mfma_f32_16x16x32_bf16 v[72:75], v[166:169], v[216:219], v[72:75]
	s_setprio 0
	s_setprio 1
	v_mfma_f32_16x16x32_bf16 v[116:119], v[170:173], v[186:189], v[116:119]
	v_mfma_f32_16x16x32_bf16 v[112:115], v[178:181], v[186:189], v[112:115]
	v_mfma_f32_16x16x32_bf16 v[100:103], v[170:173], v[196:199], v[100:103]
	v_mfma_f32_16x16x32_bf16 v[96:99], v[178:181], v[196:199], v[96:99]
	v_mfma_f32_16x16x32_bf16 v[84:87], v[170:173], v[204:207], v[84:87]
	v_mfma_f32_16x16x32_bf16 v[80:83], v[178:181], v[204:207], v[80:83]
	v_mfma_f32_16x16x32_bf16 v[68:71], v[170:173], v[212:215], v[68:71]
	v_mfma_f32_16x16x32_bf16 v[64:67], v[178:181], v[212:215], v[64:67]
	v_mfma_f32_16x16x32_bf16 v[116:119], v[174:177], v[190:193], v[116:119]
	v_mfma_f32_16x16x32_bf16 v[112:115], v[182:185], v[190:193], v[112:115]
	v_mfma_f32_16x16x32_bf16 v[100:103], v[174:177], v[200:203], v[100:103]
	v_mfma_f32_16x16x32_bf16 v[96:99], v[182:185], v[200:203], v[96:99]
	v_mfma_f32_16x16x32_bf16 v[84:87], v[174:177], v[208:211], v[84:87]
	v_mfma_f32_16x16x32_bf16 v[80:83], v[182:185], v[208:211], v[80:83]
	v_mfma_f32_16x16x32_bf16 v[68:71], v[174:177], v[216:219], v[68:71]
	v_mfma_f32_16x16x32_bf16 v[64:67], v[182:185], v[216:219], v[64:67]
	s_setprio 0
	s_barrier
	s_add_i32 s36, s71, s45
	v_lshl_add_u64 v[148:149], v[148:149], 0, s[18:19]
	s_mov_b32 m0, s36
	ds_read_b128 v[186:189], v155 offset:49152
	ds_read_b128 v[190:193], v155 offset:50176
	ds_read_b128 v[196:199], v155 offset:51200
	ds_read_b128 v[200:203], v155 offset:52224
	ds_read_b128 v[204:207], v155 offset:53248
	ds_read_b128 v[208:211], v155 offset:54272
	ds_read_b128 v[212:215], v155 offset:55296
	ds_read_b128 v[216:219], v155 offset:56320
	global_load_lds_dwordx4 v[148:149], off
	s_add_i32 m0, s36, 0x2000
	s_add_u32 s34, s34, 0x40080
	v_lshl_add_u64 v[148:149], v[220:221], 0, s[18:19]
	s_addc_u32 s35, s35, 0
	s_add_i32 s36, s72, s45
	global_load_lds_dwordx4 v[148:149], off
	v_lshl_add_u64 v[148:149], s[34:35], 0, v[130:131]
	s_mov_b32 m0, s36
	s_nop 0
	global_load_lds_dwordx4 v[148:149], off
	v_lshl_add_u64 v[148:149], s[34:35], 0, v[134:135]
	s_add_i32 m0, s36, 0x2000
	s_nop 0
	global_load_lds_dwordx4 v[148:149], off
	s_mov_b32 s99, 1
	s_waitcnt vmcnt(6)
	s_waitcnt lgkmcnt(0)
	s_barrier
	s_setprio 1
	s_waitcnt lgkmcnt(0)
	v_mfma_f32_16x16x32_bf16 v[60:63], v[144:147], v[186:189], v[60:63]
	v_mfma_f32_16x16x32_bf16 v[56:59], v[162:165], v[186:189], v[56:59]
	v_mfma_f32_16x16x32_bf16 v[44:47], v[144:147], v[196:199], v[44:47]
	v_mfma_f32_16x16x32_bf16 v[40:43], v[162:165], v[196:199], v[40:43]
	v_mfma_f32_16x16x32_bf16 v[28:31], v[144:147], v[204:207], v[28:31]
	v_mfma_f32_16x16x32_bf16 v[24:27], v[162:165], v[204:207], v[24:27]
	v_mfma_f32_16x16x32_bf16 v[12:15], v[144:147], v[212:215], v[12:15]
	v_mfma_f32_16x16x32_bf16 v[8:11], v[162:165], v[212:215], v[8:11]
	v_mfma_f32_16x16x32_bf16 v[60:63], v[158:161], v[190:193], v[60:63]
	v_mfma_f32_16x16x32_bf16 v[56:59], v[166:169], v[190:193], v[56:59]
	v_mfma_f32_16x16x32_bf16 v[44:47], v[158:161], v[200:203], v[44:47]
	v_mfma_f32_16x16x32_bf16 v[40:43], v[166:169], v[200:203], v[40:43]
	v_mfma_f32_16x16x32_bf16 v[28:31], v[158:161], v[208:211], v[28:31]
	v_mfma_f32_16x16x32_bf16 v[24:27], v[166:169], v[208:211], v[24:27]
	v_mfma_f32_16x16x32_bf16 v[12:15], v[158:161], v[216:219], v[12:15]
	v_mfma_f32_16x16x32_bf16 v[8:11], v[166:169], v[216:219], v[8:11]
	s_setprio 0
	s_setprio 1
	v_mfma_f32_16x16x32_bf16 v[52:55], v[170:173], v[186:189], v[52:55]
	v_mfma_f32_16x16x32_bf16 v[48:51], v[178:181], v[186:189], v[48:51]
	v_mfma_f32_16x16x32_bf16 v[36:39], v[170:173], v[196:199], v[36:39]
	v_mfma_f32_16x16x32_bf16 v[32:35], v[178:181], v[196:199], v[32:35]
	v_mfma_f32_16x16x32_bf16 v[20:23], v[170:173], v[204:207], v[20:23]
	v_mfma_f32_16x16x32_bf16 v[16:19], v[178:181], v[204:207], v[16:19]
	v_mfma_f32_16x16x32_bf16 v[4:7], v[170:173], v[212:215], v[4:7]
	v_mfma_f32_16x16x32_bf16 v[0:3], v[178:181], v[212:215], v[0:3]
	v_mfma_f32_16x16x32_bf16 v[52:55], v[174:177], v[190:193], v[52:55]
	v_mfma_f32_16x16x32_bf16 v[48:51], v[182:185], v[190:193], v[48:51]
	v_mfma_f32_16x16x32_bf16 v[36:39], v[174:177], v[200:203], v[36:39]
	v_mfma_f32_16x16x32_bf16 v[32:35], v[182:185], v[200:203], v[32:35]
	v_mfma_f32_16x16x32_bf16 v[20:23], v[174:177], v[208:211], v[20:23]
	v_mfma_f32_16x16x32_bf16 v[16:19], v[182:185], v[208:211], v[16:19]
	v_mfma_f32_16x16x32_bf16 v[4:7], v[174:177], v[216:219], v[4:7]
	v_mfma_f32_16x16x32_bf16 v[0:3], v[182:185], v[216:219], v[0:3]
	s_setprio 0
	s_barrier
	s_add_i32 s70, s70, 2
	s_add_u32 s30, s30, 0x100
	s_addc_u32 s31, s31, 0
	s_add_u32 s62, s62, 0x100
	s_addc_u32 s63, s63, 0
	s_cmp_gt_u32 s70, 13
	s_cbranch_scc0 .LBB0_2657
	v_lshl_add_u64 v[222:223], v[222:223], 0, s[18:19]
	s_mov_b32 m0, s53
	s_nop 0
	global_load_lds_dwordx4 v[222:223], off
	v_lshl_add_u64 v[224:225], v[224:225], 0, s[18:19]
	s_mov_b32 m0, s54
	s_nop 0
	global_load_lds_dwordx4 v[224:225], off
	s_and_b64 vcc, exec, s[20:21]
	s_cbranch_vccz .LBB0_2660
	s_barrier

.LBB0_3030:
	s_ashr_i32 s25, s24, 31
	s_lshl_b64 s[28:29], s[24:25], 19
	s_add_u32 s28, s40, s28
	s_addc_u32 s29, s41, s29
	s_and_b64 s[0:1], s[0:1], exec
	s_cselect_b32 s21, s29, s39
	s_cselect_b32 s23, s28, s38
	s_add_u32 s0, s38, 0x40080
	s_addc_u32 s1, s39, 0
	s_add_u32 s25, s36, 0x100
	v_mov_b32_e32 v0, 0
	s_addc_u32 s59, s37, 0
	s_mov_b32 s60, -2
	v_mov_b32_e32 v1, v0
	v_mov_b32_e32 v2, v0
	v_mov_b32_e32 v3, v0
	v_mov_b32_e32 v4, v0
	v_mov_b32_e32 v5, v0
	v_mov_b32_e32 v6, v0
	v_mov_b32_e32 v7, v0
	v_mov_b32_e32 v16, v0
	v_mov_b32_e32 v17, v0
	v_mov_b32_e32 v18, v0
	v_mov_b32_e32 v19, v0
	v_mov_b32_e32 v20, v0
	v_mov_b32_e32 v21, v0
	v_mov_b32_e32 v22, v0
	v_mov_b32_e32 v23, v0
	v_mov_b32_e32 v32, v0
	v_mov_b32_e32 v33, v0
	v_mov_b32_e32 v34, v0
	v_mov_b32_e32 v35, v0
	v_mov_b32_e32 v36, v0
	v_mov_b32_e32 v37, v0
	v_mov_b32_e32 v38, v0
	v_mov_b32_e32 v39, v0
	v_mov_b32_e32 v48, v0
	v_mov_b32_e32 v49, v0
	v_mov_b32_e32 v50, v0
	v_mov_b32_e32 v51, v0
	v_mov_b32_e32 v52, v0
	v_mov_b32_e32 v53, v0
	v_mov_b32_e32 v54, v0
	v_mov_b32_e32 v55, v0
	v_mov_b32_e32 v8, v0
	v_mov_b32_e32 v9, v0
	v_mov_b32_e32 v10, v0
	v_mov_b32_e32 v11, v0
	v_mov_b32_e32 v12, v0
	v_mov_b32_e32 v13, v0
	v_mov_b32_e32 v14, v0
	v_mov_b32_e32 v15, v0
	v_mov_b32_e32 v24, v0
	v_mov_b32_e32 v25, v0
	v_mov_b32_e32 v26, v0
	v_mov_b32_e32 v27, v0
	v_mov_b32_e32 v28, v0
	v_mov_b32_e32 v29, v0
	v_mov_b32_e32 v30, v0
	v_mov_b32_e32 v31, v0
	v_mov_b32_e32 v40, v0
	v_mov_b32_e32 v41, v0
	v_mov_b32_e32 v42, v0
	v_mov_b32_e32 v43, v0
	v_mov_b32_e32 v44, v0
	v_mov_b32_e32 v45, v0
	v_mov_b32_e32 v46, v0
	v_mov_b32_e32 v47, v0
	v_mov_b32_e32 v56, v0
	v_mov_b32_e32 v57, v0
	v_mov_b32_e32 v58, v0
	v_mov_b32_e32 v59, v0
	v_mov_b32_e32 v60, v0
	v_mov_b32_e32 v61, v0
	v_mov_b32_e32 v62, v0
	v_mov_b32_e32 v63, v0
	v_mov_b32_e32 v64, v0
	v_mov_b32_e32 v65, v0
	v_mov_b32_e32 v66, v0
	v_mov_b32_e32 v67, v0
	v_mov_b32_e32 v68, v0
	v_mov_b32_e32 v69, v0
	v_mov_b32_e32 v70, v0
	v_mov_b32_e32 v71, v0
	v_mov_b32_e32 v80, v0
	v_mov_b32_e32 v81, v0
	v_mov_b32_e32 v82, v0
	v_mov_b32_e32 v83, v0
	v_mov_b32_e32 v84, v0
	v_mov_b32_e32 v85, v0
	v_mov_b32_e32 v86, v0
	v_mov_b32_e32 v87, v0
	v_mov_b32_e32 v96, v0
	v_mov_b32_e32 v97, v0
	v_mov_b32_e32 v98, v0
	v_mov_b32_e32 v99, v0
	v_mov_b32_e32 v100, v0
	v_mov_b32_e32 v101, v0
	v_mov_b32_e32 v102, v0
	v_mov_b32_e32 v103, v0
	v_mov_b32_e32 v112, v0
	v_mov_b32_e32 v113, v0
	v_mov_b32_e32 v114, v0
	v_mov_b32_e32 v115, v0
	v_mov_b32_e32 v116, v0
	v_mov_b32_e32 v117, v0
	v_mov_b32_e32 v118, v0
	v_mov_b32_e32 v119, v0
	v_mov_b32_e32 v72, v0
	v_mov_b32_e32 v73, v0
	v_mov_b32_e32 v74, v0
	v_mov_b32_e32 v75, v0
	v_mov_b32_e32 v76, v0
	v_mov_b32_e32 v77, v0
	v_mov_b32_e32 v78, v0
	v_mov_b32_e32 v79, v0
	v_mov_b32_e32 v88, v0
	v_mov_b32_e32 v89, v0
	v_mov_b32_e32 v90, v0
	v_mov_b32_e32 v91, v0
	v_mov_b32_e32 v92, v0
	v_mov_b32_e32 v93, v0
	v_mov_b32_e32 v94, v0
	v_mov_b32_e32 v95, v0
	v_mov_b32_e32 v104, v0
	v_mov_b32_e32 v105, v0
	v_mov_b32_e32 v106, v0
	v_mov_b32_e32 v107, v0
	v_mov_b32_e32 v108, v0
	v_mov_b32_e32 v109, v0
	v_mov_b32_e32 v110, v0
	v_mov_b32_e32 v111, v0
	v_mov_b32_e32 v120, v0
	v_mov_b32_e32 v121, v0
	v_mov_b32_e32 v122, v0
	v_mov_b32_e32 v123, v0
	v_mov_b32_e32 v124, v0
	v_mov_b32_e32 v125, v0
	v_mov_b32_e32 v126, v0
	v_mov_b32_e32 v127, v0
	s_mov_b32 s99, 0
.LBB0_3031:
	ds_read_b128 v[146:149], v155
	ds_read_b128 v[160:163], v155 offset:1024
	ds_read_b128 v[164:167], v155 offset:2048
	ds_read_b128 v[168:171], v155 offset:3072
	ds_read_b128 v[172:175], v156
	ds_read_b128 v[176:179], v156 offset:1024
	ds_read_b128 v[180:183], v156 offset:2048
	ds_read_b128 v[184:187], v156 offset:3072
	s_add_u32 s36, s0, 0xfffc0080
	s_addc_u32 s37, s1, -1
	s_cmp_eq_u32 s60, 12
	s_cselect_b32 s39, s21, s37
	s_cselect_b32 s38, s23, s36
	s_cselect_b32 s37, s27, s59
	s_cselect_b32 s36, s26, s25
	v_lshl_add_u64 v[150:151], s[0:1], 0, v[138:139]
	ds_read_b128 v[188:191], v157
	ds_read_b128 v[196:199], v157 offset:1024
	ds_read_b128 v[200:203], v157 offset:2048
	ds_read_b128 v[204:207], v157 offset:3072
	ds_read_b128 v[208:211], v157 offset:4096
	ds_read_b128 v[212:215], v157 offset:5120
	ds_read_b128 v[216:219], v157 offset:6144
	ds_read_b128 v[220:223], v157 offset:7168
	s_cmp_eq_u32 s99, 0
	s_cbranch_scc1 .Lkb_first_23
	v_lshl_add_u64 v[224:225], v[224:225], 0, s[16:17]
	s_mov_b32 m0, s50
	s_nop 0
	global_load_lds_dwordx4 v[224:225], off
	v_lshl_add_u64 v[226:227], v[226:227], 0, s[16:17]
	s_mov_b32 m0, s51
	s_nop 0
	global_load_lds_dwordx4 v[226:227], off
	s_branch .Lkb_join_23
.Lkb_first_23:
	s_add_i32 m0, s35, 0xc000
	s_nop 0
	global_load_lds_dwordx4 v[150:151], off
	global_load_lds_dwordx4 v[150:151], off
.Lkb_join_23:
	s_add_i32 m0, s35, 0xc000
	s_nop 0
	global_load_lds_dwordx4 v[150:151], off
	v_lshl_add_u64 v[150:151], s[0:1], 0, v[140:141]
	s_add_i32 m0, s35, 0xe000
	s_nop 0
	global_load_lds_dwordx4 v[150:151], off
	s_waitcnt vmcnt(8)
	s_waitcnt lgkmcnt(0)
	s_barrier
	s_setprio 1
	s_waitcnt lgkmcnt(0)
	v_mfma_f32_16x16x32_bf16 v[124:127], v[146:149], v[188:191], v[124:127]
	v_mfma_f32_16x16x32_bf16 v[120:123], v[164:167], v[188:191], v[120:123]
	v_mfma_f32_16x16x32_bf16 v[108:111], v[146:149], v[200:203], v[108:111]
	v_mfma_f32_16x16x32_bf16 v[104:107], v[164:167], v[200:203], v[104:107]
	v_mfma_f32_16x16x32_bf16 v[92:95], v[146:149], v[208:211], v[92:95]
	v_mfma_f32_16x16x32_bf16 v[88:91], v[164:167], v[208:211], v[88:91]
	v_mfma_f32_16x16x32_bf16 v[76:79], v[146:149], v[216:219], v[76:79]
	v_mfma_f32_16x16x32_bf16 v[72:75], v[164:167], v[216:219], v[72:75]
	v_mfma_f32_16x16x32_bf16 v[124:127], v[160:163], v[196:199], v[124:127]
	v_mfma_f32_16x16x32_bf16 v[120:123], v[168:171], v[196:199], v[120:123]
	v_mfma_f32_16x16x32_bf16 v[108:111], v[160:163], v[204:207], v[108:111]
	v_mfma_f32_16x16x32_bf16 v[104:107], v[168:171], v[204:207], v[104:107]
	v_mfma_f32_16x16x32_bf16 v[92:95], v[160:163], v[212:215], v[92:95]
	v_mfma_f32_16x16x32_bf16 v[88:91], v[168:171], v[212:215], v[88:91]
	v_mfma_f32_16x16x32_bf16 v[76:79], v[160:163], v[220:223], v[76:79]
	v_mfma_f32_16x16x32_bf16 v[72:75], v[168:171], v[220:223], v[72:75]
	s_setprio 0
	s_setprio 1
	v_mfma_f32_16x16x32_bf16 v[116:119], v[172:175], v[188:191], v[116:119]
	v_mfma_f32_16x16x32_bf16 v[112:115], v[180:183], v[188:191], v[112:115]
	v_mfma_f32_16x16x32_bf16 v[100:103], v[172:175], v[200:203], v[100:103]
	v_mfma_f32_16x16x32_bf16 v[96:99], v[180:183], v[200:203], v[96:99]
	v_mfma_f32_16x16x32_bf16 v[84:87], v[172:175], v[208:211], v[84:87]
	v_mfma_f32_16x16x32_bf16 v[80:83], v[180:183], v[208:211], v[80:83]
	v_mfma_f32_16x16x32_bf16 v[68:71], v[172:175], v[216:219], v[68:71]
	v_mfma_f32_16x16x32_bf16 v[64:67], v[180:183], v[216:219], v[64:67]
	v_mfma_f32_16x16x32_bf16 v[116:119], v[176:179], v[196:199], v[116:119]
	v_mfma_f32_16x16x32_bf16 v[112:115], v[184:187], v[196:199], v[112:115]
	v_mfma_f32_16x16x32_bf16 v[100:103], v[176:179], v[204:207], v[100:103]
	v_mfma_f32_16x16x32_bf16 v[96:99], v[184:187], v[204:207], v[96:99]
	v_mfma_f32_16x16x32_bf16 v[84:87], v[176:179], v[212:215], v[84:87]
	v_mfma_f32_16x16x32_bf16 v[80:83], v[184:187], v[212:215], v[80:83]
	v_mfma_f32_16x16x32_bf16 v[68:71], v[176:179], v[220:223], v[68:71]
	v_mfma_f32_16x16x32_bf16 v[64:67], v[184:187], v[220:223], v[64:67]
	s_setprio 0
	s_barrier
	s_add_i32 s61, s55, s44
	v_lshl_add_u64 v[150:151], s[36:37], 0, v[130:131]
	s_mov_b32 m0, s61
	ds_read_b128 v[188:191], v157 offset:16384
	ds_read_b128 v[196:199], v157 offset:17408
	ds_read_b128 v[200:203], v157 offset:18432
	ds_read_b128 v[204:207], v157 offset:19456
	ds_read_b128 v[208:211], v157 offset:20480
	ds_read_b128 v[212:215], v157 offset:21504
	ds_read_b128 v[216:219], v157 offset:22528
	ds_read_b128 v[220:223], v157 offset:23552
	global_load_lds_dwordx4 v[150:151], off
	s_add_i32 m0, s61, 0x2000
	s_add_u32 s62, s36, 0x40000
	v_lshl_add_u64 v[192:193], s[36:37], 0, v[134:135]
	s_addc_u32 s63, s37, 0
	s_add_i32 s61, s56, s44
	global_load_lds_dwordx4 v[192:193], off
	v_lshl_add_u64 v[224:225], s[62:63], 0, v[130:131]
	s_mov_b32 m0, s61
	v_lshl_add_u64 v[226:227], s[38:39], 0, v[132:133]
	global_load_lds_dwordx4 v[224:225], off
	v_lshl_add_u64 v[224:225], s[62:63], 0, v[134:135]
	s_add_i32 m0, s61, 0x2000
	s_nop 0
	global_load_lds_dwordx4 v[224:225], off
	v_lshl_add_u64 v[224:225], s[38:39], 0, v[128:129]
	s_waitcnt vmcnt(6)
	s_waitcnt lgkmcnt(0)
	s_barrier
	s_setprio 1
	s_waitcnt lgkmcnt(0)
	v_mfma_f32_16x16x32_bf16 v[60:63], v[146:149], v[188:191], v[60:63]
	v_mfma_f32_16x16x32_bf16 v[56:59], v[164:167], v[188:191], v[56:59]
	v_mfma_f32_16x16x32_bf16 v[44:47], v[146:149], v[200:203], v[44:47]
	v_mfma_f32_16x16x32_bf16 v[40:43], v[164:167], v[200:203], v[40:43]
	v_mfma_f32_16x16x32_bf16 v[28:31], v[146:149], v[208:211], v[28:31]
	v_mfma_f32_16x16x32_bf16 v[24:27], v[164:167], v[208:211], v[24:27]
	v_mfma_f32_16x16x32_bf16 v[12:15], v[146:149], v[216:219], v[12:15]
	v_mfma_f32_16x16x32_bf16 v[8:11], v[164:167], v[216:219], v[8:11]
	v_mfma_f32_16x16x32_bf16 v[60:63], v[160:163], v[196:199], v[60:63]
	v_mfma_f32_16x16x32_bf16 v[56:59], v[168:171], v[196:199], v[56:59]
	v_mfma_f32_16x16x32_bf16 v[44:47], v[160:163], v[204:207], v[44:47]
	v_mfma_f32_16x16x32_bf16 v[40:43], v[168:171], v[204:207], v[40:43]
	v_mfma_f32_16x16x32_bf16 v[28:31], v[160:163], v[212:215], v[28:31]
	v_mfma_f32_16x16x32_bf16 v[24:27], v[168:171], v[212:215], v[24:27]
	v_mfma_f32_16x16x32_bf16 v[12:15], v[160:163], v[220:223], v[12:15]
	v_mfma_f32_16x16x32_bf16 v[8:11], v[168:171], v[220:223], v[8:11]
	s_setprio 0
	s_setprio 1
	v_mfma_f32_16x16x32_bf16 v[52:55], v[172:175], v[188:191], v[52:55]
	v_mfma_f32_16x16x32_bf16 v[48:51], v[180:183], v[188:191], v[48:51]
	v_mfma_f32_16x16x32_bf16 v[36:39], v[172:175], v[200:203], v[36:39]
	v_mfma_f32_16x16x32_bf16 v[32:35], v[180:183], v[200:203], v[32:35]
	v_mfma_f32_16x16x32_bf16 v[20:23], v[172:175], v[208:211], v[20:23]
	v_mfma_f32_16x16x32_bf16 v[16:19], v[180:183], v[208:211], v[16:19]
	v_mfma_f32_16x16x32_bf16 v[4:7], v[172:175], v[216:219], v[4:7]
	v_mfma_f32_16x16x32_bf16 v[0:3], v[180:183], v[216:219], v[0:3]
	v_mfma_f32_16x16x32_bf16 v[52:55], v[176:179], v[196:199], v[52:55]
	v_mfma_f32_16x16x32_bf16 v[48:51], v[184:187], v[196:199], v[48:51]
	v_mfma_f32_16x16x32_bf16 v[36:39], v[176:179], v[204:207], v[36:39]
	v_mfma_f32_16x16x32_bf16 v[32:35], v[184:187], v[204:207], v[32:35]
	v_mfma_f32_16x16x32_bf16 v[20:23], v[176:179], v[212:215], v[20:23]
	v_mfma_f32_16x16x32_bf16 v[16:19], v[184:187], v[212:215], v[16:19]
	v_mfma_f32_16x16x32_bf16 v[4:7], v[176:179], v[220:223], v[4:7]
	v_mfma_f32_16x16x32_bf16 v[0:3], v[184:187], v[220:223], v[0:3]
	s_setprio 0
	s_barrier
	s_add_i32 s61, 0, 0x18000
	v_add_u32_e32 v159, s61, v153
	s_add_i32 s62, 0, 0x1c000
	ds_read_b128 v[146:149], v159
	ds_read_b128 v[160:163], v159 offset:1024
	ds_read_b128 v[164:167], v159 offset:2048
	ds_read_b128 v[168:171], v159 offset:3072
	v_add_u32_e32 v159, s62, v153
	ds_read_b128 v[172:175], v159
	ds_read_b128 v[176:179], v159 offset:1024
	ds_read_b128 v[180:183], v159 offset:2048
	ds_read_b128 v[184:187], v159 offset:3072
	s_add_u32 s38, s38, 0x40000
	s_addc_u32 s39, s39, 0
	v_lshl_add_u64 v[228:229], s[38:39], 0, v[128:129]
	ds_read_b128 v[188:191], v157 offset:32768
	ds_read_b128 v[196:199], v157 offset:33792
	ds_read_b128 v[200:203], v157 offset:34816
	ds_read_b128 v[204:207], v157 offset:35840
	ds_read_b128 v[208:211], v157 offset:36864
	ds_read_b128 v[212:215], v157 offset:37888
	ds_read_b128 v[216:219], v157 offset:38912
	ds_read_b128 v[220:223], v157 offset:39936
	s_mov_b32 m0, s35
	s_nop 0
	global_load_lds_dwordx4 v[224:225], off
	s_mov_b32 m0, s45
	s_nop 0
	global_load_lds_dwordx4 v[226:227], off
	s_mov_b32 m0, s48
	s_nop 0
	global_load_lds_dwordx4 v[228:229], off
	v_lshl_add_u64 v[228:229], s[38:39], 0, v[132:133]
	s_mov_b32 m0, s49
	s_nop 0
	global_load_lds_dwordx4 v[228:229], off
	s_waitcnt vmcnt(8)
	s_waitcnt lgkmcnt(0)
	s_barrier
	s_setprio 1
	s_waitcnt lgkmcnt(0)
	v_mfma_f32_16x16x32_bf16 v[124:127], v[146:149], v[188:191], v[124:127]
	v_mfma_f32_16x16x32_bf16 v[120:123], v[164:167], v[188:191], v[120:123]
	v_mfma_f32_16x16x32_bf16 v[108:111], v[146:149], v[200:203], v[108:111]
	v_mfma_f32_16x16x32_bf16 v[104:107], v[164:167], v[200:203], v[104:107]
	v_mfma_f32_16x16x32_bf16 v[92:95], v[146:149], v[208:211], v[92:95]
	v_mfma_f32_16x16x32_bf16 v[88:91], v[164:167], v[208:211], v[88:91]
	v_mfma_f32_16x16x32_bf16 v[76:79], v[146:149], v[216:219], v[76:79]
	v_mfma_f32_16x16x32_bf16 v[72:75], v[164:167], v[216:219], v[72:75]
	v_mfma_f32_16x16x32_bf16 v[124:127], v[160:163], v[196:199], v[124:127]
	v_mfma_f32_16x16x32_bf16 v[120:123], v[168:171], v[196:199], v[120:123]
	v_mfma_f32_16x16x32_bf16 v[108:111], v[160:163], v[204:207], v[108:111]
	v_mfma_f32_16x16x32_bf16 v[104:107], v[168:171], v[204:207], v[104:107]
	v_mfma_f32_16x16x32_bf16 v[92:95], v[160:163], v[212:215], v[92:95]
	v_mfma_f32_16x16x32_bf16 v[88:91], v[168:171], v[212:215], v[88:91]
	v_mfma_f32_16x16x32_bf16 v[76:79], v[160:163], v[220:223], v[76:79]
	v_mfma_f32_16x16x32_bf16 v[72:75], v[168:171], v[220:223], v[72:75]
	s_setprio 0
	s_setprio 1
	v_mfma_f32_16x16x32_bf16 v[116:119], v[172:175], v[188:191], v[116:119]
	v_mfma_f32_16x16x32_bf16 v[112:115], v[180:183], v[188:191], v[112:115]
	v_mfma_f32_16x16x32_bf16 v[100:103], v[172:175], v[200:203], v[100:103]
	v_mfma_f32_16x16x32_bf16 v[96:99], v[180:183], v[200:203], v[96:99]
	v_mfma_f32_16x16x32_bf16 v[84:87], v[172:175], v[208:211], v[84:87]
	v_mfma_f32_16x16x32_bf16 v[80:83], v[180:183], v[208:211], v[80:83]
	v_mfma_f32_16x16x32_bf16 v[68:71], v[172:175], v[216:219], v[68:71]
	v_mfma_f32_16x16x32_bf16 v[64:67], v[180:183], v[216:219], v[64:67]
	v_mfma_f32_16x16x32_bf16 v[116:119], v[176:179], v[196:199], v[116:119]
	v_mfma_f32_16x16x32_bf16 v[112:115], v[184:187], v[196:199], v[112:115]
	v_mfma_f32_16x16x32_bf16 v[100:103], v[176:179], v[204:207], v[100:103]
	v_mfma_f32_16x16x32_bf16 v[96:99], v[184:187], v[204:207], v[96:99]
	v_mfma_f32_16x16x32_bf16 v[84:87], v[176:179], v[212:215], v[84:87]
	v_mfma_f32_16x16x32_bf16 v[80:83], v[184:187], v[212:215], v[80:83]
	v_mfma_f32_16x16x32_bf16 v[68:71], v[176:179], v[220:223], v[68:71]
	v_mfma_f32_16x16x32_bf16 v[64:67], v[184:187], v[220:223], v[64:67]
	s_setprio 0
	s_barrier
	s_add_i32 s38, s61, s44
	v_lshl_add_u64 v[150:151], v[150:151], 0, s[16:17]
	s_mov_b32 m0, s38
	ds_read_b128 v[188:191], v157 offset:49152
	ds_read_b128 v[196:199], v157 offset:50176
	ds_read_b128 v[200:203], v157 offset:51200
	ds_read_b128 v[204:207], v157 offset:52224
	ds_read_b128 v[208:211], v157 offset:53248
	ds_read_b128 v[212:215], v157 offset:54272
	ds_read_b128 v[216:219], v157 offset:55296
	ds_read_b128 v[220:223], v157 offset:56320
	global_load_lds_dwordx4 v[150:151], off
	s_add_i32 m0, s38, 0x2000
	s_add_u32 s36, s36, 0x40080
	v_lshl_add_u64 v[150:151], v[192:193], 0, s[16:17]
	s_addc_u32 s37, s37, 0
	s_add_i32 s38, s62, s44
	global_load_lds_dwordx4 v[150:151], off
	v_lshl_add_u64 v[150:151], s[36:37], 0, v[130:131]
	s_mov_b32 m0, s38
	s_nop 0
	global_load_lds_dwordx4 v[150:151], off
	v_lshl_add_u64 v[150:151], s[36:37], 0, v[134:135]
	s_add_i32 m0, s38, 0x2000
	s_nop 0
	global_load_lds_dwordx4 v[150:151], off
	s_mov_b32 s99, 1
	s_waitcnt vmcnt(6)
	s_waitcnt lgkmcnt(0)
	s_barrier
	s_setprio 1
	s_waitcnt lgkmcnt(0)
	v_mfma_f32_16x16x32_bf16 v[60:63], v[146:149], v[188:191], v[60:63]
	v_mfma_f32_16x16x32_bf16 v[56:59], v[164:167], v[188:191], v[56:59]
	v_mfma_f32_16x16x32_bf16 v[44:47], v[146:149], v[200:203], v[44:47]
	v_mfma_f32_16x16x32_bf16 v[40:43], v[164:167], v[200:203], v[40:43]
	v_mfma_f32_16x16x32_bf16 v[28:31], v[146:149], v[208:211], v[28:31]
	v_mfma_f32_16x16x32_bf16 v[24:27], v[164:167], v[208:211], v[24:27]
	v_mfma_f32_16x16x32_bf16 v[12:15], v[146:149], v[216:219], v[12:15]
	v_mfma_f32_16x16x32_bf16 v[8:11], v[164:167], v[216:219], v[8:11]
	v_mfma_f32_16x16x32_bf16 v[60:63], v[160:163], v[196:199], v[60:63]
	v_mfma_f32_16x16x32_bf16 v[56:59], v[168:171], v[196:199], v[56:59]
	v_mfma_f32_16x16x32_bf16 v[44:47], v[160:163], v[204:207], v[44:47]
	v_mfma_f32_16x16x32_bf16 v[40:43], v[168:171], v[204:207], v[40:43]
	v_mfma_f32_16x16x32_bf16 v[28:31], v[160:163], v[212:215], v[28:31]
	v_mfma_f32_16x16x32_bf16 v[24:27], v[168:171], v[212:215], v[24:27]
	v_mfma_f32_16x16x32_bf16 v[12:15], v[160:163], v[220:223], v[12:15]
	v_mfma_f32_16x16x32_bf16 v[8:11], v[168:171], v[220:223], v[8:11]
	s_setprio 0
	s_setprio 1
	v_mfma_f32_16x16x32_bf16 v[52:55], v[172:175], v[188:191], v[52:55]
	v_mfma_f32_16x16x32_bf16 v[48:51], v[180:183], v[188:191], v[48:51]
	v_mfma_f32_16x16x32_bf16 v[36:39], v[172:175], v[200:203], v[36:39]
	v_mfma_f32_16x16x32_bf16 v[32:35], v[180:183], v[200:203], v[32:35]
	v_mfma_f32_16x16x32_bf16 v[20:23], v[172:175], v[208:211], v[20:23]
	v_mfma_f32_16x16x32_bf16 v[16:19], v[180:183], v[208:211], v[16:19]
	v_mfma_f32_16x16x32_bf16 v[4:7], v[172:175], v[216:219], v[4:7]
	v_mfma_f32_16x16x32_bf16 v[0:3], v[180:183], v[216:219], v[0:3]
	v_mfma_f32_16x16x32_bf16 v[52:55], v[176:179], v[196:199], v[52:55]
	v_mfma_f32_16x16x32_bf16 v[48:51], v[184:187], v[196:199], v[48:51]
	v_mfma_f32_16x16x32_bf16 v[36:39], v[176:179], v[204:207], v[36:39]
	v_mfma_f32_16x16x32_bf16 v[32:35], v[184:187], v[204:207], v[32:35]
	v_mfma_f32_16x16x32_bf16 v[20:23], v[176:179], v[212:215], v[20:23]
	v_mfma_f32_16x16x32_bf16 v[16:19], v[184:187], v[212:215], v[16:19]
	v_mfma_f32_16x16x32_bf16 v[4:7], v[176:179], v[220:223], v[4:7]
	v_mfma_f32_16x16x32_bf16 v[0:3], v[184:187], v[220:223], v[0:3]
	s_setprio 0
	s_barrier
	s_add_i32 s60, s60, 2
	s_add_u32 s0, s0, 0x100
	s_addc_u32 s1, s1, 0
	s_add_u32 s25, s25, 0x100
	s_addc_u32 s59, s59, 0
	s_cmp_gt_u32 s60, 13
	s_cbranch_scc0 .LBB0_3031
	v_lshl_add_u64 v[224:225], v[224:225], 0, s[16:17]
	s_mov_b32 m0, s50
	s_nop 0
	global_load_lds_dwordx4 v[224:225], off
	v_lshl_add_u64 v[226:227], v[226:227], 0, s[16:17]
	s_mov_b32 m0, s51
	s_nop 0
	global_load_lds_dwordx4 v[226:227], off
	s_and_b64 vcc, exec, s[18:19]
	s_cbranch_vccz .LBB0_3034
	s_barrier

.LBB0_3060:
	s_add_u32 s42, s42, 0x20080
	s_addc_u32 s43, s43, 0
	s_add_u32 s11, s48, 0x100
	v_mov_b32_e32 v0, 0
	s_addc_u32 s13, s49, 0
	s_mov_b32 s35, -2
	v_mov_b32_e32 v1, v0
	v_mov_b32_e32 v2, v0
	v_mov_b32_e32 v3, v0
	v_mov_b32_e32 v4, v0
	v_mov_b32_e32 v5, v0
	v_mov_b32_e32 v6, v0
	v_mov_b32_e32 v7, v0
	v_mov_b32_e32 v16, v0
	v_mov_b32_e32 v17, v0
	v_mov_b32_e32 v18, v0
	v_mov_b32_e32 v19, v0
	v_mov_b32_e32 v20, v0
	v_mov_b32_e32 v21, v0
	v_mov_b32_e32 v22, v0
	v_mov_b32_e32 v23, v0
	v_mov_b32_e32 v32, v0
	v_mov_b32_e32 v33, v0
	v_mov_b32_e32 v34, v0
	v_mov_b32_e32 v35, v0
	v_mov_b32_e32 v36, v0
	v_mov_b32_e32 v37, v0
	v_mov_b32_e32 v38, v0
	v_mov_b32_e32 v39, v0
	v_mov_b32_e32 v48, v0
	v_mov_b32_e32 v49, v0
	v_mov_b32_e32 v50, v0
	v_mov_b32_e32 v51, v0
	v_mov_b32_e32 v52, v0
	v_mov_b32_e32 v53, v0
	v_mov_b32_e32 v54, v0
	v_mov_b32_e32 v55, v0
	v_mov_b32_e32 v8, v0
	v_mov_b32_e32 v9, v0
	v_mov_b32_e32 v10, v0
	v_mov_b32_e32 v11, v0
	v_mov_b32_e32 v12, v0
	v_mov_b32_e32 v13, v0
	v_mov_b32_e32 v14, v0
	v_mov_b32_e32 v15, v0
	v_mov_b32_e32 v24, v0
	v_mov_b32_e32 v25, v0
	v_mov_b32_e32 v26, v0
	v_mov_b32_e32 v27, v0
	v_mov_b32_e32 v28, v0
	v_mov_b32_e32 v29, v0
	v_mov_b32_e32 v30, v0
	v_mov_b32_e32 v31, v0
	v_mov_b32_e32 v40, v0
	v_mov_b32_e32 v41, v0
	v_mov_b32_e32 v42, v0
	v_mov_b32_e32 v43, v0
	v_mov_b32_e32 v44, v0
	v_mov_b32_e32 v45, v0
	v_mov_b32_e32 v46, v0
	v_mov_b32_e32 v47, v0
	v_mov_b32_e32 v56, v0
	v_mov_b32_e32 v57, v0
	v_mov_b32_e32 v58, v0
	v_mov_b32_e32 v59, v0
	v_mov_b32_e32 v60, v0
	v_mov_b32_e32 v61, v0
	v_mov_b32_e32 v62, v0
	v_mov_b32_e32 v63, v0
	v_mov_b32_e32 v64, v0
	v_mov_b32_e32 v65, v0
	v_mov_b32_e32 v66, v0
	v_mov_b32_e32 v67, v0
	v_mov_b32_e32 v68, v0
	v_mov_b32_e32 v69, v0
	v_mov_b32_e32 v70, v0
	v_mov_b32_e32 v71, v0
	v_mov_b32_e32 v80, v0
	v_mov_b32_e32 v81, v0
	v_mov_b32_e32 v82, v0
	v_mov_b32_e32 v83, v0
	v_mov_b32_e32 v84, v0
	v_mov_b32_e32 v85, v0
	v_mov_b32_e32 v86, v0
	v_mov_b32_e32 v87, v0
	v_mov_b32_e32 v96, v0
	v_mov_b32_e32 v97, v0
	v_mov_b32_e32 v98, v0
	v_mov_b32_e32 v99, v0
	v_mov_b32_e32 v100, v0
	v_mov_b32_e32 v101, v0
	v_mov_b32_e32 v102, v0
	v_mov_b32_e32 v103, v0
	v_mov_b32_e32 v112, v0
	v_mov_b32_e32 v113, v0
	v_mov_b32_e32 v114, v0
	v_mov_b32_e32 v115, v0
	v_mov_b32_e32 v116, v0
	v_mov_b32_e32 v117, v0
	v_mov_b32_e32 v118, v0
	v_mov_b32_e32 v119, v0
	v_mov_b32_e32 v72, v0
	v_mov_b32_e32 v73, v0
	v_mov_b32_e32 v74, v0
	v_mov_b32_e32 v75, v0
	v_mov_b32_e32 v76, v0
	v_mov_b32_e32 v77, v0
	v_mov_b32_e32 v78, v0
	v_mov_b32_e32 v79, v0
	v_mov_b32_e32 v88, v0
	v_mov_b32_e32 v89, v0
	v_mov_b32_e32 v90, v0
	v_mov_b32_e32 v91, v0
	v_mov_b32_e32 v92, v0
	v_mov_b32_e32 v93, v0
	v_mov_b32_e32 v94, v0
	v_mov_b32_e32 v95, v0
	v_mov_b32_e32 v104, v0
	v_mov_b32_e32 v105, v0
	v_mov_b32_e32 v106, v0
	v_mov_b32_e32 v107, v0
	v_mov_b32_e32 v108, v0
	v_mov_b32_e32 v109, v0
	v_mov_b32_e32 v110, v0
	v_mov_b32_e32 v111, v0
	v_mov_b32_e32 v120, v0
	v_mov_b32_e32 v121, v0
	v_mov_b32_e32 v122, v0
	v_mov_b32_e32 v123, v0
	v_mov_b32_e32 v124, v0
	v_mov_b32_e32 v125, v0
	v_mov_b32_e32 v126, v0
	v_mov_b32_e32 v127, v0
	s_mov_b32 s99, 0
.LBB0_3061:
	ds_read_b128 v[144:147], v159
	ds_read_b128 v[148:151], v159 offset:1024
	ds_read_b128 v[152:155], v159 offset:2048
	ds_read_b128 v[162:165], v159 offset:3072
	ds_read_b128 v[166:169], v160
	ds_read_b128 v[170:173], v160 offset:1024
	ds_read_b128 v[174:177], v160 offset:2048
	ds_read_b128 v[178:181], v160 offset:3072
	s_add_u32 s37, s42, 0xfffe0080
	s_addc_u32 s39, s43, -1
	s_cmp_eq_u32 s35, 4
	s_cselect_b32 s51, s1, s39
	s_cselect_b32 s50, s0, s37
	s_cselect_b32 s49, s41, s13
	s_cselect_b32 s48, s40, s11
	v_lshl_add_u64 v[216:217], s[42:43], 0, v[136:137]
	ds_read_b128 v[182:185], v161
	ds_read_b128 v[186:189], v161 offset:1024
	ds_read_b128 v[190:193], v161 offset:2048
	ds_read_b128 v[196:199], v161 offset:3072
	ds_read_b128 v[200:203], v161 offset:4096
	ds_read_b128 v[204:207], v161 offset:5120
	ds_read_b128 v[208:211], v161 offset:6144
	ds_read_b128 v[212:215], v161 offset:7168
	s_cmp_eq_u32 s99, 0
	s_cbranch_scc1 .Lkb_first_24
	v_lshl_add_u64 v[220:221], v[220:221], 0, s[22:23]
	s_mov_b32 m0, s70
	s_nop 0
	global_load_lds_dwordx4 v[220:221], off
	v_lshl_add_u64 v[222:223], v[222:223], 0, s[22:23]
	s_mov_b32 m0, s71
	s_nop 0
	global_load_lds_dwordx4 v[222:223], off
	s_branch .Lkb_join_24
.Lkb_first_24:
	s_add_i32 m0, s60, 0xc000
	s_nop 0
	global_load_lds_dwordx4 v[216:217], off
	global_load_lds_dwordx4 v[216:217], off
.Lkb_join_24:
	s_add_i32 m0, s60, 0xc000
	s_nop 0
	global_load_lds_dwordx4 v[216:217], off
	v_lshl_add_u64 v[216:217], s[42:43], 0, v[138:139]
	s_add_i32 m0, s60, 0xe000
	s_nop 0
	global_load_lds_dwordx4 v[216:217], off
	s_waitcnt vmcnt(8)
	s_waitcnt lgkmcnt(0)
	s_barrier
	s_setprio 1
	s_waitcnt lgkmcnt(0)
	v_mfma_f32_16x16x32_bf16 v[124:127], v[144:147], v[182:185], v[124:127]
	v_mfma_f32_16x16x32_bf16 v[120:123], v[152:155], v[182:185], v[120:123]
	v_mfma_f32_16x16x32_bf16 v[108:111], v[144:147], v[190:193], v[108:111]
	v_mfma_f32_16x16x32_bf16 v[104:107], v[152:155], v[190:193], v[104:107]
	v_mfma_f32_16x16x32_bf16 v[92:95], v[144:147], v[200:203], v[92:95]
	v_mfma_f32_16x16x32_bf16 v[88:91], v[152:155], v[200:203], v[88:91]
	v_mfma_f32_16x16x32_bf16 v[76:79], v[144:147], v[208:211], v[76:79]
	v_mfma_f32_16x16x32_bf16 v[72:75], v[152:155], v[208:211], v[72:75]
	v_mfma_f32_16x16x32_bf16 v[124:127], v[148:151], v[186:189], v[124:127]
	v_mfma_f32_16x16x32_bf16 v[120:123], v[162:165], v[186:189], v[120:123]
	v_mfma_f32_16x16x32_bf16 v[108:111], v[148:151], v[196:199], v[108:111]
	v_mfma_f32_16x16x32_bf16 v[104:107], v[162:165], v[196:199], v[104:107]
	v_mfma_f32_16x16x32_bf16 v[92:95], v[148:151], v[204:207], v[92:95]
	v_mfma_f32_16x16x32_bf16 v[88:91], v[162:165], v[204:207], v[88:91]
	v_mfma_f32_16x16x32_bf16 v[76:79], v[148:151], v[212:215], v[76:79]
	v_mfma_f32_16x16x32_bf16 v[72:75], v[162:165], v[212:215], v[72:75]
	s_setprio 0
	s_setprio 1
	v_mfma_f32_16x16x32_bf16 v[116:119], v[166:169], v[182:185], v[116:119]
	v_mfma_f32_16x16x32_bf16 v[112:115], v[174:177], v[182:185], v[112:115]
	v_mfma_f32_16x16x32_bf16 v[100:103], v[166:169], v[190:193], v[100:103]
	v_mfma_f32_16x16x32_bf16 v[96:99], v[174:177], v[190:193], v[96:99]
	v_mfma_f32_16x16x32_bf16 v[84:87], v[166:169], v[200:203], v[84:87]
	v_mfma_f32_16x16x32_bf16 v[80:83], v[174:177], v[200:203], v[80:83]
	v_mfma_f32_16x16x32_bf16 v[68:71], v[166:169], v[208:211], v[68:71]
	v_mfma_f32_16x16x32_bf16 v[64:67], v[174:177], v[208:211], v[64:67]
	v_mfma_f32_16x16x32_bf16 v[116:119], v[170:173], v[186:189], v[116:119]
	v_mfma_f32_16x16x32_bf16 v[112:115], v[178:181], v[186:189], v[112:115]
	v_mfma_f32_16x16x32_bf16 v[100:103], v[170:173], v[196:199], v[100:103]
	v_mfma_f32_16x16x32_bf16 v[96:99], v[178:181], v[196:199], v[96:99]
	v_mfma_f32_16x16x32_bf16 v[84:87], v[170:173], v[204:207], v[84:87]
	v_mfma_f32_16x16x32_bf16 v[80:83], v[178:181], v[204:207], v[80:83]
	v_mfma_f32_16x16x32_bf16 v[68:71], v[170:173], v[212:215], v[68:71]
	v_mfma_f32_16x16x32_bf16 v[64:67], v[178:181], v[212:215], v[64:67]
	s_setprio 0
	s_barrier
	s_add_i32 s37, s73, s57
	v_lshl_add_u64 v[216:217], s[48:49], 0, v[130:131]
	s_mov_b32 m0, s37
	ds_read_b128 v[182:185], v161 offset:16384
	ds_read_b128 v[186:189], v161 offset:17408
	ds_read_b128 v[190:193], v161 offset:18432
	ds_read_b128 v[196:199], v161 offset:19456
	ds_read_b128 v[200:203], v161 offset:20480
	ds_read_b128 v[204:207], v161 offset:21504
	ds_read_b128 v[208:211], v161 offset:22528
	ds_read_b128 v[212:215], v161 offset:23552
	global_load_lds_dwordx4 v[216:217], off
	s_add_i32 m0, s37, 0x2000
	s_add_u32 s80, s48, 0x20000
	v_lshl_add_u64 v[218:219], s[48:49], 0, v[134:135]
	s_addc_u32 s81, s49, 0
	s_add_i32 s37, s77, s57
	global_load_lds_dwordx4 v[218:219], off
	v_lshl_add_u64 v[220:221], s[80:81], 0, v[130:131]
	s_mov_b32 m0, s37
	v_lshl_add_u64 v[222:223], s[50:51], 0, v[132:133]
	global_load_lds_dwordx4 v[220:221], off
	v_lshl_add_u64 v[220:221], s[80:81], 0, v[134:135]
	s_add_i32 m0, s37, 0x2000
	s_nop 0
	global_load_lds_dwordx4 v[220:221], off
	v_lshl_add_u64 v[220:221], s[50:51], 0, v[128:129]
	s_waitcnt vmcnt(6)
	s_waitcnt lgkmcnt(0)
	s_barrier
	s_setprio 1
	s_waitcnt lgkmcnt(0)
	v_mfma_f32_16x16x32_bf16 v[60:63], v[144:147], v[182:185], v[60:63]
	v_mfma_f32_16x16x32_bf16 v[56:59], v[152:155], v[182:185], v[56:59]
	v_mfma_f32_16x16x32_bf16 v[44:47], v[144:147], v[190:193], v[44:47]
	v_mfma_f32_16x16x32_bf16 v[40:43], v[152:155], v[190:193], v[40:43]
	v_mfma_f32_16x16x32_bf16 v[28:31], v[144:147], v[200:203], v[28:31]
	v_mfma_f32_16x16x32_bf16 v[24:27], v[152:155], v[200:203], v[24:27]
	v_mfma_f32_16x16x32_bf16 v[12:15], v[144:147], v[208:211], v[12:15]
	v_mfma_f32_16x16x32_bf16 v[8:11], v[152:155], v[208:211], v[8:11]
	v_mfma_f32_16x16x32_bf16 v[60:63], v[148:151], v[186:189], v[60:63]
	v_mfma_f32_16x16x32_bf16 v[56:59], v[162:165], v[186:189], v[56:59]
	v_mfma_f32_16x16x32_bf16 v[44:47], v[148:151], v[196:199], v[44:47]
	v_mfma_f32_16x16x32_bf16 v[40:43], v[162:165], v[196:199], v[40:43]
	v_mfma_f32_16x16x32_bf16 v[28:31], v[148:151], v[204:207], v[28:31]
	v_mfma_f32_16x16x32_bf16 v[24:27], v[162:165], v[204:207], v[24:27]
	v_mfma_f32_16x16x32_bf16 v[12:15], v[148:151], v[212:215], v[12:15]
	v_mfma_f32_16x16x32_bf16 v[8:11], v[162:165], v[212:215], v[8:11]
	s_setprio 0
	s_setprio 1
	v_mfma_f32_16x16x32_bf16 v[52:55], v[166:169], v[182:185], v[52:55]
	v_mfma_f32_16x16x32_bf16 v[48:51], v[174:177], v[182:185], v[48:51]
	v_mfma_f32_16x16x32_bf16 v[36:39], v[166:169], v[190:193], v[36:39]
	v_mfma_f32_16x16x32_bf16 v[32:35], v[174:177], v[190:193], v[32:35]
	v_mfma_f32_16x16x32_bf16 v[20:23], v[166:169], v[200:203], v[20:23]
	v_mfma_f32_16x16x32_bf16 v[16:19], v[174:177], v[200:203], v[16:19]
	v_mfma_f32_16x16x32_bf16 v[4:7], v[166:169], v[208:211], v[4:7]
	v_mfma_f32_16x16x32_bf16 v[0:3], v[174:177], v[208:211], v[0:3]
	v_mfma_f32_16x16x32_bf16 v[52:55], v[170:173], v[186:189], v[52:55]
	v_mfma_f32_16x16x32_bf16 v[48:51], v[178:181], v[186:189], v[48:51]
	v_mfma_f32_16x16x32_bf16 v[36:39], v[170:173], v[196:199], v[36:39]
	v_mfma_f32_16x16x32_bf16 v[32:35], v[178:181], v[196:199], v[32:35]
	v_mfma_f32_16x16x32_bf16 v[20:23], v[170:173], v[204:207], v[20:23]
	v_mfma_f32_16x16x32_bf16 v[16:19], v[178:181], v[204:207], v[16:19]
	v_mfma_f32_16x16x32_bf16 v[4:7], v[170:173], v[212:215], v[4:7]
	v_mfma_f32_16x16x32_bf16 v[0:3], v[178:181], v[212:215], v[0:3]
	s_setprio 0
	s_barrier
	s_add_i32 s37, 0, 0x18000
	s_add_i32 s39, 0, 0x1c000
	v_add_u32_e32 v162, s37, v157
	v_add_u32_e32 v178, s39, v157
	ds_read_b128 v[144:147], v162
	ds_read_b128 v[148:151], v162 offset:1024
	ds_read_b128 v[152:155], v162 offset:2048
	ds_read_b128 v[162:165], v162 offset:3072
	ds_read_b128 v[166:169], v178
	ds_read_b128 v[170:173], v178 offset:1024
	ds_read_b128 v[174:177], v178 offset:2048
	ds_read_b128 v[178:181], v178 offset:3072
	s_add_u32 s50, s50, 0x20000
	s_addc_u32 s51, s51, 0
	v_lshl_add_u64 v[224:225], s[50:51], 0, v[128:129]
	ds_read_b128 v[182:185], v161 offset:32768
	ds_read_b128 v[186:189], v161 offset:33792
	ds_read_b128 v[190:193], v161 offset:34816
	ds_read_b128 v[196:199], v161 offset:35840
	ds_read_b128 v[200:203], v161 offset:36864
	ds_read_b128 v[204:207], v161 offset:37888
	ds_read_b128 v[208:211], v161 offset:38912
	ds_read_b128 v[212:215], v161 offset:39936
	s_mov_b32 m0, s60
	s_nop 0
	global_load_lds_dwordx4 v[220:221], off
	s_mov_b32 m0, s61
	s_nop 0
	global_load_lds_dwordx4 v[222:223], off
	s_mov_b32 m0, s62
	s_nop 0
	global_load_lds_dwordx4 v[224:225], off
	v_lshl_add_u64 v[224:225], s[50:51], 0, v[132:133]
	s_mov_b32 m0, s63
	s_nop 0
	global_load_lds_dwordx4 v[224:225], off
	s_waitcnt vmcnt(8)
	s_waitcnt lgkmcnt(0)
	s_barrier
	s_setprio 1
	s_waitcnt lgkmcnt(0)
	v_mfma_f32_16x16x32_bf16 v[124:127], v[144:147], v[182:185], v[124:127]
	v_mfma_f32_16x16x32_bf16 v[120:123], v[152:155], v[182:185], v[120:123]
	v_mfma_f32_16x16x32_bf16 v[108:111], v[144:147], v[190:193], v[108:111]
	v_mfma_f32_16x16x32_bf16 v[104:107], v[152:155], v[190:193], v[104:107]
	v_mfma_f32_16x16x32_bf16 v[92:95], v[144:147], v[200:203], v[92:95]
	v_mfma_f32_16x16x32_bf16 v[88:91], v[152:155], v[200:203], v[88:91]
	v_mfma_f32_16x16x32_bf16 v[76:79], v[144:147], v[208:211], v[76:79]
	v_mfma_f32_16x16x32_bf16 v[72:75], v[152:155], v[208:211], v[72:75]
	v_mfma_f32_16x16x32_bf16 v[124:127], v[148:151], v[186:189], v[124:127]
	v_mfma_f32_16x16x32_bf16 v[120:123], v[162:165], v[186:189], v[120:123]
	v_mfma_f32_16x16x32_bf16 v[108:111], v[148:151], v[196:199], v[108:111]
	v_mfma_f32_16x16x32_bf16 v[104:107], v[162:165], v[196:199], v[104:107]
	v_mfma_f32_16x16x32_bf16 v[92:95], v[148:151], v[204:207], v[92:95]
	v_mfma_f32_16x16x32_bf16 v[88:91], v[162:165], v[204:207], v[88:91]
	v_mfma_f32_16x16x32_bf16 v[76:79], v[148:151], v[212:215], v[76:79]
	v_mfma_f32_16x16x32_bf16 v[72:75], v[162:165], v[212:215], v[72:75]
	s_setprio 0
	s_setprio 1
	v_mfma_f32_16x16x32_bf16 v[116:119], v[166:169], v[182:185], v[116:119]
	v_mfma_f32_16x16x32_bf16 v[112:115], v[174:177], v[182:185], v[112:115]
	v_mfma_f32_16x16x32_bf16 v[100:103], v[166:169], v[190:193], v[100:103]
	v_mfma_f32_16x16x32_bf16 v[96:99], v[174:177], v[190:193], v[96:99]
	v_mfma_f32_16x16x32_bf16 v[84:87], v[166:169], v[200:203], v[84:87]
	v_mfma_f32_16x16x32_bf16 v[80:83], v[174:177], v[200:203], v[80:83]
	v_mfma_f32_16x16x32_bf16 v[68:71], v[166:169], v[208:211], v[68:71]
	v_mfma_f32_16x16x32_bf16 v[64:67], v[174:177], v[208:211], v[64:67]
	v_mfma_f32_16x16x32_bf16 v[116:119], v[170:173], v[186:189], v[116:119]
	v_mfma_f32_16x16x32_bf16 v[112:115], v[178:181], v[186:189], v[112:115]
	v_mfma_f32_16x16x32_bf16 v[100:103], v[170:173], v[196:199], v[100:103]
	v_mfma_f32_16x16x32_bf16 v[96:99], v[178:181], v[196:199], v[96:99]
	v_mfma_f32_16x16x32_bf16 v[84:87], v[170:173], v[204:207], v[84:87]
	v_mfma_f32_16x16x32_bf16 v[80:83], v[178:181], v[204:207], v[80:83]
	v_mfma_f32_16x16x32_bf16 v[68:71], v[170:173], v[212:215], v[68:71]
	v_mfma_f32_16x16x32_bf16 v[64:67], v[178:181], v[212:215], v[64:67]
	s_setprio 0
	s_barrier
	s_add_i32 s37, s37, s57
	v_lshl_add_u64 v[216:217], v[216:217], 0, s[22:23]
	s_mov_b32 m0, s37
	ds_read_b128 v[182:185], v161 offset:49152
	ds_read_b128 v[186:189], v161 offset:50176
	ds_read_b128 v[190:193], v161 offset:51200
	ds_read_b128 v[196:199], v161 offset:52224
	ds_read_b128 v[200:203], v161 offset:53248
	ds_read_b128 v[204:207], v161 offset:54272
	ds_read_b128 v[208:211], v161 offset:55296
	ds_read_b128 v[212:215], v161 offset:56320
	global_load_lds_dwordx4 v[216:217], off
	s_add_i32 m0, s37, 0x2000
	s_add_u32 s48, s48, 0x20080
	v_lshl_add_u64 v[216:217], v[218:219], 0, s[22:23]
	s_addc_u32 s49, s49, 0
	s_add_i32 s37, s39, s57
	global_load_lds_dwordx4 v[216:217], off
	v_lshl_add_u64 v[216:217], s[48:49], 0, v[130:131]
	s_mov_b32 m0, s37
	s_nop 0
	global_load_lds_dwordx4 v[216:217], off
	v_lshl_add_u64 v[216:217], s[48:49], 0, v[134:135]
	s_add_i32 m0, s37, 0x2000
	s_nop 0
	global_load_lds_dwordx4 v[216:217], off
	s_mov_b32 s99, 1
	s_waitcnt vmcnt(6)
	s_waitcnt lgkmcnt(0)
	s_barrier
	s_setprio 1
	s_waitcnt lgkmcnt(0)
	v_mfma_f32_16x16x32_bf16 v[60:63], v[144:147], v[182:185], v[60:63]
	v_mfma_f32_16x16x32_bf16 v[56:59], v[152:155], v[182:185], v[56:59]
	v_mfma_f32_16x16x32_bf16 v[44:47], v[144:147], v[190:193], v[44:47]
	v_mfma_f32_16x16x32_bf16 v[40:43], v[152:155], v[190:193], v[40:43]
	v_mfma_f32_16x16x32_bf16 v[28:31], v[144:147], v[200:203], v[28:31]
	v_mfma_f32_16x16x32_bf16 v[24:27], v[152:155], v[200:203], v[24:27]
	v_mfma_f32_16x16x32_bf16 v[12:15], v[144:147], v[208:211], v[12:15]
	v_mfma_f32_16x16x32_bf16 v[8:11], v[152:155], v[208:211], v[8:11]
	v_mfma_f32_16x16x32_bf16 v[60:63], v[148:151], v[186:189], v[60:63]
	v_mfma_f32_16x16x32_bf16 v[56:59], v[162:165], v[186:189], v[56:59]
	v_mfma_f32_16x16x32_bf16 v[44:47], v[148:151], v[196:199], v[44:47]
	v_mfma_f32_16x16x32_bf16 v[40:43], v[162:165], v[196:199], v[40:43]
	v_mfma_f32_16x16x32_bf16 v[28:31], v[148:151], v[204:207], v[28:31]
	v_mfma_f32_16x16x32_bf16 v[24:27], v[162:165], v[204:207], v[24:27]
	v_mfma_f32_16x16x32_bf16 v[12:15], v[148:151], v[212:215], v[12:15]
	v_mfma_f32_16x16x32_bf16 v[8:11], v[162:165], v[212:215], v[8:11]
	s_setprio 0
	s_setprio 1
	v_mfma_f32_16x16x32_bf16 v[52:55], v[166:169], v[182:185], v[52:55]
	v_mfma_f32_16x16x32_bf16 v[48:51], v[174:177], v[182:185], v[48:51]
	v_mfma_f32_16x16x32_bf16 v[36:39], v[166:169], v[190:193], v[36:39]
	v_mfma_f32_16x16x32_bf16 v[32:35], v[174:177], v[190:193], v[32:35]
	v_mfma_f32_16x16x32_bf16 v[20:23], v[166:169], v[200:203], v[20:23]
	v_mfma_f32_16x16x32_bf16 v[16:19], v[174:177], v[200:203], v[16:19]
	v_mfma_f32_16x16x32_bf16 v[4:7], v[166:169], v[208:211], v[4:7]
	v_mfma_f32_16x16x32_bf16 v[0:3], v[174:177], v[208:211], v[0:3]
	v_mfma_f32_16x16x32_bf16 v[52:55], v[170:173], v[186:189], v[52:55]
	v_mfma_f32_16x16x32_bf16 v[48:51], v[178:181], v[186:189], v[48:51]
	v_mfma_f32_16x16x32_bf16 v[36:39], v[170:173], v[196:199], v[36:39]
	v_mfma_f32_16x16x32_bf16 v[32:35], v[178:181], v[196:199], v[32:35]
	v_mfma_f32_16x16x32_bf16 v[20:23], v[170:173], v[204:207], v[20:23]
	v_mfma_f32_16x16x32_bf16 v[16:19], v[178:181], v[204:207], v[16:19]
	v_mfma_f32_16x16x32_bf16 v[4:7], v[170:173], v[212:215], v[4:7]
	v_mfma_f32_16x16x32_bf16 v[0:3], v[178:181], v[212:215], v[0:3]
	s_setprio 0
	s_barrier
	s_add_i32 s35, s35, 2
	s_add_u32 s42, s42, 0x100
	s_addc_u32 s43, s43, 0
	s_add_u32 s11, s11, 0x100
	s_addc_u32 s13, s13, 0
	s_cmp_gt_u32 s35, 5
	s_cbranch_scc0 .LBB0_3061
	v_lshl_add_u64 v[220:221], v[220:221], 0, s[22:23]
	s_mov_b32 m0, s70
	s_nop 0
	global_load_lds_dwordx4 v[220:221], off
	v_lshl_add_u64 v[222:223], v[222:223], 0, s[22:23]
	s_mov_b32 m0, s71
	s_nop 0
	global_load_lds_dwordx4 v[222:223], off
	s_and_b64 vcc, exec, s[24:25]
	s_cbranch_vccz .LBB0_3064
	s_barrier

.LBB0_3234:
	s_ashr_i32 s27, s26, 31
	s_lshl_b64 s[28:29], s[26:27], 19
	s_add_u32 s28, s43, s28
	s_addc_u32 s29, s44, s29
	s_and_b64 s[30:31], s[10:11], exec
	s_cselect_b32 s27, s29, s37
	s_cselect_b32 s35, s28, s36
	s_ashr_i32 s25, s24, 31
	s_lshl_b64 s[30:31], s[24:25], 19
	s_add_u32 s30, s45, s30
	s_addc_u32 s31, s48, s31
	s_and_b64 s[40:41], s[10:11], exec
	s_cselect_b32 s25, s31, s39
	s_cselect_b32 s61, s30, s38
	s_add_u32 s36, s36, 0x40080
	s_addc_u32 s37, s37, 0
	s_add_u32 s62, s38, 0x100
	v_mov_b32_e32 v0, 0
	s_addc_u32 s63, s39, 0
	s_mov_b32 s70, -2
	s_waitcnt lgkmcnt(0)
	v_mov_b32_e32 v1, v0
	v_mov_b32_e32 v2, v0
	v_mov_b32_e32 v3, v0
	v_mov_b32_e32 v4, v0
	v_mov_b32_e32 v5, v0
	v_mov_b32_e32 v6, v0
	v_mov_b32_e32 v7, v0
	v_mov_b32_e32 v16, v0
	v_mov_b32_e32 v17, v0
	v_mov_b32_e32 v18, v0
	v_mov_b32_e32 v19, v0
	v_mov_b32_e32 v20, v0
	v_mov_b32_e32 v21, v0
	v_mov_b32_e32 v22, v0
	v_mov_b32_e32 v23, v0
	v_mov_b32_e32 v32, v0
	v_mov_b32_e32 v33, v0
	v_mov_b32_e32 v34, v0
	v_mov_b32_e32 v35, v0
	v_mov_b32_e32 v36, v0
	v_mov_b32_e32 v37, v0
	v_mov_b32_e32 v38, v0
	v_mov_b32_e32 v39, v0
	v_mov_b32_e32 v48, v0
	v_mov_b32_e32 v49, v0
	v_mov_b32_e32 v50, v0
	v_mov_b32_e32 v51, v0
	v_mov_b32_e32 v52, v0
	v_mov_b32_e32 v53, v0
	v_mov_b32_e32 v54, v0
	v_mov_b32_e32 v55, v0
	v_mov_b32_e32 v8, v0
	v_mov_b32_e32 v9, v0
	v_mov_b32_e32 v10, v0
	v_mov_b32_e32 v11, v0
	v_mov_b32_e32 v12, v0
	v_mov_b32_e32 v13, v0
	v_mov_b32_e32 v14, v0
	v_mov_b32_e32 v15, v0
	v_mov_b32_e32 v24, v0
	v_mov_b32_e32 v25, v0
	v_mov_b32_e32 v26, v0
	v_mov_b32_e32 v27, v0
	v_mov_b32_e32 v28, v0
	v_mov_b32_e32 v29, v0
	v_mov_b32_e32 v30, v0
	v_mov_b32_e32 v31, v0
	v_mov_b32_e32 v40, v0
	v_mov_b32_e32 v41, v0
	v_mov_b32_e32 v42, v0
	v_mov_b32_e32 v43, v0
	v_mov_b32_e32 v44, v0
	v_mov_b32_e32 v45, v0
	v_mov_b32_e32 v46, v0
	v_mov_b32_e32 v47, v0
	v_mov_b32_e32 v56, v0
	v_mov_b32_e32 v57, v0
	v_mov_b32_e32 v58, v0
	v_mov_b32_e32 v59, v0
	v_mov_b32_e32 v60, v0
	v_mov_b32_e32 v61, v0
	v_mov_b32_e32 v62, v0
	v_mov_b32_e32 v63, v0
	v_mov_b32_e32 v64, v0
	v_mov_b32_e32 v65, v0
	v_mov_b32_e32 v66, v0
	v_mov_b32_e32 v67, v0
	v_mov_b32_e32 v68, v0
	v_mov_b32_e32 v69, v0
	v_mov_b32_e32 v70, v0
	v_mov_b32_e32 v71, v0
	v_mov_b32_e32 v80, v0
	v_mov_b32_e32 v81, v0
	v_mov_b32_e32 v82, v0
	v_mov_b32_e32 v83, v0
	v_mov_b32_e32 v84, v0
	v_mov_b32_e32 v85, v0
	v_mov_b32_e32 v86, v0
	v_mov_b32_e32 v87, v0
	v_mov_b32_e32 v96, v0
	v_mov_b32_e32 v97, v0
	v_mov_b32_e32 v98, v0
	v_mov_b32_e32 v99, v0
	v_mov_b32_e32 v100, v0
	v_mov_b32_e32 v101, v0
	v_mov_b32_e32 v102, v0
	v_mov_b32_e32 v103, v0
	v_mov_b32_e32 v112, v0
	v_mov_b32_e32 v113, v0
	v_mov_b32_e32 v114, v0
	v_mov_b32_e32 v115, v0
	v_mov_b32_e32 v116, v0
	v_mov_b32_e32 v117, v0
	v_mov_b32_e32 v118, v0
	v_mov_b32_e32 v119, v0
	v_mov_b32_e32 v72, v0
	v_mov_b32_e32 v73, v0
	v_mov_b32_e32 v74, v0
	v_mov_b32_e32 v75, v0
	v_mov_b32_e32 v76, v0
	v_mov_b32_e32 v77, v0
	v_mov_b32_e32 v78, v0
	v_mov_b32_e32 v79, v0
	v_mov_b32_e32 v88, v0
	v_mov_b32_e32 v89, v0
	v_mov_b32_e32 v90, v0
	v_mov_b32_e32 v91, v0
	v_mov_b32_e32 v92, v0
	v_mov_b32_e32 v93, v0
	v_mov_b32_e32 v94, v0
	v_mov_b32_e32 v95, v0
	v_mov_b32_e32 v104, v0
	v_mov_b32_e32 v105, v0
	v_mov_b32_e32 v106, v0
	v_mov_b32_e32 v107, v0
	v_mov_b32_e32 v108, v0
	v_mov_b32_e32 v109, v0
	v_mov_b32_e32 v110, v0
	v_mov_b32_e32 v111, v0
	v_mov_b32_e32 v120, v0
	v_mov_b32_e32 v121, v0
	v_mov_b32_e32 v122, v0
	v_mov_b32_e32 v123, v0
	v_mov_b32_e32 v124, v0
	v_mov_b32_e32 v125, v0
	v_mov_b32_e32 v126, v0
	v_mov_b32_e32 v127, v0
	s_mov_b32 s99, 0
.LBB0_3235:
	ds_read_b128 v[144:147], v151
	ds_read_b128 v[156:159], v151 offset:1024
	ds_read_b128 v[160:163], v151 offset:2048
	ds_read_b128 v[164:167], v151 offset:3072
	ds_read_b128 v[168:171], v152
	ds_read_b128 v[172:175], v152 offset:1024
	ds_read_b128 v[176:179], v152 offset:2048
	ds_read_b128 v[180:183], v152 offset:3072
	s_add_u32 s38, s36, 0xfffc0080
	s_addc_u32 s39, s37, -1
	s_cmp_eq_u32 s70, 12
	s_cselect_b32 s41, s27, s39
	s_cselect_b32 s40, s35, s38
	s_cselect_b32 s39, s25, s63
	s_cselect_b32 s38, s61, s62
	v_lshl_add_u64 v[192:193], s[36:37], 0, v[136:137]
	ds_read_b128 v[184:187], v153
	ds_read_b128 v[188:191], v153 offset:1024
	ds_read_b128 v[196:199], v153 offset:2048
	ds_read_b128 v[200:203], v153 offset:3072
	ds_read_b128 v[204:207], v153 offset:4096
	ds_read_b128 v[208:211], v153 offset:5120
	ds_read_b128 v[212:215], v153 offset:6144
	ds_read_b128 v[216:219], v153 offset:7168
	s_cmp_eq_u32 s99, 0
	s_cbranch_scc1 .Lkb_first_25
	v_lshl_add_u64 v[222:223], v[222:223], 0, s[20:21]
	s_mov_b32 m0, s55
	s_nop 0
	global_load_lds_dwordx4 v[222:223], off
	v_lshl_add_u64 v[224:225], v[224:225], 0, s[20:21]
	s_mov_b32 m0, s56
	s_nop 0
	global_load_lds_dwordx4 v[224:225], off
	s_branch .Lkb_join_25
.Lkb_first_25:
	s_add_i32 m0, s50, 0xc000
	s_nop 0
	global_load_lds_dwordx4 v[192:193], off
	global_load_lds_dwordx4 v[192:193], off
.Lkb_join_25:
	s_add_i32 m0, s50, 0xc000
	s_nop 0
	global_load_lds_dwordx4 v[192:193], off
	v_lshl_add_u64 v[192:193], s[36:37], 0, v[138:139]
	s_add_i32 m0, s50, 0xe000
	s_nop 0
	global_load_lds_dwordx4 v[192:193], off
	s_waitcnt vmcnt(8)
	s_waitcnt lgkmcnt(0)
	s_barrier
	s_setprio 1
	s_waitcnt lgkmcnt(0)
	v_mfma_f32_16x16x32_bf16 v[124:127], v[144:147], v[184:187], v[124:127]
	v_mfma_f32_16x16x32_bf16 v[120:123], v[160:163], v[184:187], v[120:123]
	v_mfma_f32_16x16x32_bf16 v[108:111], v[144:147], v[196:199], v[108:111]
	v_mfma_f32_16x16x32_bf16 v[104:107], v[160:163], v[196:199], v[104:107]
	v_mfma_f32_16x16x32_bf16 v[92:95], v[144:147], v[204:207], v[92:95]
	v_mfma_f32_16x16x32_bf16 v[88:91], v[160:163], v[204:207], v[88:91]
	v_mfma_f32_16x16x32_bf16 v[76:79], v[144:147], v[212:215], v[76:79]
	v_mfma_f32_16x16x32_bf16 v[72:75], v[160:163], v[212:215], v[72:75]
	v_mfma_f32_16x16x32_bf16 v[124:127], v[156:159], v[188:191], v[124:127]
	v_mfma_f32_16x16x32_bf16 v[120:123], v[164:167], v[188:191], v[120:123]
	v_mfma_f32_16x16x32_bf16 v[108:111], v[156:159], v[200:203], v[108:111]
	v_mfma_f32_16x16x32_bf16 v[104:107], v[164:167], v[200:203], v[104:107]
	v_mfma_f32_16x16x32_bf16 v[92:95], v[156:159], v[208:211], v[92:95]
	v_mfma_f32_16x16x32_bf16 v[88:91], v[164:167], v[208:211], v[88:91]
	v_mfma_f32_16x16x32_bf16 v[76:79], v[156:159], v[216:219], v[76:79]
	v_mfma_f32_16x16x32_bf16 v[72:75], v[164:167], v[216:219], v[72:75]
	s_setprio 0
	s_setprio 1
	v_mfma_f32_16x16x32_bf16 v[116:119], v[168:171], v[184:187], v[116:119]
	v_mfma_f32_16x16x32_bf16 v[112:115], v[176:179], v[184:187], v[112:115]
	v_mfma_f32_16x16x32_bf16 v[100:103], v[168:171], v[196:199], v[100:103]
	v_mfma_f32_16x16x32_bf16 v[96:99], v[176:179], v[196:199], v[96:99]
	v_mfma_f32_16x16x32_bf16 v[84:87], v[168:171], v[204:207], v[84:87]
	v_mfma_f32_16x16x32_bf16 v[80:83], v[176:179], v[204:207], v[80:83]
	v_mfma_f32_16x16x32_bf16 v[68:71], v[168:171], v[212:215], v[68:71]
	v_mfma_f32_16x16x32_bf16 v[64:67], v[176:179], v[212:215], v[64:67]
	v_mfma_f32_16x16x32_bf16 v[116:119], v[172:175], v[188:191], v[116:119]
	v_mfma_f32_16x16x32_bf16 v[112:115], v[180:183], v[188:191], v[112:115]
	v_mfma_f32_16x16x32_bf16 v[100:103], v[172:175], v[200:203], v[100:103]
	v_mfma_f32_16x16x32_bf16 v[96:99], v[180:183], v[200:203], v[96:99]
	v_mfma_f32_16x16x32_bf16 v[84:87], v[172:175], v[208:211], v[84:87]
	v_mfma_f32_16x16x32_bf16 v[80:83], v[180:183], v[208:211], v[80:83]
	v_mfma_f32_16x16x32_bf16 v[68:71], v[172:175], v[216:219], v[68:71]
	v_mfma_f32_16x16x32_bf16 v[64:67], v[180:183], v[216:219], v[64:67]
	s_setprio 0
	s_barrier
	s_add_i32 s71, s58, s49
	v_lshl_add_u64 v[192:193], s[38:39], 0, v[130:131]
	s_mov_b32 m0, s71
	ds_read_b128 v[184:187], v153 offset:16384
	ds_read_b128 v[188:191], v153 offset:17408
	ds_read_b128 v[196:199], v153 offset:18432
	ds_read_b128 v[200:203], v153 offset:19456
	ds_read_b128 v[204:207], v153 offset:20480
	ds_read_b128 v[208:211], v153 offset:21504
	ds_read_b128 v[212:215], v153 offset:22528
	ds_read_b128 v[216:219], v153 offset:23552
	global_load_lds_dwordx4 v[192:193], off
	s_add_i32 m0, s71, 0x2000
	s_add_u32 s72, s38, 0x40000
	v_lshl_add_u64 v[220:221], s[38:39], 0, v[134:135]
	s_addc_u32 s73, s39, 0
	s_add_i32 s71, s59, s49
	global_load_lds_dwordx4 v[220:221], off
	v_lshl_add_u64 v[222:223], s[72:73], 0, v[130:131]
	s_mov_b32 m0, s71
	v_lshl_add_u64 v[224:225], s[40:41], 0, v[132:133]
	global_load_lds_dwordx4 v[222:223], off
	v_lshl_add_u64 v[222:223], s[72:73], 0, v[134:135]
	s_add_i32 m0, s71, 0x2000
	s_nop 0
	global_load_lds_dwordx4 v[222:223], off
	v_lshl_add_u64 v[222:223], s[40:41], 0, v[128:129]
	s_waitcnt vmcnt(6)
	s_waitcnt lgkmcnt(0)
	s_barrier
	s_setprio 1
	s_waitcnt lgkmcnt(0)
	v_mfma_f32_16x16x32_bf16 v[60:63], v[144:147], v[184:187], v[60:63]
	v_mfma_f32_16x16x32_bf16 v[56:59], v[160:163], v[184:187], v[56:59]
	v_mfma_f32_16x16x32_bf16 v[44:47], v[144:147], v[196:199], v[44:47]
	v_mfma_f32_16x16x32_bf16 v[40:43], v[160:163], v[196:199], v[40:43]
	v_mfma_f32_16x16x32_bf16 v[28:31], v[144:147], v[204:207], v[28:31]
	v_mfma_f32_16x16x32_bf16 v[24:27], v[160:163], v[204:207], v[24:27]
	v_mfma_f32_16x16x32_bf16 v[12:15], v[144:147], v[212:215], v[12:15]
	v_mfma_f32_16x16x32_bf16 v[8:11], v[160:163], v[212:215], v[8:11]
	v_mfma_f32_16x16x32_bf16 v[60:63], v[156:159], v[188:191], v[60:63]
	v_mfma_f32_16x16x32_bf16 v[56:59], v[164:167], v[188:191], v[56:59]
	v_mfma_f32_16x16x32_bf16 v[44:47], v[156:159], v[200:203], v[44:47]
	v_mfma_f32_16x16x32_bf16 v[40:43], v[164:167], v[200:203], v[40:43]
	v_mfma_f32_16x16x32_bf16 v[28:31], v[156:159], v[208:211], v[28:31]
	v_mfma_f32_16x16x32_bf16 v[24:27], v[164:167], v[208:211], v[24:27]
	v_mfma_f32_16x16x32_bf16 v[12:15], v[156:159], v[216:219], v[12:15]
	v_mfma_f32_16x16x32_bf16 v[8:11], v[164:167], v[216:219], v[8:11]
	s_setprio 0
	s_setprio 1
	v_mfma_f32_16x16x32_bf16 v[52:55], v[168:171], v[184:187], v[52:55]
	v_mfma_f32_16x16x32_bf16 v[48:51], v[176:179], v[184:187], v[48:51]
	v_mfma_f32_16x16x32_bf16 v[36:39], v[168:171], v[196:199], v[36:39]
	v_mfma_f32_16x16x32_bf16 v[32:35], v[176:179], v[196:199], v[32:35]
	v_mfma_f32_16x16x32_bf16 v[20:23], v[168:171], v[204:207], v[20:23]
	v_mfma_f32_16x16x32_bf16 v[16:19], v[176:179], v[204:207], v[16:19]
	v_mfma_f32_16x16x32_bf16 v[4:7], v[168:171], v[212:215], v[4:7]
	v_mfma_f32_16x16x32_bf16 v[0:3], v[176:179], v[212:215], v[0:3]
	v_mfma_f32_16x16x32_bf16 v[52:55], v[172:175], v[188:191], v[52:55]
	v_mfma_f32_16x16x32_bf16 v[48:51], v[180:183], v[188:191], v[48:51]
	v_mfma_f32_16x16x32_bf16 v[36:39], v[172:175], v[200:203], v[36:39]
	v_mfma_f32_16x16x32_bf16 v[32:35], v[180:183], v[200:203], v[32:35]
	v_mfma_f32_16x16x32_bf16 v[20:23], v[172:175], v[208:211], v[20:23]
	v_mfma_f32_16x16x32_bf16 v[16:19], v[180:183], v[208:211], v[16:19]
	v_mfma_f32_16x16x32_bf16 v[4:7], v[172:175], v[216:219], v[4:7]
	v_mfma_f32_16x16x32_bf16 v[0:3], v[180:183], v[216:219], v[0:3]
	s_setprio 0
	s_barrier
	s_add_i32 s71, 0, 0x18000
	v_add_u32_e32 v155, s71, v149
	s_add_i32 s72, 0, 0x1c000
	ds_read_b128 v[144:147], v155
	ds_read_b128 v[156:159], v155 offset:1024
	ds_read_b128 v[160:163], v155 offset:2048
	ds_read_b128 v[164:167], v155 offset:3072
	v_add_u32_e32 v155, s72, v149
	ds_read_b128 v[168:171], v155
	ds_read_b128 v[172:175], v155 offset:1024
	ds_read_b128 v[176:179], v155 offset:2048
	ds_read_b128 v[180:183], v155 offset:3072
	s_add_u32 s40, s40, 0x40000
	s_addc_u32 s41, s41, 0
	v_lshl_add_u64 v[226:227], s[40:41], 0, v[128:129]
	ds_read_b128 v[184:187], v153 offset:32768
	ds_read_b128 v[188:191], v153 offset:33792
	ds_read_b128 v[196:199], v153 offset:34816
	ds_read_b128 v[200:203], v153 offset:35840
	ds_read_b128 v[204:207], v153 offset:36864
	ds_read_b128 v[208:211], v153 offset:37888
	ds_read_b128 v[212:215], v153 offset:38912
	ds_read_b128 v[216:219], v153 offset:39936
	s_mov_b32 m0, s50
	s_nop 0
	global_load_lds_dwordx4 v[222:223], off
	s_mov_b32 m0, s51
	s_nop 0
	global_load_lds_dwordx4 v[224:225], off
	s_mov_b32 m0, s52
	s_nop 0
	global_load_lds_dwordx4 v[226:227], off
	v_lshl_add_u64 v[226:227], s[40:41], 0, v[132:133]
	s_mov_b32 m0, s53
	s_nop 0
	global_load_lds_dwordx4 v[226:227], off
	s_waitcnt vmcnt(8)
	s_waitcnt lgkmcnt(0)
	s_barrier
	s_setprio 1
	s_waitcnt lgkmcnt(0)
	v_mfma_f32_16x16x32_bf16 v[124:127], v[144:147], v[184:187], v[124:127]
	v_mfma_f32_16x16x32_bf16 v[120:123], v[160:163], v[184:187], v[120:123]
	v_mfma_f32_16x16x32_bf16 v[108:111], v[144:147], v[196:199], v[108:111]
	v_mfma_f32_16x16x32_bf16 v[104:107], v[160:163], v[196:199], v[104:107]
	v_mfma_f32_16x16x32_bf16 v[92:95], v[144:147], v[204:207], v[92:95]
	v_mfma_f32_16x16x32_bf16 v[88:91], v[160:163], v[204:207], v[88:91]
	v_mfma_f32_16x16x32_bf16 v[76:79], v[144:147], v[212:215], v[76:79]
	v_mfma_f32_16x16x32_bf16 v[72:75], v[160:163], v[212:215], v[72:75]
	v_mfma_f32_16x16x32_bf16 v[124:127], v[156:159], v[188:191], v[124:127]
	v_mfma_f32_16x16x32_bf16 v[120:123], v[164:167], v[188:191], v[120:123]
	v_mfma_f32_16x16x32_bf16 v[108:111], v[156:159], v[200:203], v[108:111]
	v_mfma_f32_16x16x32_bf16 v[104:107], v[164:167], v[200:203], v[104:107]
	v_mfma_f32_16x16x32_bf16 v[92:95], v[156:159], v[208:211], v[92:95]
	v_mfma_f32_16x16x32_bf16 v[88:91], v[164:167], v[208:211], v[88:91]
	v_mfma_f32_16x16x32_bf16 v[76:79], v[156:159], v[216:219], v[76:79]
	v_mfma_f32_16x16x32_bf16 v[72:75], v[164:167], v[216:219], v[72:75]
	s_setprio 0
	s_setprio 1
	v_mfma_f32_16x16x32_bf16 v[116:119], v[168:171], v[184:187], v[116:119]
	v_mfma_f32_16x16x32_bf16 v[112:115], v[176:179], v[184:187], v[112:115]
	v_mfma_f32_16x16x32_bf16 v[100:103], v[168:171], v[196:199], v[100:103]
	v_mfma_f32_16x16x32_bf16 v[96:99], v[176:179], v[196:199], v[96:99]
	v_mfma_f32_16x16x32_bf16 v[84:87], v[168:171], v[204:207], v[84:87]
	v_mfma_f32_16x16x32_bf16 v[80:83], v[176:179], v[204:207], v[80:83]
	v_mfma_f32_16x16x32_bf16 v[68:71], v[168:171], v[212:215], v[68:71]
	v_mfma_f32_16x16x32_bf16 v[64:67], v[176:179], v[212:215], v[64:67]
	v_mfma_f32_16x16x32_bf16 v[116:119], v[172:175], v[188:191], v[116:119]
	v_mfma_f32_16x16x32_bf16 v[112:115], v[180:183], v[188:191], v[112:115]
	v_mfma_f32_16x16x32_bf16 v[100:103], v[172:175], v[200:203], v[100:103]
	v_mfma_f32_16x16x32_bf16 v[96:99], v[180:183], v[200:203], v[96:99]
	v_mfma_f32_16x16x32_bf16 v[84:87], v[172:175], v[208:211], v[84:87]
	v_mfma_f32_16x16x32_bf16 v[80:83], v[180:183], v[208:211], v[80:83]
	v_mfma_f32_16x16x32_bf16 v[68:71], v[172:175], v[216:219], v[68:71]
	v_mfma_f32_16x16x32_bf16 v[64:67], v[180:183], v[216:219], v[64:67]
	s_setprio 0
	s_barrier
	s_add_i32 s40, s71, s49
	v_lshl_add_u64 v[192:193], v[192:193], 0, s[20:21]
	s_mov_b32 m0, s40
	ds_read_b128 v[184:187], v153 offset:49152
	ds_read_b128 v[188:191], v153 offset:50176
	ds_read_b128 v[196:199], v153 offset:51200
	ds_read_b128 v[200:203], v153 offset:52224
	ds_read_b128 v[204:207], v153 offset:53248
	ds_read_b128 v[208:211], v153 offset:54272
	ds_read_b128 v[212:215], v153 offset:55296
	ds_read_b128 v[216:219], v153 offset:56320
	global_load_lds_dwordx4 v[192:193], off
	s_add_i32 m0, s40, 0x2000
	s_add_u32 s38, s38, 0x40080
	v_lshl_add_u64 v[192:193], v[220:221], 0, s[20:21]
	s_addc_u32 s39, s39, 0
	s_add_i32 s40, s72, s49
	global_load_lds_dwordx4 v[192:193], off
	v_lshl_add_u64 v[192:193], s[38:39], 0, v[130:131]
	s_mov_b32 m0, s40
	s_nop 0
	global_load_lds_dwordx4 v[192:193], off
	v_lshl_add_u64 v[192:193], s[38:39], 0, v[134:135]
	s_add_i32 m0, s40, 0x2000
	s_nop 0
	global_load_lds_dwordx4 v[192:193], off
	s_mov_b32 s99, 1
	s_waitcnt vmcnt(6)
	s_waitcnt lgkmcnt(0)
	s_barrier
	s_setprio 1
	s_waitcnt lgkmcnt(0)
	v_mfma_f32_16x16x32_bf16 v[60:63], v[144:147], v[184:187], v[60:63]
	v_mfma_f32_16x16x32_bf16 v[56:59], v[160:163], v[184:187], v[56:59]
	v_mfma_f32_16x16x32_bf16 v[44:47], v[144:147], v[196:199], v[44:47]
	v_mfma_f32_16x16x32_bf16 v[40:43], v[160:163], v[196:199], v[40:43]
	v_mfma_f32_16x16x32_bf16 v[28:31], v[144:147], v[204:207], v[28:31]
	v_mfma_f32_16x16x32_bf16 v[24:27], v[160:163], v[204:207], v[24:27]
	v_mfma_f32_16x16x32_bf16 v[12:15], v[144:147], v[212:215], v[12:15]
	v_mfma_f32_16x16x32_bf16 v[8:11], v[160:163], v[212:215], v[8:11]
	v_mfma_f32_16x16x32_bf16 v[60:63], v[156:159], v[188:191], v[60:63]
	v_mfma_f32_16x16x32_bf16 v[56:59], v[164:167], v[188:191], v[56:59]
	v_mfma_f32_16x16x32_bf16 v[44:47], v[156:159], v[200:203], v[44:47]
	v_mfma_f32_16x16x32_bf16 v[40:43], v[164:167], v[200:203], v[40:43]
	v_mfma_f32_16x16x32_bf16 v[28:31], v[156:159], v[208:211], v[28:31]
	v_mfma_f32_16x16x32_bf16 v[24:27], v[164:167], v[208:211], v[24:27]
	v_mfma_f32_16x16x32_bf16 v[12:15], v[156:159], v[216:219], v[12:15]
	v_mfma_f32_16x16x32_bf16 v[8:11], v[164:167], v[216:219], v[8:11]
	s_setprio 0
	s_setprio 1
	v_mfma_f32_16x16x32_bf16 v[52:55], v[168:171], v[184:187], v[52:55]
	v_mfma_f32_16x16x32_bf16 v[48:51], v[176:179], v[184:187], v[48:51]
	v_mfma_f32_16x16x32_bf16 v[36:39], v[168:171], v[196:199], v[36:39]
	v_mfma_f32_16x16x32_bf16 v[32:35], v[176:179], v[196:199], v[32:35]
	v_mfma_f32_16x16x32_bf16 v[20:23], v[168:171], v[204:207], v[20:23]
	v_mfma_f32_16x16x32_bf16 v[16:19], v[176:179], v[204:207], v[16:19]
	v_mfma_f32_16x16x32_bf16 v[4:7], v[168:171], v[212:215], v[4:7]
	v_mfma_f32_16x16x32_bf16 v[0:3], v[176:179], v[212:215], v[0:3]
	v_mfma_f32_16x16x32_bf16 v[52:55], v[172:175], v[188:191], v[52:55]
	v_mfma_f32_16x16x32_bf16 v[48:51], v[180:183], v[188:191], v[48:51]
	v_mfma_f32_16x16x32_bf16 v[36:39], v[172:175], v[200:203], v[36:39]
	v_mfma_f32_16x16x32_bf16 v[32:35], v[180:183], v[200:203], v[32:35]
	v_mfma_f32_16x16x32_bf16 v[20:23], v[172:175], v[208:211], v[20:23]
	v_mfma_f32_16x16x32_bf16 v[16:19], v[180:183], v[208:211], v[16:19]
	v_mfma_f32_16x16x32_bf16 v[4:7], v[172:175], v[216:219], v[4:7]
	v_mfma_f32_16x16x32_bf16 v[0:3], v[180:183], v[216:219], v[0:3]
	s_setprio 0
	s_barrier
	s_add_i32 s70, s70, 2
	s_add_u32 s36, s36, 0x100
	s_addc_u32 s37, s37, 0
	s_add_u32 s62, s62, 0x100
	s_addc_u32 s63, s63, 0
	s_cmp_gt_u32 s70, 13
	s_cbranch_scc0 .LBB0_3235
	v_lshl_add_u64 v[222:223], v[222:223], 0, s[20:21]
	s_mov_b32 m0, s55
	s_nop 0
	global_load_lds_dwordx4 v[222:223], off
	v_lshl_add_u64 v[224:225], v[224:225], 0, s[20:21]
	s_mov_b32 m0, s56
	s_nop 0
	global_load_lds_dwordx4 v[224:225], off
	s_and_b64 vcc, exec, s[22:23]
	s_cbranch_vccz .LBB0_3238
	s_barrier

.LBB0_3318:
	s_ashr_i32 s19, s18, 31
	s_lshl_b64 s[20:21], s[18:19], 19
	s_add_u32 s20, s35, s20
	s_addc_u32 s21, s36, s21
	s_and_b64 s[22:23], s[6:7], exec
	s_cselect_b32 s19, s21, s27
	s_cselect_b32 s55, s20, s26
	s_ashr_i32 s17, s16, 31
	s_lshl_b64 s[22:23], s[16:17], 19
	s_add_u32 s22, s37, s22
	s_addc_u32 s23, s38, s23
	s_and_b64 s[30:31], s[6:7], exec
	s_cselect_b32 s17, s23, s29
	s_cselect_b32 s56, s22, s28
	s_add_u32 s26, s26, 0x40080
	s_addc_u32 s27, s27, 0
	s_add_u32 s57, s28, 0x100
	v_mov_b32_e32 v8, 0
	s_addc_u32 s58, s29, 0
	s_mov_b32 s59, -2
	v_mov_b32_e32 v9, v8
	v_mov_b32_e32 v10, v8
	v_mov_b32_e32 v11, v8
	v_mov_b32_e32 v12, v8
	v_mov_b32_e32 v13, v8
	v_mov_b32_e32 v14, v8
	v_mov_b32_e32 v15, v8
	v_mov_b32_e32 v24, v8
	v_mov_b32_e32 v25, v8
	v_mov_b32_e32 v26, v8
	v_mov_b32_e32 v27, v8
	v_mov_b32_e32 v28, v8
	v_mov_b32_e32 v29, v8
	v_mov_b32_e32 v30, v8
	v_mov_b32_e32 v31, v8
	v_mov_b32_e32 v40, v8
	v_mov_b32_e32 v41, v8
	v_mov_b32_e32 v42, v8
	v_mov_b32_e32 v43, v8
	v_mov_b32_e32 v44, v8
	v_mov_b32_e32 v45, v8
	v_mov_b32_e32 v46, v8
	v_mov_b32_e32 v47, v8
	v_mov_b32_e32 v56, v8
	v_mov_b32_e32 v57, v8
	v_mov_b32_e32 v58, v8
	v_mov_b32_e32 v59, v8
	v_mov_b32_e32 v60, v8
	v_mov_b32_e32 v61, v8
	v_mov_b32_e32 v62, v8
	v_mov_b32_e32 v63, v8
	v_mov_b32_e32 v0, v8
	v_mov_b32_e32 v1, v8
	v_mov_b32_e32 v2, v8
	v_mov_b32_e32 v3, v8
	v_mov_b32_e32 v4, v8
	v_mov_b32_e32 v5, v8
	v_mov_b32_e32 v6, v8
	v_mov_b32_e32 v7, v8
	v_mov_b32_e32 v16, v8
	v_mov_b32_e32 v17, v8
	v_mov_b32_e32 v18, v8
	v_mov_b32_e32 v19, v8
	v_mov_b32_e32 v20, v8
	v_mov_b32_e32 v21, v8
	v_mov_b32_e32 v22, v8
	v_mov_b32_e32 v23, v8
	v_mov_b32_e32 v32, v8
	v_mov_b32_e32 v33, v8
	v_mov_b32_e32 v34, v8
	v_mov_b32_e32 v35, v8
	v_mov_b32_e32 v36, v8
	v_mov_b32_e32 v37, v8
	v_mov_b32_e32 v38, v8
	v_mov_b32_e32 v39, v8
	v_mov_b32_e32 v48, v8
	v_mov_b32_e32 v49, v8
	v_mov_b32_e32 v50, v8
	v_mov_b32_e32 v51, v8
	v_mov_b32_e32 v52, v8
	v_mov_b32_e32 v53, v8
	v_mov_b32_e32 v54, v8
	v_mov_b32_e32 v55, v8
	v_mov_b32_e32 v72, v8
	v_mov_b32_e32 v73, v8
	v_mov_b32_e32 v74, v8
	v_mov_b32_e32 v75, v8
	v_mov_b32_e32 v76, v8
	v_mov_b32_e32 v77, v8
	v_mov_b32_e32 v78, v8
	v_mov_b32_e32 v79, v8
	v_mov_b32_e32 v88, v8
	v_mov_b32_e32 v89, v8
	v_mov_b32_e32 v90, v8
	v_mov_b32_e32 v91, v8
	v_mov_b32_e32 v92, v8
	v_mov_b32_e32 v93, v8
	v_mov_b32_e32 v94, v8
	v_mov_b32_e32 v95, v8
	v_mov_b32_e32 v104, v8
	v_mov_b32_e32 v105, v8
	v_mov_b32_e32 v106, v8
	v_mov_b32_e32 v107, v8
	v_mov_b32_e32 v108, v8
	v_mov_b32_e32 v109, v8
	v_mov_b32_e32 v110, v8
	v_mov_b32_e32 v111, v8
	v_mov_b32_e32 v120, v8
	v_mov_b32_e32 v121, v8
	v_mov_b32_e32 v122, v8
	v_mov_b32_e32 v123, v8
	v_mov_b32_e32 v124, v8
	v_mov_b32_e32 v125, v8
	v_mov_b32_e32 v126, v8
	v_mov_b32_e32 v127, v8
	v_mov_b32_e32 v64, v8
	v_mov_b32_e32 v65, v8
	v_mov_b32_e32 v66, v8
	v_mov_b32_e32 v67, v8
	v_mov_b32_e32 v68, v8
	v_mov_b32_e32 v69, v8
	v_mov_b32_e32 v70, v8
	v_mov_b32_e32 v71, v8
	v_mov_b32_e32 v80, v8
	v_mov_b32_e32 v81, v8
	v_mov_b32_e32 v82, v8
	v_mov_b32_e32 v83, v8
	v_mov_b32_e32 v84, v8
	v_mov_b32_e32 v85, v8
	v_mov_b32_e32 v86, v8
	v_mov_b32_e32 v87, v8
	v_mov_b32_e32 v96, v8
	v_mov_b32_e32 v97, v8
	v_mov_b32_e32 v98, v8
	v_mov_b32_e32 v99, v8
	v_mov_b32_e32 v100, v8
	v_mov_b32_e32 v101, v8
	v_mov_b32_e32 v102, v8
	v_mov_b32_e32 v103, v8
	v_mov_b32_e32 v112, v8
	v_mov_b32_e32 v113, v8
	v_mov_b32_e32 v114, v8
	v_mov_b32_e32 v115, v8
	v_mov_b32_e32 v116, v8
	v_mov_b32_e32 v117, v8
	v_mov_b32_e32 v118, v8
	v_mov_b32_e32 v119, v8
	s_mov_b32 s99, 0
.LBB0_3319:
	ds_read_b128 v[154:157], v149
	ds_read_b128 v[158:161], v149 offset:1024
	ds_read_b128 v[162:165], v149 offset:2048
	ds_read_b128 v[166:169], v149 offset:3072
	ds_read_b128 v[170:173], v150
	ds_read_b128 v[174:177], v150 offset:1024
	ds_read_b128 v[178:181], v150 offset:2048
	ds_read_b128 v[182:185], v150 offset:3072
	s_add_u32 s28, s26, 0xfffc0080
	s_addc_u32 s29, s27, -1
	s_cmp_eq_u32 s59, 12
	s_cselect_b32 s31, s19, s29
	s_cselect_b32 s30, s55, s28
	s_cselect_b32 s29, s17, s58
	s_cselect_b32 s28, s56, s57
	v_lshl_add_u64 v[144:145], s[26:27], 0, v[136:137]
	ds_read_b128 v[186:189], v151
	ds_read_b128 v[190:193], v151 offset:1024
	ds_read_b128 v[196:199], v151 offset:2048
	ds_read_b128 v[200:203], v151 offset:3072
	ds_read_b128 v[204:207], v151 offset:4096
	ds_read_b128 v[208:211], v151 offset:5120
	ds_read_b128 v[212:215], v151 offset:6144
	ds_read_b128 v[216:219], v151 offset:7168
	s_cmp_eq_u32 s99, 0
	s_cbranch_scc1 .Lkb_first_26
	v_lshl_add_u64 v[222:223], v[222:223], 0, s[12:13]
	s_mov_b32 m0, s45
	s_nop 0
	global_load_lds_dwordx4 v[222:223], off
	v_lshl_add_u64 v[224:225], v[224:225], 0, s[12:13]
	s_mov_b32 m0, s48
	s_nop 0
	global_load_lds_dwordx4 v[224:225], off
	s_branch .Lkb_join_26
.Lkb_first_26:
	s_add_i32 m0, s25, 0xc000
	s_nop 0
	global_load_lds_dwordx4 v[144:145], off
	global_load_lds_dwordx4 v[144:145], off
.Lkb_join_26:
	s_add_i32 m0, s25, 0xc000
	s_nop 0
	global_load_lds_dwordx4 v[144:145], off
	v_lshl_add_u64 v[144:145], s[26:27], 0, v[138:139]
	s_add_i32 m0, s25, 0xe000
	s_nop 0
	global_load_lds_dwordx4 v[144:145], off
	s_waitcnt vmcnt(8)
	s_waitcnt lgkmcnt(0)
	s_barrier
	s_setprio 1
	s_waitcnt lgkmcnt(0)
	v_mfma_f32_16x16x32_bf16 v[116:119], v[154:157], v[186:189], v[116:119]
	v_mfma_f32_16x16x32_bf16 v[112:115], v[162:165], v[186:189], v[112:115]
	v_mfma_f32_16x16x32_bf16 v[100:103], v[154:157], v[196:199], v[100:103]
	v_mfma_f32_16x16x32_bf16 v[96:99], v[162:165], v[196:199], v[96:99]
	v_mfma_f32_16x16x32_bf16 v[84:87], v[154:157], v[204:207], v[84:87]
	v_mfma_f32_16x16x32_bf16 v[80:83], v[162:165], v[204:207], v[80:83]
	v_mfma_f32_16x16x32_bf16 v[68:71], v[154:157], v[212:215], v[68:71]
	v_mfma_f32_16x16x32_bf16 v[64:67], v[162:165], v[212:215], v[64:67]
	v_mfma_f32_16x16x32_bf16 v[116:119], v[158:161], v[190:193], v[116:119]
	v_mfma_f32_16x16x32_bf16 v[112:115], v[166:169], v[190:193], v[112:115]
	v_mfma_f32_16x16x32_bf16 v[100:103], v[158:161], v[200:203], v[100:103]
	v_mfma_f32_16x16x32_bf16 v[96:99], v[166:169], v[200:203], v[96:99]
	v_mfma_f32_16x16x32_bf16 v[84:87], v[158:161], v[208:211], v[84:87]
	v_mfma_f32_16x16x32_bf16 v[80:83], v[166:169], v[208:211], v[80:83]
	v_mfma_f32_16x16x32_bf16 v[68:71], v[158:161], v[216:219], v[68:71]
	v_mfma_f32_16x16x32_bf16 v[64:67], v[166:169], v[216:219], v[64:67]
	s_setprio 0
	s_setprio 1
	v_mfma_f32_16x16x32_bf16 v[124:127], v[170:173], v[186:189], v[124:127]
	v_mfma_f32_16x16x32_bf16 v[120:123], v[178:181], v[186:189], v[120:123]
	v_mfma_f32_16x16x32_bf16 v[108:111], v[170:173], v[196:199], v[108:111]
	v_mfma_f32_16x16x32_bf16 v[104:107], v[178:181], v[196:199], v[104:107]
	v_mfma_f32_16x16x32_bf16 v[92:95], v[170:173], v[204:207], v[92:95]
	v_mfma_f32_16x16x32_bf16 v[88:91], v[178:181], v[204:207], v[88:91]
	v_mfma_f32_16x16x32_bf16 v[76:79], v[170:173], v[212:215], v[76:79]
	v_mfma_f32_16x16x32_bf16 v[72:75], v[178:181], v[212:215], v[72:75]
	v_mfma_f32_16x16x32_bf16 v[124:127], v[174:177], v[190:193], v[124:127]
	v_mfma_f32_16x16x32_bf16 v[120:123], v[182:185], v[190:193], v[120:123]
	v_mfma_f32_16x16x32_bf16 v[108:111], v[174:177], v[200:203], v[108:111]
	v_mfma_f32_16x16x32_bf16 v[104:107], v[182:185], v[200:203], v[104:107]
	v_mfma_f32_16x16x32_bf16 v[92:95], v[174:177], v[208:211], v[92:95]
	v_mfma_f32_16x16x32_bf16 v[88:91], v[182:185], v[208:211], v[88:91]
	v_mfma_f32_16x16x32_bf16 v[76:79], v[174:177], v[216:219], v[76:79]
	v_mfma_f32_16x16x32_bf16 v[72:75], v[182:185], v[216:219], v[72:75]
	s_setprio 0
	s_barrier
	s_add_i32 s60, s50, s39
	v_lshl_add_u64 v[144:145], s[28:29], 0, v[132:133]
	s_mov_b32 m0, s60
	ds_read_b128 v[186:189], v151 offset:16384
	ds_read_b128 v[190:193], v151 offset:17408
	ds_read_b128 v[196:199], v151 offset:18432
	ds_read_b128 v[200:203], v151 offset:19456
	ds_read_b128 v[204:207], v151 offset:20480
	ds_read_b128 v[208:211], v151 offset:21504
	ds_read_b128 v[212:215], v151 offset:22528
	ds_read_b128 v[216:219], v151 offset:23552
	global_load_lds_dwordx4 v[144:145], off
	s_add_i32 m0, s60, 0x2000
	s_add_u32 s60, s28, 0x40000
	v_lshl_add_u64 v[220:221], s[28:29], 0, v[128:129]
	s_addc_u32 s61, s29, 0
	s_add_i32 s62, s51, s39
	global_load_lds_dwordx4 v[220:221], off
	v_lshl_add_u64 v[222:223], s[60:61], 0, v[132:133]
	s_mov_b32 m0, s62
	v_lshl_add_u64 v[224:225], s[30:31], 0, v[130:131]
	global_load_lds_dwordx4 v[222:223], off
	v_lshl_add_u64 v[222:223], s[60:61], 0, v[128:129]
	s_add_i32 m0, s62, 0x2000
	s_nop 0
	global_load_lds_dwordx4 v[222:223], off
	v_lshl_add_u64 v[222:223], s[30:31], 0, v[134:135]
	s_waitcnt vmcnt(6)
	s_waitcnt lgkmcnt(0)
	s_barrier
	s_setprio 1
	s_waitcnt lgkmcnt(0)
	v_mfma_f32_16x16x32_bf16 v[52:55], v[154:157], v[186:189], v[52:55]
	v_mfma_f32_16x16x32_bf16 v[48:51], v[162:165], v[186:189], v[48:51]
	v_mfma_f32_16x16x32_bf16 v[36:39], v[154:157], v[196:199], v[36:39]
	v_mfma_f32_16x16x32_bf16 v[32:35], v[162:165], v[196:199], v[32:35]
	v_mfma_f32_16x16x32_bf16 v[20:23], v[154:157], v[204:207], v[20:23]
	v_mfma_f32_16x16x32_bf16 v[16:19], v[162:165], v[204:207], v[16:19]
	v_mfma_f32_16x16x32_bf16 v[4:7], v[154:157], v[212:215], v[4:7]
	v_mfma_f32_16x16x32_bf16 v[0:3], v[162:165], v[212:215], v[0:3]
	v_mfma_f32_16x16x32_bf16 v[52:55], v[158:161], v[190:193], v[52:55]
	v_mfma_f32_16x16x32_bf16 v[48:51], v[166:169], v[190:193], v[48:51]
	v_mfma_f32_16x16x32_bf16 v[36:39], v[158:161], v[200:203], v[36:39]
	v_mfma_f32_16x16x32_bf16 v[32:35], v[166:169], v[200:203], v[32:35]
	v_mfma_f32_16x16x32_bf16 v[20:23], v[158:161], v[208:211], v[20:23]
	v_mfma_f32_16x16x32_bf16 v[16:19], v[166:169], v[208:211], v[16:19]
	v_mfma_f32_16x16x32_bf16 v[4:7], v[158:161], v[216:219], v[4:7]
	v_mfma_f32_16x16x32_bf16 v[0:3], v[166:169], v[216:219], v[0:3]
	s_setprio 0
	s_setprio 1
	v_mfma_f32_16x16x32_bf16 v[60:63], v[170:173], v[186:189], v[60:63]
	v_mfma_f32_16x16x32_bf16 v[56:59], v[178:181], v[186:189], v[56:59]
	v_mfma_f32_16x16x32_bf16 v[44:47], v[170:173], v[196:199], v[44:47]
	v_mfma_f32_16x16x32_bf16 v[40:43], v[178:181], v[196:199], v[40:43]
	v_mfma_f32_16x16x32_bf16 v[28:31], v[170:173], v[204:207], v[28:31]
	v_mfma_f32_16x16x32_bf16 v[24:27], v[178:181], v[204:207], v[24:27]
	v_mfma_f32_16x16x32_bf16 v[12:15], v[170:173], v[212:215], v[12:15]
	v_mfma_f32_16x16x32_bf16 v[8:11], v[178:181], v[212:215], v[8:11]
	v_mfma_f32_16x16x32_bf16 v[60:63], v[174:177], v[190:193], v[60:63]
	v_mfma_f32_16x16x32_bf16 v[56:59], v[182:185], v[190:193], v[56:59]
	v_mfma_f32_16x16x32_bf16 v[44:47], v[174:177], v[200:203], v[44:47]
	v_mfma_f32_16x16x32_bf16 v[40:43], v[182:185], v[200:203], v[40:43]
	v_mfma_f32_16x16x32_bf16 v[28:31], v[174:177], v[208:211], v[28:31]
	v_mfma_f32_16x16x32_bf16 v[24:27], v[182:185], v[208:211], v[24:27]
	v_mfma_f32_16x16x32_bf16 v[12:15], v[174:177], v[216:219], v[12:15]
	v_mfma_f32_16x16x32_bf16 v[8:11], v[182:185], v[216:219], v[8:11]
	s_setprio 0
	s_barrier
	s_add_i32 s60, 0, 0x18000
	v_add_u32_e32 v153, s60, v147
	s_add_i32 s61, 0, 0x1c000
	ds_read_b128 v[154:157], v153
	ds_read_b128 v[158:161], v153 offset:1024
	ds_read_b128 v[162:165], v153 offset:2048
	ds_read_b128 v[166:169], v153 offset:3072
	v_add_u32_e32 v153, s61, v147
	ds_read_b128 v[170:173], v153
	ds_read_b128 v[174:177], v153 offset:1024
	ds_read_b128 v[178:181], v153 offset:2048
	ds_read_b128 v[182:185], v153 offset:3072
	s_add_u32 s30, s30, 0x40000
	s_addc_u32 s31, s31, 0
	v_lshl_add_u64 v[226:227], s[30:31], 0, v[134:135]
	ds_read_b128 v[186:189], v151 offset:32768
	ds_read_b128 v[190:193], v151 offset:33792
	ds_read_b128 v[196:199], v151 offset:34816
	ds_read_b128 v[200:203], v151 offset:35840
	ds_read_b128 v[204:207], v151 offset:36864
	ds_read_b128 v[208:211], v151 offset:37888
	ds_read_b128 v[212:215], v151 offset:38912
	ds_read_b128 v[216:219], v151 offset:39936
	s_mov_b32 m0, s25
	s_nop 0
	global_load_lds_dwordx4 v[222:223], off
	s_mov_b32 m0, s41
	s_nop 0
	global_load_lds_dwordx4 v[224:225], off
	s_mov_b32 m0, s42
	s_nop 0
	global_load_lds_dwordx4 v[226:227], off
	v_lshl_add_u64 v[226:227], s[30:31], 0, v[130:131]
	s_mov_b32 m0, s43
	s_nop 0
	global_load_lds_dwordx4 v[226:227], off
	s_waitcnt vmcnt(8)
	s_waitcnt lgkmcnt(0)
	s_barrier
	s_setprio 1
	s_waitcnt lgkmcnt(0)
	v_mfma_f32_16x16x32_bf16 v[116:119], v[154:157], v[186:189], v[116:119]
	v_mfma_f32_16x16x32_bf16 v[112:115], v[162:165], v[186:189], v[112:115]
	v_mfma_f32_16x16x32_bf16 v[100:103], v[154:157], v[196:199], v[100:103]
	v_mfma_f32_16x16x32_bf16 v[96:99], v[162:165], v[196:199], v[96:99]
	v_mfma_f32_16x16x32_bf16 v[84:87], v[154:157], v[204:207], v[84:87]
	v_mfma_f32_16x16x32_bf16 v[80:83], v[162:165], v[204:207], v[80:83]
	v_mfma_f32_16x16x32_bf16 v[68:71], v[154:157], v[212:215], v[68:71]
	v_mfma_f32_16x16x32_bf16 v[64:67], v[162:165], v[212:215], v[64:67]
	v_mfma_f32_16x16x32_bf16 v[116:119], v[158:161], v[190:193], v[116:119]
	v_mfma_f32_16x16x32_bf16 v[112:115], v[166:169], v[190:193], v[112:115]
	v_mfma_f32_16x16x32_bf16 v[100:103], v[158:161], v[200:203], v[100:103]
	v_mfma_f32_16x16x32_bf16 v[96:99], v[166:169], v[200:203], v[96:99]
	v_mfma_f32_16x16x32_bf16 v[84:87], v[158:161], v[208:211], v[84:87]
	v_mfma_f32_16x16x32_bf16 v[80:83], v[166:169], v[208:211], v[80:83]
	v_mfma_f32_16x16x32_bf16 v[68:71], v[158:161], v[216:219], v[68:71]
	v_mfma_f32_16x16x32_bf16 v[64:67], v[166:169], v[216:219], v[64:67]
	s_setprio 0
	s_setprio 1
	v_mfma_f32_16x16x32_bf16 v[124:127], v[170:173], v[186:189], v[124:127]
	v_mfma_f32_16x16x32_bf16 v[120:123], v[178:181], v[186:189], v[120:123]
	v_mfma_f32_16x16x32_bf16 v[108:111], v[170:173], v[196:199], v[108:111]
	v_mfma_f32_16x16x32_bf16 v[104:107], v[178:181], v[196:199], v[104:107]
	v_mfma_f32_16x16x32_bf16 v[92:95], v[170:173], v[204:207], v[92:95]
	v_mfma_f32_16x16x32_bf16 v[88:91], v[178:181], v[204:207], v[88:91]
	v_mfma_f32_16x16x32_bf16 v[76:79], v[170:173], v[212:215], v[76:79]
	v_mfma_f32_16x16x32_bf16 v[72:75], v[178:181], v[212:215], v[72:75]
	v_mfma_f32_16x16x32_bf16 v[124:127], v[174:177], v[190:193], v[124:127]
	v_mfma_f32_16x16x32_bf16 v[120:123], v[182:185], v[190:193], v[120:123]
	v_mfma_f32_16x16x32_bf16 v[108:111], v[174:177], v[200:203], v[108:111]
	v_mfma_f32_16x16x32_bf16 v[104:107], v[182:185], v[200:203], v[104:107]
	v_mfma_f32_16x16x32_bf16 v[92:95], v[174:177], v[208:211], v[92:95]
	v_mfma_f32_16x16x32_bf16 v[88:91], v[182:185], v[208:211], v[88:91]
	v_mfma_f32_16x16x32_bf16 v[76:79], v[174:177], v[216:219], v[76:79]
	v_mfma_f32_16x16x32_bf16 v[72:75], v[182:185], v[216:219], v[72:75]
	s_setprio 0
	s_barrier
	s_add_i32 s30, s60, s39
	v_lshl_add_u64 v[144:145], v[144:145], 0, s[12:13]
	s_mov_b32 m0, s30
	ds_read_b128 v[186:189], v151 offset:49152
	ds_read_b128 v[190:193], v151 offset:50176
	ds_read_b128 v[196:199], v151 offset:51200
	ds_read_b128 v[200:203], v151 offset:52224
	ds_read_b128 v[204:207], v151 offset:53248
	ds_read_b128 v[208:211], v151 offset:54272
	ds_read_b128 v[212:215], v151 offset:55296
	ds_read_b128 v[216:219], v151 offset:56320
	global_load_lds_dwordx4 v[144:145], off
	s_add_i32 m0, s30, 0x2000
	s_add_u32 s28, s28, 0x40080
	v_lshl_add_u64 v[144:145], v[220:221], 0, s[12:13]
	s_addc_u32 s29, s29, 0
	s_add_i32 s30, s61, s39
	global_load_lds_dwordx4 v[144:145], off
	v_lshl_add_u64 v[144:145], s[28:29], 0, v[132:133]
	s_mov_b32 m0, s30
	s_nop 0
	global_load_lds_dwordx4 v[144:145], off
	v_lshl_add_u64 v[144:145], s[28:29], 0, v[128:129]
	s_add_i32 m0, s30, 0x2000
	s_nop 0
	global_load_lds_dwordx4 v[144:145], off
	s_mov_b32 s99, 1
	s_waitcnt vmcnt(6)
	s_waitcnt lgkmcnt(0)
	s_barrier
	s_setprio 1
	s_waitcnt lgkmcnt(0)
	v_mfma_f32_16x16x32_bf16 v[52:55], v[154:157], v[186:189], v[52:55]
	v_mfma_f32_16x16x32_bf16 v[48:51], v[162:165], v[186:189], v[48:51]
	v_mfma_f32_16x16x32_bf16 v[36:39], v[154:157], v[196:199], v[36:39]
	v_mfma_f32_16x16x32_bf16 v[32:35], v[162:165], v[196:199], v[32:35]
	v_mfma_f32_16x16x32_bf16 v[20:23], v[154:157], v[204:207], v[20:23]
	v_mfma_f32_16x16x32_bf16 v[16:19], v[162:165], v[204:207], v[16:19]
	v_mfma_f32_16x16x32_bf16 v[4:7], v[154:157], v[212:215], v[4:7]
	v_mfma_f32_16x16x32_bf16 v[0:3], v[162:165], v[212:215], v[0:3]
	v_mfma_f32_16x16x32_bf16 v[52:55], v[158:161], v[190:193], v[52:55]
	v_mfma_f32_16x16x32_bf16 v[48:51], v[166:169], v[190:193], v[48:51]
	v_mfma_f32_16x16x32_bf16 v[36:39], v[158:161], v[200:203], v[36:39]
	v_mfma_f32_16x16x32_bf16 v[32:35], v[166:169], v[200:203], v[32:35]
	v_mfma_f32_16x16x32_bf16 v[20:23], v[158:161], v[208:211], v[20:23]
	v_mfma_f32_16x16x32_bf16 v[16:19], v[166:169], v[208:211], v[16:19]
	v_mfma_f32_16x16x32_bf16 v[4:7], v[158:161], v[216:219], v[4:7]
	v_mfma_f32_16x16x32_bf16 v[0:3], v[166:169], v[216:219], v[0:3]
	s_setprio 0
	s_setprio 1
	v_mfma_f32_16x16x32_bf16 v[60:63], v[170:173], v[186:189], v[60:63]
	v_mfma_f32_16x16x32_bf16 v[56:59], v[178:181], v[186:189], v[56:59]
	v_mfma_f32_16x16x32_bf16 v[44:47], v[170:173], v[196:199], v[44:47]
	v_mfma_f32_16x16x32_bf16 v[40:43], v[178:181], v[196:199], v[40:43]
	v_mfma_f32_16x16x32_bf16 v[28:31], v[170:173], v[204:207], v[28:31]
	v_mfma_f32_16x16x32_bf16 v[24:27], v[178:181], v[204:207], v[24:27]
	v_mfma_f32_16x16x32_bf16 v[12:15], v[170:173], v[212:215], v[12:15]
	v_mfma_f32_16x16x32_bf16 v[8:11], v[178:181], v[212:215], v[8:11]
	v_mfma_f32_16x16x32_bf16 v[60:63], v[174:177], v[190:193], v[60:63]
	v_mfma_f32_16x16x32_bf16 v[56:59], v[182:185], v[190:193], v[56:59]
	v_mfma_f32_16x16x32_bf16 v[44:47], v[174:177], v[200:203], v[44:47]
	v_mfma_f32_16x16x32_bf16 v[40:43], v[182:185], v[200:203], v[40:43]
	v_mfma_f32_16x16x32_bf16 v[28:31], v[174:177], v[208:211], v[28:31]
	v_mfma_f32_16x16x32_bf16 v[24:27], v[182:185], v[208:211], v[24:27]
	v_mfma_f32_16x16x32_bf16 v[12:15], v[174:177], v[216:219], v[12:15]
	v_mfma_f32_16x16x32_bf16 v[8:11], v[182:185], v[216:219], v[8:11]
	s_setprio 0
	s_barrier
	s_add_i32 s59, s59, 2
	s_add_u32 s26, s26, 0x100
	s_addc_u32 s27, s27, 0
	s_add_u32 s57, s57, 0x100
	s_addc_u32 s58, s58, 0
	s_cmp_gt_u32 s59, 13
	s_cbranch_scc0 .LBB0_3319
	v_lshl_add_u64 v[222:223], v[222:223], 0, s[12:13]
	s_mov_b32 m0, s45
	s_nop 0
	global_load_lds_dwordx4 v[222:223], off
	v_lshl_add_u64 v[224:225], v[224:225], 0, s[12:13]
	s_mov_b32 m0, s48
	s_nop 0
	global_load_lds_dwordx4 v[224:225], off
	s_and_b64 vcc, exec, s[14:15]
	s_cbranch_vccz .LBB0_3322
	s_barrier

.LBB0_3400:
	s_add_u32 s54, s24, 0x100
	v_mov_b32_e32 v0, 0
	s_addc_u32 s55, s25, 0
	s_mov_b32 s56, -2
	s_waitcnt lgkmcnt(0)
	v_mov_b32_e32 v1, v0
	v_mov_b32_e32 v2, v0
	v_mov_b32_e32 v3, v0
	v_mov_b32_e32 v4, v0
	v_mov_b32_e32 v5, v0
	v_mov_b32_e32 v6, v0
	v_mov_b32_e32 v7, v0
	v_mov_b32_e32 v16, v0
	v_mov_b32_e32 v17, v0
	v_mov_b32_e32 v18, v0
	v_mov_b32_e32 v19, v0
	v_mov_b32_e32 v20, v0
	v_mov_b32_e32 v21, v0
	v_mov_b32_e32 v22, v0
	v_mov_b32_e32 v23, v0
	v_mov_b32_e32 v32, v0
	v_mov_b32_e32 v33, v0
	v_mov_b32_e32 v34, v0
	v_mov_b32_e32 v35, v0
	v_mov_b32_e32 v36, v0
	v_mov_b32_e32 v37, v0
	v_mov_b32_e32 v38, v0
	v_mov_b32_e32 v39, v0
	v_mov_b32_e32 v48, v0
	v_mov_b32_e32 v49, v0
	v_mov_b32_e32 v50, v0
	v_mov_b32_e32 v51, v0
	v_mov_b32_e32 v52, v0
	v_mov_b32_e32 v53, v0
	v_mov_b32_e32 v54, v0
	v_mov_b32_e32 v55, v0
	v_mov_b32_e32 v8, v0
	v_mov_b32_e32 v9, v0
	v_mov_b32_e32 v10, v0
	v_mov_b32_e32 v11, v0
	v_mov_b32_e32 v12, v0
	v_mov_b32_e32 v13, v0
	v_mov_b32_e32 v14, v0
	v_mov_b32_e32 v15, v0
	v_mov_b32_e32 v24, v0
	v_mov_b32_e32 v25, v0
	v_mov_b32_e32 v26, v0
	v_mov_b32_e32 v27, v0
	v_mov_b32_e32 v28, v0
	v_mov_b32_e32 v29, v0
	v_mov_b32_e32 v30, v0
	v_mov_b32_e32 v31, v0
	v_mov_b32_e32 v40, v0
	v_mov_b32_e32 v41, v0
	v_mov_b32_e32 v42, v0
	v_mov_b32_e32 v43, v0
	v_mov_b32_e32 v44, v0
	v_mov_b32_e32 v45, v0
	v_mov_b32_e32 v46, v0
	v_mov_b32_e32 v47, v0
	v_mov_b32_e32 v56, v0
	v_mov_b32_e32 v57, v0
	v_mov_b32_e32 v58, v0
	v_mov_b32_e32 v59, v0
	v_mov_b32_e32 v60, v0
	v_mov_b32_e32 v61, v0
	v_mov_b32_e32 v62, v0
	v_mov_b32_e32 v63, v0
	v_mov_b32_e32 v64, v0
	v_mov_b32_e32 v65, v0
	v_mov_b32_e32 v66, v0
	v_mov_b32_e32 v67, v0
	v_mov_b32_e32 v68, v0
	v_mov_b32_e32 v69, v0
	v_mov_b32_e32 v70, v0
	v_mov_b32_e32 v71, v0
	v_mov_b32_e32 v80, v0
	v_mov_b32_e32 v81, v0
	v_mov_b32_e32 v82, v0
	v_mov_b32_e32 v83, v0
	v_mov_b32_e32 v84, v0
	v_mov_b32_e32 v85, v0
	v_mov_b32_e32 v86, v0
	v_mov_b32_e32 v87, v0
	v_mov_b32_e32 v96, v0
	v_mov_b32_e32 v97, v0
	v_mov_b32_e32 v98, v0
	v_mov_b32_e32 v99, v0
	v_mov_b32_e32 v100, v0
	v_mov_b32_e32 v101, v0
	v_mov_b32_e32 v102, v0
	v_mov_b32_e32 v103, v0
	v_mov_b32_e32 v112, v0
	v_mov_b32_e32 v113, v0
	v_mov_b32_e32 v114, v0
	v_mov_b32_e32 v115, v0
	v_mov_b32_e32 v116, v0
	v_mov_b32_e32 v117, v0
	v_mov_b32_e32 v118, v0
	v_mov_b32_e32 v119, v0
	v_mov_b32_e32 v72, v0
	v_mov_b32_e32 v73, v0
	v_mov_b32_e32 v74, v0
	v_mov_b32_e32 v75, v0
	v_mov_b32_e32 v76, v0
	v_mov_b32_e32 v77, v0
	v_mov_b32_e32 v78, v0
	v_mov_b32_e32 v79, v0
	v_mov_b32_e32 v88, v0
	v_mov_b32_e32 v89, v0
	v_mov_b32_e32 v90, v0
	v_mov_b32_e32 v91, v0
	v_mov_b32_e32 v92, v0
	v_mov_b32_e32 v93, v0
	v_mov_b32_e32 v94, v0
	v_mov_b32_e32 v95, v0
	v_mov_b32_e32 v104, v0
	v_mov_b32_e32 v105, v0
	v_mov_b32_e32 v106, v0
	v_mov_b32_e32 v107, v0
	v_mov_b32_e32 v108, v0
	v_mov_b32_e32 v109, v0
	v_mov_b32_e32 v110, v0
	v_mov_b32_e32 v111, v0
	v_mov_b32_e32 v120, v0
	v_mov_b32_e32 v121, v0
	v_mov_b32_e32 v122, v0
	v_mov_b32_e32 v123, v0
	v_mov_b32_e32 v124, v0
	v_mov_b32_e32 v125, v0
	v_mov_b32_e32 v126, v0
	v_mov_b32_e32 v127, v0
	s_mov_b32 s99, 0
.LBB0_3401:
	ds_read_b128 v[144:147], v151
	ds_read_b128 v[156:159], v151 offset:1024
	ds_read_b128 v[160:163], v151 offset:2048
	ds_read_b128 v[164:167], v151 offset:3072
	ds_read_b128 v[168:171], v152
	ds_read_b128 v[172:175], v152 offset:1024
	ds_read_b128 v[176:179], v152 offset:2048
	ds_read_b128 v[180:183], v152 offset:3072
	s_add_u32 s24, s22, 0x100
	s_addc_u32 s25, s23, 0
	s_cmp_eq_u32 s56, 40
	s_cselect_b32 s29, s1, s25
	s_cselect_b32 s28, s0, s24
	s_cselect_b32 s27, s21, s55
	s_cselect_b32 s26, s20, s54
	v_lshl_add_u64 v[192:193], s[22:23], 0, v[136:137]
	ds_read_b128 v[184:187], v153
	ds_read_b128 v[188:191], v153 offset:1024
	ds_read_b128 v[196:199], v153 offset:2048
	ds_read_b128 v[200:203], v153 offset:3072
	ds_read_b128 v[204:207], v153 offset:4096
	ds_read_b128 v[208:211], v153 offset:5120
	ds_read_b128 v[212:215], v153 offset:6144
	ds_read_b128 v[216:219], v153 offset:7168
	s_cmp_eq_u32 s99, 0
	s_cbranch_scc1 .Lkb_first_27
	v_lshl_add_u64 v[222:223], v[222:223], 0, s[16:17]
	s_mov_b32 m0, s43
	s_nop 0
	global_load_lds_dwordx4 v[222:223], off
	v_lshl_add_u64 v[224:225], v[224:225], 0, s[16:17]
	s_mov_b32 m0, s44
	s_nop 0
	global_load_lds_dwordx4 v[224:225], off
	s_branch .Lkb_join_27
.Lkb_first_27:
	s_add_i32 m0, s38, 0xc000
	s_nop 0
	global_load_lds_dwordx4 v[192:193], off
	global_load_lds_dwordx4 v[192:193], off
.Lkb_join_27:
	s_add_i32 m0, s38, 0xc000
	s_nop 0
	global_load_lds_dwordx4 v[192:193], off
	v_lshl_add_u64 v[192:193], s[22:23], 0, v[138:139]
	s_add_i32 m0, s38, 0xe000
	s_nop 0
	global_load_lds_dwordx4 v[192:193], off
	s_waitcnt vmcnt(8)
	s_waitcnt lgkmcnt(0)
	s_barrier
	s_setprio 1
	s_waitcnt lgkmcnt(0)
	v_mfma_f32_16x16x32_bf16 v[124:127], v[144:147], v[184:187], v[124:127]
	v_mfma_f32_16x16x32_bf16 v[120:123], v[160:163], v[184:187], v[120:123]
	v_mfma_f32_16x16x32_bf16 v[108:111], v[144:147], v[196:199], v[108:111]
	v_mfma_f32_16x16x32_bf16 v[104:107], v[160:163], v[196:199], v[104:107]
	v_mfma_f32_16x16x32_bf16 v[92:95], v[144:147], v[204:207], v[92:95]
	v_mfma_f32_16x16x32_bf16 v[88:91], v[160:163], v[204:207], v[88:91]
	v_mfma_f32_16x16x32_bf16 v[76:79], v[144:147], v[212:215], v[76:79]
	v_mfma_f32_16x16x32_bf16 v[72:75], v[160:163], v[212:215], v[72:75]
	v_mfma_f32_16x16x32_bf16 v[124:127], v[156:159], v[188:191], v[124:127]
	v_mfma_f32_16x16x32_bf16 v[120:123], v[164:167], v[188:191], v[120:123]
	v_mfma_f32_16x16x32_bf16 v[108:111], v[156:159], v[200:203], v[108:111]
	v_mfma_f32_16x16x32_bf16 v[104:107], v[164:167], v[200:203], v[104:107]
	v_mfma_f32_16x16x32_bf16 v[92:95], v[156:159], v[208:211], v[92:95]
	v_mfma_f32_16x16x32_bf16 v[88:91], v[164:167], v[208:211], v[88:91]
	v_mfma_f32_16x16x32_bf16 v[76:79], v[156:159], v[216:219], v[76:79]
	v_mfma_f32_16x16x32_bf16 v[72:75], v[164:167], v[216:219], v[72:75]
	s_setprio 0
	s_setprio 1
	v_mfma_f32_16x16x32_bf16 v[116:119], v[168:171], v[184:187], v[116:119]
	v_mfma_f32_16x16x32_bf16 v[112:115], v[176:179], v[184:187], v[112:115]
	v_mfma_f32_16x16x32_bf16 v[100:103], v[168:171], v[196:199], v[100:103]
	v_mfma_f32_16x16x32_bf16 v[96:99], v[176:179], v[196:199], v[96:99]
	v_mfma_f32_16x16x32_bf16 v[84:87], v[168:171], v[204:207], v[84:87]
	v_mfma_f32_16x16x32_bf16 v[80:83], v[176:179], v[204:207], v[80:83]
	v_mfma_f32_16x16x32_bf16 v[68:71], v[168:171], v[212:215], v[68:71]
	v_mfma_f32_16x16x32_bf16 v[64:67], v[176:179], v[212:215], v[64:67]
	v_mfma_f32_16x16x32_bf16 v[116:119], v[172:175], v[188:191], v[116:119]
	v_mfma_f32_16x16x32_bf16 v[112:115], v[180:183], v[188:191], v[112:115]
	v_mfma_f32_16x16x32_bf16 v[100:103], v[172:175], v[200:203], v[100:103]
	v_mfma_f32_16x16x32_bf16 v[96:99], v[180:183], v[200:203], v[96:99]
	v_mfma_f32_16x16x32_bf16 v[84:87], v[172:175], v[208:211], v[84:87]
	v_mfma_f32_16x16x32_bf16 v[80:83], v[180:183], v[208:211], v[80:83]
	v_mfma_f32_16x16x32_bf16 v[68:71], v[172:175], v[216:219], v[68:71]
	v_mfma_f32_16x16x32_bf16 v[64:67], v[180:183], v[216:219], v[64:67]
	s_setprio 0
	s_barrier
	s_add_i32 s22, s48, s37
	v_lshl_add_u64 v[192:193], s[26:27], 0, v[130:131]
	s_mov_b32 m0, s22
	ds_read_b128 v[184:187], v153 offset:16384
	ds_read_b128 v[188:191], v153 offset:17408
	ds_read_b128 v[196:199], v153 offset:18432
	ds_read_b128 v[200:203], v153 offset:19456
	ds_read_b128 v[204:207], v153 offset:20480
	ds_read_b128 v[208:211], v153 offset:21504
	ds_read_b128 v[212:215], v153 offset:22528
	ds_read_b128 v[216:219], v153 offset:23552
	global_load_lds_dwordx4 v[192:193], off
	s_add_i32 m0, s22, 0x2000
	s_add_u32 s22, s26, 0xb0000
	v_lshl_add_u64 v[220:221], s[26:27], 0, v[134:135]
	s_addc_u32 s23, s27, 0
	s_add_i32 s57, s49, s37
	global_load_lds_dwordx4 v[220:221], off
	v_lshl_add_u64 v[222:223], s[22:23], 0, v[130:131]
	s_mov_b32 m0, s57
	v_lshl_add_u64 v[224:225], s[28:29], 0, v[132:133]
	global_load_lds_dwordx4 v[222:223], off
	v_lshl_add_u64 v[222:223], s[22:23], 0, v[134:135]
	s_add_i32 m0, s57, 0x2000
	s_nop 0
	global_load_lds_dwordx4 v[222:223], off
	v_lshl_add_u64 v[222:223], s[28:29], 0, v[128:129]
	s_waitcnt vmcnt(6)
	s_waitcnt lgkmcnt(0)
	s_barrier
	s_setprio 1
	s_waitcnt lgkmcnt(0)
	v_mfma_f32_16x16x32_bf16 v[60:63], v[144:147], v[184:187], v[60:63]
	v_mfma_f32_16x16x32_bf16 v[56:59], v[160:163], v[184:187], v[56:59]
	v_mfma_f32_16x16x32_bf16 v[44:47], v[144:147], v[196:199], v[44:47]
	v_mfma_f32_16x16x32_bf16 v[40:43], v[160:163], v[196:199], v[40:43]
	v_mfma_f32_16x16x32_bf16 v[28:31], v[144:147], v[204:207], v[28:31]
	v_mfma_f32_16x16x32_bf16 v[24:27], v[160:163], v[204:207], v[24:27]
	v_mfma_f32_16x16x32_bf16 v[12:15], v[144:147], v[212:215], v[12:15]
	v_mfma_f32_16x16x32_bf16 v[8:11], v[160:163], v[212:215], v[8:11]
	v_mfma_f32_16x16x32_bf16 v[60:63], v[156:159], v[188:191], v[60:63]
	v_mfma_f32_16x16x32_bf16 v[56:59], v[164:167], v[188:191], v[56:59]
	v_mfma_f32_16x16x32_bf16 v[44:47], v[156:159], v[200:203], v[44:47]
	v_mfma_f32_16x16x32_bf16 v[40:43], v[164:167], v[200:203], v[40:43]
	v_mfma_f32_16x16x32_bf16 v[28:31], v[156:159], v[208:211], v[28:31]
	v_mfma_f32_16x16x32_bf16 v[24:27], v[164:167], v[208:211], v[24:27]
	v_mfma_f32_16x16x32_bf16 v[12:15], v[156:159], v[216:219], v[12:15]
	v_mfma_f32_16x16x32_bf16 v[8:11], v[164:167], v[216:219], v[8:11]
	s_setprio 0
	s_setprio 1
	v_mfma_f32_16x16x32_bf16 v[52:55], v[168:171], v[184:187], v[52:55]
	v_mfma_f32_16x16x32_bf16 v[48:51], v[176:179], v[184:187], v[48:51]
	v_mfma_f32_16x16x32_bf16 v[36:39], v[168:171], v[196:199], v[36:39]
	v_mfma_f32_16x16x32_bf16 v[32:35], v[176:179], v[196:199], v[32:35]
	v_mfma_f32_16x16x32_bf16 v[20:23], v[168:171], v[204:207], v[20:23]
	v_mfma_f32_16x16x32_bf16 v[16:19], v[176:179], v[204:207], v[16:19]
	v_mfma_f32_16x16x32_bf16 v[4:7], v[168:171], v[212:215], v[4:7]
	v_mfma_f32_16x16x32_bf16 v[0:3], v[176:179], v[212:215], v[0:3]
	v_mfma_f32_16x16x32_bf16 v[52:55], v[172:175], v[188:191], v[52:55]
	v_mfma_f32_16x16x32_bf16 v[48:51], v[180:183], v[188:191], v[48:51]
	v_mfma_f32_16x16x32_bf16 v[36:39], v[172:175], v[200:203], v[36:39]
	v_mfma_f32_16x16x32_bf16 v[32:35], v[180:183], v[200:203], v[32:35]
	v_mfma_f32_16x16x32_bf16 v[20:23], v[172:175], v[208:211], v[20:23]
	v_mfma_f32_16x16x32_bf16 v[16:19], v[180:183], v[208:211], v[16:19]
	v_mfma_f32_16x16x32_bf16 v[4:7], v[172:175], v[216:219], v[4:7]
	v_mfma_f32_16x16x32_bf16 v[0:3], v[180:183], v[216:219], v[0:3]
	s_setprio 0
	s_barrier
	s_add_i32 s57, 0, 0x18000
	v_add_u32_e32 v155, s57, v149
	s_add_i32 s58, 0, 0x1c000
	ds_read_b128 v[144:147], v155
	ds_read_b128 v[156:159], v155 offset:1024
	ds_read_b128 v[160:163], v155 offset:2048
	ds_read_b128 v[164:167], v155 offset:3072
	v_add_u32_e32 v155, s58, v149
	ds_read_b128 v[168:171], v155
	ds_read_b128 v[172:175], v155 offset:1024
	ds_read_b128 v[176:179], v155 offset:2048
	ds_read_b128 v[180:183], v155 offset:3072
	s_add_u32 s22, s28, 0xb0000
	s_addc_u32 s23, s29, 0
	v_lshl_add_u64 v[226:227], s[22:23], 0, v[128:129]
	ds_read_b128 v[184:187], v153 offset:32768
	ds_read_b128 v[188:191], v153 offset:33792
	ds_read_b128 v[196:199], v153 offset:34816
	ds_read_b128 v[200:203], v153 offset:35840
	ds_read_b128 v[204:207], v153 offset:36864
	ds_read_b128 v[208:211], v153 offset:37888
	ds_read_b128 v[212:215], v153 offset:38912
	ds_read_b128 v[216:219], v153 offset:39936
	s_mov_b32 m0, s38
	s_nop 0
	global_load_lds_dwordx4 v[222:223], off
	s_mov_b32 m0, s39
	s_nop 0
	global_load_lds_dwordx4 v[224:225], off
	s_mov_b32 m0, s40
	s_nop 0
	global_load_lds_dwordx4 v[226:227], off
	v_lshl_add_u64 v[226:227], s[22:23], 0, v[132:133]
	s_mov_b32 m0, s41
	s_nop 0
	global_load_lds_dwordx4 v[226:227], off
	s_waitcnt vmcnt(8)
	s_waitcnt lgkmcnt(0)
	s_barrier
	s_setprio 1
	s_waitcnt lgkmcnt(0)
	v_mfma_f32_16x16x32_bf16 v[124:127], v[144:147], v[184:187], v[124:127]
	v_mfma_f32_16x16x32_bf16 v[120:123], v[160:163], v[184:187], v[120:123]
	v_mfma_f32_16x16x32_bf16 v[108:111], v[144:147], v[196:199], v[108:111]
	v_mfma_f32_16x16x32_bf16 v[104:107], v[160:163], v[196:199], v[104:107]
	v_mfma_f32_16x16x32_bf16 v[92:95], v[144:147], v[204:207], v[92:95]
	v_mfma_f32_16x16x32_bf16 v[88:91], v[160:163], v[204:207], v[88:91]
	v_mfma_f32_16x16x32_bf16 v[76:79], v[144:147], v[212:215], v[76:79]
	v_mfma_f32_16x16x32_bf16 v[72:75], v[160:163], v[212:215], v[72:75]
	v_mfma_f32_16x16x32_bf16 v[124:127], v[156:159], v[188:191], v[124:127]
	v_mfma_f32_16x16x32_bf16 v[120:123], v[164:167], v[188:191], v[120:123]
	v_mfma_f32_16x16x32_bf16 v[108:111], v[156:159], v[200:203], v[108:111]
	v_mfma_f32_16x16x32_bf16 v[104:107], v[164:167], v[200:203], v[104:107]
	v_mfma_f32_16x16x32_bf16 v[92:95], v[156:159], v[208:211], v[92:95]
	v_mfma_f32_16x16x32_bf16 v[88:91], v[164:167], v[208:211], v[88:91]
	v_mfma_f32_16x16x32_bf16 v[76:79], v[156:159], v[216:219], v[76:79]
	v_mfma_f32_16x16x32_bf16 v[72:75], v[164:167], v[216:219], v[72:75]
	s_setprio 0
	s_setprio 1
	v_mfma_f32_16x16x32_bf16 v[116:119], v[168:171], v[184:187], v[116:119]
	v_mfma_f32_16x16x32_bf16 v[112:115], v[176:179], v[184:187], v[112:115]
	v_mfma_f32_16x16x32_bf16 v[100:103], v[168:171], v[196:199], v[100:103]
	v_mfma_f32_16x16x32_bf16 v[96:99], v[176:179], v[196:199], v[96:99]
	v_mfma_f32_16x16x32_bf16 v[84:87], v[168:171], v[204:207], v[84:87]
	v_mfma_f32_16x16x32_bf16 v[80:83], v[176:179], v[204:207], v[80:83]
	v_mfma_f32_16x16x32_bf16 v[68:71], v[168:171], v[212:215], v[68:71]
	v_mfma_f32_16x16x32_bf16 v[64:67], v[176:179], v[212:215], v[64:67]
	v_mfma_f32_16x16x32_bf16 v[116:119], v[172:175], v[188:191], v[116:119]
	v_mfma_f32_16x16x32_bf16 v[112:115], v[180:183], v[188:191], v[112:115]
	v_mfma_f32_16x16x32_bf16 v[100:103], v[172:175], v[200:203], v[100:103]
	v_mfma_f32_16x16x32_bf16 v[96:99], v[180:183], v[200:203], v[96:99]
	v_mfma_f32_16x16x32_bf16 v[84:87], v[172:175], v[208:211], v[84:87]
	v_mfma_f32_16x16x32_bf16 v[80:83], v[180:183], v[208:211], v[80:83]
	v_mfma_f32_16x16x32_bf16 v[68:71], v[172:175], v[216:219], v[68:71]
	v_mfma_f32_16x16x32_bf16 v[64:67], v[180:183], v[216:219], v[64:67]
	s_setprio 0
	s_barrier
	s_add_i32 s22, s57, s37
	v_lshl_add_u64 v[192:193], v[192:193], 0, s[16:17]
	s_mov_b32 m0, s22
	ds_read_b128 v[184:187], v153 offset:49152
	ds_read_b128 v[188:191], v153 offset:50176
	ds_read_b128 v[196:199], v153 offset:51200
	ds_read_b128 v[200:203], v153 offset:52224
	ds_read_b128 v[204:207], v153 offset:53248
	ds_read_b128 v[208:211], v153 offset:54272
	ds_read_b128 v[212:215], v153 offset:55296
	ds_read_b128 v[216:219], v153 offset:56320
	global_load_lds_dwordx4 v[192:193], off
	s_add_i32 m0, s22, 0x2000
	s_add_u32 s22, s26, 0xb0080
	v_lshl_add_u64 v[192:193], v[220:221], 0, s[16:17]
	s_addc_u32 s23, s27, 0
	s_add_i32 s26, s58, s37
	global_load_lds_dwordx4 v[192:193], off
	v_lshl_add_u64 v[192:193], s[22:23], 0, v[130:131]
	s_mov_b32 m0, s26
	s_nop 0
	global_load_lds_dwordx4 v[192:193], off
	v_lshl_add_u64 v[192:193], s[22:23], 0, v[134:135]
	s_add_i32 m0, s26, 0x2000
	s_nop 0
	global_load_lds_dwordx4 v[192:193], off
	s_mov_b32 s99, 1
	s_waitcnt vmcnt(6)
	s_waitcnt lgkmcnt(0)
	s_barrier
	s_setprio 1
	s_waitcnt lgkmcnt(0)
	v_mfma_f32_16x16x32_bf16 v[60:63], v[144:147], v[184:187], v[60:63]
	v_mfma_f32_16x16x32_bf16 v[56:59], v[160:163], v[184:187], v[56:59]
	v_mfma_f32_16x16x32_bf16 v[44:47], v[144:147], v[196:199], v[44:47]
	v_mfma_f32_16x16x32_bf16 v[40:43], v[160:163], v[196:199], v[40:43]
	v_mfma_f32_16x16x32_bf16 v[28:31], v[144:147], v[204:207], v[28:31]
	v_mfma_f32_16x16x32_bf16 v[24:27], v[160:163], v[204:207], v[24:27]
	v_mfma_f32_16x16x32_bf16 v[12:15], v[144:147], v[212:215], v[12:15]
	v_mfma_f32_16x16x32_bf16 v[8:11], v[160:163], v[212:215], v[8:11]
	v_mfma_f32_16x16x32_bf16 v[60:63], v[156:159], v[188:191], v[60:63]
	v_mfma_f32_16x16x32_bf16 v[56:59], v[164:167], v[188:191], v[56:59]
	v_mfma_f32_16x16x32_bf16 v[44:47], v[156:159], v[200:203], v[44:47]
	v_mfma_f32_16x16x32_bf16 v[40:43], v[164:167], v[200:203], v[40:43]
	v_mfma_f32_16x16x32_bf16 v[28:31], v[156:159], v[208:211], v[28:31]
	v_mfma_f32_16x16x32_bf16 v[24:27], v[164:167], v[208:211], v[24:27]
	v_mfma_f32_16x16x32_bf16 v[12:15], v[156:159], v[216:219], v[12:15]
	v_mfma_f32_16x16x32_bf16 v[8:11], v[164:167], v[216:219], v[8:11]
	s_setprio 0
	s_setprio 1
	v_mfma_f32_16x16x32_bf16 v[52:55], v[168:171], v[184:187], v[52:55]
	v_mfma_f32_16x16x32_bf16 v[48:51], v[176:179], v[184:187], v[48:51]
	v_mfma_f32_16x16x32_bf16 v[36:39], v[168:171], v[196:199], v[36:39]
	v_mfma_f32_16x16x32_bf16 v[32:35], v[176:179], v[196:199], v[32:35]
	v_mfma_f32_16x16x32_bf16 v[20:23], v[168:171], v[204:207], v[20:23]
	v_mfma_f32_16x16x32_bf16 v[16:19], v[176:179], v[204:207], v[16:19]
	v_mfma_f32_16x16x32_bf16 v[4:7], v[168:171], v[212:215], v[4:7]
	v_mfma_f32_16x16x32_bf16 v[0:3], v[176:179], v[212:215], v[0:3]
	v_mfma_f32_16x16x32_bf16 v[52:55], v[172:175], v[188:191], v[52:55]
	v_mfma_f32_16x16x32_bf16 v[48:51], v[180:183], v[188:191], v[48:51]
	v_mfma_f32_16x16x32_bf16 v[36:39], v[172:175], v[200:203], v[36:39]
	v_mfma_f32_16x16x32_bf16 v[32:35], v[180:183], v[200:203], v[32:35]
	v_mfma_f32_16x16x32_bf16 v[20:23], v[172:175], v[208:211], v[20:23]
	v_mfma_f32_16x16x32_bf16 v[16:19], v[180:183], v[208:211], v[16:19]
	v_mfma_f32_16x16x32_bf16 v[4:7], v[172:175], v[216:219], v[4:7]
	v_mfma_f32_16x16x32_bf16 v[0:3], v[180:183], v[216:219], v[0:3]
	s_setprio 0
	s_barrier
	s_add_i32 s56, s56, 2
	s_add_u32 s54, s54, 0x100
	s_addc_u32 s55, s55, 0
	s_cmp_gt_u32 s56, 41
	s_mov_b64 s[22:23], s[24:25]
	s_cbranch_scc0 .LBB0_3401
	v_lshl_add_u64 v[222:223], v[222:223], 0, s[16:17]
	s_mov_b32 m0, s43
	s_nop 0
	global_load_lds_dwordx4 v[222:223], off
	v_lshl_add_u64 v[224:225], v[224:225], 0, s[16:17]
	s_mov_b32 m0, s44
	s_nop 0
	global_load_lds_dwordx4 v[224:225], off
	s_and_b64 vcc, exec, s[18:19]
	s_cbranch_vccz .LBB0_3404
	s_barrier
